# static priority: one s_setprio 1 for waves 4-7 at kernel entry, all per-segment s_setprio flips in the GEMM K-loops removed
# baseline (speedup 1.0000x reference)
; #define LAS __attribute__((address_space(3)))
; __device__ __forceinline__ unsigned xb_xcc_id() { return (unsigned)__builtin_amdgcn_s_getreg((3 << 11) | 20) & 0xFu; }
; #define tid  (fresh_tid_w(wave_s))
; #define ws   (fresh_ptr(a.ws))
; __global__ void __launch_bounds__(512, 2) fwd_megakernel(Args a) {
;     extern __shared__ __attribute__((aligned(16))) unsigned char lds_raw[];
;     LAS unsigned char* lds = (LAS unsigned char*)lds_raw;
;     cg::grid_group grid = cg::this_grid();
;     const int wave_s = __builtin_amdgcn_readfirstlane((int)threadIdx.x >> 6);
;     ...
;     const int G = gridDim.x, bx = blockIdx.x, NGW = G * 8;
;     ...
;     float* hres = a.out;
;     unsigned* barw = (unsigned*)ws;
;     if (bx == 0) for (int i = tid; i < GB_XCCTAB; i += 512) __hip_atomic_store(barw + i, 0u, __ATOMIC_RELAXED, __HIP_MEMORY_SCOPE_AGENT);
;     if (tid == 0) __hip_atomic_store(barw + GB_XCCTAB + bx, xb_xcc_id() + 1u, __ATOMIC_RELAXED, __HIP_MEMORY_SCOPE_AGENT);
;     volatile LAS unsigned* bst = (volatile LAS unsigned*)(lds + MISC_OFF);
;     if (tid == 0) { bst[0] = 0u; bst[1] = 0u; }
_Z14fwd_megakernel4Args:
	v_mov_b32_e32 v1, 0
	global_load_dword v1, v1, s[0:1] offset:206
	s_load_dwordx16 s[44:59], s[0:1], 0x80
	s_load_dword s60, s[0:1], 0xc8
	s_load_dwordx2 s[8:9], s[0:1], 0xc0
	v_and_b32_e32 v34, 0x3ff, v0
	s_add_u32 s6, s0, 0xc0
	v_readfirstlane_b32 s14, v34
	s_waitcnt lgkmcnt(0)
	s_mov_b64 s[4:5], s[58:59]
	s_mov_b32 s92, s2
	s_addc_u32 s7, s1, 0
	s_and_b32 s2, s14, 0xffffffc0
	s_cmp_lt_u32 s2, 0x100
	s_cbranch_scc1 .Lprio_done
	s_setprio 1
.Lprio_done:
	v_writelane_b32 v253, s4, 0
	s_cmp_lg_u32 s92, 0
	s_waitcnt vmcnt(0)
	v_readfirstlane_b32 s62, v1
	v_writelane_b32 v253, s5, 1
	s_cbranch_scc1 .LBB0_5
	v_mbcnt_lo_u32_b32 v1, -1, 0
	v_mbcnt_hi_u32_b32 v1, -1, v1
	s_movk_i32 s3, 0x2000
	v_or_b32_e32 v2, s2, v1
	s_nop 0
	v_cmp_gt_i32_e32 vcc, s3, v2
	s_and_saveexec_b64 s[4:5], vcc
	s_cbranch_execz .LBB0_4
	v_readlane_b32 s10, v253, 0
	v_ashrrev_i32_e32 v3, 31, v2
	v_readlane_b32 s11, v253, 1
	v_add_u32_e32 v1, 0xfffffe00, v2
	v_mov_b32_e32 v4, 0
	v_lshl_add_u64 v[2:3], v[2:3], 2, s[10:11]
	s_mov_b64 s[10:11], 0
	s_mov_b64 s[12:13], 0x800
	s_movk_i32 s3, 0x1dff

; #define PG8_STAGE(bufoff, gbase, voff) do { _Pragma("unroll") for (int _i = 0; _i < 2; ++_i) \
;         __builtin_amdgcn_global_load_lds((const unsigned*)((const char*)(gbase) + (voff)[_i]), (PG8_LAS unsigned*)(lds + (bufoff) + ldsw + _i * 8192), 16, 0, 0); } while (0)
; #define PG8_LDA(dst, b, h) do { _Pragma("unroll") for (int m = 0; m < 4; ++m) _Pragma("unroll") for (int k = 0; k < 2; ++k) dst[m][k] = *(const PG8_LAS bf16x8*)(lds + PG8_SA(b, h) + aoff + m * 2048 + k * 1024); } while (0)
; #define PG8_LDB(dst, b, h) do { _Pragma("unroll") for (int n = 0; n < 2; ++n) _Pragma("unroll") for (int k = 0; k < 2; ++k) dst[n][k] = *(const PG8_LAS bf16x8*)(lds + PG8_SB(b, h) + boff + n * 2048 + k * 1024); } while (0)
; #define PG8_MMA(ai, bj, At, Bt) do { __builtin_amdgcn_s_setprio(1); _Pragma("unroll") for (int m = 0; m < 4; ++m) _Pragma("unroll") for (int n = 0; n < 2; ++n) _Pragma("unroll") for (int k = 0; k < 2; ++k) \
;         acc[ai][bj][m][n] = __builtin_amdgcn_mfma_f32_16x16x32_bf16(Bt[n][k], At[m][k], acc[ai][bj][m][n], 0, 0, 0); __builtin_amdgcn_s_setprio(0); } while (0)
; template <class Epi, class Sched, bool ALIGN_EPI = false, bool SP2 = false>
; __device__ __forceinline__ void gemm_phase(PG8_LAS unsigned char* lds, const Gemm g, const Sched& S, const Epi& E, int wave_in) {
;     ...
;         const char* nA = has_next ? (const char*)g.A + (size_t)(nxt.pm >> g.ash) * g.astride + (size_t)nxt.pm * tstep : cA; const char* nB = has_next ? (const char*)g.Bt + (size_t)(nxt.pm >> g.bsh) * g.bstride + (size_t)nxt.pn * tstep : cB;
;         for (int t = 0; t < nt; t += 2) {
;             const bool last = (t == nt - 2);
;             const char* a1 = cA + (size_t)(t + 1) * kstep;
;             const char* a2 = last ? nA : cA + (size_t)(t + 2) * kstep; const char* b2 = last ? nB : cB + (size_t)(t + 2) * kstep;
;             const char* a3 = a2 + kstep; const char* b3 = b2 + kstep;
;             if (last && has_next) S.a_ready(nxt);
;             if constexpr (SP2) {
;             PG8_LDB(B0, 0, 0); PG8_LDB(B1, 0, 1); PG8_SCHED; PG8_LDA(At, 0, 0); PG8_STAGE(PG8_SA(1, 1), a1 + hstep, voffA);
;             PG8_WAIT_V(8); PG8_WAIT_L(0); PG8_BAR; PG8_MMA(0, 0, At, B0); PG8_MMA(0, 1, At, B1); PG8_BAR; PG8_SCHED;
;             PG8_LDA(At, 0, 1); PG8_STAGE(PG8_SB(0, 0), b2, voffB); PG8_STAGE(PG8_SB(0, 1), b2 + hstep, voffB); PG8_STAGE(PG8_SA(0, 0), a2, voffA);
.LBB0_253:
	s_ashr_i32 s23, s22, 31
	s_lshl_b64 s[24:25], s[22:23], 19
	s_add_u32 s24, s62, s24
	s_addc_u32 s25, s63, s25
	s_and_b64 s[26:27], s[18:19], exec
	s_cselect_b32 s23, s25, s37
	s_cselect_b32 s29, s24, s36
	s_ashr_i32 s21, s20, 31
	s_lshl_b64 s[26:27], s[20:21], 19
	s_add_u32 s26, s64, s26
	s_addc_u32 s27, s65, s27
	s_and_b64 s[38:39], s[18:19], exec
	s_cselect_b32 s21, s27, s35
	s_cselect_b32 s31, s26, s34
	s_add_u32 s76, s34, 0x100
	s_addc_u32 s77, s35, 0
	s_add_u32 s34, s36, 0x40080
	s_addc_u32 s35, s37, 0
	s_mov_b32 s78, -2
	v_add_u32_e32 v174, s43, v160
	v_add_u32_e32 v190, s44, v160
	ds_read_b128 v[162:165], v174
	ds_read_b128 v[166:169], v174 offset:1024
	ds_read_b128 v[170:173], v174 offset:2048
	ds_read_b128 v[174:177], v174 offset:3072
	ds_read_b128 v[178:181], v190
	ds_read_b128 v[182:185], v190 offset:1024
	ds_read_b128 v[186:189], v190 offset:2048
	ds_read_b128 v[190:193], v190 offset:3072
	s_add_u32 s36, s34, 0xfffc0080
	s_addc_u32 s37, s35, -1
	s_cmp_eq_u32 s78, 12
	s_cselect_b32 s39, s23, s37
	s_cselect_b32 s38, s29, s36
	s_cselect_b32 s37, s21, s77
	s_cselect_b32 s36, s31, s76
	v_lshl_add_u64 v[226:227], s[34:35], 0, v[156:157]
	s_add_i32 m0, s67, 0xc000
	ds_read_b128 v[194:197], v161
	ds_read_b128 v[198:201], v161 offset:1024
	ds_read_b128 v[202:205], v161 offset:2048
	ds_read_b128 v[206:209], v161 offset:3072
	ds_read_b128 v[210:213], v161 offset:4096
	ds_read_b128 v[214:217], v161 offset:5120
	ds_read_b128 v[218:221], v161 offset:6144
	ds_read_b128 v[222:225], v161 offset:7168
	global_load_lds_dwordx4 v[226:227], off
	v_lshl_add_u64 v[226:227], s[34:35], 0, v[154:155]
	s_add_i32 m0, s67, 0xe000
	s_nop 0
	global_load_lds_dwordx4 v[226:227], off
	s_waitcnt vmcnt(8)
	s_waitcnt lgkmcnt(0)
	s_barrier
	s_waitcnt lgkmcnt(0)
	v_mfma_f32_16x16x32_bf16 v[124:127], v[162:165], v[194:197], 0
	v_mfma_f32_16x16x32_bf16 v[120:123], v[170:173], v[194:197], 0
	v_mfma_f32_16x16x32_bf16 v[116:119], v[162:165], v[202:205], 0
	v_mfma_f32_16x16x32_bf16 v[108:111], v[170:173], v[202:205], 0
	v_mfma_f32_16x16x32_bf16 v[100:103], v[162:165], v[210:213], 0
	v_mfma_f32_16x16x32_bf16 v[92:95], v[170:173], v[210:213], 0
	v_mfma_f32_16x16x32_bf16 v[84:87], v[162:165], v[218:221], 0
	v_mfma_f32_16x16x32_bf16 v[76:79], v[170:173], v[218:221], 0
	v_mfma_f32_16x16x32_bf16 v[124:127], v[166:169], v[198:201], v[124:127]
	v_mfma_f32_16x16x32_bf16 v[120:123], v[174:177], v[198:201], v[120:123]
	v_mfma_f32_16x16x32_bf16 v[116:119], v[166:169], v[206:209], v[116:119]
	v_mfma_f32_16x16x32_bf16 v[108:111], v[174:177], v[206:209], v[108:111]
	v_mfma_f32_16x16x32_bf16 v[100:103], v[166:169], v[214:217], v[100:103]
	v_mfma_f32_16x16x32_bf16 v[92:95], v[174:177], v[214:217], v[92:95]
	v_mfma_f32_16x16x32_bf16 v[84:87], v[166:169], v[222:225], v[84:87]
	v_mfma_f32_16x16x32_bf16 v[76:79], v[174:177], v[222:225], v[76:79]
	v_mfma_f32_16x16x32_bf16 v[112:115], v[178:181], v[194:197], 0
	v_mfma_f32_16x16x32_bf16 v[104:107], v[186:189], v[194:197], 0
	v_mfma_f32_16x16x32_bf16 v[96:99], v[178:181], v[202:205], 0
	v_mfma_f32_16x16x32_bf16 v[88:91], v[186:189], v[202:205], 0
	v_mfma_f32_16x16x32_bf16 v[80:83], v[178:181], v[210:213], 0
	v_mfma_f32_16x16x32_bf16 v[72:75], v[186:189], v[210:213], 0
	v_mfma_f32_16x16x32_bf16 v[68:71], v[178:181], v[218:221], 0
	v_mfma_f32_16x16x32_bf16 v[64:67], v[186:189], v[218:221], 0
	v_mfma_f32_16x16x32_bf16 v[112:115], v[182:185], v[198:201], v[112:115]
	v_mfma_f32_16x16x32_bf16 v[104:107], v[190:193], v[198:201], v[104:107]
	v_mfma_f32_16x16x32_bf16 v[96:99], v[182:185], v[206:209], v[96:99]
	v_mfma_f32_16x16x32_bf16 v[88:91], v[190:193], v[206:209], v[88:91]
	v_mfma_f32_16x16x32_bf16 v[80:83], v[182:185], v[214:217], v[80:83]
	v_mfma_f32_16x16x32_bf16 v[72:75], v[190:193], v[214:217], v[72:75]
	v_mfma_f32_16x16x32_bf16 v[68:71], v[182:185], v[222:225], v[68:71]
	v_mfma_f32_16x16x32_bf16 v[64:67], v[190:193], v[222:225], v[64:67]
	s_barrier
	s_add_i32 s79, s43, s66
	v_lshl_add_u64 v[226:227], s[36:37], 0, v[132:133]
	s_mov_b32 m0, s79
	ds_read_b128 v[194:197], v161 offset:16384
	ds_read_b128 v[198:201], v161 offset:17408
	ds_read_b128 v[202:205], v161 offset:18432
	ds_read_b128 v[206:209], v161 offset:19456
	ds_read_b128 v[210:213], v161 offset:20480
	ds_read_b128 v[214:217], v161 offset:21504
	ds_read_b128 v[218:221], v161 offset:22528
	ds_read_b128 v[222:225], v161 offset:23552
	global_load_lds_dwordx4 v[226:227], off
	s_add_i32 m0, s79, 0x2000
	s_add_u32 s80, s36, 0x40000
	v_lshl_add_u64 v[228:229], s[36:37], 0, v[136:137]
	s_addc_u32 s81, s37, 0
	s_add_i32 s79, s44, s66
	global_load_lds_dwordx4 v[228:229], off
	v_lshl_add_u64 v[230:231], s[80:81], 0, v[132:133]
	s_mov_b32 m0, s79
	v_lshl_add_u64 v[232:233], s[38:39], 0, v[134:135]
	global_load_lds_dwordx4 v[230:231], off
	v_lshl_add_u64 v[230:231], s[80:81], 0, v[136:137]
	s_add_i32 m0, s79, 0x2000
	s_nop 0
	global_load_lds_dwordx4 v[230:231], off
	v_lshl_add_u64 v[230:231], s[38:39], 0, v[130:131]
	s_mov_b32 m0, s67
	s_nop 0
	global_load_lds_dwordx4 v[230:231], off
	s_mov_b32 m0, s68
	s_nop 0
	global_load_lds_dwordx4 v[232:233], off
	s_waitcnt vmcnt(8)
	s_waitcnt lgkmcnt(0)
	s_barrier
; #define PG8_STAGE(bufoff, gbase, voff) do { _Pragma("unroll") for (int _i = 0; _i < 2; ++_i) \
;         __builtin_amdgcn_global_load_lds((const unsigned*)((const char*)(gbase) + (voff)[_i]), (PG8_LAS unsigned*)(lds + (bufoff) + ldsw + _i * 8192), 16, 0, 0); } while (0)
; #define PG8_LDA(dst, b, h) do { _Pragma("unroll") for (int m = 0; m < 4; ++m) _Pragma("unroll") for (int k = 0; k < 2; ++k) dst[m][k] = *(const PG8_LAS bf16x8*)(lds + PG8_SA(b, h) + aoff + m * 2048 + k * 1024); } while (0)
; #define PG8_LDB(dst, b, h) do { _Pragma("unroll") for (int n = 0; n < 2; ++n) _Pragma("unroll") for (int k = 0; k < 2; ++k) dst[n][k] = *(const PG8_LAS bf16x8*)(lds + PG8_SB(b, h) + boff + n * 2048 + k * 1024); } while (0)
; #define PG8_MMA(ai, bj, At, Bt) do { __builtin_amdgcn_s_setprio(1); _Pragma("unroll") for (int m = 0; m < 4; ++m) _Pragma("unroll") for (int n = 0; n < 2; ++n) _Pragma("unroll") for (int k = 0; k < 2; ++k) \
;         acc[ai][bj][m][n] = __builtin_amdgcn_mfma_f32_16x16x32_bf16(Bt[n][k], At[m][k], acc[ai][bj][m][n], 0, 0, 0); __builtin_amdgcn_s_setprio(0); } while (0)
; #define PG8_WAIT_V(n) asm volatile("s_waitcnt vmcnt(" #n ")" ::: "memory")
; #define PG8_WAIT_L(n) asm volatile("s_waitcnt lgkmcnt(" #n ")" ::: "memory")
; #define PG8_BAR __builtin_amdgcn_s_barrier()
; #define PG8_SCHED __builtin_amdgcn_sched_barrier(0)
; template <class Epi, class Sched, bool ALIGN_EPI = false, bool SP2 = false>
; __device__ __forceinline__ void gemm_phase(PG8_LAS unsigned char* lds, const Gemm g, const Sched& S, const Epi& E, int wave_in) {
;     ...
;             PG8_WAIT_V(8); PG8_WAIT_L(0); PG8_BAR; PG8_MMA(1, 0, At, B0); PG8_MMA(1, 1, At, B1); PG8_BAR; PG8_SCHED;
;             PG8_LDB(B0, 1, 0); PG8_LDB(B1, 1, 1); PG8_SCHED; PG8_LDA(At, 1, 0); PG8_STAGE(PG8_SA(0, 1), a2 + hstep, voffA);
;             PG8_WAIT_V(8); PG8_WAIT_L(0); PG8_BAR; PG8_MMA(0, 0, At, B0); PG8_MMA(0, 1, At, B1); PG8_BAR; PG8_SCHED;
	s_waitcnt lgkmcnt(0)
	v_mfma_f32_16x16x32_bf16 v[60:63], v[162:165], v[194:197], 0
	v_mfma_f32_16x16x32_bf16 v[56:59], v[170:173], v[194:197], 0
	v_mfma_f32_16x16x32_bf16 v[52:55], v[162:165], v[202:205], 0
	v_mfma_f32_16x16x32_bf16 v[44:47], v[170:173], v[202:205], 0
	v_mfma_f32_16x16x32_bf16 v[36:39], v[162:165], v[210:213], 0
	v_mfma_f32_16x16x32_bf16 v[28:31], v[170:173], v[210:213], 0
	v_mfma_f32_16x16x32_bf16 v[20:23], v[162:165], v[218:221], 0
	v_mfma_f32_16x16x32_bf16 v[12:15], v[170:173], v[218:221], 0
	v_mfma_f32_16x16x32_bf16 v[60:63], v[166:169], v[198:201], v[60:63]
	v_mfma_f32_16x16x32_bf16 v[56:59], v[174:177], v[198:201], v[56:59]
	v_mfma_f32_16x16x32_bf16 v[52:55], v[166:169], v[206:209], v[52:55]
	v_mfma_f32_16x16x32_bf16 v[44:47], v[174:177], v[206:209], v[44:47]
	v_mfma_f32_16x16x32_bf16 v[36:39], v[166:169], v[214:217], v[36:39]
	v_mfma_f32_16x16x32_bf16 v[28:31], v[174:177], v[214:217], v[28:31]
	v_mfma_f32_16x16x32_bf16 v[20:23], v[166:169], v[222:225], v[20:23]
	v_mfma_f32_16x16x32_bf16 v[12:15], v[174:177], v[222:225], v[12:15]
	v_mfma_f32_16x16x32_bf16 v[48:51], v[178:181], v[194:197], 0
	v_mfma_f32_16x16x32_bf16 v[40:43], v[186:189], v[194:197], 0
	v_mfma_f32_16x16x32_bf16 v[32:35], v[178:181], v[202:205], 0
	v_mfma_f32_16x16x32_bf16 v[24:27], v[186:189], v[202:205], 0
	v_mfma_f32_16x16x32_bf16 v[16:19], v[178:181], v[210:213], 0
	v_mfma_f32_16x16x32_bf16 v[8:11], v[186:189], v[210:213], 0
	v_mfma_f32_16x16x32_bf16 v[4:7], v[178:181], v[218:221], 0
	v_mfma_f32_16x16x32_bf16 v[0:3], v[186:189], v[218:221], 0
	v_mfma_f32_16x16x32_bf16 v[48:51], v[182:185], v[198:201], v[48:51]
	v_mfma_f32_16x16x32_bf16 v[40:43], v[190:193], v[198:201], v[40:43]
	v_mfma_f32_16x16x32_bf16 v[32:35], v[182:185], v[206:209], v[32:35]
	v_mfma_f32_16x16x32_bf16 v[24:27], v[190:193], v[206:209], v[24:27]
	v_mfma_f32_16x16x32_bf16 v[16:19], v[182:185], v[214:217], v[16:19]
	v_mfma_f32_16x16x32_bf16 v[8:11], v[190:193], v[214:217], v[8:11]
	v_mfma_f32_16x16x32_bf16 v[4:7], v[182:185], v[222:225], v[4:7]
	v_mfma_f32_16x16x32_bf16 v[0:3], v[190:193], v[222:225], v[0:3]
	s_barrier
	v_add_u32_e32 v174, s45, v160
	v_add_u32_e32 v190, s46, v160
	ds_read_b128 v[162:165], v174
	ds_read_b128 v[166:169], v174 offset:1024
	ds_read_b128 v[170:173], v174 offset:2048
	ds_read_b128 v[174:177], v174 offset:3072
	ds_read_b128 v[178:181], v190
	ds_read_b128 v[182:185], v190 offset:1024
	ds_read_b128 v[186:189], v190 offset:2048
	ds_read_b128 v[190:193], v190 offset:3072
	s_add_u32 s38, s38, 0x40000
	s_addc_u32 s39, s39, 0
	s_mov_b32 m0, s69
	v_lshl_add_u64 v[234:235], s[38:39], 0, v[130:131]
	ds_read_b128 v[194:197], v161 offset:32768
	ds_read_b128 v[198:201], v161 offset:33792
	ds_read_b128 v[202:205], v161 offset:34816
	ds_read_b128 v[206:209], v161 offset:35840
	ds_read_b128 v[210:213], v161 offset:36864
	ds_read_b128 v[214:217], v161 offset:37888
	ds_read_b128 v[218:221], v161 offset:38912
	ds_read_b128 v[222:225], v161 offset:39936
	global_load_lds_dwordx4 v[234:235], off
	v_lshl_add_u64 v[234:235], s[38:39], 0, v[134:135]
	s_mov_b32 m0, s70
	s_nop 0
	global_load_lds_dwordx4 v[234:235], off
	s_waitcnt vmcnt(8)
	s_waitcnt lgkmcnt(0)
	s_barrier
	s_waitcnt lgkmcnt(0)
	v_mfma_f32_16x16x32_bf16 v[124:127], v[162:165], v[194:197], v[124:127]
	v_mfma_f32_16x16x32_bf16 v[120:123], v[170:173], v[194:197], v[120:123]
	v_mfma_f32_16x16x32_bf16 v[116:119], v[162:165], v[202:205], v[116:119]
	v_mfma_f32_16x16x32_bf16 v[108:111], v[170:173], v[202:205], v[108:111]
	v_mfma_f32_16x16x32_bf16 v[100:103], v[162:165], v[210:213], v[100:103]
	v_mfma_f32_16x16x32_bf16 v[92:95], v[170:173], v[210:213], v[92:95]
	v_mfma_f32_16x16x32_bf16 v[84:87], v[162:165], v[218:221], v[84:87]
	v_mfma_f32_16x16x32_bf16 v[76:79], v[170:173], v[218:221], v[76:79]
	v_mfma_f32_16x16x32_bf16 v[124:127], v[166:169], v[198:201], v[124:127]
	v_mfma_f32_16x16x32_bf16 v[120:123], v[174:177], v[198:201], v[120:123]
	v_mfma_f32_16x16x32_bf16 v[116:119], v[166:169], v[206:209], v[116:119]
	v_mfma_f32_16x16x32_bf16 v[108:111], v[174:177], v[206:209], v[108:111]
	v_mfma_f32_16x16x32_bf16 v[100:103], v[166:169], v[214:217], v[100:103]
	v_mfma_f32_16x16x32_bf16 v[92:95], v[174:177], v[214:217], v[92:95]
	v_mfma_f32_16x16x32_bf16 v[84:87], v[166:169], v[222:225], v[84:87]
	v_mfma_f32_16x16x32_bf16 v[76:79], v[174:177], v[222:225], v[76:79]
	v_mfma_f32_16x16x32_bf16 v[112:115], v[178:181], v[194:197], v[112:115]
	v_mfma_f32_16x16x32_bf16 v[104:107], v[186:189], v[194:197], v[104:107]
	v_mfma_f32_16x16x32_bf16 v[96:99], v[178:181], v[202:205], v[96:99]
	v_mfma_f32_16x16x32_bf16 v[88:91], v[186:189], v[202:205], v[88:91]
	v_mfma_f32_16x16x32_bf16 v[80:83], v[178:181], v[210:213], v[80:83]
	v_mfma_f32_16x16x32_bf16 v[72:75], v[186:189], v[210:213], v[72:75]
	v_mfma_f32_16x16x32_bf16 v[68:71], v[178:181], v[218:221], v[68:71]
	v_mfma_f32_16x16x32_bf16 v[64:67], v[186:189], v[218:221], v[64:67]
	v_mfma_f32_16x16x32_bf16 v[112:115], v[182:185], v[198:201], v[112:115]
	v_mfma_f32_16x16x32_bf16 v[104:107], v[190:193], v[198:201], v[104:107]
	v_mfma_f32_16x16x32_bf16 v[96:99], v[182:185], v[206:209], v[96:99]
	v_mfma_f32_16x16x32_bf16 v[88:91], v[190:193], v[206:209], v[88:91]
	v_mfma_f32_16x16x32_bf16 v[80:83], v[182:185], v[214:217], v[80:83]
	v_mfma_f32_16x16x32_bf16 v[72:75], v[190:193], v[214:217], v[72:75]
	v_mfma_f32_16x16x32_bf16 v[68:71], v[182:185], v[222:225], v[68:71]
	v_mfma_f32_16x16x32_bf16 v[64:67], v[190:193], v[222:225], v[64:67]
	s_barrier
; #define PG8_STAGE(bufoff, gbase, voff) do { _Pragma("unroll") for (int _i = 0; _i < 2; ++_i) \
;         __builtin_amdgcn_global_load_lds((const unsigned*)((const char*)(gbase) + (voff)[_i]), (PG8_LAS unsigned*)(lds + (bufoff) + ldsw + _i * 8192), 16, 0, 0); } while (0)
; #define PG8_LDA(dst, b, h) do { _Pragma("unroll") for (int m = 0; m < 4; ++m) _Pragma("unroll") for (int k = 0; k < 2; ++k) dst[m][k] = *(const PG8_LAS bf16x8*)(lds + PG8_SA(b, h) + aoff + m * 2048 + k * 1024); } while (0)
; #define PG8_LDB(dst, b, h) do { _Pragma("unroll") for (int n = 0; n < 2; ++n) _Pragma("unroll") for (int k = 0; k < 2; ++k) dst[n][k] = *(const PG8_LAS bf16x8*)(lds + PG8_SB(b, h) + boff + n * 2048 + k * 1024); } while (0)
; #define PG8_MMA(ai, bj, At, Bt) do { __builtin_amdgcn_s_setprio(1); _Pragma("unroll") for (int m = 0; m < 4; ++m) _Pragma("unroll") for (int n = 0; n < 2; ++n) _Pragma("unroll") for (int k = 0; k < 2; ++k) \
;         acc[ai][bj][m][n] = __builtin_amdgcn_mfma_f32_16x16x32_bf16(Bt[n][k], At[m][k], acc[ai][bj][m][n], 0, 0, 0); __builtin_amdgcn_s_setprio(0); } while (0)
; #define PG8_BAR __builtin_amdgcn_s_barrier()
; template <class Epi, class Sched, bool ALIGN_EPI = false, bool SP2 = false>
; __device__ __forceinline__ void gemm_phase(PG8_LAS unsigned char* lds, const Gemm g, const Sched& S, const Epi& E, int wave_in) {
;     ...
;             PG8_LDB(B0, 0, 0); PG8_LDB(B1, 0, 1); PG8_SCHED; PG8_LDA(At, 0, 0); PG8_STAGE(PG8_SA(1, 1), a1 + hstep, voffA);
;             PG8_WAIT_V(8); PG8_WAIT_L(0); PG8_BAR; PG8_MMA(0, 0, At, B0); PG8_MMA(0, 1, At, B1); PG8_BAR; PG8_SCHED;
;             PG8_LDA(At, 0, 1); PG8_STAGE(PG8_SB(0, 0), b2, voffB); PG8_STAGE(PG8_SB(0, 1), b2 + hstep, voffB); PG8_STAGE(PG8_SA(0, 0), a2, voffA);
;             PG8_WAIT_V(8); PG8_WAIT_L(0); PG8_BAR; PG8_MMA(1, 0, At, B0); PG8_MMA(1, 1, At, B1); PG8_BAR; PG8_SCHED;
;             PG8_LDB(B0, 1, 0); PG8_LDB(B1, 1, 1); PG8_SCHED; PG8_LDA(At, 1, 0); PG8_STAGE(PG8_SA(0, 1), a2 + hstep, voffA);
;             PG8_WAIT_V(8); PG8_WAIT_L(0); PG8_BAR; PG8_MMA(0, 0, At, B0); PG8_MMA(0, 1, At, B1); PG8_BAR; PG8_SCHED;
;             PG8_LDA(At, 1, 1); PG8_STAGE(PG8_SB(1, 0), b3, voffB); PG8_STAGE(PG8_SB(1, 1), b3 + hstep, voffB); PG8_STAGE(PG8_SA(1, 0), a3, voffA);
;             PG8_WAIT_V(8); PG8_WAIT_L(0); PG8_BAR; PG8_MMA(1, 0, At, B0); PG8_MMA(1, 1, At, B1); PG8_BAR; PG8_SCHED;
	s_add_i32 s38, s45, s66
	v_lshl_add_u64 v[226:227], v[226:227], 0, s[6:7]
	s_mov_b32 m0, s38
	ds_read_b128 v[194:197], v161 offset:49152
	ds_read_b128 v[198:201], v161 offset:50176
	ds_read_b128 v[202:205], v161 offset:51200
	ds_read_b128 v[206:209], v161 offset:52224
	ds_read_b128 v[210:213], v161 offset:53248
	ds_read_b128 v[214:217], v161 offset:54272
	ds_read_b128 v[218:221], v161 offset:55296
	ds_read_b128 v[222:225], v161 offset:56320
	global_load_lds_dwordx4 v[226:227], off
	s_add_i32 m0, s38, 0x2000
	s_add_u32 s36, s36, 0x40080
	v_lshl_add_u64 v[226:227], v[228:229], 0, s[6:7]
	s_addc_u32 s37, s37, 0
	s_add_i32 s38, s46, s66
	global_load_lds_dwordx4 v[226:227], off
	v_lshl_add_u64 v[226:227], s[36:37], 0, v[132:133]
	s_mov_b32 m0, s38
	s_nop 0
	global_load_lds_dwordx4 v[226:227], off
	v_lshl_add_u64 v[226:227], s[36:37], 0, v[136:137]
	s_add_i32 m0, s38, 0x2000
	s_nop 0
	global_load_lds_dwordx4 v[226:227], off
	v_lshl_add_u64 v[226:227], v[230:231], 0, s[6:7]
	s_mov_b32 m0, s73
	s_nop 0
	global_load_lds_dwordx4 v[226:227], off
	v_lshl_add_u64 v[226:227], v[232:233], 0, s[6:7]
	s_mov_b32 m0, s74
	s_nop 0
	global_load_lds_dwordx4 v[226:227], off
	s_waitcnt vmcnt(8)
	s_waitcnt lgkmcnt(0)
	s_barrier
	s_waitcnt lgkmcnt(0)
	v_mfma_f32_16x16x32_bf16 v[60:63], v[162:165], v[194:197], v[60:63]
	v_mfma_f32_16x16x32_bf16 v[56:59], v[170:173], v[194:197], v[56:59]
	v_mfma_f32_16x16x32_bf16 v[52:55], v[162:165], v[202:205], v[52:55]
	v_mfma_f32_16x16x32_bf16 v[44:47], v[170:173], v[202:205], v[44:47]
	v_mfma_f32_16x16x32_bf16 v[36:39], v[162:165], v[210:213], v[36:39]
	v_mfma_f32_16x16x32_bf16 v[28:31], v[170:173], v[210:213], v[28:31]
	v_mfma_f32_16x16x32_bf16 v[20:23], v[162:165], v[218:221], v[20:23]
	v_mfma_f32_16x16x32_bf16 v[12:15], v[170:173], v[218:221], v[12:15]
	v_mfma_f32_16x16x32_bf16 v[60:63], v[166:169], v[198:201], v[60:63]
	v_mfma_f32_16x16x32_bf16 v[56:59], v[174:177], v[198:201], v[56:59]
	v_mfma_f32_16x16x32_bf16 v[52:55], v[166:169], v[206:209], v[52:55]
	v_mfma_f32_16x16x32_bf16 v[44:47], v[174:177], v[206:209], v[44:47]
	v_mfma_f32_16x16x32_bf16 v[36:39], v[166:169], v[214:217], v[36:39]
	v_mfma_f32_16x16x32_bf16 v[28:31], v[174:177], v[214:217], v[28:31]
	v_mfma_f32_16x16x32_bf16 v[20:23], v[166:169], v[222:225], v[20:23]
	v_mfma_f32_16x16x32_bf16 v[12:15], v[174:177], v[222:225], v[12:15]
	v_mfma_f32_16x16x32_bf16 v[48:51], v[178:181], v[194:197], v[48:51]
	v_mfma_f32_16x16x32_bf16 v[40:43], v[186:189], v[194:197], v[40:43]
	v_mfma_f32_16x16x32_bf16 v[32:35], v[178:181], v[202:205], v[32:35]
	v_mfma_f32_16x16x32_bf16 v[24:27], v[186:189], v[202:205], v[24:27]
	v_mfma_f32_16x16x32_bf16 v[16:19], v[178:181], v[210:213], v[16:19]
	v_mfma_f32_16x16x32_bf16 v[8:11], v[186:189], v[210:213], v[8:11]
	v_mfma_f32_16x16x32_bf16 v[4:7], v[178:181], v[218:221], v[4:7]
	v_mfma_f32_16x16x32_bf16 v[0:3], v[186:189], v[218:221], v[0:3]
	v_mfma_f32_16x16x32_bf16 v[48:51], v[182:185], v[198:201], v[48:51]
	v_mfma_f32_16x16x32_bf16 v[40:43], v[190:193], v[198:201], v[40:43]
	v_mfma_f32_16x16x32_bf16 v[32:35], v[182:185], v[206:209], v[32:35]
	v_mfma_f32_16x16x32_bf16 v[24:27], v[190:193], v[206:209], v[24:27]
	v_mfma_f32_16x16x32_bf16 v[16:19], v[182:185], v[214:217], v[16:19]
	v_mfma_f32_16x16x32_bf16 v[8:11], v[190:193], v[214:217], v[8:11]
	v_mfma_f32_16x16x32_bf16 v[4:7], v[182:185], v[222:225], v[4:7]
	v_mfma_f32_16x16x32_bf16 v[0:3], v[190:193], v[222:225], v[0:3]
	s_barrier
	s_add_i32 s78, s78, 2
	s_add_u32 s76, s76, 0x100
	s_addc_u32 s77, s77, 0
	s_add_u32 s34, s34, 0x100
	s_addc_u32 s35, s35, 0
	s_cmp_gt_u32 s78, 13
	s_cbranch_scc1 .Lkexit_0
.LBB0_254:
	v_add_u32_e32 v174, s43, v160
	v_add_u32_e32 v190, s44, v160
	ds_read_b128 v[162:165], v174
	ds_read_b128 v[166:169], v174 offset:1024
	ds_read_b128 v[170:173], v174 offset:2048
	ds_read_b128 v[174:177], v174 offset:3072
	ds_read_b128 v[178:181], v190
	ds_read_b128 v[182:185], v190 offset:1024
	ds_read_b128 v[186:189], v190 offset:2048
	ds_read_b128 v[190:193], v190 offset:3072
	s_add_u32 s36, s34, 0xfffc0080
	s_addc_u32 s37, s35, -1
	s_cmp_eq_u32 s78, 12
	s_cselect_b32 s39, s23, s37
	s_cselect_b32 s38, s29, s36
	s_cselect_b32 s37, s21, s77
	s_cselect_b32 s36, s31, s76
	v_lshl_add_u64 v[226:227], s[34:35], 0, v[156:157]
	s_add_i32 m0, s67, 0xc000
	ds_read_b128 v[194:197], v161
	ds_read_b128 v[198:201], v161 offset:1024
	ds_read_b128 v[202:205], v161 offset:2048
	ds_read_b128 v[206:209], v161 offset:3072
	ds_read_b128 v[210:213], v161 offset:4096
	ds_read_b128 v[214:217], v161 offset:5120
	ds_read_b128 v[218:221], v161 offset:6144
	ds_read_b128 v[222:225], v161 offset:7168
	global_load_lds_dwordx4 v[226:227], off
	v_lshl_add_u64 v[226:227], s[34:35], 0, v[154:155]
	s_add_i32 m0, s67, 0xe000
	s_nop 0
	global_load_lds_dwordx4 v[226:227], off
	s_waitcnt vmcnt(8)
	s_waitcnt lgkmcnt(0)
	s_barrier
; #define PG8_STAGE(bufoff, gbase, voff) do { _Pragma("unroll") for (int _i = 0; _i < 2; ++_i) \
;         __builtin_amdgcn_global_load_lds((const unsigned*)((const char*)(gbase) + (voff)[_i]), (PG8_LAS unsigned*)(lds + (bufoff) + ldsw + _i * 8192), 16, 0, 0); } while (0)
; #define PG8_LDA(dst, b, h) do { _Pragma("unroll") for (int m = 0; m < 4; ++m) _Pragma("unroll") for (int k = 0; k < 2; ++k) dst[m][k] = *(const PG8_LAS bf16x8*)(lds + PG8_SA(b, h) + aoff + m * 2048 + k * 1024); } while (0)
; #define PG8_LDB(dst, b, h) do { _Pragma("unroll") for (int n = 0; n < 2; ++n) _Pragma("unroll") for (int k = 0; k < 2; ++k) dst[n][k] = *(const PG8_LAS bf16x8*)(lds + PG8_SB(b, h) + boff + n * 2048 + k * 1024); } while (0)
; #define PG8_MMA(ai, bj, At, Bt) do { __builtin_amdgcn_s_setprio(1); _Pragma("unroll") for (int m = 0; m < 4; ++m) _Pragma("unroll") for (int n = 0; n < 2; ++n) _Pragma("unroll") for (int k = 0; k < 2; ++k) \
;         acc[ai][bj][m][n] = __builtin_amdgcn_mfma_f32_16x16x32_bf16(Bt[n][k], At[m][k], acc[ai][bj][m][n], 0, 0, 0); __builtin_amdgcn_s_setprio(0); } while (0)
; #define PG8_WAIT_V(n) asm volatile("s_waitcnt vmcnt(" #n ")" ::: "memory")
; #define PG8_WAIT_L(n) asm volatile("s_waitcnt lgkmcnt(" #n ")" ::: "memory")
; #define PG8_BAR __builtin_amdgcn_s_barrier()
; #define PG8_SCHED __builtin_amdgcn_sched_barrier(0)
; template <class Epi, class Sched, bool ALIGN_EPI = false, bool SP2 = false>
; __device__ __forceinline__ void gemm_phase(PG8_LAS unsigned char* lds, const Gemm g, const Sched& S, const Epi& E, int wave_in) {
;     ...
;             PG8_WAIT_V(8); PG8_WAIT_L(0); PG8_BAR; PG8_MMA(0, 0, At, B0); PG8_MMA(0, 1, At, B1); PG8_BAR; PG8_SCHED;
;             PG8_LDA(At, 0, 1); PG8_STAGE(PG8_SB(0, 0), b2, voffB); PG8_STAGE(PG8_SB(0, 1), b2 + hstep, voffB); PG8_STAGE(PG8_SA(0, 0), a2, voffA);
;             PG8_WAIT_V(8); PG8_WAIT_L(0); PG8_BAR; PG8_MMA(1, 0, At, B0); PG8_MMA(1, 1, At, B1); PG8_BAR; PG8_SCHED;
;             PG8_LDB(B0, 1, 0); PG8_LDB(B1, 1, 1); PG8_SCHED; PG8_LDA(At, 1, 0); PG8_STAGE(PG8_SA(0, 1), a2 + hstep, voffA);
;             PG8_WAIT_V(8); PG8_WAIT_L(0); PG8_BAR; PG8_MMA(0, 0, At, B0); PG8_MMA(0, 1, At, B1); PG8_BAR; PG8_SCHED;
	s_waitcnt lgkmcnt(0)
	v_mfma_f32_16x16x32_bf16 v[124:127], v[162:165], v[194:197], v[124:127]
	v_mfma_f32_16x16x32_bf16 v[120:123], v[170:173], v[194:197], v[120:123]
	v_mfma_f32_16x16x32_bf16 v[116:119], v[162:165], v[202:205], v[116:119]
	v_mfma_f32_16x16x32_bf16 v[108:111], v[170:173], v[202:205], v[108:111]
	v_mfma_f32_16x16x32_bf16 v[100:103], v[162:165], v[210:213], v[100:103]
	v_mfma_f32_16x16x32_bf16 v[92:95], v[170:173], v[210:213], v[92:95]
	v_mfma_f32_16x16x32_bf16 v[84:87], v[162:165], v[218:221], v[84:87]
	v_mfma_f32_16x16x32_bf16 v[76:79], v[170:173], v[218:221], v[76:79]
	v_mfma_f32_16x16x32_bf16 v[124:127], v[166:169], v[198:201], v[124:127]
	v_mfma_f32_16x16x32_bf16 v[120:123], v[174:177], v[198:201], v[120:123]
	v_mfma_f32_16x16x32_bf16 v[116:119], v[166:169], v[206:209], v[116:119]
	v_mfma_f32_16x16x32_bf16 v[108:111], v[174:177], v[206:209], v[108:111]
	v_mfma_f32_16x16x32_bf16 v[100:103], v[166:169], v[214:217], v[100:103]
	v_mfma_f32_16x16x32_bf16 v[92:95], v[174:177], v[214:217], v[92:95]
	v_mfma_f32_16x16x32_bf16 v[84:87], v[166:169], v[222:225], v[84:87]
	v_mfma_f32_16x16x32_bf16 v[76:79], v[174:177], v[222:225], v[76:79]
	v_mfma_f32_16x16x32_bf16 v[112:115], v[178:181], v[194:197], v[112:115]
	v_mfma_f32_16x16x32_bf16 v[104:107], v[186:189], v[194:197], v[104:107]
	v_mfma_f32_16x16x32_bf16 v[96:99], v[178:181], v[202:205], v[96:99]
	v_mfma_f32_16x16x32_bf16 v[88:91], v[186:189], v[202:205], v[88:91]
	v_mfma_f32_16x16x32_bf16 v[80:83], v[178:181], v[210:213], v[80:83]
	v_mfma_f32_16x16x32_bf16 v[72:75], v[186:189], v[210:213], v[72:75]
	v_mfma_f32_16x16x32_bf16 v[68:71], v[178:181], v[218:221], v[68:71]
	v_mfma_f32_16x16x32_bf16 v[64:67], v[186:189], v[218:221], v[64:67]
	v_mfma_f32_16x16x32_bf16 v[112:115], v[182:185], v[198:201], v[112:115]
	v_mfma_f32_16x16x32_bf16 v[104:107], v[190:193], v[198:201], v[104:107]
	v_mfma_f32_16x16x32_bf16 v[96:99], v[182:185], v[206:209], v[96:99]
	v_mfma_f32_16x16x32_bf16 v[88:91], v[190:193], v[206:209], v[88:91]
	v_mfma_f32_16x16x32_bf16 v[80:83], v[182:185], v[214:217], v[80:83]
	v_mfma_f32_16x16x32_bf16 v[72:75], v[190:193], v[214:217], v[72:75]
	v_mfma_f32_16x16x32_bf16 v[68:71], v[182:185], v[222:225], v[68:71]
	v_mfma_f32_16x16x32_bf16 v[64:67], v[190:193], v[222:225], v[64:67]
	s_barrier
	s_add_i32 s79, s43, s66
	v_lshl_add_u64 v[226:227], s[36:37], 0, v[132:133]
	s_mov_b32 m0, s79
	ds_read_b128 v[194:197], v161 offset:16384
	ds_read_b128 v[198:201], v161 offset:17408
	ds_read_b128 v[202:205], v161 offset:18432
	ds_read_b128 v[206:209], v161 offset:19456
	ds_read_b128 v[210:213], v161 offset:20480
	ds_read_b128 v[214:217], v161 offset:21504
	ds_read_b128 v[218:221], v161 offset:22528
	ds_read_b128 v[222:225], v161 offset:23552
	global_load_lds_dwordx4 v[226:227], off
	s_add_i32 m0, s79, 0x2000
	s_add_u32 s80, s36, 0x40000
	v_lshl_add_u64 v[228:229], s[36:37], 0, v[136:137]
	s_addc_u32 s81, s37, 0
	s_add_i32 s79, s44, s66
	global_load_lds_dwordx4 v[228:229], off
	v_lshl_add_u64 v[230:231], s[80:81], 0, v[132:133]
	s_mov_b32 m0, s79
	v_lshl_add_u64 v[232:233], s[38:39], 0, v[134:135]
	global_load_lds_dwordx4 v[230:231], off
	v_lshl_add_u64 v[230:231], s[80:81], 0, v[136:137]
	s_add_i32 m0, s79, 0x2000
	s_nop 0
	global_load_lds_dwordx4 v[230:231], off
	v_lshl_add_u64 v[230:231], s[38:39], 0, v[130:131]
	s_mov_b32 m0, s67
	s_nop 0
	global_load_lds_dwordx4 v[230:231], off
	s_mov_b32 m0, s68
	s_nop 0
	global_load_lds_dwordx4 v[232:233], off
	s_waitcnt vmcnt(8)
	s_waitcnt lgkmcnt(0)
	s_barrier
	s_waitcnt lgkmcnt(0)
	v_mfma_f32_16x16x32_bf16 v[60:63], v[162:165], v[194:197], v[60:63]
	v_mfma_f32_16x16x32_bf16 v[56:59], v[170:173], v[194:197], v[56:59]
	v_mfma_f32_16x16x32_bf16 v[52:55], v[162:165], v[202:205], v[52:55]
	v_mfma_f32_16x16x32_bf16 v[44:47], v[170:173], v[202:205], v[44:47]
	v_mfma_f32_16x16x32_bf16 v[36:39], v[162:165], v[210:213], v[36:39]
	v_mfma_f32_16x16x32_bf16 v[28:31], v[170:173], v[210:213], v[28:31]
	v_mfma_f32_16x16x32_bf16 v[20:23], v[162:165], v[218:221], v[20:23]
	v_mfma_f32_16x16x32_bf16 v[12:15], v[170:173], v[218:221], v[12:15]
	v_mfma_f32_16x16x32_bf16 v[60:63], v[166:169], v[198:201], v[60:63]
	v_mfma_f32_16x16x32_bf16 v[56:59], v[174:177], v[198:201], v[56:59]
	v_mfma_f32_16x16x32_bf16 v[52:55], v[166:169], v[206:209], v[52:55]
	v_mfma_f32_16x16x32_bf16 v[44:47], v[174:177], v[206:209], v[44:47]
	v_mfma_f32_16x16x32_bf16 v[36:39], v[166:169], v[214:217], v[36:39]
	v_mfma_f32_16x16x32_bf16 v[28:31], v[174:177], v[214:217], v[28:31]
	v_mfma_f32_16x16x32_bf16 v[20:23], v[166:169], v[222:225], v[20:23]
	v_mfma_f32_16x16x32_bf16 v[12:15], v[174:177], v[222:225], v[12:15]
	v_mfma_f32_16x16x32_bf16 v[48:51], v[178:181], v[194:197], v[48:51]
	v_mfma_f32_16x16x32_bf16 v[40:43], v[186:189], v[194:197], v[40:43]
	v_mfma_f32_16x16x32_bf16 v[32:35], v[178:181], v[202:205], v[32:35]
	v_mfma_f32_16x16x32_bf16 v[24:27], v[186:189], v[202:205], v[24:27]
	v_mfma_f32_16x16x32_bf16 v[16:19], v[178:181], v[210:213], v[16:19]
	v_mfma_f32_16x16x32_bf16 v[8:11], v[186:189], v[210:213], v[8:11]
	v_mfma_f32_16x16x32_bf16 v[4:7], v[178:181], v[218:221], v[4:7]
	v_mfma_f32_16x16x32_bf16 v[0:3], v[186:189], v[218:221], v[0:3]
	v_mfma_f32_16x16x32_bf16 v[48:51], v[182:185], v[198:201], v[48:51]
	v_mfma_f32_16x16x32_bf16 v[40:43], v[190:193], v[198:201], v[40:43]
	v_mfma_f32_16x16x32_bf16 v[32:35], v[182:185], v[206:209], v[32:35]
	v_mfma_f32_16x16x32_bf16 v[24:27], v[190:193], v[206:209], v[24:27]
	v_mfma_f32_16x16x32_bf16 v[16:19], v[182:185], v[214:217], v[16:19]
	v_mfma_f32_16x16x32_bf16 v[8:11], v[190:193], v[214:217], v[8:11]
	v_mfma_f32_16x16x32_bf16 v[4:7], v[182:185], v[222:225], v[4:7]
	v_mfma_f32_16x16x32_bf16 v[0:3], v[190:193], v[222:225], v[0:3]
	s_barrier
; #define PG8_STAGE(bufoff, gbase, voff) do { _Pragma("unroll") for (int _i = 0; _i < 2; ++_i) \
;         __builtin_amdgcn_global_load_lds((const unsigned*)((const char*)(gbase) + (voff)[_i]), (PG8_LAS unsigned*)(lds + (bufoff) + ldsw + _i * 8192), 16, 0, 0); } while (0)
; #define PG8_LDA(dst, b, h) do { _Pragma("unroll") for (int m = 0; m < 4; ++m) _Pragma("unroll") for (int k = 0; k < 2; ++k) dst[m][k] = *(const PG8_LAS bf16x8*)(lds + PG8_SA(b, h) + aoff + m * 2048 + k * 1024); } while (0)
; #define PG8_LDB(dst, b, h) do { _Pragma("unroll") for (int n = 0; n < 2; ++n) _Pragma("unroll") for (int k = 0; k < 2; ++k) dst[n][k] = *(const PG8_LAS bf16x8*)(lds + PG8_SB(b, h) + boff + n * 2048 + k * 1024); } while (0)
; #define PG8_MMA(ai, bj, At, Bt) do { __builtin_amdgcn_s_setprio(1); _Pragma("unroll") for (int m = 0; m < 4; ++m) _Pragma("unroll") for (int n = 0; n < 2; ++n) _Pragma("unroll") for (int k = 0; k < 2; ++k) \
;         acc[ai][bj][m][n] = __builtin_amdgcn_mfma_f32_16x16x32_bf16(Bt[n][k], At[m][k], acc[ai][bj][m][n], 0, 0, 0); __builtin_amdgcn_s_setprio(0); } while (0)
; #define PG8_WAIT_V(n) asm volatile("s_waitcnt vmcnt(" #n ")" ::: "memory")
; #define PG8_WAIT_L(n) asm volatile("s_waitcnt lgkmcnt(" #n ")" ::: "memory")
; #define PG8_BAR __builtin_amdgcn_s_barrier()
; #define PG8_SCHED __builtin_amdgcn_sched_barrier(0)
; template <class Epi, class Sched, bool ALIGN_EPI = false, bool SP2 = false>
; __device__ __forceinline__ void gemm_phase(PG8_LAS unsigned char* lds, const Gemm g, const Sched& S, const Epi& E, int wave_in) {
;     ...
;             PG8_LDB(B0, 1, 0); PG8_LDB(B1, 1, 1); PG8_SCHED; PG8_LDA(At, 1, 0); PG8_STAGE(PG8_SA(0, 1), a2 + hstep, voffA);
;             PG8_WAIT_V(8); PG8_WAIT_L(0); PG8_BAR; PG8_MMA(0, 0, At, B0); PG8_MMA(0, 1, At, B1); PG8_BAR; PG8_SCHED;
;             PG8_LDA(At, 1, 1); PG8_STAGE(PG8_SB(1, 0), b3, voffB); PG8_STAGE(PG8_SB(1, 1), b3 + hstep, voffB); PG8_STAGE(PG8_SA(1, 0), a3, voffA);
;             PG8_WAIT_V(8); PG8_WAIT_L(0); PG8_BAR; PG8_MMA(1, 0, At, B0); PG8_MMA(1, 1, At, B1); PG8_BAR; PG8_SCHED;
	v_add_u32_e32 v174, s45, v160
	v_add_u32_e32 v190, s46, v160
	ds_read_b128 v[162:165], v174
	ds_read_b128 v[166:169], v174 offset:1024
	ds_read_b128 v[170:173], v174 offset:2048
	ds_read_b128 v[174:177], v174 offset:3072
	ds_read_b128 v[178:181], v190
	ds_read_b128 v[182:185], v190 offset:1024
	ds_read_b128 v[186:189], v190 offset:2048
	ds_read_b128 v[190:193], v190 offset:3072
	s_add_u32 s38, s38, 0x40000
	s_addc_u32 s39, s39, 0
	s_mov_b32 m0, s69
	v_lshl_add_u64 v[234:235], s[38:39], 0, v[130:131]
	ds_read_b128 v[194:197], v161 offset:32768
	ds_read_b128 v[198:201], v161 offset:33792
	ds_read_b128 v[202:205], v161 offset:34816
	ds_read_b128 v[206:209], v161 offset:35840
	ds_read_b128 v[210:213], v161 offset:36864
	ds_read_b128 v[214:217], v161 offset:37888
	ds_read_b128 v[218:221], v161 offset:38912
	ds_read_b128 v[222:225], v161 offset:39936
	global_load_lds_dwordx4 v[234:235], off
	v_lshl_add_u64 v[234:235], s[38:39], 0, v[134:135]
	s_mov_b32 m0, s70
	s_nop 0
	global_load_lds_dwordx4 v[234:235], off
	s_waitcnt vmcnt(8)
	s_waitcnt lgkmcnt(0)
	s_barrier
	s_waitcnt lgkmcnt(0)
	v_mfma_f32_16x16x32_bf16 v[124:127], v[162:165], v[194:197], v[124:127]
	v_mfma_f32_16x16x32_bf16 v[120:123], v[170:173], v[194:197], v[120:123]
	v_mfma_f32_16x16x32_bf16 v[116:119], v[162:165], v[202:205], v[116:119]
	v_mfma_f32_16x16x32_bf16 v[108:111], v[170:173], v[202:205], v[108:111]
	v_mfma_f32_16x16x32_bf16 v[100:103], v[162:165], v[210:213], v[100:103]
	v_mfma_f32_16x16x32_bf16 v[92:95], v[170:173], v[210:213], v[92:95]
	v_mfma_f32_16x16x32_bf16 v[84:87], v[162:165], v[218:221], v[84:87]
	v_mfma_f32_16x16x32_bf16 v[76:79], v[170:173], v[218:221], v[76:79]
	v_mfma_f32_16x16x32_bf16 v[124:127], v[166:169], v[198:201], v[124:127]
	v_mfma_f32_16x16x32_bf16 v[120:123], v[174:177], v[198:201], v[120:123]
	v_mfma_f32_16x16x32_bf16 v[116:119], v[166:169], v[206:209], v[116:119]
	v_mfma_f32_16x16x32_bf16 v[108:111], v[174:177], v[206:209], v[108:111]
	v_mfma_f32_16x16x32_bf16 v[100:103], v[166:169], v[214:217], v[100:103]
	v_mfma_f32_16x16x32_bf16 v[92:95], v[174:177], v[214:217], v[92:95]
	v_mfma_f32_16x16x32_bf16 v[84:87], v[166:169], v[222:225], v[84:87]
	v_mfma_f32_16x16x32_bf16 v[76:79], v[174:177], v[222:225], v[76:79]
	v_mfma_f32_16x16x32_bf16 v[112:115], v[178:181], v[194:197], v[112:115]
	v_mfma_f32_16x16x32_bf16 v[104:107], v[186:189], v[194:197], v[104:107]
	v_mfma_f32_16x16x32_bf16 v[96:99], v[178:181], v[202:205], v[96:99]
	v_mfma_f32_16x16x32_bf16 v[88:91], v[186:189], v[202:205], v[88:91]
	v_mfma_f32_16x16x32_bf16 v[80:83], v[178:181], v[210:213], v[80:83]
	v_mfma_f32_16x16x32_bf16 v[72:75], v[186:189], v[210:213], v[72:75]
	v_mfma_f32_16x16x32_bf16 v[68:71], v[178:181], v[218:221], v[68:71]
	v_mfma_f32_16x16x32_bf16 v[64:67], v[186:189], v[218:221], v[64:67]
	v_mfma_f32_16x16x32_bf16 v[112:115], v[182:185], v[198:201], v[112:115]
	v_mfma_f32_16x16x32_bf16 v[104:107], v[190:193], v[198:201], v[104:107]
	v_mfma_f32_16x16x32_bf16 v[96:99], v[182:185], v[206:209], v[96:99]
	v_mfma_f32_16x16x32_bf16 v[88:91], v[190:193], v[206:209], v[88:91]
	v_mfma_f32_16x16x32_bf16 v[80:83], v[182:185], v[214:217], v[80:83]
	v_mfma_f32_16x16x32_bf16 v[72:75], v[190:193], v[214:217], v[72:75]
	v_mfma_f32_16x16x32_bf16 v[68:71], v[182:185], v[222:225], v[68:71]
	v_mfma_f32_16x16x32_bf16 v[64:67], v[190:193], v[222:225], v[64:67]
	s_barrier
	s_add_i32 s38, s45, s66
	v_lshl_add_u64 v[226:227], v[226:227], 0, s[6:7]
	s_mov_b32 m0, s38
	ds_read_b128 v[194:197], v161 offset:49152
	ds_read_b128 v[198:201], v161 offset:50176
	ds_read_b128 v[202:205], v161 offset:51200
	ds_read_b128 v[206:209], v161 offset:52224
	ds_read_b128 v[210:213], v161 offset:53248
	ds_read_b128 v[214:217], v161 offset:54272
	ds_read_b128 v[218:221], v161 offset:55296
	ds_read_b128 v[222:225], v161 offset:56320
	global_load_lds_dwordx4 v[226:227], off
	s_add_i32 m0, s38, 0x2000
	s_add_u32 s36, s36, 0x40080
	v_lshl_add_u64 v[226:227], v[228:229], 0, s[6:7]
	s_addc_u32 s37, s37, 0
	s_add_i32 s38, s46, s66
	global_load_lds_dwordx4 v[226:227], off
	v_lshl_add_u64 v[226:227], s[36:37], 0, v[132:133]
	s_mov_b32 m0, s38
	s_nop 0
	global_load_lds_dwordx4 v[226:227], off
	v_lshl_add_u64 v[226:227], s[36:37], 0, v[136:137]
	s_add_i32 m0, s38, 0x2000
	s_nop 0
	global_load_lds_dwordx4 v[226:227], off
	v_lshl_add_u64 v[226:227], v[230:231], 0, s[6:7]
	s_mov_b32 m0, s73
	s_nop 0
	global_load_lds_dwordx4 v[226:227], off
	v_lshl_add_u64 v[226:227], v[232:233], 0, s[6:7]
	s_mov_b32 m0, s74
	s_nop 0
	global_load_lds_dwordx4 v[226:227], off
	s_waitcnt vmcnt(8)
	s_waitcnt lgkmcnt(0)
	s_barrier
	s_waitcnt lgkmcnt(0)
	v_mfma_f32_16x16x32_bf16 v[60:63], v[162:165], v[194:197], v[60:63]
	v_mfma_f32_16x16x32_bf16 v[56:59], v[170:173], v[194:197], v[56:59]
	v_mfma_f32_16x16x32_bf16 v[52:55], v[162:165], v[202:205], v[52:55]
	v_mfma_f32_16x16x32_bf16 v[44:47], v[170:173], v[202:205], v[44:47]
	v_mfma_f32_16x16x32_bf16 v[36:39], v[162:165], v[210:213], v[36:39]
	v_mfma_f32_16x16x32_bf16 v[28:31], v[170:173], v[210:213], v[28:31]
	v_mfma_f32_16x16x32_bf16 v[20:23], v[162:165], v[218:221], v[20:23]
	v_mfma_f32_16x16x32_bf16 v[12:15], v[170:173], v[218:221], v[12:15]
	v_mfma_f32_16x16x32_bf16 v[60:63], v[166:169], v[198:201], v[60:63]
	v_mfma_f32_16x16x32_bf16 v[56:59], v[174:177], v[198:201], v[56:59]
	v_mfma_f32_16x16x32_bf16 v[52:55], v[166:169], v[206:209], v[52:55]
	v_mfma_f32_16x16x32_bf16 v[44:47], v[174:177], v[206:209], v[44:47]
	v_mfma_f32_16x16x32_bf16 v[36:39], v[166:169], v[214:217], v[36:39]
	v_mfma_f32_16x16x32_bf16 v[28:31], v[174:177], v[214:217], v[28:31]
	v_mfma_f32_16x16x32_bf16 v[20:23], v[166:169], v[222:225], v[20:23]
	v_mfma_f32_16x16x32_bf16 v[12:15], v[174:177], v[222:225], v[12:15]
	v_mfma_f32_16x16x32_bf16 v[48:51], v[178:181], v[194:197], v[48:51]
	v_mfma_f32_16x16x32_bf16 v[40:43], v[186:189], v[194:197], v[40:43]
	v_mfma_f32_16x16x32_bf16 v[32:35], v[178:181], v[202:205], v[32:35]
	v_mfma_f32_16x16x32_bf16 v[24:27], v[186:189], v[202:205], v[24:27]
	v_mfma_f32_16x16x32_bf16 v[16:19], v[178:181], v[210:213], v[16:19]
	v_mfma_f32_16x16x32_bf16 v[8:11], v[186:189], v[210:213], v[8:11]
	v_mfma_f32_16x16x32_bf16 v[4:7], v[178:181], v[218:221], v[4:7]
	v_mfma_f32_16x16x32_bf16 v[0:3], v[186:189], v[218:221], v[0:3]
	v_mfma_f32_16x16x32_bf16 v[48:51], v[182:185], v[198:201], v[48:51]
	v_mfma_f32_16x16x32_bf16 v[40:43], v[190:193], v[198:201], v[40:43]
	v_mfma_f32_16x16x32_bf16 v[32:35], v[182:185], v[206:209], v[32:35]
	v_mfma_f32_16x16x32_bf16 v[24:27], v[190:193], v[206:209], v[24:27]
	v_mfma_f32_16x16x32_bf16 v[16:19], v[182:185], v[214:217], v[16:19]
	v_mfma_f32_16x16x32_bf16 v[8:11], v[190:193], v[214:217], v[8:11]
	v_mfma_f32_16x16x32_bf16 v[4:7], v[182:185], v[222:225], v[4:7]
	v_mfma_f32_16x16x32_bf16 v[0:3], v[190:193], v[222:225], v[0:3]
	s_barrier
	s_add_i32 s78, s78, 2
	s_add_u32 s76, s76, 0x100
	s_addc_u32 s77, s77, 0
	s_add_u32 s34, s34, 0x100
	s_addc_u32 s35, s35, 0
	s_cmp_gt_u32 s78, 13
	s_cbranch_scc0 .LBB0_254

; #define PG8_STAGE(bufoff, gbase, voff) do { _Pragma("unroll") for (int _i = 0; _i < 2; ++_i) \
;         __builtin_amdgcn_global_load_lds((const unsigned*)((const char*)(gbase) + (voff)[_i]), (PG8_LAS unsigned*)(lds + (bufoff) + ldsw + _i * 8192), 16, 0, 0); } while (0)
; #define PG8_LDA(dst, b, h) do { _Pragma("unroll") for (int m = 0; m < 4; ++m) _Pragma("unroll") for (int k = 0; k < 2; ++k) dst[m][k] = *(const PG8_LAS bf16x8*)(lds + PG8_SA(b, h) + aoff + m * 2048 + k * 1024); } while (0)
; #define PG8_LDB(dst, b, h) do { _Pragma("unroll") for (int n = 0; n < 2; ++n) _Pragma("unroll") for (int k = 0; k < 2; ++k) dst[n][k] = *(const PG8_LAS bf16x8*)(lds + PG8_SB(b, h) + boff + n * 2048 + k * 1024); } while (0)
; #define PG8_MMA(ai, bj, At, Bt) do { __builtin_amdgcn_s_setprio(1); _Pragma("unroll") for (int m = 0; m < 4; ++m) _Pragma("unroll") for (int n = 0; n < 2; ++n) _Pragma("unroll") for (int k = 0; k < 2; ++k) \
;         acc[ai][bj][m][n] = __builtin_amdgcn_mfma_f32_16x16x32_bf16(Bt[n][k], At[m][k], acc[ai][bj][m][n], 0, 0, 0); __builtin_amdgcn_s_setprio(0); } while (0)
; template <class Epi, class Sched, bool ALIGN_EPI = false, bool SP2 = false>
; __device__ __forceinline__ void gemm_phase(PG8_LAS unsigned char* lds, const Gemm g, const Sched& S, const Epi& E, int wave_in) {
;     ...
;         const char* nA = has_next ? (const char*)g.A + (size_t)(nxt.pm >> g.ash) * g.astride + (size_t)nxt.pm * tstep : cA; const char* nB = has_next ? (const char*)g.Bt + (size_t)(nxt.pm >> g.bsh) * g.bstride + (size_t)nxt.pn * tstep : cB;
;         for (int t = 0; t < nt; t += 2) {
;             const bool last = (t == nt - 2);
;             const char* a1 = cA + (size_t)(t + 1) * kstep;
;             const char* a2 = last ? nA : cA + (size_t)(t + 2) * kstep; const char* b2 = last ? nB : cB + (size_t)(t + 2) * kstep;
;             const char* a3 = a2 + kstep; const char* b3 = b2 + kstep;
;             if (last && has_next) S.a_ready(nxt);
;             if constexpr (SP2) {
;             PG8_LDB(B0, 0, 0); PG8_LDB(B1, 0, 1); PG8_SCHED; PG8_LDA(At, 0, 0); PG8_STAGE(PG8_SA(1, 1), a1 + hstep, voffA);
;             PG8_WAIT_V(8); PG8_WAIT_L(0); PG8_BAR; PG8_MMA(0, 0, At, B0); PG8_MMA(0, 1, At, B1); PG8_BAR; PG8_SCHED;
;             PG8_LDA(At, 0, 1); PG8_STAGE(PG8_SB(0, 0), b2, voffB); PG8_STAGE(PG8_SB(0, 1), b2 + hstep, voffB); PG8_STAGE(PG8_SA(0, 0), a2, voffA);
.LBB0_272:
	s_ashr_i32 s77, s76, 31
	s_lshl_b64 s[8:9], s[76:77], 19
	s_add_u32 s84, s22, s8
	s_addc_u32 s85, s23, s9
	s_and_b64 s[8:9], s[40:41], exec
	s_cselect_b32 s8, s85, s5
	s_cselect_b32 s9, s84, s4
	s_ashr_i32 s95, s94, 31
	s_lshl_b64 s[10:11], s[94:95], 19
	v_readlane_b32 s16, v255, 39
	v_readlane_b32 s17, v255, 40
	s_add_u32 s24, s16, s10
	s_addc_u32 s25, s17, s11
	s_and_b64 s[10:11], s[40:41], exec
	s_cselect_b32 s16, s25, s1
	s_cselect_b32 s17, s24, s0
	s_add_u32 s31, s0, 0x100
	s_addc_u32 s33, s1, 0
	s_add_u32 s0, s4, 0x40080
	s_addc_u32 s1, s5, 0
	s_mov_b32 s34, -2
	s_waitcnt lgkmcnt(0)
	s_add_u32 s4, s0, 0xfffc0080
	s_addc_u32 s5, s1, -1
	s_add_i32 s42, s35, 0x100
	s_cmp_eq_u32 s34, 12
	s_cselect_b32 s11, s8, s5
	s_cselect_b32 s10, s9, s4
	s_cselect_b32 s5, s16, s33
	s_cselect_b32 s4, s17, s31
	s_add_i32 s44, s90, 0x100
	v_add_u32_e32 v168, s42, v177
	v_add_u32_e32 v188, s44, v177
	ds_read_b128 v[156:159], v168
	ds_read_b128 v[160:163], v168 offset:1024
	ds_read_b128 v[164:167], v168 offset:2048
	ds_read_b128 v[168:171], v168 offset:3072
	ds_read_b128 v[172:175], v188
	ds_read_b128 v[180:183], v188 offset:1024
	ds_read_b128 v[184:187], v188 offset:2048
	ds_read_b128 v[188:191], v188 offset:3072
	v_lshl_add_u64 v[230:231], s[0:1], 0, v[154:155]
	s_add_i32 m0, s67, 0xc000
	ds_read_b128 v[198:201], v179
	ds_read_b128 v[202:205], v179 offset:1024
	ds_read_b128 v[206:209], v179 offset:2048
	ds_read_b128 v[210:213], v179 offset:3072
	ds_read_b128 v[214:217], v179 offset:4096
	ds_read_b128 v[218:221], v179 offset:5120
	ds_read_b128 v[222:225], v179 offset:6144
	ds_read_b128 v[226:229], v179 offset:7168
	global_load_lds_dwordx4 v[230:231], off
	v_lshl_add_u64 v[230:231], s[0:1], 0, v[152:153]
	s_add_i32 m0, s67, 0xe000
	s_nop 0
	global_load_lds_dwordx4 v[230:231], off
	s_waitcnt vmcnt(8)
	s_waitcnt lgkmcnt(0)
	s_barrier
	s_waitcnt lgkmcnt(0)
	v_mfma_f32_16x16x32_bf16 v[124:127], v[156:159], v[198:201], 0
	v_mfma_f32_16x16x32_bf16 v[120:123], v[164:167], v[198:201], 0
	v_mfma_f32_16x16x32_bf16 v[108:111], v[156:159], v[206:209], 0
	v_mfma_f32_16x16x32_bf16 v[104:107], v[164:167], v[206:209], 0
	v_mfma_f32_16x16x32_bf16 v[92:95], v[156:159], v[214:217], 0
	v_mfma_f32_16x16x32_bf16 v[88:91], v[164:167], v[214:217], 0
	v_mfma_f32_16x16x32_bf16 v[76:79], v[156:159], v[222:225], 0
	v_mfma_f32_16x16x32_bf16 v[72:75], v[164:167], v[222:225], 0
	v_mfma_f32_16x16x32_bf16 v[124:127], v[160:163], v[202:205], v[124:127]
	v_mfma_f32_16x16x32_bf16 v[120:123], v[168:171], v[202:205], v[120:123]
	v_mfma_f32_16x16x32_bf16 v[108:111], v[160:163], v[210:213], v[108:111]
	v_mfma_f32_16x16x32_bf16 v[104:107], v[168:171], v[210:213], v[104:107]
	v_mfma_f32_16x16x32_bf16 v[92:95], v[160:163], v[218:221], v[92:95]
	v_mfma_f32_16x16x32_bf16 v[88:91], v[168:171], v[218:221], v[88:91]
	v_mfma_f32_16x16x32_bf16 v[76:79], v[160:163], v[226:229], v[76:79]
	v_mfma_f32_16x16x32_bf16 v[72:75], v[168:171], v[226:229], v[72:75]
	v_mfma_f32_16x16x32_bf16 v[116:119], v[172:175], v[198:201], 0
	v_mfma_f32_16x16x32_bf16 v[112:115], v[184:187], v[198:201], 0
	v_mfma_f32_16x16x32_bf16 v[100:103], v[172:175], v[206:209], 0
	v_mfma_f32_16x16x32_bf16 v[96:99], v[184:187], v[206:209], 0
	v_mfma_f32_16x16x32_bf16 v[84:87], v[172:175], v[214:217], 0
	v_mfma_f32_16x16x32_bf16 v[80:83], v[184:187], v[214:217], 0
	v_mfma_f32_16x16x32_bf16 v[68:71], v[172:175], v[222:225], 0
	v_mfma_f32_16x16x32_bf16 v[64:67], v[184:187], v[222:225], 0
	v_mfma_f32_16x16x32_bf16 v[116:119], v[180:183], v[202:205], v[116:119]
	v_mfma_f32_16x16x32_bf16 v[112:115], v[188:191], v[202:205], v[112:115]
	v_mfma_f32_16x16x32_bf16 v[100:103], v[180:183], v[210:213], v[100:103]
	v_mfma_f32_16x16x32_bf16 v[96:99], v[188:191], v[210:213], v[96:99]
	v_mfma_f32_16x16x32_bf16 v[84:87], v[180:183], v[218:221], v[84:87]
	v_mfma_f32_16x16x32_bf16 v[80:83], v[188:191], v[218:221], v[80:83]
	v_mfma_f32_16x16x32_bf16 v[68:71], v[180:183], v[226:229], v[68:71]
	v_mfma_f32_16x16x32_bf16 v[64:67], v[188:191], v[226:229], v[64:67]
	s_barrier
	s_add_i32 s42, s42, s66
	v_lshl_add_u64 v[230:231], s[4:5], 0, v[132:133]
	s_mov_b32 m0, s42
	ds_read_b128 v[198:201], v179 offset:16384
	ds_read_b128 v[202:205], v179 offset:17408
	ds_read_b128 v[206:209], v179 offset:18432
	ds_read_b128 v[210:213], v179 offset:19456
	ds_read_b128 v[214:217], v179 offset:20480
	ds_read_b128 v[218:221], v179 offset:21504
	ds_read_b128 v[222:225], v179 offset:22528
	ds_read_b128 v[226:229], v179 offset:23552
	global_load_lds_dwordx4 v[230:231], off
	s_add_i32 m0, s42, 0x2000
	s_add_u32 s42, s4, 0x40000
	v_lshl_add_u64 v[232:233], s[4:5], 0, v[128:129]
	s_addc_u32 s43, s5, 0
	s_add_i32 s44, s44, s66
	global_load_lds_dwordx4 v[232:233], off
	v_lshl_add_u64 v[234:235], s[42:43], 0, v[132:133]
	s_mov_b32 m0, s44
	v_lshl_add_u64 v[236:237], s[10:11], 0, v[130:131]
	global_load_lds_dwordx4 v[234:235], off
	v_lshl_add_u64 v[234:235], s[42:43], 0, v[128:129]
	s_add_i32 m0, s44, 0x2000
	s_nop 0
	global_load_lds_dwordx4 v[234:235], off
	v_lshl_add_u64 v[234:235], s[10:11], 0, v[134:135]
	s_mov_b32 m0, s67
	s_nop 0
	global_load_lds_dwordx4 v[234:235], off
	s_mov_b32 m0, s78
	s_nop 0
	global_load_lds_dwordx4 v[236:237], off
	s_waitcnt vmcnt(8)
	s_waitcnt lgkmcnt(0)
	s_barrier
; #define PG8_STAGE(bufoff, gbase, voff) do { _Pragma("unroll") for (int _i = 0; _i < 2; ++_i) \
;         __builtin_amdgcn_global_load_lds((const unsigned*)((const char*)(gbase) + (voff)[_i]), (PG8_LAS unsigned*)(lds + (bufoff) + ldsw + _i * 8192), 16, 0, 0); } while (0)
; #define PG8_LDA(dst, b, h) do { _Pragma("unroll") for (int m = 0; m < 4; ++m) _Pragma("unroll") for (int k = 0; k < 2; ++k) dst[m][k] = *(const PG8_LAS bf16x8*)(lds + PG8_SA(b, h) + aoff + m * 2048 + k * 1024); } while (0)
; #define PG8_LDB(dst, b, h) do { _Pragma("unroll") for (int n = 0; n < 2; ++n) _Pragma("unroll") for (int k = 0; k < 2; ++k) dst[n][k] = *(const PG8_LAS bf16x8*)(lds + PG8_SB(b, h) + boff + n * 2048 + k * 1024); } while (0)
; #define PG8_MMA(ai, bj, At, Bt) do { __builtin_amdgcn_s_setprio(1); _Pragma("unroll") for (int m = 0; m < 4; ++m) _Pragma("unroll") for (int n = 0; n < 2; ++n) _Pragma("unroll") for (int k = 0; k < 2; ++k) \
;         acc[ai][bj][m][n] = __builtin_amdgcn_mfma_f32_16x16x32_bf16(Bt[n][k], At[m][k], acc[ai][bj][m][n], 0, 0, 0); __builtin_amdgcn_s_setprio(0); } while (0)
; #define PG8_WAIT_V(n) asm volatile("s_waitcnt vmcnt(" #n ")" ::: "memory")
; #define PG8_WAIT_L(n) asm volatile("s_waitcnt lgkmcnt(" #n ")" ::: "memory")
; #define PG8_BAR __builtin_amdgcn_s_barrier()
; #define PG8_SCHED __builtin_amdgcn_sched_barrier(0)
; template <class Epi, class Sched, bool ALIGN_EPI = false, bool SP2 = false>
; __device__ __forceinline__ void gemm_phase(PG8_LAS unsigned char* lds, const Gemm g, const Sched& S, const Epi& E, int wave_in) {
;     ...
;             PG8_WAIT_V(8); PG8_WAIT_L(0); PG8_BAR; PG8_MMA(1, 0, At, B0); PG8_MMA(1, 1, At, B1); PG8_BAR; PG8_SCHED;
;             PG8_LDB(B0, 1, 0); PG8_LDB(B1, 1, 1); PG8_SCHED; PG8_LDA(At, 1, 0); PG8_STAGE(PG8_SA(0, 1), a2 + hstep, voffA);
;             PG8_WAIT_V(8); PG8_WAIT_L(0); PG8_BAR; PG8_MMA(0, 0, At, B0); PG8_MMA(0, 1, At, B1); PG8_BAR; PG8_SCHED;
	s_waitcnt lgkmcnt(0)
	v_mfma_f32_16x16x32_bf16 v[60:63], v[156:159], v[198:201], 0
	v_mfma_f32_16x16x32_bf16 v[56:59], v[164:167], v[198:201], 0
	v_mfma_f32_16x16x32_bf16 v[44:47], v[156:159], v[206:209], 0
	v_mfma_f32_16x16x32_bf16 v[40:43], v[164:167], v[206:209], 0
	v_mfma_f32_16x16x32_bf16 v[28:31], v[156:159], v[214:217], 0
	v_mfma_f32_16x16x32_bf16 v[24:27], v[164:167], v[214:217], 0
	v_mfma_f32_16x16x32_bf16 v[12:15], v[156:159], v[222:225], 0
	v_mfma_f32_16x16x32_bf16 v[8:11], v[164:167], v[222:225], 0
	v_mfma_f32_16x16x32_bf16 v[60:63], v[160:163], v[202:205], v[60:63]
	v_mfma_f32_16x16x32_bf16 v[56:59], v[168:171], v[202:205], v[56:59]
	v_mfma_f32_16x16x32_bf16 v[44:47], v[160:163], v[210:213], v[44:47]
	v_mfma_f32_16x16x32_bf16 v[40:43], v[168:171], v[210:213], v[40:43]
	v_mfma_f32_16x16x32_bf16 v[28:31], v[160:163], v[218:221], v[28:31]
	v_mfma_f32_16x16x32_bf16 v[24:27], v[168:171], v[218:221], v[24:27]
	v_mfma_f32_16x16x32_bf16 v[12:15], v[160:163], v[226:229], v[12:15]
	v_mfma_f32_16x16x32_bf16 v[8:11], v[168:171], v[226:229], v[8:11]
	v_mfma_f32_16x16x32_bf16 v[52:55], v[172:175], v[198:201], 0
	v_mfma_f32_16x16x32_bf16 v[48:51], v[184:187], v[198:201], 0
	v_mfma_f32_16x16x32_bf16 v[36:39], v[172:175], v[206:209], 0
	v_mfma_f32_16x16x32_bf16 v[32:35], v[184:187], v[206:209], 0
	v_mfma_f32_16x16x32_bf16 v[20:23], v[172:175], v[214:217], 0
	v_mfma_f32_16x16x32_bf16 v[16:19], v[184:187], v[214:217], 0
	v_mfma_f32_16x16x32_bf16 v[4:7], v[172:175], v[222:225], 0
	v_mfma_f32_16x16x32_bf16 v[0:3], v[184:187], v[222:225], 0
	v_mfma_f32_16x16x32_bf16 v[52:55], v[180:183], v[202:205], v[52:55]
	v_mfma_f32_16x16x32_bf16 v[48:51], v[188:191], v[202:205], v[48:51]
	v_mfma_f32_16x16x32_bf16 v[36:39], v[180:183], v[210:213], v[36:39]
	v_mfma_f32_16x16x32_bf16 v[32:35], v[188:191], v[210:213], v[32:35]
	v_mfma_f32_16x16x32_bf16 v[20:23], v[180:183], v[218:221], v[20:23]
	v_mfma_f32_16x16x32_bf16 v[16:19], v[188:191], v[218:221], v[16:19]
	v_mfma_f32_16x16x32_bf16 v[4:7], v[180:183], v[226:229], v[4:7]
	v_mfma_f32_16x16x32_bf16 v[0:3], v[188:191], v[226:229], v[0:3]
	s_barrier
	s_add_i32 s42, s65, 0x100
	s_add_i32 s43, s52, 0x100
	v_add_u32_e32 v168, s42, v177
	v_add_u32_e32 v188, s43, v177
	ds_read_b128 v[156:159], v168
	ds_read_b128 v[160:163], v168 offset:1024
	ds_read_b128 v[164:167], v168 offset:2048
	ds_read_b128 v[168:171], v168 offset:3072
	ds_read_b128 v[172:175], v188
	ds_read_b128 v[180:183], v188 offset:1024
	ds_read_b128 v[184:187], v188 offset:2048
	ds_read_b128 v[188:191], v188 offset:3072
	s_add_u32 s10, s10, 0x40000
	s_addc_u32 s11, s11, 0
	s_mov_b32 m0, s79
	v_lshl_add_u64 v[238:239], s[10:11], 0, v[134:135]
	ds_read_b128 v[198:201], v179 offset:32768
	ds_read_b128 v[202:205], v179 offset:33792
	ds_read_b128 v[206:209], v179 offset:34816
	ds_read_b128 v[210:213], v179 offset:35840
	ds_read_b128 v[214:217], v179 offset:36864
	ds_read_b128 v[218:221], v179 offset:37888
	ds_read_b128 v[222:225], v179 offset:38912
	ds_read_b128 v[226:229], v179 offset:39936
	global_load_lds_dwordx4 v[238:239], off
	v_lshl_add_u64 v[238:239], s[10:11], 0, v[130:131]
	s_mov_b32 m0, s82
	s_nop 0
	global_load_lds_dwordx4 v[238:239], off
	s_waitcnt vmcnt(8)
	s_waitcnt lgkmcnt(0)
	s_barrier
	s_waitcnt lgkmcnt(0)
	v_mfma_f32_16x16x32_bf16 v[124:127], v[156:159], v[198:201], v[124:127]
	v_mfma_f32_16x16x32_bf16 v[120:123], v[164:167], v[198:201], v[120:123]
	v_mfma_f32_16x16x32_bf16 v[108:111], v[156:159], v[206:209], v[108:111]
	v_mfma_f32_16x16x32_bf16 v[104:107], v[164:167], v[206:209], v[104:107]
	v_mfma_f32_16x16x32_bf16 v[92:95], v[156:159], v[214:217], v[92:95]
	v_mfma_f32_16x16x32_bf16 v[88:91], v[164:167], v[214:217], v[88:91]
	v_mfma_f32_16x16x32_bf16 v[76:79], v[156:159], v[222:225], v[76:79]
	v_mfma_f32_16x16x32_bf16 v[72:75], v[164:167], v[222:225], v[72:75]
	v_mfma_f32_16x16x32_bf16 v[124:127], v[160:163], v[202:205], v[124:127]
	v_mfma_f32_16x16x32_bf16 v[120:123], v[168:171], v[202:205], v[120:123]
	v_mfma_f32_16x16x32_bf16 v[108:111], v[160:163], v[210:213], v[108:111]
	v_mfma_f32_16x16x32_bf16 v[104:107], v[168:171], v[210:213], v[104:107]
	v_mfma_f32_16x16x32_bf16 v[92:95], v[160:163], v[218:221], v[92:95]
	v_mfma_f32_16x16x32_bf16 v[88:91], v[168:171], v[218:221], v[88:91]
	v_mfma_f32_16x16x32_bf16 v[76:79], v[160:163], v[226:229], v[76:79]
	v_mfma_f32_16x16x32_bf16 v[72:75], v[168:171], v[226:229], v[72:75]
	v_mfma_f32_16x16x32_bf16 v[116:119], v[172:175], v[198:201], v[116:119]
	v_mfma_f32_16x16x32_bf16 v[112:115], v[184:187], v[198:201], v[112:115]
	v_mfma_f32_16x16x32_bf16 v[100:103], v[172:175], v[206:209], v[100:103]
	v_mfma_f32_16x16x32_bf16 v[96:99], v[184:187], v[206:209], v[96:99]
	v_mfma_f32_16x16x32_bf16 v[84:87], v[172:175], v[214:217], v[84:87]
	v_mfma_f32_16x16x32_bf16 v[80:83], v[184:187], v[214:217], v[80:83]
	v_mfma_f32_16x16x32_bf16 v[68:71], v[172:175], v[222:225], v[68:71]
	v_mfma_f32_16x16x32_bf16 v[64:67], v[184:187], v[222:225], v[64:67]
	v_mfma_f32_16x16x32_bf16 v[116:119], v[180:183], v[202:205], v[116:119]
	v_mfma_f32_16x16x32_bf16 v[112:115], v[188:191], v[202:205], v[112:115]
	v_mfma_f32_16x16x32_bf16 v[100:103], v[180:183], v[210:213], v[100:103]
	v_mfma_f32_16x16x32_bf16 v[96:99], v[188:191], v[210:213], v[96:99]
	v_mfma_f32_16x16x32_bf16 v[84:87], v[180:183], v[218:221], v[84:87]
	v_mfma_f32_16x16x32_bf16 v[80:83], v[188:191], v[218:221], v[80:83]
	v_mfma_f32_16x16x32_bf16 v[68:71], v[180:183], v[226:229], v[68:71]
	v_mfma_f32_16x16x32_bf16 v[64:67], v[188:191], v[226:229], v[64:67]
	s_barrier
; #define PG8_STAGE(bufoff, gbase, voff) do { _Pragma("unroll") for (int _i = 0; _i < 2; ++_i) \
;         __builtin_amdgcn_global_load_lds((const unsigned*)((const char*)(gbase) + (voff)[_i]), (PG8_LAS unsigned*)(lds + (bufoff) + ldsw + _i * 8192), 16, 0, 0); } while (0)
; #define PG8_LDA(dst, b, h) do { _Pragma("unroll") for (int m = 0; m < 4; ++m) _Pragma("unroll") for (int k = 0; k < 2; ++k) dst[m][k] = *(const PG8_LAS bf16x8*)(lds + PG8_SA(b, h) + aoff + m * 2048 + k * 1024); } while (0)
; #define PG8_LDB(dst, b, h) do { _Pragma("unroll") for (int n = 0; n < 2; ++n) _Pragma("unroll") for (int k = 0; k < 2; ++k) dst[n][k] = *(const PG8_LAS bf16x8*)(lds + PG8_SB(b, h) + boff + n * 2048 + k * 1024); } while (0)
; #define PG8_MMA(ai, bj, At, Bt) do { __builtin_amdgcn_s_setprio(1); _Pragma("unroll") for (int m = 0; m < 4; ++m) _Pragma("unroll") for (int n = 0; n < 2; ++n) _Pragma("unroll") for (int k = 0; k < 2; ++k) \
;         acc[ai][bj][m][n] = __builtin_amdgcn_mfma_f32_16x16x32_bf16(Bt[n][k], At[m][k], acc[ai][bj][m][n], 0, 0, 0); __builtin_amdgcn_s_setprio(0); } while (0)
; #define PG8_BAR __builtin_amdgcn_s_barrier()
; template <class Epi, class Sched, bool ALIGN_EPI = false, bool SP2 = false>
; __device__ __forceinline__ void gemm_phase(PG8_LAS unsigned char* lds, const Gemm g, const Sched& S, const Epi& E, int wave_in) {
;     ...
;             PG8_LDB(B0, 0, 0); PG8_LDB(B1, 0, 1); PG8_SCHED; PG8_LDA(At, 0, 0); PG8_STAGE(PG8_SA(1, 1), a1 + hstep, voffA);
;             PG8_WAIT_V(8); PG8_WAIT_L(0); PG8_BAR; PG8_MMA(0, 0, At, B0); PG8_MMA(0, 1, At, B1); PG8_BAR; PG8_SCHED;
;             PG8_LDA(At, 0, 1); PG8_STAGE(PG8_SB(0, 0), b2, voffB); PG8_STAGE(PG8_SB(0, 1), b2 + hstep, voffB); PG8_STAGE(PG8_SA(0, 0), a2, voffA);
;             PG8_WAIT_V(8); PG8_WAIT_L(0); PG8_BAR; PG8_MMA(1, 0, At, B0); PG8_MMA(1, 1, At, B1); PG8_BAR; PG8_SCHED;
;             PG8_LDB(B0, 1, 0); PG8_LDB(B1, 1, 1); PG8_SCHED; PG8_LDA(At, 1, 0); PG8_STAGE(PG8_SA(0, 1), a2 + hstep, voffA);
;             PG8_WAIT_V(8); PG8_WAIT_L(0); PG8_BAR; PG8_MMA(0, 0, At, B0); PG8_MMA(0, 1, At, B1); PG8_BAR; PG8_SCHED;
;             PG8_LDA(At, 1, 1); PG8_STAGE(PG8_SB(1, 0), b3, voffB); PG8_STAGE(PG8_SB(1, 1), b3 + hstep, voffB); PG8_STAGE(PG8_SA(1, 0), a3, voffA);
;             PG8_WAIT_V(8); PG8_WAIT_L(0); PG8_BAR; PG8_MMA(1, 0, At, B0); PG8_MMA(1, 1, At, B1); PG8_BAR; PG8_SCHED;
	s_add_i32 s10, s42, s66
	v_lshl_add_u64 v[230:231], v[230:231], 0, s[88:89]
	s_mov_b32 m0, s10
	ds_read_b128 v[198:201], v179 offset:49152
	ds_read_b128 v[202:205], v179 offset:50176
	ds_read_b128 v[206:209], v179 offset:51200
	ds_read_b128 v[210:213], v179 offset:52224
	ds_read_b128 v[214:217], v179 offset:53248
	ds_read_b128 v[218:221], v179 offset:54272
	ds_read_b128 v[222:225], v179 offset:55296
	ds_read_b128 v[226:229], v179 offset:56320
	global_load_lds_dwordx4 v[230:231], off
	s_add_i32 m0, s10, 0x2000
	s_add_u32 s4, s4, 0x40080
	v_lshl_add_u64 v[230:231], v[232:233], 0, s[88:89]
	s_addc_u32 s5, s5, 0
	s_add_i32 s10, s43, s66
	global_load_lds_dwordx4 v[230:231], off
	v_lshl_add_u64 v[230:231], s[4:5], 0, v[132:133]
	s_mov_b32 m0, s10
	s_nop 0
	global_load_lds_dwordx4 v[230:231], off
	v_lshl_add_u64 v[230:231], s[4:5], 0, v[128:129]
	s_add_i32 m0, s10, 0x2000
	s_nop 0
	global_load_lds_dwordx4 v[230:231], off
	v_lshl_add_u64 v[230:231], v[234:235], 0, s[88:89]
	s_mov_b32 m0, s72
	s_nop 0
	global_load_lds_dwordx4 v[230:231], off
	v_lshl_add_u64 v[230:231], v[236:237], 0, s[88:89]
	s_mov_b32 m0, s73
	s_nop 0
	global_load_lds_dwordx4 v[230:231], off
	s_waitcnt vmcnt(8)
	s_waitcnt lgkmcnt(0)
	s_barrier
	s_waitcnt lgkmcnt(0)
	v_mfma_f32_16x16x32_bf16 v[60:63], v[156:159], v[198:201], v[60:63]
	v_mfma_f32_16x16x32_bf16 v[56:59], v[164:167], v[198:201], v[56:59]
	v_mfma_f32_16x16x32_bf16 v[44:47], v[156:159], v[206:209], v[44:47]
	v_mfma_f32_16x16x32_bf16 v[40:43], v[164:167], v[206:209], v[40:43]
	v_mfma_f32_16x16x32_bf16 v[28:31], v[156:159], v[214:217], v[28:31]
	v_mfma_f32_16x16x32_bf16 v[24:27], v[164:167], v[214:217], v[24:27]
	v_mfma_f32_16x16x32_bf16 v[12:15], v[156:159], v[222:225], v[12:15]
	v_mfma_f32_16x16x32_bf16 v[8:11], v[164:167], v[222:225], v[8:11]
	v_mfma_f32_16x16x32_bf16 v[60:63], v[160:163], v[202:205], v[60:63]
	v_mfma_f32_16x16x32_bf16 v[56:59], v[168:171], v[202:205], v[56:59]
	v_mfma_f32_16x16x32_bf16 v[44:47], v[160:163], v[210:213], v[44:47]
	v_mfma_f32_16x16x32_bf16 v[40:43], v[168:171], v[210:213], v[40:43]
	v_mfma_f32_16x16x32_bf16 v[28:31], v[160:163], v[218:221], v[28:31]
	v_mfma_f32_16x16x32_bf16 v[24:27], v[168:171], v[218:221], v[24:27]
	v_mfma_f32_16x16x32_bf16 v[12:15], v[160:163], v[226:229], v[12:15]
	v_mfma_f32_16x16x32_bf16 v[8:11], v[168:171], v[226:229], v[8:11]
	v_mfma_f32_16x16x32_bf16 v[52:55], v[172:175], v[198:201], v[52:55]
	v_mfma_f32_16x16x32_bf16 v[48:51], v[184:187], v[198:201], v[48:51]
	v_mfma_f32_16x16x32_bf16 v[36:39], v[172:175], v[206:209], v[36:39]
	v_mfma_f32_16x16x32_bf16 v[32:35], v[184:187], v[206:209], v[32:35]
	v_mfma_f32_16x16x32_bf16 v[20:23], v[172:175], v[214:217], v[20:23]
	v_mfma_f32_16x16x32_bf16 v[16:19], v[184:187], v[214:217], v[16:19]
	v_mfma_f32_16x16x32_bf16 v[4:7], v[172:175], v[222:225], v[4:7]
	v_mfma_f32_16x16x32_bf16 v[0:3], v[184:187], v[222:225], v[0:3]
	v_mfma_f32_16x16x32_bf16 v[52:55], v[180:183], v[202:205], v[52:55]
	v_mfma_f32_16x16x32_bf16 v[48:51], v[188:191], v[202:205], v[48:51]
	v_mfma_f32_16x16x32_bf16 v[36:39], v[180:183], v[210:213], v[36:39]
	v_mfma_f32_16x16x32_bf16 v[32:35], v[188:191], v[210:213], v[32:35]
	v_mfma_f32_16x16x32_bf16 v[20:23], v[180:183], v[218:221], v[20:23]
	v_mfma_f32_16x16x32_bf16 v[16:19], v[188:191], v[218:221], v[16:19]
	v_mfma_f32_16x16x32_bf16 v[4:7], v[180:183], v[226:229], v[4:7]
	v_mfma_f32_16x16x32_bf16 v[0:3], v[188:191], v[226:229], v[0:3]
	s_barrier
	s_add_i32 s34, s34, 2
	s_add_u32 s31, s31, 0x100
	s_addc_u32 s33, s33, 0
	s_add_u32 s0, s0, 0x100
	s_addc_u32 s1, s1, 0
	s_cmp_gt_u32 s34, 13
	s_cbranch_scc1 .Lkexit_1
.LBB0_273:
	s_add_u32 s4, s0, 0xfffc0080
	s_addc_u32 s5, s1, -1
	s_add_i32 s42, s35, 0x100
	s_cmp_eq_u32 s34, 12
	s_cselect_b32 s11, s8, s5
	s_cselect_b32 s10, s9, s4
	s_cselect_b32 s5, s16, s33
	s_cselect_b32 s4, s17, s31
	s_add_i32 s44, s90, 0x100
	v_add_u32_e32 v168, s42, v177
	v_add_u32_e32 v188, s44, v177
	ds_read_b128 v[156:159], v168
	ds_read_b128 v[160:163], v168 offset:1024
	ds_read_b128 v[164:167], v168 offset:2048
	ds_read_b128 v[168:171], v168 offset:3072
	ds_read_b128 v[172:175], v188
	ds_read_b128 v[180:183], v188 offset:1024
	ds_read_b128 v[184:187], v188 offset:2048
	ds_read_b128 v[188:191], v188 offset:3072
	v_lshl_add_u64 v[230:231], s[0:1], 0, v[154:155]
	s_add_i32 m0, s67, 0xc000
	ds_read_b128 v[198:201], v179
	ds_read_b128 v[202:205], v179 offset:1024
	ds_read_b128 v[206:209], v179 offset:2048
	ds_read_b128 v[210:213], v179 offset:3072
	ds_read_b128 v[214:217], v179 offset:4096
	ds_read_b128 v[218:221], v179 offset:5120
	ds_read_b128 v[222:225], v179 offset:6144
	ds_read_b128 v[226:229], v179 offset:7168
	global_load_lds_dwordx4 v[230:231], off
	v_lshl_add_u64 v[230:231], s[0:1], 0, v[152:153]
	s_add_i32 m0, s67, 0xe000
	s_nop 0
	global_load_lds_dwordx4 v[230:231], off
	s_waitcnt vmcnt(8)
	s_waitcnt lgkmcnt(0)
	s_barrier
; #define PG8_STAGE(bufoff, gbase, voff) do { _Pragma("unroll") for (int _i = 0; _i < 2; ++_i) \
;         __builtin_amdgcn_global_load_lds((const unsigned*)((const char*)(gbase) + (voff)[_i]), (PG8_LAS unsigned*)(lds + (bufoff) + ldsw + _i * 8192), 16, 0, 0); } while (0)
; #define PG8_LDA(dst, b, h) do { _Pragma("unroll") for (int m = 0; m < 4; ++m) _Pragma("unroll") for (int k = 0; k < 2; ++k) dst[m][k] = *(const PG8_LAS bf16x8*)(lds + PG8_SA(b, h) + aoff + m * 2048 + k * 1024); } while (0)
; #define PG8_LDB(dst, b, h) do { _Pragma("unroll") for (int n = 0; n < 2; ++n) _Pragma("unroll") for (int k = 0; k < 2; ++k) dst[n][k] = *(const PG8_LAS bf16x8*)(lds + PG8_SB(b, h) + boff + n * 2048 + k * 1024); } while (0)
; #define PG8_MMA(ai, bj, At, Bt) do { __builtin_amdgcn_s_setprio(1); _Pragma("unroll") for (int m = 0; m < 4; ++m) _Pragma("unroll") for (int n = 0; n < 2; ++n) _Pragma("unroll") for (int k = 0; k < 2; ++k) \
;         acc[ai][bj][m][n] = __builtin_amdgcn_mfma_f32_16x16x32_bf16(Bt[n][k], At[m][k], acc[ai][bj][m][n], 0, 0, 0); __builtin_amdgcn_s_setprio(0); } while (0)
; #define PG8_WAIT_V(n) asm volatile("s_waitcnt vmcnt(" #n ")" ::: "memory")
; #define PG8_WAIT_L(n) asm volatile("s_waitcnt lgkmcnt(" #n ")" ::: "memory")
; #define PG8_BAR __builtin_amdgcn_s_barrier()
; #define PG8_SCHED __builtin_amdgcn_sched_barrier(0)
; template <class Epi, class Sched, bool ALIGN_EPI = false, bool SP2 = false>
; __device__ __forceinline__ void gemm_phase(PG8_LAS unsigned char* lds, const Gemm g, const Sched& S, const Epi& E, int wave_in) {
;     ...
;             PG8_WAIT_V(8); PG8_WAIT_L(0); PG8_BAR; PG8_MMA(0, 0, At, B0); PG8_MMA(0, 1, At, B1); PG8_BAR; PG8_SCHED;
;             PG8_LDA(At, 0, 1); PG8_STAGE(PG8_SB(0, 0), b2, voffB); PG8_STAGE(PG8_SB(0, 1), b2 + hstep, voffB); PG8_STAGE(PG8_SA(0, 0), a2, voffA);
;             PG8_WAIT_V(8); PG8_WAIT_L(0); PG8_BAR; PG8_MMA(1, 0, At, B0); PG8_MMA(1, 1, At, B1); PG8_BAR; PG8_SCHED;
;             PG8_LDB(B0, 1, 0); PG8_LDB(B1, 1, 1); PG8_SCHED; PG8_LDA(At, 1, 0); PG8_STAGE(PG8_SA(0, 1), a2 + hstep, voffA);
;             PG8_WAIT_V(8); PG8_WAIT_L(0); PG8_BAR; PG8_MMA(0, 0, At, B0); PG8_MMA(0, 1, At, B1); PG8_BAR; PG8_SCHED;
	s_waitcnt lgkmcnt(0)
	v_mfma_f32_16x16x32_bf16 v[124:127], v[156:159], v[198:201], v[124:127]
	v_mfma_f32_16x16x32_bf16 v[120:123], v[164:167], v[198:201], v[120:123]
	v_mfma_f32_16x16x32_bf16 v[108:111], v[156:159], v[206:209], v[108:111]
	v_mfma_f32_16x16x32_bf16 v[104:107], v[164:167], v[206:209], v[104:107]
	v_mfma_f32_16x16x32_bf16 v[92:95], v[156:159], v[214:217], v[92:95]
	v_mfma_f32_16x16x32_bf16 v[88:91], v[164:167], v[214:217], v[88:91]
	v_mfma_f32_16x16x32_bf16 v[76:79], v[156:159], v[222:225], v[76:79]
	v_mfma_f32_16x16x32_bf16 v[72:75], v[164:167], v[222:225], v[72:75]
	v_mfma_f32_16x16x32_bf16 v[124:127], v[160:163], v[202:205], v[124:127]
	v_mfma_f32_16x16x32_bf16 v[120:123], v[168:171], v[202:205], v[120:123]
	v_mfma_f32_16x16x32_bf16 v[108:111], v[160:163], v[210:213], v[108:111]
	v_mfma_f32_16x16x32_bf16 v[104:107], v[168:171], v[210:213], v[104:107]
	v_mfma_f32_16x16x32_bf16 v[92:95], v[160:163], v[218:221], v[92:95]
	v_mfma_f32_16x16x32_bf16 v[88:91], v[168:171], v[218:221], v[88:91]
	v_mfma_f32_16x16x32_bf16 v[76:79], v[160:163], v[226:229], v[76:79]
	v_mfma_f32_16x16x32_bf16 v[72:75], v[168:171], v[226:229], v[72:75]
	v_mfma_f32_16x16x32_bf16 v[116:119], v[172:175], v[198:201], v[116:119]
	v_mfma_f32_16x16x32_bf16 v[112:115], v[184:187], v[198:201], v[112:115]
	v_mfma_f32_16x16x32_bf16 v[100:103], v[172:175], v[206:209], v[100:103]
	v_mfma_f32_16x16x32_bf16 v[96:99], v[184:187], v[206:209], v[96:99]
	v_mfma_f32_16x16x32_bf16 v[84:87], v[172:175], v[214:217], v[84:87]
	v_mfma_f32_16x16x32_bf16 v[80:83], v[184:187], v[214:217], v[80:83]
	v_mfma_f32_16x16x32_bf16 v[68:71], v[172:175], v[222:225], v[68:71]
	v_mfma_f32_16x16x32_bf16 v[64:67], v[184:187], v[222:225], v[64:67]
	v_mfma_f32_16x16x32_bf16 v[116:119], v[180:183], v[202:205], v[116:119]
	v_mfma_f32_16x16x32_bf16 v[112:115], v[188:191], v[202:205], v[112:115]
	v_mfma_f32_16x16x32_bf16 v[100:103], v[180:183], v[210:213], v[100:103]
	v_mfma_f32_16x16x32_bf16 v[96:99], v[188:191], v[210:213], v[96:99]
	v_mfma_f32_16x16x32_bf16 v[84:87], v[180:183], v[218:221], v[84:87]
	v_mfma_f32_16x16x32_bf16 v[80:83], v[188:191], v[218:221], v[80:83]
	v_mfma_f32_16x16x32_bf16 v[68:71], v[180:183], v[226:229], v[68:71]
	v_mfma_f32_16x16x32_bf16 v[64:67], v[188:191], v[226:229], v[64:67]
	s_barrier
	s_add_i32 s42, s42, s66
	v_lshl_add_u64 v[230:231], s[4:5], 0, v[132:133]
	s_mov_b32 m0, s42
	ds_read_b128 v[198:201], v179 offset:16384
	ds_read_b128 v[202:205], v179 offset:17408
	ds_read_b128 v[206:209], v179 offset:18432
	ds_read_b128 v[210:213], v179 offset:19456
	ds_read_b128 v[214:217], v179 offset:20480
	ds_read_b128 v[218:221], v179 offset:21504
	ds_read_b128 v[222:225], v179 offset:22528
	ds_read_b128 v[226:229], v179 offset:23552
	global_load_lds_dwordx4 v[230:231], off
	s_add_i32 m0, s42, 0x2000
	s_add_u32 s42, s4, 0x40000
	v_lshl_add_u64 v[232:233], s[4:5], 0, v[128:129]
	s_addc_u32 s43, s5, 0
	s_add_i32 s44, s44, s66
	global_load_lds_dwordx4 v[232:233], off
	v_lshl_add_u64 v[234:235], s[42:43], 0, v[132:133]
	s_mov_b32 m0, s44
	v_lshl_add_u64 v[236:237], s[10:11], 0, v[130:131]
	global_load_lds_dwordx4 v[234:235], off
	v_lshl_add_u64 v[234:235], s[42:43], 0, v[128:129]
	s_add_i32 m0, s44, 0x2000
	s_nop 0
	global_load_lds_dwordx4 v[234:235], off
	v_lshl_add_u64 v[234:235], s[10:11], 0, v[134:135]
	s_mov_b32 m0, s67
	s_nop 0
	global_load_lds_dwordx4 v[234:235], off
	s_mov_b32 m0, s78
	s_nop 0
	global_load_lds_dwordx4 v[236:237], off
	s_waitcnt vmcnt(8)
	s_waitcnt lgkmcnt(0)
	s_barrier
	s_waitcnt lgkmcnt(0)
	v_mfma_f32_16x16x32_bf16 v[60:63], v[156:159], v[198:201], v[60:63]
	v_mfma_f32_16x16x32_bf16 v[56:59], v[164:167], v[198:201], v[56:59]
	v_mfma_f32_16x16x32_bf16 v[44:47], v[156:159], v[206:209], v[44:47]
	v_mfma_f32_16x16x32_bf16 v[40:43], v[164:167], v[206:209], v[40:43]
	v_mfma_f32_16x16x32_bf16 v[28:31], v[156:159], v[214:217], v[28:31]
	v_mfma_f32_16x16x32_bf16 v[24:27], v[164:167], v[214:217], v[24:27]
	v_mfma_f32_16x16x32_bf16 v[12:15], v[156:159], v[222:225], v[12:15]
	v_mfma_f32_16x16x32_bf16 v[8:11], v[164:167], v[222:225], v[8:11]
	v_mfma_f32_16x16x32_bf16 v[60:63], v[160:163], v[202:205], v[60:63]
	v_mfma_f32_16x16x32_bf16 v[56:59], v[168:171], v[202:205], v[56:59]
	v_mfma_f32_16x16x32_bf16 v[44:47], v[160:163], v[210:213], v[44:47]
	v_mfma_f32_16x16x32_bf16 v[40:43], v[168:171], v[210:213], v[40:43]
	v_mfma_f32_16x16x32_bf16 v[28:31], v[160:163], v[218:221], v[28:31]
	v_mfma_f32_16x16x32_bf16 v[24:27], v[168:171], v[218:221], v[24:27]
	v_mfma_f32_16x16x32_bf16 v[12:15], v[160:163], v[226:229], v[12:15]
	v_mfma_f32_16x16x32_bf16 v[8:11], v[168:171], v[226:229], v[8:11]
	v_mfma_f32_16x16x32_bf16 v[52:55], v[172:175], v[198:201], v[52:55]
	v_mfma_f32_16x16x32_bf16 v[48:51], v[184:187], v[198:201], v[48:51]
	v_mfma_f32_16x16x32_bf16 v[36:39], v[172:175], v[206:209], v[36:39]
	v_mfma_f32_16x16x32_bf16 v[32:35], v[184:187], v[206:209], v[32:35]
	v_mfma_f32_16x16x32_bf16 v[20:23], v[172:175], v[214:217], v[20:23]
	v_mfma_f32_16x16x32_bf16 v[16:19], v[184:187], v[214:217], v[16:19]
	v_mfma_f32_16x16x32_bf16 v[4:7], v[172:175], v[222:225], v[4:7]
	v_mfma_f32_16x16x32_bf16 v[0:3], v[184:187], v[222:225], v[0:3]
	v_mfma_f32_16x16x32_bf16 v[52:55], v[180:183], v[202:205], v[52:55]
	v_mfma_f32_16x16x32_bf16 v[48:51], v[188:191], v[202:205], v[48:51]
	v_mfma_f32_16x16x32_bf16 v[36:39], v[180:183], v[210:213], v[36:39]
	v_mfma_f32_16x16x32_bf16 v[32:35], v[188:191], v[210:213], v[32:35]
	v_mfma_f32_16x16x32_bf16 v[20:23], v[180:183], v[218:221], v[20:23]
	v_mfma_f32_16x16x32_bf16 v[16:19], v[188:191], v[218:221], v[16:19]
	v_mfma_f32_16x16x32_bf16 v[4:7], v[180:183], v[226:229], v[4:7]
	v_mfma_f32_16x16x32_bf16 v[0:3], v[188:191], v[226:229], v[0:3]
	s_barrier
; #define PG8_STAGE(bufoff, gbase, voff) do { _Pragma("unroll") for (int _i = 0; _i < 2; ++_i) \
;         __builtin_amdgcn_global_load_lds((const unsigned*)((const char*)(gbase) + (voff)[_i]), (PG8_LAS unsigned*)(lds + (bufoff) + ldsw + _i * 8192), 16, 0, 0); } while (0)
; #define PG8_LDA(dst, b, h) do { _Pragma("unroll") for (int m = 0; m < 4; ++m) _Pragma("unroll") for (int k = 0; k < 2; ++k) dst[m][k] = *(const PG8_LAS bf16x8*)(lds + PG8_SA(b, h) + aoff + m * 2048 + k * 1024); } while (0)
; #define PG8_LDB(dst, b, h) do { _Pragma("unroll") for (int n = 0; n < 2; ++n) _Pragma("unroll") for (int k = 0; k < 2; ++k) dst[n][k] = *(const PG8_LAS bf16x8*)(lds + PG8_SB(b, h) + boff + n * 2048 + k * 1024); } while (0)
; #define PG8_MMA(ai, bj, At, Bt) do { __builtin_amdgcn_s_setprio(1); _Pragma("unroll") for (int m = 0; m < 4; ++m) _Pragma("unroll") for (int n = 0; n < 2; ++n) _Pragma("unroll") for (int k = 0; k < 2; ++k) \
;         acc[ai][bj][m][n] = __builtin_amdgcn_mfma_f32_16x16x32_bf16(Bt[n][k], At[m][k], acc[ai][bj][m][n], 0, 0, 0); __builtin_amdgcn_s_setprio(0); } while (0)
; #define PG8_WAIT_V(n) asm volatile("s_waitcnt vmcnt(" #n ")" ::: "memory")
; #define PG8_WAIT_L(n) asm volatile("s_waitcnt lgkmcnt(" #n ")" ::: "memory")
; #define PG8_BAR __builtin_amdgcn_s_barrier()
; #define PG8_SCHED __builtin_amdgcn_sched_barrier(0)
; template <class Epi, class Sched, bool ALIGN_EPI = false, bool SP2 = false>
; __device__ __forceinline__ void gemm_phase(PG8_LAS unsigned char* lds, const Gemm g, const Sched& S, const Epi& E, int wave_in) {
;     ...
;             PG8_LDB(B0, 1, 0); PG8_LDB(B1, 1, 1); PG8_SCHED; PG8_LDA(At, 1, 0); PG8_STAGE(PG8_SA(0, 1), a2 + hstep, voffA);
;             PG8_WAIT_V(8); PG8_WAIT_L(0); PG8_BAR; PG8_MMA(0, 0, At, B0); PG8_MMA(0, 1, At, B1); PG8_BAR; PG8_SCHED;
;             PG8_LDA(At, 1, 1); PG8_STAGE(PG8_SB(1, 0), b3, voffB); PG8_STAGE(PG8_SB(1, 1), b3 + hstep, voffB); PG8_STAGE(PG8_SA(1, 0), a3, voffA);
;             PG8_WAIT_V(8); PG8_WAIT_L(0); PG8_BAR; PG8_MMA(1, 0, At, B0); PG8_MMA(1, 1, At, B1); PG8_BAR; PG8_SCHED;
	s_add_i32 s42, s65, 0x100
	s_add_i32 s43, s52, 0x100
	v_add_u32_e32 v168, s42, v177
	v_add_u32_e32 v188, s43, v177
	ds_read_b128 v[156:159], v168
	ds_read_b128 v[160:163], v168 offset:1024
	ds_read_b128 v[164:167], v168 offset:2048
	ds_read_b128 v[168:171], v168 offset:3072
	ds_read_b128 v[172:175], v188
	ds_read_b128 v[180:183], v188 offset:1024
	ds_read_b128 v[184:187], v188 offset:2048
	ds_read_b128 v[188:191], v188 offset:3072
	s_add_u32 s10, s10, 0x40000
	s_addc_u32 s11, s11, 0
	s_mov_b32 m0, s79
	v_lshl_add_u64 v[238:239], s[10:11], 0, v[134:135]
	ds_read_b128 v[198:201], v179 offset:32768
	ds_read_b128 v[202:205], v179 offset:33792
	ds_read_b128 v[206:209], v179 offset:34816
	ds_read_b128 v[210:213], v179 offset:35840
	ds_read_b128 v[214:217], v179 offset:36864
	ds_read_b128 v[218:221], v179 offset:37888
	ds_read_b128 v[222:225], v179 offset:38912
	ds_read_b128 v[226:229], v179 offset:39936
	global_load_lds_dwordx4 v[238:239], off
	v_lshl_add_u64 v[238:239], s[10:11], 0, v[130:131]
	s_mov_b32 m0, s82
	s_nop 0
	global_load_lds_dwordx4 v[238:239], off
	s_waitcnt vmcnt(8)
	s_waitcnt lgkmcnt(0)
	s_barrier
	s_waitcnt lgkmcnt(0)
	v_mfma_f32_16x16x32_bf16 v[124:127], v[156:159], v[198:201], v[124:127]
	v_mfma_f32_16x16x32_bf16 v[120:123], v[164:167], v[198:201], v[120:123]
	v_mfma_f32_16x16x32_bf16 v[108:111], v[156:159], v[206:209], v[108:111]
	v_mfma_f32_16x16x32_bf16 v[104:107], v[164:167], v[206:209], v[104:107]
	v_mfma_f32_16x16x32_bf16 v[92:95], v[156:159], v[214:217], v[92:95]
	v_mfma_f32_16x16x32_bf16 v[88:91], v[164:167], v[214:217], v[88:91]
	v_mfma_f32_16x16x32_bf16 v[76:79], v[156:159], v[222:225], v[76:79]
	v_mfma_f32_16x16x32_bf16 v[72:75], v[164:167], v[222:225], v[72:75]
	v_mfma_f32_16x16x32_bf16 v[124:127], v[160:163], v[202:205], v[124:127]
	v_mfma_f32_16x16x32_bf16 v[120:123], v[168:171], v[202:205], v[120:123]
	v_mfma_f32_16x16x32_bf16 v[108:111], v[160:163], v[210:213], v[108:111]
	v_mfma_f32_16x16x32_bf16 v[104:107], v[168:171], v[210:213], v[104:107]
	v_mfma_f32_16x16x32_bf16 v[92:95], v[160:163], v[218:221], v[92:95]
	v_mfma_f32_16x16x32_bf16 v[88:91], v[168:171], v[218:221], v[88:91]
	v_mfma_f32_16x16x32_bf16 v[76:79], v[160:163], v[226:229], v[76:79]
	v_mfma_f32_16x16x32_bf16 v[72:75], v[168:171], v[226:229], v[72:75]
	v_mfma_f32_16x16x32_bf16 v[116:119], v[172:175], v[198:201], v[116:119]
	v_mfma_f32_16x16x32_bf16 v[112:115], v[184:187], v[198:201], v[112:115]
	v_mfma_f32_16x16x32_bf16 v[100:103], v[172:175], v[206:209], v[100:103]
	v_mfma_f32_16x16x32_bf16 v[96:99], v[184:187], v[206:209], v[96:99]
	v_mfma_f32_16x16x32_bf16 v[84:87], v[172:175], v[214:217], v[84:87]
	v_mfma_f32_16x16x32_bf16 v[80:83], v[184:187], v[214:217], v[80:83]
	v_mfma_f32_16x16x32_bf16 v[68:71], v[172:175], v[222:225], v[68:71]
	v_mfma_f32_16x16x32_bf16 v[64:67], v[184:187], v[222:225], v[64:67]
	v_mfma_f32_16x16x32_bf16 v[116:119], v[180:183], v[202:205], v[116:119]
	v_mfma_f32_16x16x32_bf16 v[112:115], v[188:191], v[202:205], v[112:115]
	v_mfma_f32_16x16x32_bf16 v[100:103], v[180:183], v[210:213], v[100:103]
	v_mfma_f32_16x16x32_bf16 v[96:99], v[188:191], v[210:213], v[96:99]
	v_mfma_f32_16x16x32_bf16 v[84:87], v[180:183], v[218:221], v[84:87]
	v_mfma_f32_16x16x32_bf16 v[80:83], v[188:191], v[218:221], v[80:83]
	v_mfma_f32_16x16x32_bf16 v[68:71], v[180:183], v[226:229], v[68:71]
	v_mfma_f32_16x16x32_bf16 v[64:67], v[188:191], v[226:229], v[64:67]
	s_barrier
	s_add_i32 s10, s42, s66
	v_lshl_add_u64 v[230:231], v[230:231], 0, s[88:89]
	s_mov_b32 m0, s10
	ds_read_b128 v[198:201], v179 offset:49152
	ds_read_b128 v[202:205], v179 offset:50176
	ds_read_b128 v[206:209], v179 offset:51200
	ds_read_b128 v[210:213], v179 offset:52224
	ds_read_b128 v[214:217], v179 offset:53248
	ds_read_b128 v[218:221], v179 offset:54272
	ds_read_b128 v[222:225], v179 offset:55296
	ds_read_b128 v[226:229], v179 offset:56320
	global_load_lds_dwordx4 v[230:231], off
	s_add_i32 m0, s10, 0x2000
	s_add_u32 s4, s4, 0x40080
	v_lshl_add_u64 v[230:231], v[232:233], 0, s[88:89]
	s_addc_u32 s5, s5, 0
	s_add_i32 s10, s43, s66
	global_load_lds_dwordx4 v[230:231], off
	v_lshl_add_u64 v[230:231], s[4:5], 0, v[132:133]
	s_mov_b32 m0, s10
	s_nop 0
	global_load_lds_dwordx4 v[230:231], off
	v_lshl_add_u64 v[230:231], s[4:5], 0, v[128:129]
	s_add_i32 m0, s10, 0x2000
	s_nop 0
	global_load_lds_dwordx4 v[230:231], off
	v_lshl_add_u64 v[230:231], v[234:235], 0, s[88:89]
	s_mov_b32 m0, s72
	s_nop 0
	global_load_lds_dwordx4 v[230:231], off
	v_lshl_add_u64 v[230:231], v[236:237], 0, s[88:89]
	s_mov_b32 m0, s73
	s_nop 0
	global_load_lds_dwordx4 v[230:231], off
	s_waitcnt vmcnt(8)
	s_waitcnt lgkmcnt(0)
	s_barrier
	s_waitcnt lgkmcnt(0)
	v_mfma_f32_16x16x32_bf16 v[60:63], v[156:159], v[198:201], v[60:63]
	v_mfma_f32_16x16x32_bf16 v[56:59], v[164:167], v[198:201], v[56:59]
	v_mfma_f32_16x16x32_bf16 v[44:47], v[156:159], v[206:209], v[44:47]
	v_mfma_f32_16x16x32_bf16 v[40:43], v[164:167], v[206:209], v[40:43]
	v_mfma_f32_16x16x32_bf16 v[28:31], v[156:159], v[214:217], v[28:31]
	v_mfma_f32_16x16x32_bf16 v[24:27], v[164:167], v[214:217], v[24:27]
	v_mfma_f32_16x16x32_bf16 v[12:15], v[156:159], v[222:225], v[12:15]
	v_mfma_f32_16x16x32_bf16 v[8:11], v[164:167], v[222:225], v[8:11]
	v_mfma_f32_16x16x32_bf16 v[60:63], v[160:163], v[202:205], v[60:63]
	v_mfma_f32_16x16x32_bf16 v[56:59], v[168:171], v[202:205], v[56:59]
	v_mfma_f32_16x16x32_bf16 v[44:47], v[160:163], v[210:213], v[44:47]
	v_mfma_f32_16x16x32_bf16 v[40:43], v[168:171], v[210:213], v[40:43]
	v_mfma_f32_16x16x32_bf16 v[28:31], v[160:163], v[218:221], v[28:31]
	v_mfma_f32_16x16x32_bf16 v[24:27], v[168:171], v[218:221], v[24:27]
	v_mfma_f32_16x16x32_bf16 v[12:15], v[160:163], v[226:229], v[12:15]
	v_mfma_f32_16x16x32_bf16 v[8:11], v[168:171], v[226:229], v[8:11]
	v_mfma_f32_16x16x32_bf16 v[52:55], v[172:175], v[198:201], v[52:55]
	v_mfma_f32_16x16x32_bf16 v[48:51], v[184:187], v[198:201], v[48:51]
	v_mfma_f32_16x16x32_bf16 v[36:39], v[172:175], v[206:209], v[36:39]
	v_mfma_f32_16x16x32_bf16 v[32:35], v[184:187], v[206:209], v[32:35]
	v_mfma_f32_16x16x32_bf16 v[20:23], v[172:175], v[214:217], v[20:23]
	v_mfma_f32_16x16x32_bf16 v[16:19], v[184:187], v[214:217], v[16:19]
	v_mfma_f32_16x16x32_bf16 v[4:7], v[172:175], v[222:225], v[4:7]
	v_mfma_f32_16x16x32_bf16 v[0:3], v[184:187], v[222:225], v[0:3]
	v_mfma_f32_16x16x32_bf16 v[52:55], v[180:183], v[202:205], v[52:55]
	v_mfma_f32_16x16x32_bf16 v[48:51], v[188:191], v[202:205], v[48:51]
	v_mfma_f32_16x16x32_bf16 v[36:39], v[180:183], v[210:213], v[36:39]
	v_mfma_f32_16x16x32_bf16 v[32:35], v[188:191], v[210:213], v[32:35]
	v_mfma_f32_16x16x32_bf16 v[20:23], v[180:183], v[218:221], v[20:23]
	v_mfma_f32_16x16x32_bf16 v[16:19], v[188:191], v[218:221], v[16:19]
	v_mfma_f32_16x16x32_bf16 v[4:7], v[180:183], v[226:229], v[4:7]
	v_mfma_f32_16x16x32_bf16 v[0:3], v[188:191], v[226:229], v[0:3]
	s_barrier
	s_add_i32 s34, s34, 2
	s_add_u32 s31, s31, 0x100
	s_addc_u32 s33, s33, 0
	s_add_u32 s0, s0, 0x100
	s_addc_u32 s1, s1, 0
	s_cmp_gt_u32 s34, 13
	s_cbranch_scc0 .LBB0_273

; #define PG8_STAGE(bufoff, gbase, voff) do { _Pragma("unroll") for (int _i = 0; _i < 2; ++_i) \
;         __builtin_amdgcn_global_load_lds((const unsigned*)((const char*)(gbase) + (voff)[_i]), (PG8_LAS unsigned*)(lds + (bufoff) + ldsw + _i * 8192), 16, 0, 0); } while (0)
; #define PG8_LDA(dst, b, h) do { _Pragma("unroll") for (int m = 0; m < 4; ++m) _Pragma("unroll") for (int k = 0; k < 2; ++k) dst[m][k] = *(const PG8_LAS bf16x8*)(lds + PG8_SA(b, h) + aoff + m * 2048 + k * 1024); } while (0)
; #define PG8_LDB(dst, b, h) do { _Pragma("unroll") for (int n = 0; n < 2; ++n) _Pragma("unroll") for (int k = 0; k < 2; ++k) dst[n][k] = *(const PG8_LAS bf16x8*)(lds + PG8_SB(b, h) + boff + n * 2048 + k * 1024); } while (0)
; #define PG8_MMA(ai, bj, At, Bt) do { __builtin_amdgcn_s_setprio(1); _Pragma("unroll") for (int m = 0; m < 4; ++m) _Pragma("unroll") for (int n = 0; n < 2; ++n) _Pragma("unroll") for (int k = 0; k < 2; ++k) \
;         acc[ai][bj][m][n] = __builtin_amdgcn_mfma_f32_16x16x32_bf16(Bt[n][k], At[m][k], acc[ai][bj][m][n], 0, 0, 0); __builtin_amdgcn_s_setprio(0); } while (0)
; template <class Epi, class Sched, bool ALIGN_EPI = false, bool SP2 = false>
; __device__ __forceinline__ void gemm_phase(PG8_LAS unsigned char* lds, const Gemm g, const Sched& S, const Epi& E, int wave_in) {
;     ...
;         const char* nA = has_next ? (const char*)g.A + (size_t)(nxt.pm >> g.ash) * g.astride + (size_t)nxt.pm * tstep : cA; const char* nB = has_next ? (const char*)g.Bt + (size_t)(nxt.pm >> g.bsh) * g.bstride + (size_t)nxt.pn * tstep : cB;
;         for (int t = 0; t < nt; t += 2) {
;             const bool last = (t == nt - 2);
;             const char* a1 = cA + (size_t)(t + 1) * kstep;
;             const char* a2 = last ? nA : cA + (size_t)(t + 2) * kstep; const char* b2 = last ? nB : cB + (size_t)(t + 2) * kstep;
;             const char* a3 = a2 + kstep; const char* b3 = b2 + kstep;
;             if (last && has_next) S.a_ready(nxt);
;             if constexpr (SP2) {
;             PG8_LDB(B0, 0, 0); PG8_LDB(B1, 0, 1); PG8_SCHED; PG8_LDA(At, 0, 0); PG8_STAGE(PG8_SA(1, 1), a1 + hstep, voffA);
;             PG8_WAIT_V(8); PG8_WAIT_L(0); PG8_BAR; PG8_MMA(0, 0, At, B0); PG8_MMA(0, 1, At, B1); PG8_BAR; PG8_SCHED;
;             PG8_LDA(At, 0, 1); PG8_STAGE(PG8_SB(0, 0), b2, voffB); PG8_STAGE(PG8_SB(0, 1), b2 + hstep, voffB); PG8_STAGE(PG8_SA(0, 0), a2, voffA);
.LBB0_484:
	s_ashr_i32 s15, s14, 31
	s_lshl_b64 s[16:17], s[14:15], 17
	s_add_u32 s16, s47, s16
	s_addc_u32 s17, s46, s17
	s_and_b64 s[18:19], s[10:11], exec
	s_cselect_b32 s15, s17, s25
	s_cselect_b32 s21, s16, s24
	s_ashr_i32 s13, s12, 31
	s_lshl_b64 s[18:19], s[12:13], 17
	s_add_u32 s18, s63, s18
	s_addc_u32 s19, s62, s19
	s_and_b64 s[38:39], s[10:11], exec
	s_cselect_b32 s13, s19, s23
	s_cselect_b32 s27, s18, s22
	s_mov_b32 s34, 0
	s_mov_b64 s[38:39], -1
	s_mov_b64 s[40:41], 0
	s_add_u32 s53, s24, s34
	s_addc_u32 s66, s25, 0
	s_add_u32 s44, s53, 0x100
	s_addc_u32 s45, s66, 0
	s_and_b64 s[42:43], s[40:41], exec
	s_cselect_b32 s45, s15, s45
	s_cselect_b32 s44, s21, s44
	s_add_u32 s34, s22, s34
	s_addc_u32 s42, s23, 0
	s_add_u32 s34, s34, 0x100
	s_addc_u32 s42, s42, 0
	s_add_i32 s97, s35, 0x100
	s_and_b64 s[40:41], s[40:41], exec
	s_cselect_b32 s61, s13, s42
	s_cselect_b32 s60, s27, s34
	s_add_i32 s41, s90, 0x100
	s_add_u32 s76, s53, 0x10080
	s_addc_u32 s77, s66, 0
	s_add_i32 s96, s97, s72
	s_add_i32 m0, s75, 0xc000
	s_add_i32 vcc_hi, s75, 0xe000
	s_add_i32 s81, s96, 0x2000
	s_add_u32 s66, s60, 0x10000
	v_add_u32_e32 v166, s97, v152
	v_add_u32_e32 v182, s41, v152
	s_addc_u32 s67, s61, 0
	s_add_i32 s95, s41, s72
	ds_read_b128 v[154:157], v166
	ds_read_b128 v[158:161], v166 offset:1024
	ds_read_b128 v[162:165], v166 offset:2048
	ds_read_b128 v[166:169], v166 offset:3072
	ds_read_b128 v[170:173], v182
	ds_read_b128 v[174:177], v182 offset:1024
	ds_read_b128 v[178:181], v182 offset:2048
	ds_read_b128 v[182:185], v182 offset:3072
	s_add_i32 s94, s95, 0x2000
	s_add_i32 s71, s65, 0x100
	s_add_i32 s69, s52, 0x100
	s_add_u32 s42, s44, 0x10000
	s_addc_u32 s43, s45, 0
	s_add_i32 s53, s71, s72
	s_add_i32 s34, s53, 0x2000
	s_add_u32 s40, s60, 0x10080
	s_addc_u32 s41, s61, 0
	s_add_i32 vcc_lo, s69, s72
	s_add_i32 s97, vcc_lo, 0x2000
	v_lshl_add_u64 v[190:191], s[76:77], 0, v[134:135]
	ds_read_b128 v[186:189], v153
	ds_read_b128 v[198:201], v153 offset:1024
	ds_read_b128 v[202:205], v153 offset:2048
	ds_read_b128 v[206:209], v153 offset:3072
	ds_read_b128 v[210:213], v153 offset:4096
	ds_read_b128 v[214:217], v153 offset:5120
	ds_read_b128 v[218:221], v153 offset:6144
	ds_read_b128 v[222:225], v153 offset:7168
	global_load_lds_dwordx4 v[190:191], off
	v_lshl_add_u64 v[190:191], s[76:77], 0, v[130:131]
	s_mov_b32 m0, vcc_hi
	s_nop 0
	global_load_lds_dwordx4 v[190:191], off
	s_waitcnt vmcnt(8)
	s_waitcnt lgkmcnt(0)
	s_barrier
	s_waitcnt lgkmcnt(0)
	v_mfma_f32_16x16x32_bf16 v[124:127], v[154:157], v[186:189], 0
	v_mfma_f32_16x16x32_bf16 v[120:123], v[162:165], v[186:189], 0
	v_mfma_f32_16x16x32_bf16 v[116:119], v[154:157], v[202:205], 0
	v_mfma_f32_16x16x32_bf16 v[108:111], v[162:165], v[202:205], 0
	v_mfma_f32_16x16x32_bf16 v[100:103], v[154:157], v[210:213], 0
	v_mfma_f32_16x16x32_bf16 v[92:95], v[162:165], v[210:213], 0
	v_mfma_f32_16x16x32_bf16 v[84:87], v[154:157], v[218:221], 0
	v_mfma_f32_16x16x32_bf16 v[76:79], v[162:165], v[218:221], 0
	v_mfma_f32_16x16x32_bf16 v[124:127], v[158:161], v[198:201], v[124:127]
	v_mfma_f32_16x16x32_bf16 v[120:123], v[166:169], v[198:201], v[120:123]
	v_mfma_f32_16x16x32_bf16 v[116:119], v[158:161], v[206:209], v[116:119]
	v_mfma_f32_16x16x32_bf16 v[108:111], v[166:169], v[206:209], v[108:111]
	v_mfma_f32_16x16x32_bf16 v[100:103], v[158:161], v[214:217], v[100:103]
	v_mfma_f32_16x16x32_bf16 v[92:95], v[166:169], v[214:217], v[92:95]
	v_mfma_f32_16x16x32_bf16 v[84:87], v[158:161], v[222:225], v[84:87]
	v_mfma_f32_16x16x32_bf16 v[76:79], v[166:169], v[222:225], v[76:79]
	v_mfma_f32_16x16x32_bf16 v[112:115], v[170:173], v[186:189], 0
	v_mfma_f32_16x16x32_bf16 v[104:107], v[178:181], v[186:189], 0
	v_mfma_f32_16x16x32_bf16 v[96:99], v[170:173], v[202:205], 0
	v_mfma_f32_16x16x32_bf16 v[88:91], v[178:181], v[202:205], 0
	v_mfma_f32_16x16x32_bf16 v[80:83], v[170:173], v[210:213], 0
	v_mfma_f32_16x16x32_bf16 v[72:75], v[178:181], v[210:213], 0
	v_mfma_f32_16x16x32_bf16 v[68:71], v[170:173], v[218:221], 0
	v_mfma_f32_16x16x32_bf16 v[64:67], v[178:181], v[218:221], 0
	v_mfma_f32_16x16x32_bf16 v[112:115], v[174:177], v[198:201], v[112:115]
	v_mfma_f32_16x16x32_bf16 v[104:107], v[182:185], v[198:201], v[104:107]
	v_mfma_f32_16x16x32_bf16 v[96:99], v[174:177], v[206:209], v[96:99]
	v_mfma_f32_16x16x32_bf16 v[88:91], v[182:185], v[206:209], v[88:91]
	v_mfma_f32_16x16x32_bf16 v[80:83], v[174:177], v[214:217], v[80:83]
	v_mfma_f32_16x16x32_bf16 v[72:75], v[182:185], v[214:217], v[72:75]
	v_mfma_f32_16x16x32_bf16 v[68:71], v[174:177], v[222:225], v[68:71]
	v_mfma_f32_16x16x32_bf16 v[64:67], v[182:185], v[222:225], v[64:67]
	s_barrier
	s_mov_b32 m0, s96
	v_lshl_add_u64 v[190:191], s[60:61], 0, v[132:133]
	ds_read_b128 v[186:189], v153 offset:16384
	ds_read_b128 v[198:201], v153 offset:17408
	ds_read_b128 v[202:205], v153 offset:18432
	ds_read_b128 v[206:209], v153 offset:19456
	ds_read_b128 v[210:213], v153 offset:20480
	ds_read_b128 v[214:217], v153 offset:21504
	ds_read_b128 v[218:221], v153 offset:22528
	ds_read_b128 v[222:225], v153 offset:23552
	global_load_lds_dwordx4 v[190:191], off
	v_lshl_add_u64 v[226:227], s[60:61], 0, v[128:129]
	s_mov_b32 m0, s81
	v_lshl_add_u64 v[228:229], s[66:67], 0, v[132:133]
	global_load_lds_dwordx4 v[226:227], off
	s_mov_b32 m0, s95
	v_lshl_add_u64 v[230:231], s[44:45], 0, v[130:131]
	global_load_lds_dwordx4 v[228:229], off
	v_lshl_add_u64 v[228:229], s[66:67], 0, v[128:129]
	s_mov_b32 m0, s94
	s_nop 0
	global_load_lds_dwordx4 v[228:229], off
	v_lshl_add_u64 v[228:229], s[44:45], 0, v[134:135]
	s_mov_b32 m0, s75
	s_nop 0
	global_load_lds_dwordx4 v[228:229], off
	s_mov_b32 m0, s78
	s_nop 0
	global_load_lds_dwordx4 v[230:231], off
	s_waitcnt vmcnt(8)
	s_waitcnt lgkmcnt(0)
	s_barrier
; #define PG8_STAGE(bufoff, gbase, voff) do { _Pragma("unroll") for (int _i = 0; _i < 2; ++_i) \
;         __builtin_amdgcn_global_load_lds((const unsigned*)((const char*)(gbase) + (voff)[_i]), (PG8_LAS unsigned*)(lds + (bufoff) + ldsw + _i * 8192), 16, 0, 0); } while (0)
; #define PG8_LDA(dst, b, h) do { _Pragma("unroll") for (int m = 0; m < 4; ++m) _Pragma("unroll") for (int k = 0; k < 2; ++k) dst[m][k] = *(const PG8_LAS bf16x8*)(lds + PG8_SA(b, h) + aoff + m * 2048 + k * 1024); } while (0)
; #define PG8_LDB(dst, b, h) do { _Pragma("unroll") for (int n = 0; n < 2; ++n) _Pragma("unroll") for (int k = 0; k < 2; ++k) dst[n][k] = *(const PG8_LAS bf16x8*)(lds + PG8_SB(b, h) + boff + n * 2048 + k * 1024); } while (0)
; #define PG8_MMA(ai, bj, At, Bt) do { __builtin_amdgcn_s_setprio(1); _Pragma("unroll") for (int m = 0; m < 4; ++m) _Pragma("unroll") for (int n = 0; n < 2; ++n) _Pragma("unroll") for (int k = 0; k < 2; ++k) \
;         acc[ai][bj][m][n] = __builtin_amdgcn_mfma_f32_16x16x32_bf16(Bt[n][k], At[m][k], acc[ai][bj][m][n], 0, 0, 0); __builtin_amdgcn_s_setprio(0); } while (0)
; #define PG8_WAIT_V(n) asm volatile("s_waitcnt vmcnt(" #n ")" ::: "memory")
; #define PG8_WAIT_L(n) asm volatile("s_waitcnt lgkmcnt(" #n ")" ::: "memory")
; #define PG8_BAR __builtin_amdgcn_s_barrier()
; #define PG8_SCHED __builtin_amdgcn_sched_barrier(0)
; template <class Epi, class Sched, bool ALIGN_EPI = false, bool SP2 = false>
; __device__ __forceinline__ void gemm_phase(PG8_LAS unsigned char* lds, const Gemm g, const Sched& S, const Epi& E, int wave_in) {
;     ...
;             PG8_WAIT_V(8); PG8_WAIT_L(0); PG8_BAR; PG8_MMA(1, 0, At, B0); PG8_MMA(1, 1, At, B1); PG8_BAR; PG8_SCHED;
;             PG8_LDB(B0, 1, 0); PG8_LDB(B1, 1, 1); PG8_SCHED; PG8_LDA(At, 1, 0); PG8_STAGE(PG8_SA(0, 1), a2 + hstep, voffA);
;             PG8_WAIT_V(8); PG8_WAIT_L(0); PG8_BAR; PG8_MMA(0, 0, At, B0); PG8_MMA(0, 1, At, B1); PG8_BAR; PG8_SCHED;
	s_waitcnt lgkmcnt(0)
	v_mfma_f32_16x16x32_bf16 v[60:63], v[154:157], v[186:189], 0
	v_mfma_f32_16x16x32_bf16 v[56:59], v[162:165], v[186:189], 0
	v_mfma_f32_16x16x32_bf16 v[52:55], v[154:157], v[202:205], 0
	v_mfma_f32_16x16x32_bf16 v[44:47], v[162:165], v[202:205], 0
	v_mfma_f32_16x16x32_bf16 v[36:39], v[154:157], v[210:213], 0
	v_mfma_f32_16x16x32_bf16 v[28:31], v[162:165], v[210:213], 0
	v_mfma_f32_16x16x32_bf16 v[20:23], v[154:157], v[218:221], 0
	v_mfma_f32_16x16x32_bf16 v[12:15], v[162:165], v[218:221], 0
	v_mfma_f32_16x16x32_bf16 v[60:63], v[158:161], v[198:201], v[60:63]
	v_mfma_f32_16x16x32_bf16 v[56:59], v[166:169], v[198:201], v[56:59]
	v_mfma_f32_16x16x32_bf16 v[52:55], v[158:161], v[206:209], v[52:55]
	v_mfma_f32_16x16x32_bf16 v[44:47], v[166:169], v[206:209], v[44:47]
	v_mfma_f32_16x16x32_bf16 v[36:39], v[158:161], v[214:217], v[36:39]
	v_mfma_f32_16x16x32_bf16 v[28:31], v[166:169], v[214:217], v[28:31]
	v_mfma_f32_16x16x32_bf16 v[20:23], v[158:161], v[222:225], v[20:23]
	v_mfma_f32_16x16x32_bf16 v[12:15], v[166:169], v[222:225], v[12:15]
	v_mfma_f32_16x16x32_bf16 v[48:51], v[170:173], v[186:189], 0
	v_mfma_f32_16x16x32_bf16 v[40:43], v[178:181], v[186:189], 0
	v_mfma_f32_16x16x32_bf16 v[32:35], v[170:173], v[202:205], 0
	v_mfma_f32_16x16x32_bf16 v[24:27], v[178:181], v[202:205], 0
	v_mfma_f32_16x16x32_bf16 v[16:19], v[170:173], v[210:213], 0
	v_mfma_f32_16x16x32_bf16 v[8:11], v[178:181], v[210:213], 0
	v_mfma_f32_16x16x32_bf16 v[4:7], v[170:173], v[218:221], 0
	v_mfma_f32_16x16x32_bf16 v[0:3], v[178:181], v[218:221], 0
	v_mfma_f32_16x16x32_bf16 v[48:51], v[174:177], v[198:201], v[48:51]
	v_mfma_f32_16x16x32_bf16 v[40:43], v[182:185], v[198:201], v[40:43]
	v_mfma_f32_16x16x32_bf16 v[32:35], v[174:177], v[206:209], v[32:35]
	v_mfma_f32_16x16x32_bf16 v[24:27], v[182:185], v[206:209], v[24:27]
	v_mfma_f32_16x16x32_bf16 v[16:19], v[174:177], v[214:217], v[16:19]
	v_mfma_f32_16x16x32_bf16 v[8:11], v[182:185], v[214:217], v[8:11]
	v_mfma_f32_16x16x32_bf16 v[4:7], v[174:177], v[222:225], v[4:7]
	v_mfma_f32_16x16x32_bf16 v[0:3], v[182:185], v[222:225], v[0:3]
	s_barrier
	v_add_u32_e32 v166, s71, v152
	v_add_u32_e32 v182, s69, v152
	ds_read_b128 v[154:157], v166
	ds_read_b128 v[158:161], v166 offset:1024
	ds_read_b128 v[162:165], v166 offset:2048
	ds_read_b128 v[166:169], v166 offset:3072
	ds_read_b128 v[170:173], v182
	ds_read_b128 v[174:177], v182 offset:1024
	ds_read_b128 v[178:181], v182 offset:2048
	ds_read_b128 v[182:185], v182 offset:3072
	s_mov_b32 m0, s79
	v_lshl_add_u64 v[232:233], s[42:43], 0, v[134:135]
	ds_read_b128 v[186:189], v153 offset:32768
	ds_read_b128 v[198:201], v153 offset:33792
	ds_read_b128 v[202:205], v153 offset:34816
	ds_read_b128 v[206:209], v153 offset:35840
	ds_read_b128 v[210:213], v153 offset:36864
	ds_read_b128 v[214:217], v153 offset:37888
	ds_read_b128 v[218:221], v153 offset:38912
	ds_read_b128 v[222:225], v153 offset:39936
	global_load_lds_dwordx4 v[232:233], off
	v_lshl_add_u64 v[232:233], s[42:43], 0, v[130:131]
	s_mov_b32 m0, s82
	s_nop 0
	global_load_lds_dwordx4 v[232:233], off
	s_waitcnt vmcnt(8)
	s_waitcnt lgkmcnt(0)
	s_barrier
	s_waitcnt lgkmcnt(0)
	v_mfma_f32_16x16x32_bf16 v[124:127], v[154:157], v[186:189], v[124:127]
	v_mfma_f32_16x16x32_bf16 v[120:123], v[162:165], v[186:189], v[120:123]
	v_mfma_f32_16x16x32_bf16 v[116:119], v[154:157], v[202:205], v[116:119]
	v_mfma_f32_16x16x32_bf16 v[108:111], v[162:165], v[202:205], v[108:111]
	v_mfma_f32_16x16x32_bf16 v[100:103], v[154:157], v[210:213], v[100:103]
	v_mfma_f32_16x16x32_bf16 v[92:95], v[162:165], v[210:213], v[92:95]
	v_mfma_f32_16x16x32_bf16 v[84:87], v[154:157], v[218:221], v[84:87]
	v_mfma_f32_16x16x32_bf16 v[76:79], v[162:165], v[218:221], v[76:79]
	v_mfma_f32_16x16x32_bf16 v[124:127], v[158:161], v[198:201], v[124:127]
	v_mfma_f32_16x16x32_bf16 v[120:123], v[166:169], v[198:201], v[120:123]
	v_mfma_f32_16x16x32_bf16 v[116:119], v[158:161], v[206:209], v[116:119]
	v_mfma_f32_16x16x32_bf16 v[108:111], v[166:169], v[206:209], v[108:111]
	v_mfma_f32_16x16x32_bf16 v[100:103], v[158:161], v[214:217], v[100:103]
	v_mfma_f32_16x16x32_bf16 v[92:95], v[166:169], v[214:217], v[92:95]
	v_mfma_f32_16x16x32_bf16 v[84:87], v[158:161], v[222:225], v[84:87]
	v_mfma_f32_16x16x32_bf16 v[76:79], v[166:169], v[222:225], v[76:79]
	v_mfma_f32_16x16x32_bf16 v[112:115], v[170:173], v[186:189], v[112:115]
	v_mfma_f32_16x16x32_bf16 v[104:107], v[178:181], v[186:189], v[104:107]
	v_mfma_f32_16x16x32_bf16 v[96:99], v[170:173], v[202:205], v[96:99]
	v_mfma_f32_16x16x32_bf16 v[88:91], v[178:181], v[202:205], v[88:91]
	v_mfma_f32_16x16x32_bf16 v[80:83], v[170:173], v[210:213], v[80:83]
	v_mfma_f32_16x16x32_bf16 v[72:75], v[178:181], v[210:213], v[72:75]
	v_mfma_f32_16x16x32_bf16 v[68:71], v[170:173], v[218:221], v[68:71]
	v_mfma_f32_16x16x32_bf16 v[64:67], v[178:181], v[218:221], v[64:67]
	v_mfma_f32_16x16x32_bf16 v[112:115], v[174:177], v[198:201], v[112:115]
	v_mfma_f32_16x16x32_bf16 v[104:107], v[182:185], v[198:201], v[104:107]
	v_mfma_f32_16x16x32_bf16 v[96:99], v[174:177], v[206:209], v[96:99]
	v_mfma_f32_16x16x32_bf16 v[88:91], v[182:185], v[206:209], v[88:91]
	v_mfma_f32_16x16x32_bf16 v[80:83], v[174:177], v[214:217], v[80:83]
	v_mfma_f32_16x16x32_bf16 v[72:75], v[182:185], v[214:217], v[72:75]
	v_mfma_f32_16x16x32_bf16 v[68:71], v[174:177], v[222:225], v[68:71]
	v_mfma_f32_16x16x32_bf16 v[64:67], v[182:185], v[222:225], v[64:67]
	s_barrier
; #define PG8_STAGE(bufoff, gbase, voff) do { _Pragma("unroll") for (int _i = 0; _i < 2; ++_i) \
;         __builtin_amdgcn_global_load_lds((const unsigned*)((const char*)(gbase) + (voff)[_i]), (PG8_LAS unsigned*)(lds + (bufoff) + ldsw + _i * 8192), 16, 0, 0); } while (0)
; #define PG8_LDA(dst, b, h) do { _Pragma("unroll") for (int m = 0; m < 4; ++m) _Pragma("unroll") for (int k = 0; k < 2; ++k) dst[m][k] = *(const PG8_LAS bf16x8*)(lds + PG8_SA(b, h) + aoff + m * 2048 + k * 1024); } while (0)
; #define PG8_LDB(dst, b, h) do { _Pragma("unroll") for (int n = 0; n < 2; ++n) _Pragma("unroll") for (int k = 0; k < 2; ++k) dst[n][k] = *(const PG8_LAS bf16x8*)(lds + PG8_SB(b, h) + boff + n * 2048 + k * 1024); } while (0)
; #define PG8_MMA(ai, bj, At, Bt) do { __builtin_amdgcn_s_setprio(1); _Pragma("unroll") for (int m = 0; m < 4; ++m) _Pragma("unroll") for (int n = 0; n < 2; ++n) _Pragma("unroll") for (int k = 0; k < 2; ++k) \
;         acc[ai][bj][m][n] = __builtin_amdgcn_mfma_f32_16x16x32_bf16(Bt[n][k], At[m][k], acc[ai][bj][m][n], 0, 0, 0); __builtin_amdgcn_s_setprio(0); } while (0)
; #define PG8_BAR __builtin_amdgcn_s_barrier()
; template <class Epi, class Sched, bool ALIGN_EPI = false, bool SP2 = false>
; __device__ __forceinline__ void gemm_phase(PG8_LAS unsigned char* lds, const Gemm g, const Sched& S, const Epi& E, int wave_in) {
;     ...
;             PG8_LDB(B0, 0, 0); PG8_LDB(B1, 0, 1); PG8_SCHED; PG8_LDA(At, 0, 0); PG8_STAGE(PG8_SA(1, 1), a1 + hstep, voffA);
;             PG8_WAIT_V(8); PG8_WAIT_L(0); PG8_BAR; PG8_MMA(0, 0, At, B0); PG8_MMA(0, 1, At, B1); PG8_BAR; PG8_SCHED;
;             PG8_LDA(At, 0, 1); PG8_STAGE(PG8_SB(0, 0), b2, voffB); PG8_STAGE(PG8_SB(0, 1), b2 + hstep, voffB); PG8_STAGE(PG8_SA(0, 0), a2, voffA);
;             PG8_WAIT_V(8); PG8_WAIT_L(0); PG8_BAR; PG8_MMA(1, 0, At, B0); PG8_MMA(1, 1, At, B1); PG8_BAR; PG8_SCHED;
;             PG8_LDB(B0, 1, 0); PG8_LDB(B1, 1, 1); PG8_SCHED; PG8_LDA(At, 1, 0); PG8_STAGE(PG8_SA(0, 1), a2 + hstep, voffA);
;             PG8_WAIT_V(8); PG8_WAIT_L(0); PG8_BAR; PG8_MMA(0, 0, At, B0); PG8_MMA(0, 1, At, B1); PG8_BAR; PG8_SCHED;
;             PG8_LDA(At, 1, 1); PG8_STAGE(PG8_SB(1, 0), b3, voffB); PG8_STAGE(PG8_SB(1, 1), b3 + hstep, voffB); PG8_STAGE(PG8_SA(1, 0), a3, voffA);
;             PG8_WAIT_V(8); PG8_WAIT_L(0); PG8_BAR; PG8_MMA(1, 0, At, B0); PG8_MMA(1, 1, At, B1); PG8_BAR; PG8_SCHED;
	s_mov_b32 m0, s53
	v_lshl_add_u64 v[190:191], v[190:191], 0, s[88:89]
	ds_read_b128 v[186:189], v153 offset:49152
	ds_read_b128 v[198:201], v153 offset:50176
	ds_read_b128 v[202:205], v153 offset:51200
	ds_read_b128 v[206:209], v153 offset:52224
	ds_read_b128 v[210:213], v153 offset:53248
	ds_read_b128 v[214:217], v153 offset:54272
	ds_read_b128 v[218:221], v153 offset:55296
	ds_read_b128 v[222:225], v153 offset:56320
	global_load_lds_dwordx4 v[190:191], off
	v_lshl_add_u64 v[190:191], v[226:227], 0, s[88:89]
	s_mov_b32 m0, s34
	s_nop 0
	global_load_lds_dwordx4 v[190:191], off
	v_lshl_add_u64 v[190:191], s[40:41], 0, v[132:133]
	s_mov_b32 m0, vcc_lo
	s_nop 0
	global_load_lds_dwordx4 v[190:191], off
	v_lshl_add_u64 v[190:191], s[40:41], 0, v[128:129]
	s_mov_b32 m0, s97
	s_nop 0
	global_load_lds_dwordx4 v[190:191], off
	v_lshl_add_u64 v[190:191], v[228:229], 0, s[88:89]
	s_mov_b32 m0, s85
	s_nop 0
	global_load_lds_dwordx4 v[190:191], off
	v_lshl_add_u64 v[190:191], v[230:231], 0, s[88:89]
	s_mov_b32 m0, s92
	s_nop 0
	global_load_lds_dwordx4 v[190:191], off
	s_waitcnt vmcnt(8)
	s_waitcnt lgkmcnt(0)
	s_barrier
	s_waitcnt lgkmcnt(0)
	v_mfma_f32_16x16x32_bf16 v[60:63], v[154:157], v[186:189], v[60:63]
	v_mfma_f32_16x16x32_bf16 v[56:59], v[162:165], v[186:189], v[56:59]
	v_mfma_f32_16x16x32_bf16 v[52:55], v[154:157], v[202:205], v[52:55]
	v_mfma_f32_16x16x32_bf16 v[44:47], v[162:165], v[202:205], v[44:47]
	v_mfma_f32_16x16x32_bf16 v[36:39], v[154:157], v[210:213], v[36:39]
	v_mfma_f32_16x16x32_bf16 v[28:31], v[162:165], v[210:213], v[28:31]
	v_mfma_f32_16x16x32_bf16 v[20:23], v[154:157], v[218:221], v[20:23]
	v_mfma_f32_16x16x32_bf16 v[12:15], v[162:165], v[218:221], v[12:15]
	v_mfma_f32_16x16x32_bf16 v[60:63], v[158:161], v[198:201], v[60:63]
	v_mfma_f32_16x16x32_bf16 v[56:59], v[166:169], v[198:201], v[56:59]
	v_mfma_f32_16x16x32_bf16 v[52:55], v[158:161], v[206:209], v[52:55]
	v_mfma_f32_16x16x32_bf16 v[44:47], v[166:169], v[206:209], v[44:47]
	v_mfma_f32_16x16x32_bf16 v[36:39], v[158:161], v[214:217], v[36:39]
	v_mfma_f32_16x16x32_bf16 v[28:31], v[166:169], v[214:217], v[28:31]
	v_mfma_f32_16x16x32_bf16 v[20:23], v[158:161], v[222:225], v[20:23]
	v_mfma_f32_16x16x32_bf16 v[12:15], v[166:169], v[222:225], v[12:15]
	v_mfma_f32_16x16x32_bf16 v[48:51], v[170:173], v[186:189], v[48:51]
	v_mfma_f32_16x16x32_bf16 v[40:43], v[178:181], v[186:189], v[40:43]
	v_mfma_f32_16x16x32_bf16 v[32:35], v[170:173], v[202:205], v[32:35]
	v_mfma_f32_16x16x32_bf16 v[24:27], v[178:181], v[202:205], v[24:27]
	v_mfma_f32_16x16x32_bf16 v[16:19], v[170:173], v[210:213], v[16:19]
	v_mfma_f32_16x16x32_bf16 v[8:11], v[178:181], v[210:213], v[8:11]
	v_mfma_f32_16x16x32_bf16 v[4:7], v[170:173], v[218:221], v[4:7]
	v_mfma_f32_16x16x32_bf16 v[0:3], v[178:181], v[218:221], v[0:3]
	v_mfma_f32_16x16x32_bf16 v[48:51], v[174:177], v[198:201], v[48:51]
	v_mfma_f32_16x16x32_bf16 v[40:43], v[182:185], v[198:201], v[40:43]
	v_mfma_f32_16x16x32_bf16 v[32:35], v[174:177], v[206:209], v[32:35]
	v_mfma_f32_16x16x32_bf16 v[24:27], v[182:185], v[206:209], v[24:27]
	v_mfma_f32_16x16x32_bf16 v[16:19], v[174:177], v[214:217], v[16:19]
	v_mfma_f32_16x16x32_bf16 v[8:11], v[182:185], v[214:217], v[8:11]
	v_mfma_f32_16x16x32_bf16 v[4:7], v[174:177], v[222:225], v[4:7]
	v_mfma_f32_16x16x32_bf16 v[0:3], v[182:185], v[222:225], v[0:3]
	s_barrier
	s_movk_i32 s34, 0x100
	s_andn2_b64 vcc, exec, s[38:39]
	s_mov_b64 s[40:41], -1
	s_mov_b64 s[38:39], 0
	s_cbranch_vccnz .Lkexit_2
.LBB0_485:
	s_add_u32 s53, s24, s34
	s_addc_u32 s66, s25, 0
	s_add_u32 s44, s53, 0x100
	s_addc_u32 s45, s66, 0
	s_and_b64 s[42:43], s[40:41], exec
	s_cselect_b32 s45, s15, s45
	s_cselect_b32 s44, s21, s44
	s_add_u32 s34, s22, s34
	s_addc_u32 s42, s23, 0
	s_add_u32 s34, s34, 0x100
	s_addc_u32 s42, s42, 0
	s_add_i32 s97, s35, 0x100
	s_and_b64 s[40:41], s[40:41], exec
	s_cselect_b32 s61, s13, s42
	s_cselect_b32 s60, s27, s34
	s_add_i32 s41, s90, 0x100
	s_add_u32 s76, s53, 0x10080
	s_addc_u32 s77, s66, 0
	s_add_i32 s96, s97, s72
	s_add_i32 m0, s75, 0xc000
	s_add_i32 vcc_hi, s75, 0xe000
	s_add_i32 s81, s96, 0x2000
	s_add_u32 s66, s60, 0x10000
	v_add_u32_e32 v166, s97, v152
	v_add_u32_e32 v182, s41, v152
	s_addc_u32 s67, s61, 0
	s_add_i32 s95, s41, s72
	ds_read_b128 v[154:157], v166
	ds_read_b128 v[158:161], v166 offset:1024
	ds_read_b128 v[162:165], v166 offset:2048
	ds_read_b128 v[166:169], v166 offset:3072
	ds_read_b128 v[170:173], v182
	ds_read_b128 v[174:177], v182 offset:1024
	ds_read_b128 v[178:181], v182 offset:2048
	ds_read_b128 v[182:185], v182 offset:3072
	s_add_i32 s94, s95, 0x2000
	s_add_i32 s71, s65, 0x100
	s_add_i32 s69, s52, 0x100
	s_add_u32 s42, s44, 0x10000
	s_addc_u32 s43, s45, 0
	s_add_i32 s53, s71, s72
	s_add_i32 s34, s53, 0x2000
	s_add_u32 s40, s60, 0x10080
	s_addc_u32 s41, s61, 0
	s_add_i32 vcc_lo, s69, s72
	s_add_i32 s97, vcc_lo, 0x2000
	v_lshl_add_u64 v[190:191], s[76:77], 0, v[134:135]
	ds_read_b128 v[186:189], v153
	ds_read_b128 v[198:201], v153 offset:1024
	ds_read_b128 v[202:205], v153 offset:2048
	ds_read_b128 v[206:209], v153 offset:3072
	ds_read_b128 v[210:213], v153 offset:4096
	ds_read_b128 v[214:217], v153 offset:5120
	ds_read_b128 v[218:221], v153 offset:6144
	ds_read_b128 v[222:225], v153 offset:7168
	global_load_lds_dwordx4 v[190:191], off
	v_lshl_add_u64 v[190:191], s[76:77], 0, v[130:131]
	s_mov_b32 m0, vcc_hi
	s_nop 0
	global_load_lds_dwordx4 v[190:191], off
	s_waitcnt vmcnt(8)
	s_waitcnt lgkmcnt(0)
	s_barrier
; #define PG8_STAGE(bufoff, gbase, voff) do { _Pragma("unroll") for (int _i = 0; _i < 2; ++_i) \
;         __builtin_amdgcn_global_load_lds((const unsigned*)((const char*)(gbase) + (voff)[_i]), (PG8_LAS unsigned*)(lds + (bufoff) + ldsw + _i * 8192), 16, 0, 0); } while (0)
; #define PG8_LDA(dst, b, h) do { _Pragma("unroll") for (int m = 0; m < 4; ++m) _Pragma("unroll") for (int k = 0; k < 2; ++k) dst[m][k] = *(const PG8_LAS bf16x8*)(lds + PG8_SA(b, h) + aoff + m * 2048 + k * 1024); } while (0)
; #define PG8_LDB(dst, b, h) do { _Pragma("unroll") for (int n = 0; n < 2; ++n) _Pragma("unroll") for (int k = 0; k < 2; ++k) dst[n][k] = *(const PG8_LAS bf16x8*)(lds + PG8_SB(b, h) + boff + n * 2048 + k * 1024); } while (0)
; #define PG8_MMA(ai, bj, At, Bt) do { __builtin_amdgcn_s_setprio(1); _Pragma("unroll") for (int m = 0; m < 4; ++m) _Pragma("unroll") for (int n = 0; n < 2; ++n) _Pragma("unroll") for (int k = 0; k < 2; ++k) \
;         acc[ai][bj][m][n] = __builtin_amdgcn_mfma_f32_16x16x32_bf16(Bt[n][k], At[m][k], acc[ai][bj][m][n], 0, 0, 0); __builtin_amdgcn_s_setprio(0); } while (0)
; #define PG8_WAIT_V(n) asm volatile("s_waitcnt vmcnt(" #n ")" ::: "memory")
; #define PG8_WAIT_L(n) asm volatile("s_waitcnt lgkmcnt(" #n ")" ::: "memory")
; #define PG8_BAR __builtin_amdgcn_s_barrier()
; #define PG8_SCHED __builtin_amdgcn_sched_barrier(0)
; template <class Epi, class Sched, bool ALIGN_EPI = false, bool SP2 = false>
; __device__ __forceinline__ void gemm_phase(PG8_LAS unsigned char* lds, const Gemm g, const Sched& S, const Epi& E, int wave_in) {
;     ...
;             PG8_WAIT_V(8); PG8_WAIT_L(0); PG8_BAR; PG8_MMA(0, 0, At, B0); PG8_MMA(0, 1, At, B1); PG8_BAR; PG8_SCHED;
;             PG8_LDA(At, 0, 1); PG8_STAGE(PG8_SB(0, 0), b2, voffB); PG8_STAGE(PG8_SB(0, 1), b2 + hstep, voffB); PG8_STAGE(PG8_SA(0, 0), a2, voffA);
;             PG8_WAIT_V(8); PG8_WAIT_L(0); PG8_BAR; PG8_MMA(1, 0, At, B0); PG8_MMA(1, 1, At, B1); PG8_BAR; PG8_SCHED;
;             PG8_LDB(B0, 1, 0); PG8_LDB(B1, 1, 1); PG8_SCHED; PG8_LDA(At, 1, 0); PG8_STAGE(PG8_SA(0, 1), a2 + hstep, voffA);
;             PG8_WAIT_V(8); PG8_WAIT_L(0); PG8_BAR; PG8_MMA(0, 0, At, B0); PG8_MMA(0, 1, At, B1); PG8_BAR; PG8_SCHED;
	s_waitcnt lgkmcnt(0)
	v_mfma_f32_16x16x32_bf16 v[124:127], v[154:157], v[186:189], v[124:127]
	v_mfma_f32_16x16x32_bf16 v[120:123], v[162:165], v[186:189], v[120:123]
	v_mfma_f32_16x16x32_bf16 v[116:119], v[154:157], v[202:205], v[116:119]
	v_mfma_f32_16x16x32_bf16 v[108:111], v[162:165], v[202:205], v[108:111]
	v_mfma_f32_16x16x32_bf16 v[100:103], v[154:157], v[210:213], v[100:103]
	v_mfma_f32_16x16x32_bf16 v[92:95], v[162:165], v[210:213], v[92:95]
	v_mfma_f32_16x16x32_bf16 v[84:87], v[154:157], v[218:221], v[84:87]
	v_mfma_f32_16x16x32_bf16 v[76:79], v[162:165], v[218:221], v[76:79]
	v_mfma_f32_16x16x32_bf16 v[124:127], v[158:161], v[198:201], v[124:127]
	v_mfma_f32_16x16x32_bf16 v[120:123], v[166:169], v[198:201], v[120:123]
	v_mfma_f32_16x16x32_bf16 v[116:119], v[158:161], v[206:209], v[116:119]
	v_mfma_f32_16x16x32_bf16 v[108:111], v[166:169], v[206:209], v[108:111]
	v_mfma_f32_16x16x32_bf16 v[100:103], v[158:161], v[214:217], v[100:103]
	v_mfma_f32_16x16x32_bf16 v[92:95], v[166:169], v[214:217], v[92:95]
	v_mfma_f32_16x16x32_bf16 v[84:87], v[158:161], v[222:225], v[84:87]
	v_mfma_f32_16x16x32_bf16 v[76:79], v[166:169], v[222:225], v[76:79]
	v_mfma_f32_16x16x32_bf16 v[112:115], v[170:173], v[186:189], v[112:115]
	v_mfma_f32_16x16x32_bf16 v[104:107], v[178:181], v[186:189], v[104:107]
	v_mfma_f32_16x16x32_bf16 v[96:99], v[170:173], v[202:205], v[96:99]
	v_mfma_f32_16x16x32_bf16 v[88:91], v[178:181], v[202:205], v[88:91]
	v_mfma_f32_16x16x32_bf16 v[80:83], v[170:173], v[210:213], v[80:83]
	v_mfma_f32_16x16x32_bf16 v[72:75], v[178:181], v[210:213], v[72:75]
	v_mfma_f32_16x16x32_bf16 v[68:71], v[170:173], v[218:221], v[68:71]
	v_mfma_f32_16x16x32_bf16 v[64:67], v[178:181], v[218:221], v[64:67]
	v_mfma_f32_16x16x32_bf16 v[112:115], v[174:177], v[198:201], v[112:115]
	v_mfma_f32_16x16x32_bf16 v[104:107], v[182:185], v[198:201], v[104:107]
	v_mfma_f32_16x16x32_bf16 v[96:99], v[174:177], v[206:209], v[96:99]
	v_mfma_f32_16x16x32_bf16 v[88:91], v[182:185], v[206:209], v[88:91]
	v_mfma_f32_16x16x32_bf16 v[80:83], v[174:177], v[214:217], v[80:83]
	v_mfma_f32_16x16x32_bf16 v[72:75], v[182:185], v[214:217], v[72:75]
	v_mfma_f32_16x16x32_bf16 v[68:71], v[174:177], v[222:225], v[68:71]
	v_mfma_f32_16x16x32_bf16 v[64:67], v[182:185], v[222:225], v[64:67]
	s_barrier
	s_mov_b32 m0, s96
	v_lshl_add_u64 v[190:191], s[60:61], 0, v[132:133]
	ds_read_b128 v[186:189], v153 offset:16384
	ds_read_b128 v[198:201], v153 offset:17408
	ds_read_b128 v[202:205], v153 offset:18432
	ds_read_b128 v[206:209], v153 offset:19456
	ds_read_b128 v[210:213], v153 offset:20480
	ds_read_b128 v[214:217], v153 offset:21504
	ds_read_b128 v[218:221], v153 offset:22528
	ds_read_b128 v[222:225], v153 offset:23552
	global_load_lds_dwordx4 v[190:191], off
	v_lshl_add_u64 v[226:227], s[60:61], 0, v[128:129]
	s_mov_b32 m0, s81
	v_lshl_add_u64 v[228:229], s[66:67], 0, v[132:133]
	global_load_lds_dwordx4 v[226:227], off
	s_mov_b32 m0, s95
	v_lshl_add_u64 v[230:231], s[44:45], 0, v[130:131]
	global_load_lds_dwordx4 v[228:229], off
	v_lshl_add_u64 v[228:229], s[66:67], 0, v[128:129]
	s_mov_b32 m0, s94
	s_nop 0
	global_load_lds_dwordx4 v[228:229], off
	v_lshl_add_u64 v[228:229], s[44:45], 0, v[134:135]
	s_mov_b32 m0, s75
	s_nop 0
	global_load_lds_dwordx4 v[228:229], off
	s_mov_b32 m0, s78
	s_nop 0
	global_load_lds_dwordx4 v[230:231], off
	s_waitcnt vmcnt(8)
	s_waitcnt lgkmcnt(0)
	s_barrier
	s_waitcnt lgkmcnt(0)
	v_mfma_f32_16x16x32_bf16 v[60:63], v[154:157], v[186:189], v[60:63]
	v_mfma_f32_16x16x32_bf16 v[56:59], v[162:165], v[186:189], v[56:59]
	v_mfma_f32_16x16x32_bf16 v[52:55], v[154:157], v[202:205], v[52:55]
	v_mfma_f32_16x16x32_bf16 v[44:47], v[162:165], v[202:205], v[44:47]
	v_mfma_f32_16x16x32_bf16 v[36:39], v[154:157], v[210:213], v[36:39]
	v_mfma_f32_16x16x32_bf16 v[28:31], v[162:165], v[210:213], v[28:31]
	v_mfma_f32_16x16x32_bf16 v[20:23], v[154:157], v[218:221], v[20:23]
	v_mfma_f32_16x16x32_bf16 v[12:15], v[162:165], v[218:221], v[12:15]
	v_mfma_f32_16x16x32_bf16 v[60:63], v[158:161], v[198:201], v[60:63]
	v_mfma_f32_16x16x32_bf16 v[56:59], v[166:169], v[198:201], v[56:59]
	v_mfma_f32_16x16x32_bf16 v[52:55], v[158:161], v[206:209], v[52:55]
	v_mfma_f32_16x16x32_bf16 v[44:47], v[166:169], v[206:209], v[44:47]
	v_mfma_f32_16x16x32_bf16 v[36:39], v[158:161], v[214:217], v[36:39]
	v_mfma_f32_16x16x32_bf16 v[28:31], v[166:169], v[214:217], v[28:31]
	v_mfma_f32_16x16x32_bf16 v[20:23], v[158:161], v[222:225], v[20:23]
	v_mfma_f32_16x16x32_bf16 v[12:15], v[166:169], v[222:225], v[12:15]
	v_mfma_f32_16x16x32_bf16 v[48:51], v[170:173], v[186:189], v[48:51]
	v_mfma_f32_16x16x32_bf16 v[40:43], v[178:181], v[186:189], v[40:43]
	v_mfma_f32_16x16x32_bf16 v[32:35], v[170:173], v[202:205], v[32:35]
	v_mfma_f32_16x16x32_bf16 v[24:27], v[178:181], v[202:205], v[24:27]
	v_mfma_f32_16x16x32_bf16 v[16:19], v[170:173], v[210:213], v[16:19]
	v_mfma_f32_16x16x32_bf16 v[8:11], v[178:181], v[210:213], v[8:11]
	v_mfma_f32_16x16x32_bf16 v[4:7], v[170:173], v[218:221], v[4:7]
	v_mfma_f32_16x16x32_bf16 v[0:3], v[178:181], v[218:221], v[0:3]
	v_mfma_f32_16x16x32_bf16 v[48:51], v[174:177], v[198:201], v[48:51]
	v_mfma_f32_16x16x32_bf16 v[40:43], v[182:185], v[198:201], v[40:43]
	v_mfma_f32_16x16x32_bf16 v[32:35], v[174:177], v[206:209], v[32:35]
	v_mfma_f32_16x16x32_bf16 v[24:27], v[182:185], v[206:209], v[24:27]
	v_mfma_f32_16x16x32_bf16 v[16:19], v[174:177], v[214:217], v[16:19]
	v_mfma_f32_16x16x32_bf16 v[8:11], v[182:185], v[214:217], v[8:11]
	v_mfma_f32_16x16x32_bf16 v[4:7], v[174:177], v[222:225], v[4:7]
	v_mfma_f32_16x16x32_bf16 v[0:3], v[182:185], v[222:225], v[0:3]
	s_barrier
; #define PG8_STAGE(bufoff, gbase, voff) do { _Pragma("unroll") for (int _i = 0; _i < 2; ++_i) \
;         __builtin_amdgcn_global_load_lds((const unsigned*)((const char*)(gbase) + (voff)[_i]), (PG8_LAS unsigned*)(lds + (bufoff) + ldsw + _i * 8192), 16, 0, 0); } while (0)
; #define PG8_LDA(dst, b, h) do { _Pragma("unroll") for (int m = 0; m < 4; ++m) _Pragma("unroll") for (int k = 0; k < 2; ++k) dst[m][k] = *(const PG8_LAS bf16x8*)(lds + PG8_SA(b, h) + aoff + m * 2048 + k * 1024); } while (0)
; #define PG8_LDB(dst, b, h) do { _Pragma("unroll") for (int n = 0; n < 2; ++n) _Pragma("unroll") for (int k = 0; k < 2; ++k) dst[n][k] = *(const PG8_LAS bf16x8*)(lds + PG8_SB(b, h) + boff + n * 2048 + k * 1024); } while (0)
; #define PG8_MMA(ai, bj, At, Bt) do { __builtin_amdgcn_s_setprio(1); _Pragma("unroll") for (int m = 0; m < 4; ++m) _Pragma("unroll") for (int n = 0; n < 2; ++n) _Pragma("unroll") for (int k = 0; k < 2; ++k) \
;         acc[ai][bj][m][n] = __builtin_amdgcn_mfma_f32_16x16x32_bf16(Bt[n][k], At[m][k], acc[ai][bj][m][n], 0, 0, 0); __builtin_amdgcn_s_setprio(0); } while (0)
; #define PG8_WAIT_V(n) asm volatile("s_waitcnt vmcnt(" #n ")" ::: "memory")
; #define PG8_WAIT_L(n) asm volatile("s_waitcnt lgkmcnt(" #n ")" ::: "memory")
; #define PG8_BAR __builtin_amdgcn_s_barrier()
; #define PG8_SCHED __builtin_amdgcn_sched_barrier(0)
; template <class Epi, class Sched, bool ALIGN_EPI = false, bool SP2 = false>
; __device__ __forceinline__ void gemm_phase(PG8_LAS unsigned char* lds, const Gemm g, const Sched& S, const Epi& E, int wave_in) {
;     ...
;             PG8_LDB(B0, 1, 0); PG8_LDB(B1, 1, 1); PG8_SCHED; PG8_LDA(At, 1, 0); PG8_STAGE(PG8_SA(0, 1), a2 + hstep, voffA);
;             PG8_WAIT_V(8); PG8_WAIT_L(0); PG8_BAR; PG8_MMA(0, 0, At, B0); PG8_MMA(0, 1, At, B1); PG8_BAR; PG8_SCHED;
;             PG8_LDA(At, 1, 1); PG8_STAGE(PG8_SB(1, 0), b3, voffB); PG8_STAGE(PG8_SB(1, 1), b3 + hstep, voffB); PG8_STAGE(PG8_SA(1, 0), a3, voffA);
;             PG8_WAIT_V(8); PG8_WAIT_L(0); PG8_BAR; PG8_MMA(1, 0, At, B0); PG8_MMA(1, 1, At, B1); PG8_BAR; PG8_SCHED;
	v_add_u32_e32 v166, s71, v152
	v_add_u32_e32 v182, s69, v152
	ds_read_b128 v[154:157], v166
	ds_read_b128 v[158:161], v166 offset:1024
	ds_read_b128 v[162:165], v166 offset:2048
	ds_read_b128 v[166:169], v166 offset:3072
	ds_read_b128 v[170:173], v182
	ds_read_b128 v[174:177], v182 offset:1024
	ds_read_b128 v[178:181], v182 offset:2048
	ds_read_b128 v[182:185], v182 offset:3072
	s_mov_b32 m0, s79
	v_lshl_add_u64 v[232:233], s[42:43], 0, v[134:135]
	ds_read_b128 v[186:189], v153 offset:32768
	ds_read_b128 v[198:201], v153 offset:33792
	ds_read_b128 v[202:205], v153 offset:34816
	ds_read_b128 v[206:209], v153 offset:35840
	ds_read_b128 v[210:213], v153 offset:36864
	ds_read_b128 v[214:217], v153 offset:37888
	ds_read_b128 v[218:221], v153 offset:38912
	ds_read_b128 v[222:225], v153 offset:39936
	global_load_lds_dwordx4 v[232:233], off
	v_lshl_add_u64 v[232:233], s[42:43], 0, v[130:131]
	s_mov_b32 m0, s82
	s_nop 0
	global_load_lds_dwordx4 v[232:233], off
	s_waitcnt vmcnt(8)
	s_waitcnt lgkmcnt(0)
	s_barrier
	s_waitcnt lgkmcnt(0)
	v_mfma_f32_16x16x32_bf16 v[124:127], v[154:157], v[186:189], v[124:127]
	v_mfma_f32_16x16x32_bf16 v[120:123], v[162:165], v[186:189], v[120:123]
	v_mfma_f32_16x16x32_bf16 v[116:119], v[154:157], v[202:205], v[116:119]
	v_mfma_f32_16x16x32_bf16 v[108:111], v[162:165], v[202:205], v[108:111]
	v_mfma_f32_16x16x32_bf16 v[100:103], v[154:157], v[210:213], v[100:103]
	v_mfma_f32_16x16x32_bf16 v[92:95], v[162:165], v[210:213], v[92:95]
	v_mfma_f32_16x16x32_bf16 v[84:87], v[154:157], v[218:221], v[84:87]
	v_mfma_f32_16x16x32_bf16 v[76:79], v[162:165], v[218:221], v[76:79]
	v_mfma_f32_16x16x32_bf16 v[124:127], v[158:161], v[198:201], v[124:127]
	v_mfma_f32_16x16x32_bf16 v[120:123], v[166:169], v[198:201], v[120:123]
	v_mfma_f32_16x16x32_bf16 v[116:119], v[158:161], v[206:209], v[116:119]
	v_mfma_f32_16x16x32_bf16 v[108:111], v[166:169], v[206:209], v[108:111]
	v_mfma_f32_16x16x32_bf16 v[100:103], v[158:161], v[214:217], v[100:103]
	v_mfma_f32_16x16x32_bf16 v[92:95], v[166:169], v[214:217], v[92:95]
	v_mfma_f32_16x16x32_bf16 v[84:87], v[158:161], v[222:225], v[84:87]
	v_mfma_f32_16x16x32_bf16 v[76:79], v[166:169], v[222:225], v[76:79]
	v_mfma_f32_16x16x32_bf16 v[112:115], v[170:173], v[186:189], v[112:115]
	v_mfma_f32_16x16x32_bf16 v[104:107], v[178:181], v[186:189], v[104:107]
	v_mfma_f32_16x16x32_bf16 v[96:99], v[170:173], v[202:205], v[96:99]
	v_mfma_f32_16x16x32_bf16 v[88:91], v[178:181], v[202:205], v[88:91]
	v_mfma_f32_16x16x32_bf16 v[80:83], v[170:173], v[210:213], v[80:83]
	v_mfma_f32_16x16x32_bf16 v[72:75], v[178:181], v[210:213], v[72:75]
	v_mfma_f32_16x16x32_bf16 v[68:71], v[170:173], v[218:221], v[68:71]
	v_mfma_f32_16x16x32_bf16 v[64:67], v[178:181], v[218:221], v[64:67]
	v_mfma_f32_16x16x32_bf16 v[112:115], v[174:177], v[198:201], v[112:115]
	v_mfma_f32_16x16x32_bf16 v[104:107], v[182:185], v[198:201], v[104:107]
	v_mfma_f32_16x16x32_bf16 v[96:99], v[174:177], v[206:209], v[96:99]
	v_mfma_f32_16x16x32_bf16 v[88:91], v[182:185], v[206:209], v[88:91]
	v_mfma_f32_16x16x32_bf16 v[80:83], v[174:177], v[214:217], v[80:83]
	v_mfma_f32_16x16x32_bf16 v[72:75], v[182:185], v[214:217], v[72:75]
	v_mfma_f32_16x16x32_bf16 v[68:71], v[174:177], v[222:225], v[68:71]
	v_mfma_f32_16x16x32_bf16 v[64:67], v[182:185], v[222:225], v[64:67]
	s_barrier
	s_mov_b32 m0, s53
	v_lshl_add_u64 v[190:191], v[190:191], 0, s[88:89]
	ds_read_b128 v[186:189], v153 offset:49152
	ds_read_b128 v[198:201], v153 offset:50176
	ds_read_b128 v[202:205], v153 offset:51200
	ds_read_b128 v[206:209], v153 offset:52224
	ds_read_b128 v[210:213], v153 offset:53248
	ds_read_b128 v[214:217], v153 offset:54272
	ds_read_b128 v[218:221], v153 offset:55296
	ds_read_b128 v[222:225], v153 offset:56320
	global_load_lds_dwordx4 v[190:191], off
	v_lshl_add_u64 v[190:191], v[226:227], 0, s[88:89]
	s_mov_b32 m0, s34
	s_nop 0
	global_load_lds_dwordx4 v[190:191], off
	v_lshl_add_u64 v[190:191], s[40:41], 0, v[132:133]
	s_mov_b32 m0, vcc_lo
	s_nop 0
	global_load_lds_dwordx4 v[190:191], off
	v_lshl_add_u64 v[190:191], s[40:41], 0, v[128:129]
	s_mov_b32 m0, s97
	s_nop 0
	global_load_lds_dwordx4 v[190:191], off
	v_lshl_add_u64 v[190:191], v[228:229], 0, s[88:89]
	s_mov_b32 m0, s85
	s_nop 0
	global_load_lds_dwordx4 v[190:191], off
	v_lshl_add_u64 v[190:191], v[230:231], 0, s[88:89]
	s_mov_b32 m0, s92
	s_nop 0
	global_load_lds_dwordx4 v[190:191], off
	s_waitcnt vmcnt(8)
	s_waitcnt lgkmcnt(0)
	s_barrier
	s_waitcnt lgkmcnt(0)
	v_mfma_f32_16x16x32_bf16 v[60:63], v[154:157], v[186:189], v[60:63]
	v_mfma_f32_16x16x32_bf16 v[56:59], v[162:165], v[186:189], v[56:59]
	v_mfma_f32_16x16x32_bf16 v[52:55], v[154:157], v[202:205], v[52:55]
	v_mfma_f32_16x16x32_bf16 v[44:47], v[162:165], v[202:205], v[44:47]
	v_mfma_f32_16x16x32_bf16 v[36:39], v[154:157], v[210:213], v[36:39]
	v_mfma_f32_16x16x32_bf16 v[28:31], v[162:165], v[210:213], v[28:31]
	v_mfma_f32_16x16x32_bf16 v[20:23], v[154:157], v[218:221], v[20:23]
	v_mfma_f32_16x16x32_bf16 v[12:15], v[162:165], v[218:221], v[12:15]
	v_mfma_f32_16x16x32_bf16 v[60:63], v[158:161], v[198:201], v[60:63]
	v_mfma_f32_16x16x32_bf16 v[56:59], v[166:169], v[198:201], v[56:59]
	v_mfma_f32_16x16x32_bf16 v[52:55], v[158:161], v[206:209], v[52:55]
	v_mfma_f32_16x16x32_bf16 v[44:47], v[166:169], v[206:209], v[44:47]
	v_mfma_f32_16x16x32_bf16 v[36:39], v[158:161], v[214:217], v[36:39]
	v_mfma_f32_16x16x32_bf16 v[28:31], v[166:169], v[214:217], v[28:31]
	v_mfma_f32_16x16x32_bf16 v[20:23], v[158:161], v[222:225], v[20:23]
	v_mfma_f32_16x16x32_bf16 v[12:15], v[166:169], v[222:225], v[12:15]
	v_mfma_f32_16x16x32_bf16 v[48:51], v[170:173], v[186:189], v[48:51]
	v_mfma_f32_16x16x32_bf16 v[40:43], v[178:181], v[186:189], v[40:43]
	v_mfma_f32_16x16x32_bf16 v[32:35], v[170:173], v[202:205], v[32:35]
	v_mfma_f32_16x16x32_bf16 v[24:27], v[178:181], v[202:205], v[24:27]
	v_mfma_f32_16x16x32_bf16 v[16:19], v[170:173], v[210:213], v[16:19]
	v_mfma_f32_16x16x32_bf16 v[8:11], v[178:181], v[210:213], v[8:11]
	v_mfma_f32_16x16x32_bf16 v[4:7], v[170:173], v[218:221], v[4:7]
	v_mfma_f32_16x16x32_bf16 v[0:3], v[178:181], v[218:221], v[0:3]
	v_mfma_f32_16x16x32_bf16 v[48:51], v[174:177], v[198:201], v[48:51]
	v_mfma_f32_16x16x32_bf16 v[40:43], v[182:185], v[198:201], v[40:43]
	v_mfma_f32_16x16x32_bf16 v[32:35], v[174:177], v[206:209], v[32:35]
	v_mfma_f32_16x16x32_bf16 v[24:27], v[182:185], v[206:209], v[24:27]
	v_mfma_f32_16x16x32_bf16 v[16:19], v[174:177], v[214:217], v[16:19]
	v_mfma_f32_16x16x32_bf16 v[8:11], v[182:185], v[214:217], v[8:11]
	v_mfma_f32_16x16x32_bf16 v[4:7], v[174:177], v[222:225], v[4:7]
	v_mfma_f32_16x16x32_bf16 v[0:3], v[182:185], v[222:225], v[0:3]
	s_barrier
	s_movk_i32 s34, 0x100
	s_andn2_b64 vcc, exec, s[38:39]
	s_mov_b64 s[40:41], -1
	s_mov_b64 s[38:39], 0
	s_cbranch_vccz .LBB0_485

; #define PG8_STAGE(bufoff, gbase, voff) do { _Pragma("unroll") for (int _i = 0; _i < 2; ++_i) \
;         __builtin_amdgcn_global_load_lds((const unsigned*)((const char*)(gbase) + (voff)[_i]), (PG8_LAS unsigned*)(lds + (bufoff) + ldsw + _i * 8192), 16, 0, 0); } while (0)
; #define PG8_LDA(dst, b, h) do { _Pragma("unroll") for (int m = 0; m < 4; ++m) _Pragma("unroll") for (int k = 0; k < 2; ++k) dst[m][k] = *(const PG8_LAS bf16x8*)(lds + PG8_SA(b, h) + aoff + m * 2048 + k * 1024); } while (0)
; #define PG8_LDB(dst, b, h) do { _Pragma("unroll") for (int n = 0; n < 2; ++n) _Pragma("unroll") for (int k = 0; k < 2; ++k) dst[n][k] = *(const PG8_LAS bf16x8*)(lds + PG8_SB(b, h) + boff + n * 2048 + k * 1024); } while (0)
; #define PG8_WAIT_V(n) asm volatile("s_waitcnt vmcnt(" #n ")" ::: "memory")
; #define PG8_WAIT_L(n) asm volatile("s_waitcnt lgkmcnt(" #n ")" ::: "memory")
; #define PG8_BAR __builtin_amdgcn_s_barrier()
; #define PG8_SCHED __builtin_amdgcn_sched_barrier(0)
; template <class Epi, class Sched, bool ALIGN_EPI = false, bool SP2 = false>
; __device__ __forceinline__ void gemm_phase(PG8_LAS unsigned char* lds, const Gemm g, const Sched& S, const Epi& E, int wave_in) {
;     ...
;         const char* nA = has_next ? (const char*)g.A + (size_t)(nxt.pm >> g.ash) * g.astride + (size_t)nxt.pm * tstep : cA; const char* nB = has_next ? (const char*)g.Bt + (size_t)(nxt.pm >> g.bsh) * g.bstride + (size_t)nxt.pn * tstep : cB;
;         for (int t = 0; t < nt; t += 2) {
;             const bool last = (t == nt - 2);
;             const char* a1 = cA + (size_t)(t + 1) * kstep;
;             const char* a2 = last ? nA : cA + (size_t)(t + 2) * kstep; const char* b2 = last ? nB : cB + (size_t)(t + 2) * kstep;
;             const char* a3 = a2 + kstep; const char* b3 = b2 + kstep;
;             if (last && has_next) S.a_ready(nxt);
;             if constexpr (SP2) {
;             PG8_LDB(B0, 0, 0); PG8_LDB(B1, 0, 1); PG8_SCHED; PG8_LDA(At, 0, 0); PG8_STAGE(PG8_SA(1, 1), a1 + hstep, voffA);
;             PG8_WAIT_V(8); PG8_WAIT_L(0); PG8_BAR; PG8_MMA(0, 0, At, B0); PG8_MMA(0, 1, At, B1); PG8_BAR; PG8_SCHED;
;             PG8_LDA(At, 0, 1); PG8_STAGE(PG8_SB(0, 0), b2, voffB); PG8_STAGE(PG8_SB(0, 1), b2 + hstep, voffB); PG8_STAGE(PG8_SA(0, 0), a2, voffA);
;             PG8_WAIT_V(8); PG8_WAIT_L(0); PG8_BAR; PG8_MMA(1, 0, At, B0); PG8_MMA(1, 1, At, B1); PG8_BAR; PG8_SCHED;
.LBB0_589:
	s_ashr_i32 s15, s14, 31
	s_lshl_b64 s[20:21], s[14:15], 19
	s_add_u32 s20, s31, s20
	s_addc_u32 s21, s33, s21
	s_and_b64 s[26:27], s[44:45], exec
	s_cselect_b32 s15, s21, s23
	s_cselect_b32 s17, s20, s22
	s_add_u32 s34, s22, 0x100
	s_addc_u32 s44, s23, 0
	s_add_u32 s22, s24, 0x40080
	s_addc_u32 s23, s25, 0
	s_mov_b32 s45, -2
	s_add_u32 s24, s22, 0xfffc0080
	s_addc_u32 s25, s23, -1
	s_add_i32 s53, s35, 0x100
	s_cmp_eq_u32 s45, 12
	s_cselect_b32 s27, s19, s25
	s_cselect_b32 s26, s18, s24
	s_cselect_b32 s25, s15, s44
	s_cselect_b32 s24, s17, s34
	s_add_i32 s69, s90, 0x100
	v_add_u32_e32 v128, s53, v249
	v_add_u32_e32 v156, s69, v249
	ds_read_b128 v[112:115], v128
	ds_read_b128 v[120:123], v128 offset:1024
	ds_read_b128 v[124:127], v128 offset:2048
	ds_read_b128 v[128:131], v128 offset:3072
	ds_read_b128 v[136:139], v156
	ds_read_b128 v[140:143], v156 offset:1024
	ds_read_b128 v[144:147], v156 offset:2048
	ds_read_b128 v[156:159], v156 offset:3072
	v_lshl_add_u64 v[208:209], s[22:23], 0, v[206:207]
	s_add_i32 m0, s39, 0xc000
	ds_read_b128 v[160:163], v251
	ds_read_b128 v[164:167], v251 offset:1024
	ds_read_b128 v[168:171], v251 offset:2048
	ds_read_b128 v[172:175], v251 offset:3072
	ds_read_b128 v[176:179], v251 offset:4096
	ds_read_b128 v[180:183], v251 offset:5120
	ds_read_b128 v[184:187], v251 offset:6144
	ds_read_b128 v[188:191], v251 offset:7168
	global_load_lds_dwordx4 v[208:209], off
	v_lshl_add_u64 v[208:209], s[22:23], 0, v[204:205]
	s_add_i32 m0, s39, 0xe000
	s_nop 0
	global_load_lds_dwordx4 v[208:209], off
	s_waitcnt vmcnt(8)
	s_waitcnt lgkmcnt(0)
	s_barrier
	s_waitcnt lgkmcnt(0)
	v_mfma_f32_16x16x32_bf16 v[152:155], v[112:115], v[160:163], 0
	v_mfma_f32_16x16x32_bf16 v[148:151], v[124:127], v[160:163], 0
	v_mfma_f32_16x16x32_bf16 v[108:111], v[112:115], v[168:171], 0
	v_mfma_f32_16x16x32_bf16 v[104:107], v[124:127], v[168:171], 0
	v_mfma_f32_16x16x32_bf16 v[92:95], v[112:115], v[176:179], 0
	v_mfma_f32_16x16x32_bf16 v[88:91], v[124:127], v[176:179], 0
	v_mfma_f32_16x16x32_bf16 v[76:79], v[112:115], v[184:187], 0
	v_mfma_f32_16x16x32_bf16 v[72:75], v[124:127], v[184:187], 0
	v_mfma_f32_16x16x32_bf16 v[152:155], v[120:123], v[164:167], v[152:155]
	v_mfma_f32_16x16x32_bf16 v[148:151], v[128:131], v[164:167], v[148:151]
	v_mfma_f32_16x16x32_bf16 v[108:111], v[120:123], v[172:175], v[108:111]
	v_mfma_f32_16x16x32_bf16 v[104:107], v[128:131], v[172:175], v[104:107]
	v_mfma_f32_16x16x32_bf16 v[92:95], v[120:123], v[180:183], v[92:95]
	v_mfma_f32_16x16x32_bf16 v[88:91], v[128:131], v[180:183], v[88:91]
	v_mfma_f32_16x16x32_bf16 v[76:79], v[120:123], v[188:191], v[76:79]
	v_mfma_f32_16x16x32_bf16 v[72:75], v[128:131], v[188:191], v[72:75]
	v_mfma_f32_16x16x32_bf16 v[132:135], v[136:139], v[160:163], 0
	v_mfma_f32_16x16x32_bf16 v[116:119], v[144:147], v[160:163], 0
	v_mfma_f32_16x16x32_bf16 v[100:103], v[136:139], v[168:171], 0
	v_mfma_f32_16x16x32_bf16 v[96:99], v[144:147], v[168:171], 0
	v_mfma_f32_16x16x32_bf16 v[84:87], v[136:139], v[176:179], 0
	v_mfma_f32_16x16x32_bf16 v[80:83], v[144:147], v[176:179], 0
	v_mfma_f32_16x16x32_bf16 v[68:71], v[136:139], v[184:187], 0
	v_mfma_f32_16x16x32_bf16 v[64:67], v[144:147], v[184:187], 0
	v_mfma_f32_16x16x32_bf16 v[132:135], v[140:143], v[164:167], v[132:135]
	v_mfma_f32_16x16x32_bf16 v[116:119], v[156:159], v[164:167], v[116:119]
	v_mfma_f32_16x16x32_bf16 v[100:103], v[140:143], v[172:175], v[100:103]
	v_mfma_f32_16x16x32_bf16 v[96:99], v[156:159], v[172:175], v[96:99]
	v_mfma_f32_16x16x32_bf16 v[84:87], v[140:143], v[180:183], v[84:87]
	v_mfma_f32_16x16x32_bf16 v[80:83], v[156:159], v[180:183], v[80:83]
	v_mfma_f32_16x16x32_bf16 v[68:71], v[140:143], v[188:191], v[68:71]
	v_mfma_f32_16x16x32_bf16 v[64:67], v[156:159], v[188:191], v[64:67]
	s_barrier
	s_add_i32 s53, s53, s38
	v_lshl_add_u64 v[208:209], s[24:25], 0, v[192:193]
	s_mov_b32 m0, s53
	ds_read_b128 v[160:163], v251 offset:16384
	ds_read_b128 v[164:167], v251 offset:17408
	ds_read_b128 v[168:171], v251 offset:18432
	ds_read_b128 v[172:175], v251 offset:19456
	ds_read_b128 v[176:179], v251 offset:20480
	ds_read_b128 v[180:183], v251 offset:21504
	ds_read_b128 v[184:187], v251 offset:22528
	ds_read_b128 v[188:191], v251 offset:23552
	global_load_lds_dwordx4 v[208:209], off
	s_add_i32 m0, s53, 0x2000
	s_add_u32 s72, s24, 0x40000
	v_lshl_add_u64 v[210:211], s[24:25], 0, v[198:199]
	s_addc_u32 s73, s25, 0
	s_add_i32 s53, s69, s38
	global_load_lds_dwordx4 v[210:211], off
	v_lshl_add_u64 v[212:213], s[72:73], 0, v[192:193]
	s_mov_b32 m0, s53
	v_lshl_add_u64 v[214:215], s[26:27], 0, v[200:201]
	global_load_lds_dwordx4 v[212:213], off
	v_lshl_add_u64 v[212:213], s[72:73], 0, v[198:199]
	s_add_i32 m0, s53, 0x2000
	s_nop 0
	global_load_lds_dwordx4 v[212:213], off
	v_lshl_add_u64 v[212:213], s[26:27], 0, v[202:203]
	s_mov_b32 m0, s39
	s_nop 0
	global_load_lds_dwordx4 v[212:213], off
	s_mov_b32 m0, s46
	s_nop 0
	global_load_lds_dwordx4 v[214:215], off
	s_waitcnt vmcnt(8)
	s_waitcnt lgkmcnt(0)
	s_barrier
; #define PG8_STAGE(bufoff, gbase, voff) do { _Pragma("unroll") for (int _i = 0; _i < 2; ++_i) \
;         __builtin_amdgcn_global_load_lds((const unsigned*)((const char*)(gbase) + (voff)[_i]), (PG8_LAS unsigned*)(lds + (bufoff) + ldsw + _i * 8192), 16, 0, 0); } while (0)
; #define PG8_LDA(dst, b, h) do { _Pragma("unroll") for (int m = 0; m < 4; ++m) _Pragma("unroll") for (int k = 0; k < 2; ++k) dst[m][k] = *(const PG8_LAS bf16x8*)(lds + PG8_SA(b, h) + aoff + m * 2048 + k * 1024); } while (0)
; #define PG8_LDB(dst, b, h) do { _Pragma("unroll") for (int n = 0; n < 2; ++n) _Pragma("unroll") for (int k = 0; k < 2; ++k) dst[n][k] = *(const PG8_LAS bf16x8*)(lds + PG8_SB(b, h) + boff + n * 2048 + k * 1024); } while (0)
; #define PG8_MMA(ai, bj, At, Bt) do { __builtin_amdgcn_s_setprio(1); _Pragma("unroll") for (int m = 0; m < 4; ++m) _Pragma("unroll") for (int n = 0; n < 2; ++n) _Pragma("unroll") for (int k = 0; k < 2; ++k) \
;         acc[ai][bj][m][n] = __builtin_amdgcn_mfma_f32_16x16x32_bf16(Bt[n][k], At[m][k], acc[ai][bj][m][n], 0, 0, 0); __builtin_amdgcn_s_setprio(0); } while (0)
; #define PG8_WAIT_V(n) asm volatile("s_waitcnt vmcnt(" #n ")" ::: "memory")
; #define PG8_WAIT_L(n) asm volatile("s_waitcnt lgkmcnt(" #n ")" ::: "memory")
; #define PG8_BAR __builtin_amdgcn_s_barrier()
; #define PG8_SCHED __builtin_amdgcn_sched_barrier(0)
; template <class Epi, class Sched, bool ALIGN_EPI = false, bool SP2 = false>
; __device__ __forceinline__ void gemm_phase(PG8_LAS unsigned char* lds, const Gemm g, const Sched& S, const Epi& E, int wave_in) {
;     ...
;             PG8_WAIT_V(8); PG8_WAIT_L(0); PG8_BAR; PG8_MMA(1, 0, At, B0); PG8_MMA(1, 1, At, B1); PG8_BAR; PG8_SCHED;
;             PG8_LDB(B0, 1, 0); PG8_LDB(B1, 1, 1); PG8_SCHED; PG8_LDA(At, 1, 0); PG8_STAGE(PG8_SA(0, 1), a2 + hstep, voffA);
;             PG8_WAIT_V(8); PG8_WAIT_L(0); PG8_BAR; PG8_MMA(0, 0, At, B0); PG8_MMA(0, 1, At, B1); PG8_BAR; PG8_SCHED;
	s_waitcnt lgkmcnt(0)
	v_mfma_f32_16x16x32_bf16 v[60:63], v[112:115], v[160:163], 0
	v_mfma_f32_16x16x32_bf16 v[56:59], v[124:127], v[160:163], 0
	v_mfma_f32_16x16x32_bf16 v[44:47], v[112:115], v[168:171], 0
	v_mfma_f32_16x16x32_bf16 v[40:43], v[124:127], v[168:171], 0
	v_mfma_f32_16x16x32_bf16 v[28:31], v[112:115], v[176:179], 0
	v_mfma_f32_16x16x32_bf16 v[24:27], v[124:127], v[176:179], 0
	v_mfma_f32_16x16x32_bf16 v[12:15], v[112:115], v[184:187], 0
	v_mfma_f32_16x16x32_bf16 v[8:11], v[124:127], v[184:187], 0
	v_mfma_f32_16x16x32_bf16 v[60:63], v[120:123], v[164:167], v[60:63]
	v_mfma_f32_16x16x32_bf16 v[56:59], v[128:131], v[164:167], v[56:59]
	v_mfma_f32_16x16x32_bf16 v[44:47], v[120:123], v[172:175], v[44:47]
	v_mfma_f32_16x16x32_bf16 v[40:43], v[128:131], v[172:175], v[40:43]
	v_mfma_f32_16x16x32_bf16 v[28:31], v[120:123], v[180:183], v[28:31]
	v_mfma_f32_16x16x32_bf16 v[24:27], v[128:131], v[180:183], v[24:27]
	v_mfma_f32_16x16x32_bf16 v[12:15], v[120:123], v[188:191], v[12:15]
	v_mfma_f32_16x16x32_bf16 v[8:11], v[128:131], v[188:191], v[8:11]
	v_mfma_f32_16x16x32_bf16 v[52:55], v[136:139], v[160:163], 0
	v_mfma_f32_16x16x32_bf16 v[48:51], v[144:147], v[160:163], 0
	v_mfma_f32_16x16x32_bf16 v[36:39], v[136:139], v[168:171], 0
	v_mfma_f32_16x16x32_bf16 v[32:35], v[144:147], v[168:171], 0
	v_mfma_f32_16x16x32_bf16 v[20:23], v[136:139], v[176:179], 0
	v_mfma_f32_16x16x32_bf16 v[16:19], v[144:147], v[176:179], 0
	v_mfma_f32_16x16x32_bf16 v[4:7], v[136:139], v[184:187], 0
	v_mfma_f32_16x16x32_bf16 v[0:3], v[144:147], v[184:187], 0
	v_mfma_f32_16x16x32_bf16 v[52:55], v[140:143], v[164:167], v[52:55]
	v_mfma_f32_16x16x32_bf16 v[48:51], v[156:159], v[164:167], v[48:51]
	v_mfma_f32_16x16x32_bf16 v[36:39], v[140:143], v[172:175], v[36:39]
	v_mfma_f32_16x16x32_bf16 v[32:35], v[156:159], v[172:175], v[32:35]
	v_mfma_f32_16x16x32_bf16 v[20:23], v[140:143], v[180:183], v[20:23]
	v_mfma_f32_16x16x32_bf16 v[16:19], v[156:159], v[180:183], v[16:19]
	v_mfma_f32_16x16x32_bf16 v[4:7], v[140:143], v[188:191], v[4:7]
	v_mfma_f32_16x16x32_bf16 v[0:3], v[156:159], v[188:191], v[0:3]
	s_barrier
	s_add_i32 s53, s65, 0x100
	s_add_i32 s69, s52, 0x100
	v_add_u32_e32 v128, s53, v249
	v_add_u32_e32 v156, s69, v249
	ds_read_b128 v[112:115], v128
	ds_read_b128 v[120:123], v128 offset:1024
	ds_read_b128 v[124:127], v128 offset:2048
	ds_read_b128 v[128:131], v128 offset:3072
	ds_read_b128 v[136:139], v156
	ds_read_b128 v[140:143], v156 offset:1024
	ds_read_b128 v[144:147], v156 offset:2048
	ds_read_b128 v[156:159], v156 offset:3072
	s_add_u32 s26, s26, 0x40000
	s_addc_u32 s27, s27, 0
	s_mov_b32 m0, s47
	v_lshl_add_u64 v[216:217], s[26:27], 0, v[202:203]
	ds_read_b128 v[160:163], v251 offset:32768
	ds_read_b128 v[164:167], v251 offset:33792
	ds_read_b128 v[168:171], v251 offset:34816
	ds_read_b128 v[172:175], v251 offset:35840
	ds_read_b128 v[176:179], v251 offset:36864
	ds_read_b128 v[180:183], v251 offset:37888
	ds_read_b128 v[184:187], v251 offset:38912
	ds_read_b128 v[188:191], v251 offset:39936
	global_load_lds_dwordx4 v[216:217], off
	v_lshl_add_u64 v[216:217], s[26:27], 0, v[200:201]
	s_mov_b32 m0, s60
	s_nop 0
	global_load_lds_dwordx4 v[216:217], off
	s_waitcnt vmcnt(8)
	s_waitcnt lgkmcnt(0)
	s_barrier
	s_waitcnt lgkmcnt(0)
	v_mfma_f32_16x16x32_bf16 v[152:155], v[112:115], v[160:163], v[152:155]
	v_mfma_f32_16x16x32_bf16 v[148:151], v[124:127], v[160:163], v[148:151]
	v_mfma_f32_16x16x32_bf16 v[108:111], v[112:115], v[168:171], v[108:111]
	v_mfma_f32_16x16x32_bf16 v[104:107], v[124:127], v[168:171], v[104:107]
	v_mfma_f32_16x16x32_bf16 v[92:95], v[112:115], v[176:179], v[92:95]
	v_mfma_f32_16x16x32_bf16 v[88:91], v[124:127], v[176:179], v[88:91]
	v_mfma_f32_16x16x32_bf16 v[76:79], v[112:115], v[184:187], v[76:79]
	v_mfma_f32_16x16x32_bf16 v[72:75], v[124:127], v[184:187], v[72:75]
	v_mfma_f32_16x16x32_bf16 v[152:155], v[120:123], v[164:167], v[152:155]
	v_mfma_f32_16x16x32_bf16 v[148:151], v[128:131], v[164:167], v[148:151]
	v_mfma_f32_16x16x32_bf16 v[108:111], v[120:123], v[172:175], v[108:111]
	v_mfma_f32_16x16x32_bf16 v[104:107], v[128:131], v[172:175], v[104:107]
	v_mfma_f32_16x16x32_bf16 v[92:95], v[120:123], v[180:183], v[92:95]
	v_mfma_f32_16x16x32_bf16 v[88:91], v[128:131], v[180:183], v[88:91]
	v_mfma_f32_16x16x32_bf16 v[76:79], v[120:123], v[188:191], v[76:79]
	v_mfma_f32_16x16x32_bf16 v[72:75], v[128:131], v[188:191], v[72:75]
	v_mfma_f32_16x16x32_bf16 v[132:135], v[136:139], v[160:163], v[132:135]
	v_mfma_f32_16x16x32_bf16 v[116:119], v[144:147], v[160:163], v[116:119]
	v_mfma_f32_16x16x32_bf16 v[100:103], v[136:139], v[168:171], v[100:103]
	v_mfma_f32_16x16x32_bf16 v[96:99], v[144:147], v[168:171], v[96:99]
	v_mfma_f32_16x16x32_bf16 v[84:87], v[136:139], v[176:179], v[84:87]
	v_mfma_f32_16x16x32_bf16 v[80:83], v[144:147], v[176:179], v[80:83]
	v_mfma_f32_16x16x32_bf16 v[68:71], v[136:139], v[184:187], v[68:71]
	v_mfma_f32_16x16x32_bf16 v[64:67], v[144:147], v[184:187], v[64:67]
	v_mfma_f32_16x16x32_bf16 v[132:135], v[140:143], v[164:167], v[132:135]
	v_mfma_f32_16x16x32_bf16 v[116:119], v[156:159], v[164:167], v[116:119]
	v_mfma_f32_16x16x32_bf16 v[100:103], v[140:143], v[172:175], v[100:103]
	v_mfma_f32_16x16x32_bf16 v[96:99], v[156:159], v[172:175], v[96:99]
	v_mfma_f32_16x16x32_bf16 v[84:87], v[140:143], v[180:183], v[84:87]
	v_mfma_f32_16x16x32_bf16 v[80:83], v[156:159], v[180:183], v[80:83]
	v_mfma_f32_16x16x32_bf16 v[68:71], v[140:143], v[188:191], v[68:71]
	v_mfma_f32_16x16x32_bf16 v[64:67], v[156:159], v[188:191], v[64:67]
	s_barrier
; #define PG8_STAGE(bufoff, gbase, voff) do { _Pragma("unroll") for (int _i = 0; _i < 2; ++_i) \
;         __builtin_amdgcn_global_load_lds((const unsigned*)((const char*)(gbase) + (voff)[_i]), (PG8_LAS unsigned*)(lds + (bufoff) + ldsw + _i * 8192), 16, 0, 0); } while (0)
; #define PG8_LDA(dst, b, h) do { _Pragma("unroll") for (int m = 0; m < 4; ++m) _Pragma("unroll") for (int k = 0; k < 2; ++k) dst[m][k] = *(const PG8_LAS bf16x8*)(lds + PG8_SA(b, h) + aoff + m * 2048 + k * 1024); } while (0)
; #define PG8_LDB(dst, b, h) do { _Pragma("unroll") for (int n = 0; n < 2; ++n) _Pragma("unroll") for (int k = 0; k < 2; ++k) dst[n][k] = *(const PG8_LAS bf16x8*)(lds + PG8_SB(b, h) + boff + n * 2048 + k * 1024); } while (0)
; #define PG8_MMA(ai, bj, At, Bt) do { __builtin_amdgcn_s_setprio(1); _Pragma("unroll") for (int m = 0; m < 4; ++m) _Pragma("unroll") for (int n = 0; n < 2; ++n) _Pragma("unroll") for (int k = 0; k < 2; ++k) \
;         acc[ai][bj][m][n] = __builtin_amdgcn_mfma_f32_16x16x32_bf16(Bt[n][k], At[m][k], acc[ai][bj][m][n], 0, 0, 0); __builtin_amdgcn_s_setprio(0); } while (0)
; template <class Epi, class Sched, bool ALIGN_EPI = false, bool SP2 = false>
; __device__ __forceinline__ void gemm_phase(PG8_LAS unsigned char* lds, const Gemm g, const Sched& S, const Epi& E, int wave_in) {
;     ...
;         for (int t = 0; t < nt; t += 2) {
;             const bool last = (t == nt - 2);
;             const char* a1 = cA + (size_t)(t + 1) * kstep;
;             const char* a2 = last ? nA : cA + (size_t)(t + 2) * kstep; const char* b2 = last ? nB : cB + (size_t)(t + 2) * kstep;
;             const char* a3 = a2 + kstep; const char* b3 = b2 + kstep;
;             if (last && has_next) S.a_ready(nxt);
;             if constexpr (SP2) {
;             PG8_LDB(B0, 0, 0); PG8_LDB(B1, 0, 1); PG8_SCHED; PG8_LDA(At, 0, 0); PG8_STAGE(PG8_SA(1, 1), a1 + hstep, voffA);
;             PG8_WAIT_V(8); PG8_WAIT_L(0); PG8_BAR; PG8_MMA(0, 0, At, B0); PG8_MMA(0, 1, At, B1); PG8_BAR; PG8_SCHED;
;     ...
;             PG8_WAIT_V(8); PG8_WAIT_L(0); PG8_BAR; PG8_MMA(0, 0, At, B0); PG8_MMA(0, 1, At, B1); PG8_BAR; PG8_SCHED;
;             PG8_LDA(At, 1, 1); PG8_STAGE(PG8_SB(1, 0), b3, voffB); PG8_STAGE(PG8_SB(1, 1), b3 + hstep, voffB); PG8_STAGE(PG8_SA(1, 0), a3, voffA);
;             PG8_WAIT_V(8); PG8_WAIT_L(0); PG8_BAR; PG8_MMA(1, 0, At, B0); PG8_MMA(1, 1, At, B1); PG8_BAR; PG8_SCHED;
	s_add_i32 s26, s53, s38
	v_lshl_add_u64 v[208:209], v[208:209], 0, s[88:89]
	s_mov_b32 m0, s26
	ds_read_b128 v[160:163], v251 offset:49152
	ds_read_b128 v[164:167], v251 offset:50176
	ds_read_b128 v[168:171], v251 offset:51200
	ds_read_b128 v[172:175], v251 offset:52224
	ds_read_b128 v[176:179], v251 offset:53248
	ds_read_b128 v[180:183], v251 offset:54272
	ds_read_b128 v[184:187], v251 offset:55296
	ds_read_b128 v[188:191], v251 offset:56320
	global_load_lds_dwordx4 v[208:209], off
	s_add_i32 m0, s26, 0x2000
	s_add_u32 s24, s24, 0x40080
	v_lshl_add_u64 v[208:209], v[210:211], 0, s[88:89]
	s_addc_u32 s25, s25, 0
	s_add_i32 s26, s69, s38
	global_load_lds_dwordx4 v[208:209], off
	v_lshl_add_u64 v[208:209], s[24:25], 0, v[192:193]
	s_mov_b32 m0, s26
	s_nop 0
	global_load_lds_dwordx4 v[208:209], off
	v_lshl_add_u64 v[208:209], s[24:25], 0, v[198:199]
	s_add_i32 m0, s26, 0x2000
	s_nop 0
	global_load_lds_dwordx4 v[208:209], off
	v_lshl_add_u64 v[208:209], v[212:213], 0, s[88:89]
	s_mov_b32 m0, s62
	s_nop 0
	global_load_lds_dwordx4 v[208:209], off
	v_lshl_add_u64 v[208:209], v[214:215], 0, s[88:89]
	s_mov_b32 m0, s63
	s_nop 0
	global_load_lds_dwordx4 v[208:209], off
	s_waitcnt vmcnt(8)
	s_waitcnt lgkmcnt(0)
	s_barrier
	s_waitcnt lgkmcnt(0)
	v_mfma_f32_16x16x32_bf16 v[60:63], v[112:115], v[160:163], v[60:63]
	v_mfma_f32_16x16x32_bf16 v[56:59], v[124:127], v[160:163], v[56:59]
	v_mfma_f32_16x16x32_bf16 v[44:47], v[112:115], v[168:171], v[44:47]
	v_mfma_f32_16x16x32_bf16 v[40:43], v[124:127], v[168:171], v[40:43]
	v_mfma_f32_16x16x32_bf16 v[28:31], v[112:115], v[176:179], v[28:31]
	v_mfma_f32_16x16x32_bf16 v[24:27], v[124:127], v[176:179], v[24:27]
	v_mfma_f32_16x16x32_bf16 v[12:15], v[112:115], v[184:187], v[12:15]
	v_mfma_f32_16x16x32_bf16 v[8:11], v[124:127], v[184:187], v[8:11]
	v_mfma_f32_16x16x32_bf16 v[60:63], v[120:123], v[164:167], v[60:63]
	v_mfma_f32_16x16x32_bf16 v[56:59], v[128:131], v[164:167], v[56:59]
	v_mfma_f32_16x16x32_bf16 v[44:47], v[120:123], v[172:175], v[44:47]
	v_mfma_f32_16x16x32_bf16 v[40:43], v[128:131], v[172:175], v[40:43]
	v_mfma_f32_16x16x32_bf16 v[28:31], v[120:123], v[180:183], v[28:31]
	v_mfma_f32_16x16x32_bf16 v[24:27], v[128:131], v[180:183], v[24:27]
	v_mfma_f32_16x16x32_bf16 v[12:15], v[120:123], v[188:191], v[12:15]
	v_mfma_f32_16x16x32_bf16 v[8:11], v[128:131], v[188:191], v[8:11]
	v_mfma_f32_16x16x32_bf16 v[52:55], v[136:139], v[160:163], v[52:55]
	v_mfma_f32_16x16x32_bf16 v[48:51], v[144:147], v[160:163], v[48:51]
	v_mfma_f32_16x16x32_bf16 v[36:39], v[136:139], v[168:171], v[36:39]
	v_mfma_f32_16x16x32_bf16 v[32:35], v[144:147], v[168:171], v[32:35]
	v_mfma_f32_16x16x32_bf16 v[20:23], v[136:139], v[176:179], v[20:23]
	v_mfma_f32_16x16x32_bf16 v[16:19], v[144:147], v[176:179], v[16:19]
	v_mfma_f32_16x16x32_bf16 v[4:7], v[136:139], v[184:187], v[4:7]
	v_mfma_f32_16x16x32_bf16 v[0:3], v[144:147], v[184:187], v[0:3]
	v_mfma_f32_16x16x32_bf16 v[52:55], v[140:143], v[164:167], v[52:55]
	v_mfma_f32_16x16x32_bf16 v[48:51], v[156:159], v[164:167], v[48:51]
	v_mfma_f32_16x16x32_bf16 v[36:39], v[140:143], v[172:175], v[36:39]
	v_mfma_f32_16x16x32_bf16 v[32:35], v[156:159], v[172:175], v[32:35]
	v_mfma_f32_16x16x32_bf16 v[20:23], v[140:143], v[180:183], v[20:23]
	v_mfma_f32_16x16x32_bf16 v[16:19], v[156:159], v[180:183], v[16:19]
	v_mfma_f32_16x16x32_bf16 v[4:7], v[140:143], v[188:191], v[4:7]
	v_mfma_f32_16x16x32_bf16 v[0:3], v[156:159], v[188:191], v[0:3]
	s_barrier
	s_add_i32 s45, s45, 2
	s_add_u32 s34, s34, 0x100
	s_addc_u32 s44, s44, 0
	s_add_u32 s22, s22, 0x100
	s_addc_u32 s23, s23, 0
	s_cmp_gt_u32 s45, 13
	s_cbranch_scc1 .Lkexit_3
.LBB0_590:
	s_add_u32 s24, s22, 0xfffc0080
	s_addc_u32 s25, s23, -1
	s_add_i32 s53, s35, 0x100
	s_cmp_eq_u32 s45, 12
	s_cselect_b32 s27, s19, s25
	s_cselect_b32 s26, s18, s24
	s_cselect_b32 s25, s15, s44
	s_cselect_b32 s24, s17, s34
	s_add_i32 s69, s90, 0x100
	v_add_u32_e32 v128, s53, v249
	v_add_u32_e32 v156, s69, v249
	ds_read_b128 v[112:115], v128
	ds_read_b128 v[120:123], v128 offset:1024
	ds_read_b128 v[124:127], v128 offset:2048
	ds_read_b128 v[128:131], v128 offset:3072
	ds_read_b128 v[136:139], v156
	ds_read_b128 v[140:143], v156 offset:1024
	ds_read_b128 v[144:147], v156 offset:2048
	ds_read_b128 v[156:159], v156 offset:3072
	v_lshl_add_u64 v[208:209], s[22:23], 0, v[206:207]
	s_add_i32 m0, s39, 0xc000
	ds_read_b128 v[160:163], v251
	ds_read_b128 v[164:167], v251 offset:1024
	ds_read_b128 v[168:171], v251 offset:2048
	ds_read_b128 v[172:175], v251 offset:3072
	ds_read_b128 v[176:179], v251 offset:4096
	ds_read_b128 v[180:183], v251 offset:5120
	ds_read_b128 v[184:187], v251 offset:6144
	ds_read_b128 v[188:191], v251 offset:7168
	global_load_lds_dwordx4 v[208:209], off
	v_lshl_add_u64 v[208:209], s[22:23], 0, v[204:205]
	s_add_i32 m0, s39, 0xe000
	s_nop 0
	global_load_lds_dwordx4 v[208:209], off
	s_waitcnt vmcnt(8)
	s_waitcnt lgkmcnt(0)
	s_barrier
; #define PG8_STAGE(bufoff, gbase, voff) do { _Pragma("unroll") for (int _i = 0; _i < 2; ++_i) \
;         __builtin_amdgcn_global_load_lds((const unsigned*)((const char*)(gbase) + (voff)[_i]), (PG8_LAS unsigned*)(lds + (bufoff) + ldsw + _i * 8192), 16, 0, 0); } while (0)
; #define PG8_LDA(dst, b, h) do { _Pragma("unroll") for (int m = 0; m < 4; ++m) _Pragma("unroll") for (int k = 0; k < 2; ++k) dst[m][k] = *(const PG8_LAS bf16x8*)(lds + PG8_SA(b, h) + aoff + m * 2048 + k * 1024); } while (0)
; #define PG8_LDB(dst, b, h) do { _Pragma("unroll") for (int n = 0; n < 2; ++n) _Pragma("unroll") for (int k = 0; k < 2; ++k) dst[n][k] = *(const PG8_LAS bf16x8*)(lds + PG8_SB(b, h) + boff + n * 2048 + k * 1024); } while (0)
; #define PG8_MMA(ai, bj, At, Bt) do { __builtin_amdgcn_s_setprio(1); _Pragma("unroll") for (int m = 0; m < 4; ++m) _Pragma("unroll") for (int n = 0; n < 2; ++n) _Pragma("unroll") for (int k = 0; k < 2; ++k) \
;         acc[ai][bj][m][n] = __builtin_amdgcn_mfma_f32_16x16x32_bf16(Bt[n][k], At[m][k], acc[ai][bj][m][n], 0, 0, 0); __builtin_amdgcn_s_setprio(0); } while (0)
; #define PG8_WAIT_V(n) asm volatile("s_waitcnt vmcnt(" #n ")" ::: "memory")
; #define PG8_WAIT_L(n) asm volatile("s_waitcnt lgkmcnt(" #n ")" ::: "memory")
; #define PG8_BAR __builtin_amdgcn_s_barrier()
; #define PG8_SCHED __builtin_amdgcn_sched_barrier(0)
; template <class Epi, class Sched, bool ALIGN_EPI = false, bool SP2 = false>
; __device__ __forceinline__ void gemm_phase(PG8_LAS unsigned char* lds, const Gemm g, const Sched& S, const Epi& E, int wave_in) {
;     ...
;             PG8_LDB(B0, 0, 0); PG8_LDB(B1, 0, 1); PG8_SCHED; PG8_LDA(At, 0, 0); PG8_STAGE(PG8_SA(1, 1), a1 + hstep, voffA);
;             PG8_WAIT_V(8); PG8_WAIT_L(0); PG8_BAR; PG8_MMA(0, 0, At, B0); PG8_MMA(0, 1, At, B1); PG8_BAR; PG8_SCHED;
;             PG8_LDA(At, 0, 1); PG8_STAGE(PG8_SB(0, 0), b2, voffB); PG8_STAGE(PG8_SB(0, 1), b2 + hstep, voffB); PG8_STAGE(PG8_SA(0, 0), a2, voffA);
;             PG8_WAIT_V(8); PG8_WAIT_L(0); PG8_BAR; PG8_MMA(1, 0, At, B0); PG8_MMA(1, 1, At, B1); PG8_BAR; PG8_SCHED;
	s_waitcnt lgkmcnt(0)
	v_mfma_f32_16x16x32_bf16 v[152:155], v[112:115], v[160:163], v[152:155]
	v_mfma_f32_16x16x32_bf16 v[148:151], v[124:127], v[160:163], v[148:151]
	v_mfma_f32_16x16x32_bf16 v[108:111], v[112:115], v[168:171], v[108:111]
	v_mfma_f32_16x16x32_bf16 v[104:107], v[124:127], v[168:171], v[104:107]
	v_mfma_f32_16x16x32_bf16 v[92:95], v[112:115], v[176:179], v[92:95]
	v_mfma_f32_16x16x32_bf16 v[88:91], v[124:127], v[176:179], v[88:91]
	v_mfma_f32_16x16x32_bf16 v[76:79], v[112:115], v[184:187], v[76:79]
	v_mfma_f32_16x16x32_bf16 v[72:75], v[124:127], v[184:187], v[72:75]
	v_mfma_f32_16x16x32_bf16 v[152:155], v[120:123], v[164:167], v[152:155]
	v_mfma_f32_16x16x32_bf16 v[148:151], v[128:131], v[164:167], v[148:151]
	v_mfma_f32_16x16x32_bf16 v[108:111], v[120:123], v[172:175], v[108:111]
	v_mfma_f32_16x16x32_bf16 v[104:107], v[128:131], v[172:175], v[104:107]
	v_mfma_f32_16x16x32_bf16 v[92:95], v[120:123], v[180:183], v[92:95]
	v_mfma_f32_16x16x32_bf16 v[88:91], v[128:131], v[180:183], v[88:91]
	v_mfma_f32_16x16x32_bf16 v[76:79], v[120:123], v[188:191], v[76:79]
	v_mfma_f32_16x16x32_bf16 v[72:75], v[128:131], v[188:191], v[72:75]
	v_mfma_f32_16x16x32_bf16 v[132:135], v[136:139], v[160:163], v[132:135]
	v_mfma_f32_16x16x32_bf16 v[116:119], v[144:147], v[160:163], v[116:119]
	v_mfma_f32_16x16x32_bf16 v[100:103], v[136:139], v[168:171], v[100:103]
	v_mfma_f32_16x16x32_bf16 v[96:99], v[144:147], v[168:171], v[96:99]
	v_mfma_f32_16x16x32_bf16 v[84:87], v[136:139], v[176:179], v[84:87]
	v_mfma_f32_16x16x32_bf16 v[80:83], v[144:147], v[176:179], v[80:83]
	v_mfma_f32_16x16x32_bf16 v[68:71], v[136:139], v[184:187], v[68:71]
	v_mfma_f32_16x16x32_bf16 v[64:67], v[144:147], v[184:187], v[64:67]
	v_mfma_f32_16x16x32_bf16 v[132:135], v[140:143], v[164:167], v[132:135]
	v_mfma_f32_16x16x32_bf16 v[116:119], v[156:159], v[164:167], v[116:119]
	v_mfma_f32_16x16x32_bf16 v[100:103], v[140:143], v[172:175], v[100:103]
	v_mfma_f32_16x16x32_bf16 v[96:99], v[156:159], v[172:175], v[96:99]
	v_mfma_f32_16x16x32_bf16 v[84:87], v[140:143], v[180:183], v[84:87]
	v_mfma_f32_16x16x32_bf16 v[80:83], v[156:159], v[180:183], v[80:83]
	v_mfma_f32_16x16x32_bf16 v[68:71], v[140:143], v[188:191], v[68:71]
	v_mfma_f32_16x16x32_bf16 v[64:67], v[156:159], v[188:191], v[64:67]
	s_barrier
	s_add_i32 s53, s53, s38
	v_lshl_add_u64 v[208:209], s[24:25], 0, v[192:193]
	s_mov_b32 m0, s53
	ds_read_b128 v[160:163], v251 offset:16384
	ds_read_b128 v[164:167], v251 offset:17408
	ds_read_b128 v[168:171], v251 offset:18432
	ds_read_b128 v[172:175], v251 offset:19456
	ds_read_b128 v[176:179], v251 offset:20480
	ds_read_b128 v[180:183], v251 offset:21504
	ds_read_b128 v[184:187], v251 offset:22528
	ds_read_b128 v[188:191], v251 offset:23552
	global_load_lds_dwordx4 v[208:209], off
	s_add_i32 m0, s53, 0x2000
	s_add_u32 s72, s24, 0x40000
	v_lshl_add_u64 v[210:211], s[24:25], 0, v[198:199]
	s_addc_u32 s73, s25, 0
	s_add_i32 s53, s69, s38
	global_load_lds_dwordx4 v[210:211], off
	v_lshl_add_u64 v[212:213], s[72:73], 0, v[192:193]
	s_mov_b32 m0, s53
	v_lshl_add_u64 v[214:215], s[26:27], 0, v[200:201]
	global_load_lds_dwordx4 v[212:213], off
	v_lshl_add_u64 v[212:213], s[72:73], 0, v[198:199]
	s_add_i32 m0, s53, 0x2000
	s_nop 0
	global_load_lds_dwordx4 v[212:213], off
	v_lshl_add_u64 v[212:213], s[26:27], 0, v[202:203]
	s_mov_b32 m0, s39
	s_nop 0
	global_load_lds_dwordx4 v[212:213], off
	s_mov_b32 m0, s46
	s_nop 0
	global_load_lds_dwordx4 v[214:215], off
	s_waitcnt vmcnt(8)
	s_waitcnt lgkmcnt(0)
	s_barrier
	s_waitcnt lgkmcnt(0)
	v_mfma_f32_16x16x32_bf16 v[60:63], v[112:115], v[160:163], v[60:63]
	v_mfma_f32_16x16x32_bf16 v[56:59], v[124:127], v[160:163], v[56:59]
	v_mfma_f32_16x16x32_bf16 v[44:47], v[112:115], v[168:171], v[44:47]
	v_mfma_f32_16x16x32_bf16 v[40:43], v[124:127], v[168:171], v[40:43]
	v_mfma_f32_16x16x32_bf16 v[28:31], v[112:115], v[176:179], v[28:31]
	v_mfma_f32_16x16x32_bf16 v[24:27], v[124:127], v[176:179], v[24:27]
	v_mfma_f32_16x16x32_bf16 v[12:15], v[112:115], v[184:187], v[12:15]
	v_mfma_f32_16x16x32_bf16 v[8:11], v[124:127], v[184:187], v[8:11]
	v_mfma_f32_16x16x32_bf16 v[60:63], v[120:123], v[164:167], v[60:63]
	v_mfma_f32_16x16x32_bf16 v[56:59], v[128:131], v[164:167], v[56:59]
	v_mfma_f32_16x16x32_bf16 v[44:47], v[120:123], v[172:175], v[44:47]
	v_mfma_f32_16x16x32_bf16 v[40:43], v[128:131], v[172:175], v[40:43]
	v_mfma_f32_16x16x32_bf16 v[28:31], v[120:123], v[180:183], v[28:31]
	v_mfma_f32_16x16x32_bf16 v[24:27], v[128:131], v[180:183], v[24:27]
	v_mfma_f32_16x16x32_bf16 v[12:15], v[120:123], v[188:191], v[12:15]
	v_mfma_f32_16x16x32_bf16 v[8:11], v[128:131], v[188:191], v[8:11]
	v_mfma_f32_16x16x32_bf16 v[52:55], v[136:139], v[160:163], v[52:55]
	v_mfma_f32_16x16x32_bf16 v[48:51], v[144:147], v[160:163], v[48:51]
	v_mfma_f32_16x16x32_bf16 v[36:39], v[136:139], v[168:171], v[36:39]
	v_mfma_f32_16x16x32_bf16 v[32:35], v[144:147], v[168:171], v[32:35]
	v_mfma_f32_16x16x32_bf16 v[20:23], v[136:139], v[176:179], v[20:23]
	v_mfma_f32_16x16x32_bf16 v[16:19], v[144:147], v[176:179], v[16:19]
	v_mfma_f32_16x16x32_bf16 v[4:7], v[136:139], v[184:187], v[4:7]
	v_mfma_f32_16x16x32_bf16 v[0:3], v[144:147], v[184:187], v[0:3]
	v_mfma_f32_16x16x32_bf16 v[52:55], v[140:143], v[164:167], v[52:55]
	v_mfma_f32_16x16x32_bf16 v[48:51], v[156:159], v[164:167], v[48:51]
	v_mfma_f32_16x16x32_bf16 v[36:39], v[140:143], v[172:175], v[36:39]
	v_mfma_f32_16x16x32_bf16 v[32:35], v[156:159], v[172:175], v[32:35]
	v_mfma_f32_16x16x32_bf16 v[20:23], v[140:143], v[180:183], v[20:23]
	v_mfma_f32_16x16x32_bf16 v[16:19], v[156:159], v[180:183], v[16:19]
	v_mfma_f32_16x16x32_bf16 v[4:7], v[140:143], v[188:191], v[4:7]
	v_mfma_f32_16x16x32_bf16 v[0:3], v[156:159], v[188:191], v[0:3]
	s_barrier
; #define PG8_STAGE(bufoff, gbase, voff) do { _Pragma("unroll") for (int _i = 0; _i < 2; ++_i) \
;         __builtin_amdgcn_global_load_lds((const unsigned*)((const char*)(gbase) + (voff)[_i]), (PG8_LAS unsigned*)(lds + (bufoff) + ldsw + _i * 8192), 16, 0, 0); } while (0)
; #define PG8_LDA(dst, b, h) do { _Pragma("unroll") for (int m = 0; m < 4; ++m) _Pragma("unroll") for (int k = 0; k < 2; ++k) dst[m][k] = *(const PG8_LAS bf16x8*)(lds + PG8_SA(b, h) + aoff + m * 2048 + k * 1024); } while (0)
; #define PG8_LDB(dst, b, h) do { _Pragma("unroll") for (int n = 0; n < 2; ++n) _Pragma("unroll") for (int k = 0; k < 2; ++k) dst[n][k] = *(const PG8_LAS bf16x8*)(lds + PG8_SB(b, h) + boff + n * 2048 + k * 1024); } while (0)
; #define PG8_MMA(ai, bj, At, Bt) do { __builtin_amdgcn_s_setprio(1); _Pragma("unroll") for (int m = 0; m < 4; ++m) _Pragma("unroll") for (int n = 0; n < 2; ++n) _Pragma("unroll") for (int k = 0; k < 2; ++k) \
;         acc[ai][bj][m][n] = __builtin_amdgcn_mfma_f32_16x16x32_bf16(Bt[n][k], At[m][k], acc[ai][bj][m][n], 0, 0, 0); __builtin_amdgcn_s_setprio(0); } while (0)
; #define PG8_WAIT_V(n) asm volatile("s_waitcnt vmcnt(" #n ")" ::: "memory")
; #define PG8_WAIT_L(n) asm volatile("s_waitcnt lgkmcnt(" #n ")" ::: "memory")
; #define PG8_BAR __builtin_amdgcn_s_barrier()
; #define PG8_SCHED __builtin_amdgcn_sched_barrier(0)
; template <class Epi, class Sched, bool ALIGN_EPI = false, bool SP2 = false>
; __device__ __forceinline__ void gemm_phase(PG8_LAS unsigned char* lds, const Gemm g, const Sched& S, const Epi& E, int wave_in) {
;     ...
;             PG8_LDB(B0, 1, 0); PG8_LDB(B1, 1, 1); PG8_SCHED; PG8_LDA(At, 1, 0); PG8_STAGE(PG8_SA(0, 1), a2 + hstep, voffA);
;             PG8_WAIT_V(8); PG8_WAIT_L(0); PG8_BAR; PG8_MMA(0, 0, At, B0); PG8_MMA(0, 1, At, B1); PG8_BAR; PG8_SCHED;
;             PG8_LDA(At, 1, 1); PG8_STAGE(PG8_SB(1, 0), b3, voffB); PG8_STAGE(PG8_SB(1, 1), b3 + hstep, voffB); PG8_STAGE(PG8_SA(1, 0), a3, voffA);
;             PG8_WAIT_V(8); PG8_WAIT_L(0); PG8_BAR; PG8_MMA(1, 0, At, B0); PG8_MMA(1, 1, At, B1); PG8_BAR; PG8_SCHED;
	s_add_i32 s53, s65, 0x100
	s_add_i32 s69, s52, 0x100
	v_add_u32_e32 v128, s53, v249
	v_add_u32_e32 v156, s69, v249
	ds_read_b128 v[112:115], v128
	ds_read_b128 v[120:123], v128 offset:1024
	ds_read_b128 v[124:127], v128 offset:2048
	ds_read_b128 v[128:131], v128 offset:3072
	ds_read_b128 v[136:139], v156
	ds_read_b128 v[140:143], v156 offset:1024
	ds_read_b128 v[144:147], v156 offset:2048
	ds_read_b128 v[156:159], v156 offset:3072
	s_add_u32 s26, s26, 0x40000
	s_addc_u32 s27, s27, 0
	s_mov_b32 m0, s47
	v_lshl_add_u64 v[216:217], s[26:27], 0, v[202:203]
	ds_read_b128 v[160:163], v251 offset:32768
	ds_read_b128 v[164:167], v251 offset:33792
	ds_read_b128 v[168:171], v251 offset:34816
	ds_read_b128 v[172:175], v251 offset:35840
	ds_read_b128 v[176:179], v251 offset:36864
	ds_read_b128 v[180:183], v251 offset:37888
	ds_read_b128 v[184:187], v251 offset:38912
	ds_read_b128 v[188:191], v251 offset:39936
	global_load_lds_dwordx4 v[216:217], off
	v_lshl_add_u64 v[216:217], s[26:27], 0, v[200:201]
	s_mov_b32 m0, s60
	s_nop 0
	global_load_lds_dwordx4 v[216:217], off
	s_waitcnt vmcnt(8)
	s_waitcnt lgkmcnt(0)
	s_barrier
	s_waitcnt lgkmcnt(0)
	v_mfma_f32_16x16x32_bf16 v[152:155], v[112:115], v[160:163], v[152:155]
	v_mfma_f32_16x16x32_bf16 v[148:151], v[124:127], v[160:163], v[148:151]
	v_mfma_f32_16x16x32_bf16 v[108:111], v[112:115], v[168:171], v[108:111]
	v_mfma_f32_16x16x32_bf16 v[104:107], v[124:127], v[168:171], v[104:107]
	v_mfma_f32_16x16x32_bf16 v[92:95], v[112:115], v[176:179], v[92:95]
	v_mfma_f32_16x16x32_bf16 v[88:91], v[124:127], v[176:179], v[88:91]
	v_mfma_f32_16x16x32_bf16 v[76:79], v[112:115], v[184:187], v[76:79]
	v_mfma_f32_16x16x32_bf16 v[72:75], v[124:127], v[184:187], v[72:75]
	v_mfma_f32_16x16x32_bf16 v[152:155], v[120:123], v[164:167], v[152:155]
	v_mfma_f32_16x16x32_bf16 v[148:151], v[128:131], v[164:167], v[148:151]
	v_mfma_f32_16x16x32_bf16 v[108:111], v[120:123], v[172:175], v[108:111]
	v_mfma_f32_16x16x32_bf16 v[104:107], v[128:131], v[172:175], v[104:107]
	v_mfma_f32_16x16x32_bf16 v[92:95], v[120:123], v[180:183], v[92:95]
	v_mfma_f32_16x16x32_bf16 v[88:91], v[128:131], v[180:183], v[88:91]
	v_mfma_f32_16x16x32_bf16 v[76:79], v[120:123], v[188:191], v[76:79]
	v_mfma_f32_16x16x32_bf16 v[72:75], v[128:131], v[188:191], v[72:75]
	v_mfma_f32_16x16x32_bf16 v[132:135], v[136:139], v[160:163], v[132:135]
	v_mfma_f32_16x16x32_bf16 v[116:119], v[144:147], v[160:163], v[116:119]
	v_mfma_f32_16x16x32_bf16 v[100:103], v[136:139], v[168:171], v[100:103]
	v_mfma_f32_16x16x32_bf16 v[96:99], v[144:147], v[168:171], v[96:99]
	v_mfma_f32_16x16x32_bf16 v[84:87], v[136:139], v[176:179], v[84:87]
	v_mfma_f32_16x16x32_bf16 v[80:83], v[144:147], v[176:179], v[80:83]
	v_mfma_f32_16x16x32_bf16 v[68:71], v[136:139], v[184:187], v[68:71]
	v_mfma_f32_16x16x32_bf16 v[64:67], v[144:147], v[184:187], v[64:67]
	v_mfma_f32_16x16x32_bf16 v[132:135], v[140:143], v[164:167], v[132:135]
	v_mfma_f32_16x16x32_bf16 v[116:119], v[156:159], v[164:167], v[116:119]
	v_mfma_f32_16x16x32_bf16 v[100:103], v[140:143], v[172:175], v[100:103]
	v_mfma_f32_16x16x32_bf16 v[96:99], v[156:159], v[172:175], v[96:99]
	v_mfma_f32_16x16x32_bf16 v[84:87], v[140:143], v[180:183], v[84:87]
	v_mfma_f32_16x16x32_bf16 v[80:83], v[156:159], v[180:183], v[80:83]
	v_mfma_f32_16x16x32_bf16 v[68:71], v[140:143], v[188:191], v[68:71]
	v_mfma_f32_16x16x32_bf16 v[64:67], v[156:159], v[188:191], v[64:67]
	s_barrier
	s_add_i32 s26, s53, s38
	v_lshl_add_u64 v[208:209], v[208:209], 0, s[88:89]
	s_mov_b32 m0, s26
	ds_read_b128 v[160:163], v251 offset:49152
	ds_read_b128 v[164:167], v251 offset:50176
	ds_read_b128 v[168:171], v251 offset:51200
	ds_read_b128 v[172:175], v251 offset:52224
	ds_read_b128 v[176:179], v251 offset:53248
	ds_read_b128 v[180:183], v251 offset:54272
	ds_read_b128 v[184:187], v251 offset:55296
	ds_read_b128 v[188:191], v251 offset:56320
	global_load_lds_dwordx4 v[208:209], off
	s_add_i32 m0, s26, 0x2000
	s_add_u32 s24, s24, 0x40080
	v_lshl_add_u64 v[208:209], v[210:211], 0, s[88:89]
	s_addc_u32 s25, s25, 0
	s_add_i32 s26, s69, s38
	global_load_lds_dwordx4 v[208:209], off
	v_lshl_add_u64 v[208:209], s[24:25], 0, v[192:193]
	s_mov_b32 m0, s26
	s_nop 0
	global_load_lds_dwordx4 v[208:209], off
	v_lshl_add_u64 v[208:209], s[24:25], 0, v[198:199]
	s_add_i32 m0, s26, 0x2000
	s_nop 0
	global_load_lds_dwordx4 v[208:209], off
	v_lshl_add_u64 v[208:209], v[212:213], 0, s[88:89]
	s_mov_b32 m0, s62
	s_nop 0
	global_load_lds_dwordx4 v[208:209], off
	v_lshl_add_u64 v[208:209], v[214:215], 0, s[88:89]
	s_mov_b32 m0, s63
	s_nop 0
	global_load_lds_dwordx4 v[208:209], off
	s_waitcnt vmcnt(8)
	s_waitcnt lgkmcnt(0)
	s_barrier
	s_waitcnt lgkmcnt(0)
	v_mfma_f32_16x16x32_bf16 v[60:63], v[112:115], v[160:163], v[60:63]
	v_mfma_f32_16x16x32_bf16 v[56:59], v[124:127], v[160:163], v[56:59]
	v_mfma_f32_16x16x32_bf16 v[44:47], v[112:115], v[168:171], v[44:47]
	v_mfma_f32_16x16x32_bf16 v[40:43], v[124:127], v[168:171], v[40:43]
	v_mfma_f32_16x16x32_bf16 v[28:31], v[112:115], v[176:179], v[28:31]
	v_mfma_f32_16x16x32_bf16 v[24:27], v[124:127], v[176:179], v[24:27]
	v_mfma_f32_16x16x32_bf16 v[12:15], v[112:115], v[184:187], v[12:15]
	v_mfma_f32_16x16x32_bf16 v[8:11], v[124:127], v[184:187], v[8:11]
	v_mfma_f32_16x16x32_bf16 v[60:63], v[120:123], v[164:167], v[60:63]
	v_mfma_f32_16x16x32_bf16 v[56:59], v[128:131], v[164:167], v[56:59]
	v_mfma_f32_16x16x32_bf16 v[44:47], v[120:123], v[172:175], v[44:47]
	v_mfma_f32_16x16x32_bf16 v[40:43], v[128:131], v[172:175], v[40:43]
	v_mfma_f32_16x16x32_bf16 v[28:31], v[120:123], v[180:183], v[28:31]
	v_mfma_f32_16x16x32_bf16 v[24:27], v[128:131], v[180:183], v[24:27]
	v_mfma_f32_16x16x32_bf16 v[12:15], v[120:123], v[188:191], v[12:15]
	v_mfma_f32_16x16x32_bf16 v[8:11], v[128:131], v[188:191], v[8:11]
	v_mfma_f32_16x16x32_bf16 v[52:55], v[136:139], v[160:163], v[52:55]
	v_mfma_f32_16x16x32_bf16 v[48:51], v[144:147], v[160:163], v[48:51]
	v_mfma_f32_16x16x32_bf16 v[36:39], v[136:139], v[168:171], v[36:39]
	v_mfma_f32_16x16x32_bf16 v[32:35], v[144:147], v[168:171], v[32:35]
	v_mfma_f32_16x16x32_bf16 v[20:23], v[136:139], v[176:179], v[20:23]
	v_mfma_f32_16x16x32_bf16 v[16:19], v[144:147], v[176:179], v[16:19]
	v_mfma_f32_16x16x32_bf16 v[4:7], v[136:139], v[184:187], v[4:7]
	v_mfma_f32_16x16x32_bf16 v[0:3], v[144:147], v[184:187], v[0:3]
	v_mfma_f32_16x16x32_bf16 v[52:55], v[140:143], v[164:167], v[52:55]
	v_mfma_f32_16x16x32_bf16 v[48:51], v[156:159], v[164:167], v[48:51]
	v_mfma_f32_16x16x32_bf16 v[36:39], v[140:143], v[172:175], v[36:39]
	v_mfma_f32_16x16x32_bf16 v[32:35], v[156:159], v[172:175], v[32:35]
	v_mfma_f32_16x16x32_bf16 v[20:23], v[140:143], v[180:183], v[20:23]
	v_mfma_f32_16x16x32_bf16 v[16:19], v[156:159], v[180:183], v[16:19]
	v_mfma_f32_16x16x32_bf16 v[4:7], v[140:143], v[188:191], v[4:7]
	v_mfma_f32_16x16x32_bf16 v[0:3], v[156:159], v[188:191], v[0:3]
	s_barrier
	s_add_i32 s45, s45, 2
	s_add_u32 s34, s34, 0x100
	s_addc_u32 s44, s44, 0
	s_add_u32 s22, s22, 0x100
	s_addc_u32 s23, s23, 0
	s_cmp_gt_u32 s45, 13
	s_cbranch_scc0 .LBB0_590

; #define PG8_STAGE(bufoff, gbase, voff) do { _Pragma("unroll") for (int _i = 0; _i < 2; ++_i) \
;         __builtin_amdgcn_global_load_lds((const unsigned*)((const char*)(gbase) + (voff)[_i]), (PG8_LAS unsigned*)(lds + (bufoff) + ldsw + _i * 8192), 16, 0, 0); } while (0)
; #define PG8_LDA(dst, b, h) do { _Pragma("unroll") for (int m = 0; m < 4; ++m) _Pragma("unroll") for (int k = 0; k < 2; ++k) dst[m][k] = *(const PG8_LAS bf16x8*)(lds + PG8_SA(b, h) + aoff + m * 2048 + k * 1024); } while (0)
; #define PG8_LDB(dst, b, h) do { _Pragma("unroll") for (int n = 0; n < 2; ++n) _Pragma("unroll") for (int k = 0; k < 2; ++k) dst[n][k] = *(const PG8_LAS bf16x8*)(lds + PG8_SB(b, h) + boff + n * 2048 + k * 1024); } while (0)
; #define PG8_WAIT_V(n) asm volatile("s_waitcnt vmcnt(" #n ")" ::: "memory")
; #define PG8_WAIT_L(n) asm volatile("s_waitcnt lgkmcnt(" #n ")" ::: "memory")
; #define PG8_BAR __builtin_amdgcn_s_barrier()
; template <class Epi, class Sched, bool ALIGN_EPI = false, bool SP2 = false>
; __device__ __forceinline__ void gemm_phase(PG8_LAS unsigned char* lds, const Gemm g, const Sched& S, const Epi& E, int wave_in) {
;     ...
;         const bool has_next = S.next(ui + 1, nxt);
;         const char* nA = has_next ? (const char*)g.A + (size_t)(nxt.pm >> g.ash) * g.astride + (size_t)nxt.pm * tstep : cA; const char* nB = has_next ? (const char*)g.Bt + (size_t)(nxt.pm >> g.bsh) * g.bstride + (size_t)nxt.pn * tstep : cB;
;         for (int t = 0; t < nt; t += 2) {
;             const bool last = (t == nt - 2);
;             const char* a1 = cA + (size_t)(t + 1) * kstep;
;             const char* a2 = last ? nA : cA + (size_t)(t + 2) * kstep; const char* b2 = last ? nB : cB + (size_t)(t + 2) * kstep;
;             const char* a3 = a2 + kstep; const char* b3 = b2 + kstep;
;             if (last && has_next) S.a_ready(nxt);
;             if constexpr (SP2) {
;             PG8_LDB(B0, 0, 0); PG8_LDB(B1, 0, 1); PG8_SCHED; PG8_LDA(At, 0, 0); PG8_STAGE(PG8_SA(1, 1), a1 + hstep, voffA);
;             PG8_WAIT_V(8); PG8_WAIT_L(0); PG8_BAR; PG8_MMA(0, 0, At, B0); PG8_MMA(0, 1, At, B1); PG8_BAR; PG8_SCHED;
;             PG8_LDA(At, 0, 1); PG8_STAGE(PG8_SB(0, 0), b2, voffB); PG8_STAGE(PG8_SB(0, 1), b2 + hstep, voffB); PG8_STAGE(PG8_SA(0, 0), a2, voffA);
;             PG8_WAIT_V(8); PG8_WAIT_L(0); PG8_BAR; PG8_MMA(1, 0, At, B0); PG8_MMA(1, 1, At, B1); PG8_BAR; PG8_SCHED;
.LBB0_686:
	s_ashr_i32 s17, s16, 31
	s_lshl_b64 s[18:19], s[16:17], 19
	s_add_u32 s18, s8, s18
	s_addc_u32 s19, s9, s19
	s_and_b64 s[20:21], s[42:43], exec
	s_cselect_b32 s17, s19, s25
	s_cselect_b32 s69, s18, s24
	s_ashr_i32 s20, s16, 5
	s_ashr_i32 s21, s20, 31
	s_lshl_b64 s[20:21], s[20:21], 21
	s_add_u32 s26, s31, s20
	s_addc_u32 s27, s33, s21
	s_ashr_i32 s13, s12, 31
	s_lshl_b64 s[20:21], s[12:13], 19
	s_add_u32 s20, s26, s20
	s_addc_u32 s21, s27, s21
	s_and_b64 s[26:27], s[42:43], exec
	s_cselect_b32 s13, s21, s23
	s_cselect_b32 s34, s20, s22
	s_add_u32 s53, s22, 0x100
	s_addc_u32 s71, s23, 0
	s_add_u32 s22, s24, 0x40080
	s_addc_u32 s23, s25, 0
	s_mov_b32 s72, -2
	s_add_u32 s24, s22, 0xfffc0080
	s_addc_u32 s25, s23, -1
	s_add_i32 s73, s35, 0x100
	s_cmp_eq_u32 s72, 12
	s_cselect_b32 s27, s17, s25
	s_cselect_b32 s26, s69, s24
	s_cselect_b32 s25, s13, s71
	s_cselect_b32 s24, s34, s53
	s_add_i32 s76, s90, 0x100
	v_add_u32_e32 v140, s73, v212
	v_add_u32_e32 v168, s76, v212
	ds_read_b128 v[128:131], v140
	ds_read_b128 v[132:135], v140 offset:1024
	ds_read_b128 v[136:139], v140 offset:2048
	ds_read_b128 v[140:143], v140 offset:3072
	ds_read_b128 v[156:159], v168
	ds_read_b128 v[160:163], v168 offset:1024
	ds_read_b128 v[164:167], v168 offset:2048
	ds_read_b128 v[168:171], v168 offset:3072
	v_lshl_add_u64 v[194:195], s[22:23], 0, v[154:155]
	s_add_i32 m0, s39, 0xc000
	ds_read_b128 v[172:175], v227
	ds_read_b128 v[176:179], v227 offset:1024
	ds_read_b128 v[180:183], v227 offset:2048
	ds_read_b128 v[184:187], v227 offset:3072
	ds_read_b128 v[188:191], v227 offset:4096
	ds_read_b128 v[198:201], v227 offset:5120
	ds_read_b128 v[202:205], v227 offset:6144
	ds_read_b128 v[206:209], v227 offset:7168
	global_load_lds_dwordx4 v[194:195], off
	v_lshl_add_u64 v[194:195], s[22:23], 0, v[152:153]
	s_add_i32 m0, s39, 0xe000
	s_nop 0
	global_load_lds_dwordx4 v[194:195], off
	s_waitcnt vmcnt(8)
	s_waitcnt lgkmcnt(0)
	s_barrier
	s_waitcnt lgkmcnt(0)
	v_mfma_f32_16x16x32_bf16 v[124:127], v[128:131], v[172:175], 0
	v_mfma_f32_16x16x32_bf16 v[120:123], v[136:139], v[172:175], 0
	v_mfma_f32_16x16x32_bf16 v[108:111], v[128:131], v[180:183], 0
	v_mfma_f32_16x16x32_bf16 v[104:107], v[136:139], v[180:183], 0
	v_mfma_f32_16x16x32_bf16 v[96:99], v[128:131], v[188:191], 0
	v_mfma_f32_16x16x32_bf16 v[88:91], v[136:139], v[188:191], 0
	v_mfma_f32_16x16x32_bf16 v[80:83], v[128:131], v[202:205], 0
	v_mfma_f32_16x16x32_bf16 v[72:75], v[136:139], v[202:205], 0
	v_mfma_f32_16x16x32_bf16 v[124:127], v[132:135], v[176:179], v[124:127]
	v_mfma_f32_16x16x32_bf16 v[120:123], v[140:143], v[176:179], v[120:123]
	v_mfma_f32_16x16x32_bf16 v[108:111], v[132:135], v[184:187], v[108:111]
	v_mfma_f32_16x16x32_bf16 v[104:107], v[140:143], v[184:187], v[104:107]
	v_mfma_f32_16x16x32_bf16 v[96:99], v[132:135], v[198:201], v[96:99]
	v_mfma_f32_16x16x32_bf16 v[88:91], v[140:143], v[198:201], v[88:91]
	v_mfma_f32_16x16x32_bf16 v[80:83], v[132:135], v[206:209], v[80:83]
	v_mfma_f32_16x16x32_bf16 v[72:75], v[140:143], v[206:209], v[72:75]
	v_mfma_f32_16x16x32_bf16 v[116:119], v[156:159], v[172:175], 0
	v_mfma_f32_16x16x32_bf16 v[112:115], v[164:167], v[172:175], 0
	v_mfma_f32_16x16x32_bf16 v[100:103], v[156:159], v[180:183], 0
	v_mfma_f32_16x16x32_bf16 v[92:95], v[164:167], v[180:183], 0
	v_mfma_f32_16x16x32_bf16 v[84:87], v[156:159], v[188:191], 0
	v_mfma_f32_16x16x32_bf16 v[76:79], v[164:167], v[188:191], 0
	v_mfma_f32_16x16x32_bf16 v[68:71], v[156:159], v[202:205], 0
	v_mfma_f32_16x16x32_bf16 v[64:67], v[164:167], v[202:205], 0
	v_mfma_f32_16x16x32_bf16 v[116:119], v[160:163], v[176:179], v[116:119]
	v_mfma_f32_16x16x32_bf16 v[112:115], v[168:171], v[176:179], v[112:115]
	v_mfma_f32_16x16x32_bf16 v[100:103], v[160:163], v[184:187], v[100:103]
	v_mfma_f32_16x16x32_bf16 v[92:95], v[168:171], v[184:187], v[92:95]
	v_mfma_f32_16x16x32_bf16 v[84:87], v[160:163], v[198:201], v[84:87]
	v_mfma_f32_16x16x32_bf16 v[76:79], v[168:171], v[198:201], v[76:79]
	v_mfma_f32_16x16x32_bf16 v[68:71], v[160:163], v[206:209], v[68:71]
	v_mfma_f32_16x16x32_bf16 v[64:67], v[168:171], v[206:209], v[64:67]
	s_barrier
	s_add_i32 s73, s73, s38
	v_lshl_add_u64 v[194:195], s[24:25], 0, v[148:149]
	s_mov_b32 m0, s73
	ds_read_b128 v[172:175], v227 offset:16384
	ds_read_b128 v[176:179], v227 offset:17408
	ds_read_b128 v[180:183], v227 offset:18432
	ds_read_b128 v[184:187], v227 offset:19456
	ds_read_b128 v[188:191], v227 offset:20480
	ds_read_b128 v[198:201], v227 offset:21504
	ds_read_b128 v[202:205], v227 offset:22528
	ds_read_b128 v[206:209], v227 offset:23552
	global_load_lds_dwordx4 v[194:195], off
	s_add_i32 m0, s73, 0x2000
	s_add_u32 s74, s24, 0x40000
	v_lshl_add_u64 v[196:197], s[24:25], 0, v[144:145]
	s_addc_u32 s75, s25, 0
	s_add_i32 s73, s76, s38
	global_load_lds_dwordx4 v[196:197], off
	v_lshl_add_u64 v[234:235], s[74:75], 0, v[148:149]
	s_mov_b32 m0, s73
	v_lshl_add_u64 v[236:237], s[26:27], 0, v[146:147]
	global_load_lds_dwordx4 v[234:235], off
	v_lshl_add_u64 v[234:235], s[74:75], 0, v[144:145]
	s_add_i32 m0, s73, 0x2000
	s_nop 0
	global_load_lds_dwordx4 v[234:235], off
	v_lshl_add_u64 v[234:235], s[26:27], 0, v[150:151]
	s_mov_b32 m0, s39
	s_nop 0
	global_load_lds_dwordx4 v[234:235], off
	s_mov_b32 m0, s44
	s_nop 0
	global_load_lds_dwordx4 v[236:237], off
	s_waitcnt vmcnt(8)
	s_waitcnt lgkmcnt(0)
	s_barrier
; #define PG8_STAGE(bufoff, gbase, voff) do { _Pragma("unroll") for (int _i = 0; _i < 2; ++_i) \
;         __builtin_amdgcn_global_load_lds((const unsigned*)((const char*)(gbase) + (voff)[_i]), (PG8_LAS unsigned*)(lds + (bufoff) + ldsw + _i * 8192), 16, 0, 0); } while (0)
; #define PG8_LDA(dst, b, h) do { _Pragma("unroll") for (int m = 0; m < 4; ++m) _Pragma("unroll") for (int k = 0; k < 2; ++k) dst[m][k] = *(const PG8_LAS bf16x8*)(lds + PG8_SA(b, h) + aoff + m * 2048 + k * 1024); } while (0)
; #define PG8_LDB(dst, b, h) do { _Pragma("unroll") for (int n = 0; n < 2; ++n) _Pragma("unroll") for (int k = 0; k < 2; ++k) dst[n][k] = *(const PG8_LAS bf16x8*)(lds + PG8_SB(b, h) + boff + n * 2048 + k * 1024); } while (0)
; #define PG8_MMA(ai, bj, At, Bt) do { __builtin_amdgcn_s_setprio(1); _Pragma("unroll") for (int m = 0; m < 4; ++m) _Pragma("unroll") for (int n = 0; n < 2; ++n) _Pragma("unroll") for (int k = 0; k < 2; ++k) \
;         acc[ai][bj][m][n] = __builtin_amdgcn_mfma_f32_16x16x32_bf16(Bt[n][k], At[m][k], acc[ai][bj][m][n], 0, 0, 0); __builtin_amdgcn_s_setprio(0); } while (0)
; #define PG8_WAIT_V(n) asm volatile("s_waitcnt vmcnt(" #n ")" ::: "memory")
; #define PG8_WAIT_L(n) asm volatile("s_waitcnt lgkmcnt(" #n ")" ::: "memory")
; #define PG8_BAR __builtin_amdgcn_s_barrier()
; #define PG8_SCHED __builtin_amdgcn_sched_barrier(0)
; template <class Epi, class Sched, bool ALIGN_EPI = false, bool SP2 = false>
; __device__ __forceinline__ void gemm_phase(PG8_LAS unsigned char* lds, const Gemm g, const Sched& S, const Epi& E, int wave_in) {
;     ...
;             PG8_WAIT_V(8); PG8_WAIT_L(0); PG8_BAR; PG8_MMA(1, 0, At, B0); PG8_MMA(1, 1, At, B1); PG8_BAR; PG8_SCHED;
;             PG8_LDB(B0, 1, 0); PG8_LDB(B1, 1, 1); PG8_SCHED; PG8_LDA(At, 1, 0); PG8_STAGE(PG8_SA(0, 1), a2 + hstep, voffA);
;             PG8_WAIT_V(8); PG8_WAIT_L(0); PG8_BAR; PG8_MMA(0, 0, At, B0); PG8_MMA(0, 1, At, B1); PG8_BAR; PG8_SCHED;
	s_waitcnt lgkmcnt(0)
	v_mfma_f32_16x16x32_bf16 v[60:63], v[128:131], v[172:175], 0
	v_mfma_f32_16x16x32_bf16 v[56:59], v[136:139], v[172:175], 0
	v_mfma_f32_16x16x32_bf16 v[48:51], v[128:131], v[180:183], 0
	v_mfma_f32_16x16x32_bf16 v[40:43], v[136:139], v[180:183], 0
	v_mfma_f32_16x16x32_bf16 v[32:35], v[128:131], v[188:191], 0
	v_mfma_f32_16x16x32_bf16 v[24:27], v[136:139], v[188:191], 0
	v_mfma_f32_16x16x32_bf16 v[16:19], v[128:131], v[202:205], 0
	v_mfma_f32_16x16x32_bf16 v[8:11], v[136:139], v[202:205], 0
	v_mfma_f32_16x16x32_bf16 v[60:63], v[132:135], v[176:179], v[60:63]
	v_mfma_f32_16x16x32_bf16 v[56:59], v[140:143], v[176:179], v[56:59]
	v_mfma_f32_16x16x32_bf16 v[48:51], v[132:135], v[184:187], v[48:51]
	v_mfma_f32_16x16x32_bf16 v[40:43], v[140:143], v[184:187], v[40:43]
	v_mfma_f32_16x16x32_bf16 v[32:35], v[132:135], v[198:201], v[32:35]
	v_mfma_f32_16x16x32_bf16 v[24:27], v[140:143], v[198:201], v[24:27]
	v_mfma_f32_16x16x32_bf16 v[16:19], v[132:135], v[206:209], v[16:19]
	v_mfma_f32_16x16x32_bf16 v[8:11], v[140:143], v[206:209], v[8:11]
	v_mfma_f32_16x16x32_bf16 v[52:55], v[156:159], v[172:175], 0
	v_mfma_f32_16x16x32_bf16 v[44:47], v[164:167], v[172:175], 0
	v_mfma_f32_16x16x32_bf16 v[36:39], v[156:159], v[180:183], 0
	v_mfma_f32_16x16x32_bf16 v[28:31], v[164:167], v[180:183], 0
	v_mfma_f32_16x16x32_bf16 v[20:23], v[156:159], v[188:191], 0
	v_mfma_f32_16x16x32_bf16 v[12:15], v[164:167], v[188:191], 0
	v_mfma_f32_16x16x32_bf16 v[4:7], v[156:159], v[202:205], 0
	v_mfma_f32_16x16x32_bf16 v[0:3], v[164:167], v[202:205], 0
	v_mfma_f32_16x16x32_bf16 v[52:55], v[160:163], v[176:179], v[52:55]
	v_mfma_f32_16x16x32_bf16 v[44:47], v[168:171], v[176:179], v[44:47]
	v_mfma_f32_16x16x32_bf16 v[36:39], v[160:163], v[184:187], v[36:39]
	v_mfma_f32_16x16x32_bf16 v[28:31], v[168:171], v[184:187], v[28:31]
	v_mfma_f32_16x16x32_bf16 v[20:23], v[160:163], v[198:201], v[20:23]
	v_mfma_f32_16x16x32_bf16 v[12:15], v[168:171], v[198:201], v[12:15]
	v_mfma_f32_16x16x32_bf16 v[4:7], v[160:163], v[206:209], v[4:7]
	v_mfma_f32_16x16x32_bf16 v[0:3], v[168:171], v[206:209], v[0:3]
	s_barrier
	s_add_i32 s73, s65, 0x100
	s_add_i32 s74, s52, 0x100
	v_add_u32_e32 v140, s73, v212
	v_add_u32_e32 v168, s74, v212
	ds_read_b128 v[128:131], v140
	ds_read_b128 v[132:135], v140 offset:1024
	ds_read_b128 v[136:139], v140 offset:2048
	ds_read_b128 v[140:143], v140 offset:3072
	ds_read_b128 v[156:159], v168
	ds_read_b128 v[160:163], v168 offset:1024
	ds_read_b128 v[164:167], v168 offset:2048
	ds_read_b128 v[168:171], v168 offset:3072
	s_add_u32 s26, s26, 0x40000
	s_addc_u32 s27, s27, 0
	s_mov_b32 m0, s45
	v_lshl_add_u64 v[238:239], s[26:27], 0, v[150:151]
	ds_read_b128 v[172:175], v227 offset:32768
	ds_read_b128 v[176:179], v227 offset:33792
	ds_read_b128 v[180:183], v227 offset:34816
	ds_read_b128 v[184:187], v227 offset:35840
	ds_read_b128 v[188:191], v227 offset:36864
	ds_read_b128 v[198:201], v227 offset:37888
	ds_read_b128 v[202:205], v227 offset:38912
	ds_read_b128 v[206:209], v227 offset:39936
	global_load_lds_dwordx4 v[238:239], off
	v_lshl_add_u64 v[238:239], s[26:27], 0, v[146:147]
	s_mov_b32 m0, s46
	s_nop 0
	global_load_lds_dwordx4 v[238:239], off
	s_waitcnt vmcnt(8)
	s_waitcnt lgkmcnt(0)
	s_barrier
	s_waitcnt lgkmcnt(0)
	v_mfma_f32_16x16x32_bf16 v[124:127], v[128:131], v[172:175], v[124:127]
	v_mfma_f32_16x16x32_bf16 v[120:123], v[136:139], v[172:175], v[120:123]
	v_mfma_f32_16x16x32_bf16 v[108:111], v[128:131], v[180:183], v[108:111]
	v_mfma_f32_16x16x32_bf16 v[104:107], v[136:139], v[180:183], v[104:107]
	v_mfma_f32_16x16x32_bf16 v[96:99], v[128:131], v[188:191], v[96:99]
	v_mfma_f32_16x16x32_bf16 v[88:91], v[136:139], v[188:191], v[88:91]
	v_mfma_f32_16x16x32_bf16 v[80:83], v[128:131], v[202:205], v[80:83]
	v_mfma_f32_16x16x32_bf16 v[72:75], v[136:139], v[202:205], v[72:75]
	v_mfma_f32_16x16x32_bf16 v[124:127], v[132:135], v[176:179], v[124:127]
	v_mfma_f32_16x16x32_bf16 v[120:123], v[140:143], v[176:179], v[120:123]
	v_mfma_f32_16x16x32_bf16 v[108:111], v[132:135], v[184:187], v[108:111]
	v_mfma_f32_16x16x32_bf16 v[104:107], v[140:143], v[184:187], v[104:107]
	v_mfma_f32_16x16x32_bf16 v[96:99], v[132:135], v[198:201], v[96:99]
	v_mfma_f32_16x16x32_bf16 v[88:91], v[140:143], v[198:201], v[88:91]
	v_mfma_f32_16x16x32_bf16 v[80:83], v[132:135], v[206:209], v[80:83]
	v_mfma_f32_16x16x32_bf16 v[72:75], v[140:143], v[206:209], v[72:75]
	v_mfma_f32_16x16x32_bf16 v[116:119], v[156:159], v[172:175], v[116:119]
	v_mfma_f32_16x16x32_bf16 v[112:115], v[164:167], v[172:175], v[112:115]
	v_mfma_f32_16x16x32_bf16 v[100:103], v[156:159], v[180:183], v[100:103]
	v_mfma_f32_16x16x32_bf16 v[92:95], v[164:167], v[180:183], v[92:95]
	v_mfma_f32_16x16x32_bf16 v[84:87], v[156:159], v[188:191], v[84:87]
	v_mfma_f32_16x16x32_bf16 v[76:79], v[164:167], v[188:191], v[76:79]
	v_mfma_f32_16x16x32_bf16 v[68:71], v[156:159], v[202:205], v[68:71]
	v_mfma_f32_16x16x32_bf16 v[64:67], v[164:167], v[202:205], v[64:67]
	v_mfma_f32_16x16x32_bf16 v[116:119], v[160:163], v[176:179], v[116:119]
	v_mfma_f32_16x16x32_bf16 v[112:115], v[168:171], v[176:179], v[112:115]
	v_mfma_f32_16x16x32_bf16 v[100:103], v[160:163], v[184:187], v[100:103]
	v_mfma_f32_16x16x32_bf16 v[92:95], v[168:171], v[184:187], v[92:95]
	v_mfma_f32_16x16x32_bf16 v[84:87], v[160:163], v[198:201], v[84:87]
	v_mfma_f32_16x16x32_bf16 v[76:79], v[168:171], v[198:201], v[76:79]
	v_mfma_f32_16x16x32_bf16 v[68:71], v[160:163], v[206:209], v[68:71]
	v_mfma_f32_16x16x32_bf16 v[64:67], v[168:171], v[206:209], v[64:67]
	s_barrier
; #define PG8_STAGE(bufoff, gbase, voff) do { _Pragma("unroll") for (int _i = 0; _i < 2; ++_i) \
;         __builtin_amdgcn_global_load_lds((const unsigned*)((const char*)(gbase) + (voff)[_i]), (PG8_LAS unsigned*)(lds + (bufoff) + ldsw + _i * 8192), 16, 0, 0); } while (0)
; #define PG8_LDA(dst, b, h) do { _Pragma("unroll") for (int m = 0; m < 4; ++m) _Pragma("unroll") for (int k = 0; k < 2; ++k) dst[m][k] = *(const PG8_LAS bf16x8*)(lds + PG8_SA(b, h) + aoff + m * 2048 + k * 1024); } while (0)
; #define PG8_LDB(dst, b, h) do { _Pragma("unroll") for (int n = 0; n < 2; ++n) _Pragma("unroll") for (int k = 0; k < 2; ++k) dst[n][k] = *(const PG8_LAS bf16x8*)(lds + PG8_SB(b, h) + boff + n * 2048 + k * 1024); } while (0)
; #define PG8_MMA(ai, bj, At, Bt) do { __builtin_amdgcn_s_setprio(1); _Pragma("unroll") for (int m = 0; m < 4; ++m) _Pragma("unroll") for (int n = 0; n < 2; ++n) _Pragma("unroll") for (int k = 0; k < 2; ++k) \
;         acc[ai][bj][m][n] = __builtin_amdgcn_mfma_f32_16x16x32_bf16(Bt[n][k], At[m][k], acc[ai][bj][m][n], 0, 0, 0); __builtin_amdgcn_s_setprio(0); } while (0)
; template <class Epi, class Sched, bool ALIGN_EPI = false, bool SP2 = false>
; __device__ __forceinline__ void gemm_phase(PG8_LAS unsigned char* lds, const Gemm g, const Sched& S, const Epi& E, int wave_in) {
;     ...
;         for (int t = 0; t < nt; t += 2) {
;             const bool last = (t == nt - 2);
;             const char* a1 = cA + (size_t)(t + 1) * kstep;
;             const char* a2 = last ? nA : cA + (size_t)(t + 2) * kstep; const char* b2 = last ? nB : cB + (size_t)(t + 2) * kstep;
;             const char* a3 = a2 + kstep; const char* b3 = b2 + kstep;
;             if (last && has_next) S.a_ready(nxt);
;             if constexpr (SP2) {
;             PG8_LDB(B0, 0, 0); PG8_LDB(B1, 0, 1); PG8_SCHED; PG8_LDA(At, 0, 0); PG8_STAGE(PG8_SA(1, 1), a1 + hstep, voffA);
;             PG8_WAIT_V(8); PG8_WAIT_L(0); PG8_BAR; PG8_MMA(0, 0, At, B0); PG8_MMA(0, 1, At, B1); PG8_BAR; PG8_SCHED;
;     ...
;             PG8_WAIT_V(8); PG8_WAIT_L(0); PG8_BAR; PG8_MMA(0, 0, At, B0); PG8_MMA(0, 1, At, B1); PG8_BAR; PG8_SCHED;
;             PG8_LDA(At, 1, 1); PG8_STAGE(PG8_SB(1, 0), b3, voffB); PG8_STAGE(PG8_SB(1, 1), b3 + hstep, voffB); PG8_STAGE(PG8_SA(1, 0), a3, voffA);
;             PG8_WAIT_V(8); PG8_WAIT_L(0); PG8_BAR; PG8_MMA(1, 0, At, B0); PG8_MMA(1, 1, At, B1); PG8_BAR; PG8_SCHED;
	s_add_i32 s26, s73, s38
	v_lshl_add_u64 v[194:195], v[194:195], 0, s[88:89]
	s_mov_b32 m0, s26
	ds_read_b128 v[172:175], v227 offset:49152
	ds_read_b128 v[176:179], v227 offset:50176
	ds_read_b128 v[180:183], v227 offset:51200
	ds_read_b128 v[184:187], v227 offset:52224
	ds_read_b128 v[188:191], v227 offset:53248
	ds_read_b128 v[198:201], v227 offset:54272
	ds_read_b128 v[202:205], v227 offset:55296
	ds_read_b128 v[206:209], v227 offset:56320
	global_load_lds_dwordx4 v[194:195], off
	s_add_i32 m0, s26, 0x2000
	s_add_u32 s24, s24, 0x40080
	v_lshl_add_u64 v[194:195], v[196:197], 0, s[88:89]
	s_addc_u32 s25, s25, 0
	s_add_i32 s26, s74, s38
	global_load_lds_dwordx4 v[194:195], off
	v_lshl_add_u64 v[194:195], s[24:25], 0, v[148:149]
	s_mov_b32 m0, s26
	s_nop 0
	global_load_lds_dwordx4 v[194:195], off
	v_lshl_add_u64 v[194:195], s[24:25], 0, v[144:145]
	s_add_i32 m0, s26, 0x2000
	s_nop 0
	global_load_lds_dwordx4 v[194:195], off
	v_lshl_add_u64 v[194:195], v[234:235], 0, s[88:89]
	s_mov_b32 m0, s61
	s_nop 0
	global_load_lds_dwordx4 v[194:195], off
	v_lshl_add_u64 v[194:195], v[236:237], 0, s[88:89]
	s_mov_b32 m0, s62
	s_nop 0
	global_load_lds_dwordx4 v[194:195], off
	s_waitcnt vmcnt(8)
	s_waitcnt lgkmcnt(0)
	s_barrier
	s_waitcnt lgkmcnt(0)
	v_mfma_f32_16x16x32_bf16 v[60:63], v[128:131], v[172:175], v[60:63]
	v_mfma_f32_16x16x32_bf16 v[56:59], v[136:139], v[172:175], v[56:59]
	v_mfma_f32_16x16x32_bf16 v[48:51], v[128:131], v[180:183], v[48:51]
	v_mfma_f32_16x16x32_bf16 v[40:43], v[136:139], v[180:183], v[40:43]
	v_mfma_f32_16x16x32_bf16 v[32:35], v[128:131], v[188:191], v[32:35]
	v_mfma_f32_16x16x32_bf16 v[24:27], v[136:139], v[188:191], v[24:27]
	v_mfma_f32_16x16x32_bf16 v[16:19], v[128:131], v[202:205], v[16:19]
	v_mfma_f32_16x16x32_bf16 v[8:11], v[136:139], v[202:205], v[8:11]
	v_mfma_f32_16x16x32_bf16 v[60:63], v[132:135], v[176:179], v[60:63]
	v_mfma_f32_16x16x32_bf16 v[56:59], v[140:143], v[176:179], v[56:59]
	v_mfma_f32_16x16x32_bf16 v[48:51], v[132:135], v[184:187], v[48:51]
	v_mfma_f32_16x16x32_bf16 v[40:43], v[140:143], v[184:187], v[40:43]
	v_mfma_f32_16x16x32_bf16 v[32:35], v[132:135], v[198:201], v[32:35]
	v_mfma_f32_16x16x32_bf16 v[24:27], v[140:143], v[198:201], v[24:27]
	v_mfma_f32_16x16x32_bf16 v[16:19], v[132:135], v[206:209], v[16:19]
	v_mfma_f32_16x16x32_bf16 v[8:11], v[140:143], v[206:209], v[8:11]
	v_mfma_f32_16x16x32_bf16 v[52:55], v[156:159], v[172:175], v[52:55]
	v_mfma_f32_16x16x32_bf16 v[44:47], v[164:167], v[172:175], v[44:47]
	v_mfma_f32_16x16x32_bf16 v[36:39], v[156:159], v[180:183], v[36:39]
	v_mfma_f32_16x16x32_bf16 v[28:31], v[164:167], v[180:183], v[28:31]
	v_mfma_f32_16x16x32_bf16 v[20:23], v[156:159], v[188:191], v[20:23]
	v_mfma_f32_16x16x32_bf16 v[12:15], v[164:167], v[188:191], v[12:15]
	v_mfma_f32_16x16x32_bf16 v[4:7], v[156:159], v[202:205], v[4:7]
	v_mfma_f32_16x16x32_bf16 v[0:3], v[164:167], v[202:205], v[0:3]
	v_mfma_f32_16x16x32_bf16 v[52:55], v[160:163], v[176:179], v[52:55]
	v_mfma_f32_16x16x32_bf16 v[44:47], v[168:171], v[176:179], v[44:47]
	v_mfma_f32_16x16x32_bf16 v[36:39], v[160:163], v[184:187], v[36:39]
	v_mfma_f32_16x16x32_bf16 v[28:31], v[168:171], v[184:187], v[28:31]
	v_mfma_f32_16x16x32_bf16 v[20:23], v[160:163], v[198:201], v[20:23]
	v_mfma_f32_16x16x32_bf16 v[12:15], v[168:171], v[198:201], v[12:15]
	v_mfma_f32_16x16x32_bf16 v[4:7], v[160:163], v[206:209], v[4:7]
	v_mfma_f32_16x16x32_bf16 v[0:3], v[168:171], v[206:209], v[0:3]
	s_barrier
	s_add_i32 s72, s72, 2
	s_add_u32 s53, s53, 0x100
	s_addc_u32 s71, s71, 0
	s_add_u32 s22, s22, 0x100
	s_addc_u32 s23, s23, 0
	s_cmp_gt_u32 s72, 13
	s_cbranch_scc1 .Lkexit_4
.LBB0_687:
	s_add_u32 s24, s22, 0xfffc0080
	s_addc_u32 s25, s23, -1
	s_add_i32 s73, s35, 0x100
	s_cmp_eq_u32 s72, 12
	s_cselect_b32 s27, s17, s25
	s_cselect_b32 s26, s69, s24
	s_cselect_b32 s25, s13, s71
	s_cselect_b32 s24, s34, s53
	s_add_i32 s76, s90, 0x100
	v_add_u32_e32 v140, s73, v212
	v_add_u32_e32 v168, s76, v212
	ds_read_b128 v[128:131], v140
	ds_read_b128 v[132:135], v140 offset:1024
	ds_read_b128 v[136:139], v140 offset:2048
	ds_read_b128 v[140:143], v140 offset:3072
	ds_read_b128 v[156:159], v168
	ds_read_b128 v[160:163], v168 offset:1024
	ds_read_b128 v[164:167], v168 offset:2048
	ds_read_b128 v[168:171], v168 offset:3072
	v_lshl_add_u64 v[194:195], s[22:23], 0, v[154:155]
	s_add_i32 m0, s39, 0xc000
	ds_read_b128 v[172:175], v227
	ds_read_b128 v[176:179], v227 offset:1024
	ds_read_b128 v[180:183], v227 offset:2048
	ds_read_b128 v[184:187], v227 offset:3072
	ds_read_b128 v[188:191], v227 offset:4096
	ds_read_b128 v[198:201], v227 offset:5120
	ds_read_b128 v[202:205], v227 offset:6144
	ds_read_b128 v[206:209], v227 offset:7168
	global_load_lds_dwordx4 v[194:195], off
	v_lshl_add_u64 v[194:195], s[22:23], 0, v[152:153]
	s_add_i32 m0, s39, 0xe000
	s_nop 0
	global_load_lds_dwordx4 v[194:195], off
	s_waitcnt vmcnt(8)
	s_waitcnt lgkmcnt(0)
	s_barrier
; #define PG8_STAGE(bufoff, gbase, voff) do { _Pragma("unroll") for (int _i = 0; _i < 2; ++_i) \
;         __builtin_amdgcn_global_load_lds((const unsigned*)((const char*)(gbase) + (voff)[_i]), (PG8_LAS unsigned*)(lds + (bufoff) + ldsw + _i * 8192), 16, 0, 0); } while (0)
; #define PG8_LDA(dst, b, h) do { _Pragma("unroll") for (int m = 0; m < 4; ++m) _Pragma("unroll") for (int k = 0; k < 2; ++k) dst[m][k] = *(const PG8_LAS bf16x8*)(lds + PG8_SA(b, h) + aoff + m * 2048 + k * 1024); } while (0)
; #define PG8_LDB(dst, b, h) do { _Pragma("unroll") for (int n = 0; n < 2; ++n) _Pragma("unroll") for (int k = 0; k < 2; ++k) dst[n][k] = *(const PG8_LAS bf16x8*)(lds + PG8_SB(b, h) + boff + n * 2048 + k * 1024); } while (0)
; #define PG8_MMA(ai, bj, At, Bt) do { __builtin_amdgcn_s_setprio(1); _Pragma("unroll") for (int m = 0; m < 4; ++m) _Pragma("unroll") for (int n = 0; n < 2; ++n) _Pragma("unroll") for (int k = 0; k < 2; ++k) \
;         acc[ai][bj][m][n] = __builtin_amdgcn_mfma_f32_16x16x32_bf16(Bt[n][k], At[m][k], acc[ai][bj][m][n], 0, 0, 0); __builtin_amdgcn_s_setprio(0); } while (0)
; #define PG8_WAIT_V(n) asm volatile("s_waitcnt vmcnt(" #n ")" ::: "memory")
; #define PG8_WAIT_L(n) asm volatile("s_waitcnt lgkmcnt(" #n ")" ::: "memory")
; #define PG8_BAR __builtin_amdgcn_s_barrier()
; #define PG8_SCHED __builtin_amdgcn_sched_barrier(0)
; template <class Epi, class Sched, bool ALIGN_EPI = false, bool SP2 = false>
; __device__ __forceinline__ void gemm_phase(PG8_LAS unsigned char* lds, const Gemm g, const Sched& S, const Epi& E, int wave_in) {
;     ...
;             PG8_LDB(B0, 0, 0); PG8_LDB(B1, 0, 1); PG8_SCHED; PG8_LDA(At, 0, 0); PG8_STAGE(PG8_SA(1, 1), a1 + hstep, voffA);
;             PG8_WAIT_V(8); PG8_WAIT_L(0); PG8_BAR; PG8_MMA(0, 0, At, B0); PG8_MMA(0, 1, At, B1); PG8_BAR; PG8_SCHED;
;             PG8_LDA(At, 0, 1); PG8_STAGE(PG8_SB(0, 0), b2, voffB); PG8_STAGE(PG8_SB(0, 1), b2 + hstep, voffB); PG8_STAGE(PG8_SA(0, 0), a2, voffA);
;             PG8_WAIT_V(8); PG8_WAIT_L(0); PG8_BAR; PG8_MMA(1, 0, At, B0); PG8_MMA(1, 1, At, B1); PG8_BAR; PG8_SCHED;
	s_waitcnt lgkmcnt(0)
	v_mfma_f32_16x16x32_bf16 v[124:127], v[128:131], v[172:175], v[124:127]
	v_mfma_f32_16x16x32_bf16 v[120:123], v[136:139], v[172:175], v[120:123]
	v_mfma_f32_16x16x32_bf16 v[108:111], v[128:131], v[180:183], v[108:111]
	v_mfma_f32_16x16x32_bf16 v[104:107], v[136:139], v[180:183], v[104:107]
	v_mfma_f32_16x16x32_bf16 v[96:99], v[128:131], v[188:191], v[96:99]
	v_mfma_f32_16x16x32_bf16 v[88:91], v[136:139], v[188:191], v[88:91]
	v_mfma_f32_16x16x32_bf16 v[80:83], v[128:131], v[202:205], v[80:83]
	v_mfma_f32_16x16x32_bf16 v[72:75], v[136:139], v[202:205], v[72:75]
	v_mfma_f32_16x16x32_bf16 v[124:127], v[132:135], v[176:179], v[124:127]
	v_mfma_f32_16x16x32_bf16 v[120:123], v[140:143], v[176:179], v[120:123]
	v_mfma_f32_16x16x32_bf16 v[108:111], v[132:135], v[184:187], v[108:111]
	v_mfma_f32_16x16x32_bf16 v[104:107], v[140:143], v[184:187], v[104:107]
	v_mfma_f32_16x16x32_bf16 v[96:99], v[132:135], v[198:201], v[96:99]
	v_mfma_f32_16x16x32_bf16 v[88:91], v[140:143], v[198:201], v[88:91]
	v_mfma_f32_16x16x32_bf16 v[80:83], v[132:135], v[206:209], v[80:83]
	v_mfma_f32_16x16x32_bf16 v[72:75], v[140:143], v[206:209], v[72:75]
	v_mfma_f32_16x16x32_bf16 v[116:119], v[156:159], v[172:175], v[116:119]
	v_mfma_f32_16x16x32_bf16 v[112:115], v[164:167], v[172:175], v[112:115]
	v_mfma_f32_16x16x32_bf16 v[100:103], v[156:159], v[180:183], v[100:103]
	v_mfma_f32_16x16x32_bf16 v[92:95], v[164:167], v[180:183], v[92:95]
	v_mfma_f32_16x16x32_bf16 v[84:87], v[156:159], v[188:191], v[84:87]
	v_mfma_f32_16x16x32_bf16 v[76:79], v[164:167], v[188:191], v[76:79]
	v_mfma_f32_16x16x32_bf16 v[68:71], v[156:159], v[202:205], v[68:71]
	v_mfma_f32_16x16x32_bf16 v[64:67], v[164:167], v[202:205], v[64:67]
	v_mfma_f32_16x16x32_bf16 v[116:119], v[160:163], v[176:179], v[116:119]
	v_mfma_f32_16x16x32_bf16 v[112:115], v[168:171], v[176:179], v[112:115]
	v_mfma_f32_16x16x32_bf16 v[100:103], v[160:163], v[184:187], v[100:103]
	v_mfma_f32_16x16x32_bf16 v[92:95], v[168:171], v[184:187], v[92:95]
	v_mfma_f32_16x16x32_bf16 v[84:87], v[160:163], v[198:201], v[84:87]
	v_mfma_f32_16x16x32_bf16 v[76:79], v[168:171], v[198:201], v[76:79]
	v_mfma_f32_16x16x32_bf16 v[68:71], v[160:163], v[206:209], v[68:71]
	v_mfma_f32_16x16x32_bf16 v[64:67], v[168:171], v[206:209], v[64:67]
	s_barrier
	s_add_i32 s73, s73, s38
	v_lshl_add_u64 v[194:195], s[24:25], 0, v[148:149]
	s_mov_b32 m0, s73
	ds_read_b128 v[172:175], v227 offset:16384
	ds_read_b128 v[176:179], v227 offset:17408
	ds_read_b128 v[180:183], v227 offset:18432
	ds_read_b128 v[184:187], v227 offset:19456
	ds_read_b128 v[188:191], v227 offset:20480
	ds_read_b128 v[198:201], v227 offset:21504
	ds_read_b128 v[202:205], v227 offset:22528
	ds_read_b128 v[206:209], v227 offset:23552
	global_load_lds_dwordx4 v[194:195], off
	s_add_i32 m0, s73, 0x2000
	s_add_u32 s74, s24, 0x40000
	v_lshl_add_u64 v[196:197], s[24:25], 0, v[144:145]
	s_addc_u32 s75, s25, 0
	s_add_i32 s73, s76, s38
	global_load_lds_dwordx4 v[196:197], off
	v_lshl_add_u64 v[234:235], s[74:75], 0, v[148:149]
	s_mov_b32 m0, s73
	v_lshl_add_u64 v[236:237], s[26:27], 0, v[146:147]
	global_load_lds_dwordx4 v[234:235], off
	v_lshl_add_u64 v[234:235], s[74:75], 0, v[144:145]
	s_add_i32 m0, s73, 0x2000
	s_nop 0
	global_load_lds_dwordx4 v[234:235], off
	v_lshl_add_u64 v[234:235], s[26:27], 0, v[150:151]
	s_mov_b32 m0, s39
	s_nop 0
	global_load_lds_dwordx4 v[234:235], off
	s_mov_b32 m0, s44
	s_nop 0
	global_load_lds_dwordx4 v[236:237], off
	s_waitcnt vmcnt(8)
	s_waitcnt lgkmcnt(0)
	s_barrier
	s_waitcnt lgkmcnt(0)
	v_mfma_f32_16x16x32_bf16 v[60:63], v[128:131], v[172:175], v[60:63]
	v_mfma_f32_16x16x32_bf16 v[56:59], v[136:139], v[172:175], v[56:59]
	v_mfma_f32_16x16x32_bf16 v[48:51], v[128:131], v[180:183], v[48:51]
	v_mfma_f32_16x16x32_bf16 v[40:43], v[136:139], v[180:183], v[40:43]
	v_mfma_f32_16x16x32_bf16 v[32:35], v[128:131], v[188:191], v[32:35]
	v_mfma_f32_16x16x32_bf16 v[24:27], v[136:139], v[188:191], v[24:27]
	v_mfma_f32_16x16x32_bf16 v[16:19], v[128:131], v[202:205], v[16:19]
	v_mfma_f32_16x16x32_bf16 v[8:11], v[136:139], v[202:205], v[8:11]
	v_mfma_f32_16x16x32_bf16 v[60:63], v[132:135], v[176:179], v[60:63]
	v_mfma_f32_16x16x32_bf16 v[56:59], v[140:143], v[176:179], v[56:59]
	v_mfma_f32_16x16x32_bf16 v[48:51], v[132:135], v[184:187], v[48:51]
	v_mfma_f32_16x16x32_bf16 v[40:43], v[140:143], v[184:187], v[40:43]
	v_mfma_f32_16x16x32_bf16 v[32:35], v[132:135], v[198:201], v[32:35]
	v_mfma_f32_16x16x32_bf16 v[24:27], v[140:143], v[198:201], v[24:27]
	v_mfma_f32_16x16x32_bf16 v[16:19], v[132:135], v[206:209], v[16:19]
	v_mfma_f32_16x16x32_bf16 v[8:11], v[140:143], v[206:209], v[8:11]
	v_mfma_f32_16x16x32_bf16 v[52:55], v[156:159], v[172:175], v[52:55]
	v_mfma_f32_16x16x32_bf16 v[44:47], v[164:167], v[172:175], v[44:47]
	v_mfma_f32_16x16x32_bf16 v[36:39], v[156:159], v[180:183], v[36:39]
	v_mfma_f32_16x16x32_bf16 v[28:31], v[164:167], v[180:183], v[28:31]
	v_mfma_f32_16x16x32_bf16 v[20:23], v[156:159], v[188:191], v[20:23]
	v_mfma_f32_16x16x32_bf16 v[12:15], v[164:167], v[188:191], v[12:15]
	v_mfma_f32_16x16x32_bf16 v[4:7], v[156:159], v[202:205], v[4:7]
	v_mfma_f32_16x16x32_bf16 v[0:3], v[164:167], v[202:205], v[0:3]
	v_mfma_f32_16x16x32_bf16 v[52:55], v[160:163], v[176:179], v[52:55]
	v_mfma_f32_16x16x32_bf16 v[44:47], v[168:171], v[176:179], v[44:47]
	v_mfma_f32_16x16x32_bf16 v[36:39], v[160:163], v[184:187], v[36:39]
	v_mfma_f32_16x16x32_bf16 v[28:31], v[168:171], v[184:187], v[28:31]
	v_mfma_f32_16x16x32_bf16 v[20:23], v[160:163], v[198:201], v[20:23]
	v_mfma_f32_16x16x32_bf16 v[12:15], v[168:171], v[198:201], v[12:15]
	v_mfma_f32_16x16x32_bf16 v[4:7], v[160:163], v[206:209], v[4:7]
	v_mfma_f32_16x16x32_bf16 v[0:3], v[168:171], v[206:209], v[0:3]
	s_barrier
; #define PG8_STAGE(bufoff, gbase, voff) do { _Pragma("unroll") for (int _i = 0; _i < 2; ++_i) \
;         __builtin_amdgcn_global_load_lds((const unsigned*)((const char*)(gbase) + (voff)[_i]), (PG8_LAS unsigned*)(lds + (bufoff) + ldsw + _i * 8192), 16, 0, 0); } while (0)
; #define PG8_LDA(dst, b, h) do { _Pragma("unroll") for (int m = 0; m < 4; ++m) _Pragma("unroll") for (int k = 0; k < 2; ++k) dst[m][k] = *(const PG8_LAS bf16x8*)(lds + PG8_SA(b, h) + aoff + m * 2048 + k * 1024); } while (0)
; #define PG8_LDB(dst, b, h) do { _Pragma("unroll") for (int n = 0; n < 2; ++n) _Pragma("unroll") for (int k = 0; k < 2; ++k) dst[n][k] = *(const PG8_LAS bf16x8*)(lds + PG8_SB(b, h) + boff + n * 2048 + k * 1024); } while (0)
; #define PG8_MMA(ai, bj, At, Bt) do { __builtin_amdgcn_s_setprio(1); _Pragma("unroll") for (int m = 0; m < 4; ++m) _Pragma("unroll") for (int n = 0; n < 2; ++n) _Pragma("unroll") for (int k = 0; k < 2; ++k) \
;         acc[ai][bj][m][n] = __builtin_amdgcn_mfma_f32_16x16x32_bf16(Bt[n][k], At[m][k], acc[ai][bj][m][n], 0, 0, 0); __builtin_amdgcn_s_setprio(0); } while (0)
; #define PG8_WAIT_V(n) asm volatile("s_waitcnt vmcnt(" #n ")" ::: "memory")
; #define PG8_WAIT_L(n) asm volatile("s_waitcnt lgkmcnt(" #n ")" ::: "memory")
; #define PG8_BAR __builtin_amdgcn_s_barrier()
; #define PG8_SCHED __builtin_amdgcn_sched_barrier(0)
; template <class Epi, class Sched, bool ALIGN_EPI = false, bool SP2 = false>
; __device__ __forceinline__ void gemm_phase(PG8_LAS unsigned char* lds, const Gemm g, const Sched& S, const Epi& E, int wave_in) {
;     ...
;             PG8_LDB(B0, 1, 0); PG8_LDB(B1, 1, 1); PG8_SCHED; PG8_LDA(At, 1, 0); PG8_STAGE(PG8_SA(0, 1), a2 + hstep, voffA);
;             PG8_WAIT_V(8); PG8_WAIT_L(0); PG8_BAR; PG8_MMA(0, 0, At, B0); PG8_MMA(0, 1, At, B1); PG8_BAR; PG8_SCHED;
;             PG8_LDA(At, 1, 1); PG8_STAGE(PG8_SB(1, 0), b3, voffB); PG8_STAGE(PG8_SB(1, 1), b3 + hstep, voffB); PG8_STAGE(PG8_SA(1, 0), a3, voffA);
;             PG8_WAIT_V(8); PG8_WAIT_L(0); PG8_BAR; PG8_MMA(1, 0, At, B0); PG8_MMA(1, 1, At, B1); PG8_BAR; PG8_SCHED;
	s_add_i32 s73, s65, 0x100
	s_add_i32 s74, s52, 0x100
	v_add_u32_e32 v140, s73, v212
	v_add_u32_e32 v168, s74, v212
	ds_read_b128 v[128:131], v140
	ds_read_b128 v[132:135], v140 offset:1024
	ds_read_b128 v[136:139], v140 offset:2048
	ds_read_b128 v[140:143], v140 offset:3072
	ds_read_b128 v[156:159], v168
	ds_read_b128 v[160:163], v168 offset:1024
	ds_read_b128 v[164:167], v168 offset:2048
	ds_read_b128 v[168:171], v168 offset:3072
	s_add_u32 s26, s26, 0x40000
	s_addc_u32 s27, s27, 0
	s_mov_b32 m0, s45
	v_lshl_add_u64 v[238:239], s[26:27], 0, v[150:151]
	ds_read_b128 v[172:175], v227 offset:32768
	ds_read_b128 v[176:179], v227 offset:33792
	ds_read_b128 v[180:183], v227 offset:34816
	ds_read_b128 v[184:187], v227 offset:35840
	ds_read_b128 v[188:191], v227 offset:36864
	ds_read_b128 v[198:201], v227 offset:37888
	ds_read_b128 v[202:205], v227 offset:38912
	ds_read_b128 v[206:209], v227 offset:39936
	global_load_lds_dwordx4 v[238:239], off
	v_lshl_add_u64 v[238:239], s[26:27], 0, v[146:147]
	s_mov_b32 m0, s46
	s_nop 0
	global_load_lds_dwordx4 v[238:239], off
	s_waitcnt vmcnt(8)
	s_waitcnt lgkmcnt(0)
	s_barrier
	s_waitcnt lgkmcnt(0)
	v_mfma_f32_16x16x32_bf16 v[124:127], v[128:131], v[172:175], v[124:127]
	v_mfma_f32_16x16x32_bf16 v[120:123], v[136:139], v[172:175], v[120:123]
	v_mfma_f32_16x16x32_bf16 v[108:111], v[128:131], v[180:183], v[108:111]
	v_mfma_f32_16x16x32_bf16 v[104:107], v[136:139], v[180:183], v[104:107]
	v_mfma_f32_16x16x32_bf16 v[96:99], v[128:131], v[188:191], v[96:99]
	v_mfma_f32_16x16x32_bf16 v[88:91], v[136:139], v[188:191], v[88:91]
	v_mfma_f32_16x16x32_bf16 v[80:83], v[128:131], v[202:205], v[80:83]
	v_mfma_f32_16x16x32_bf16 v[72:75], v[136:139], v[202:205], v[72:75]
	v_mfma_f32_16x16x32_bf16 v[124:127], v[132:135], v[176:179], v[124:127]
	v_mfma_f32_16x16x32_bf16 v[120:123], v[140:143], v[176:179], v[120:123]
	v_mfma_f32_16x16x32_bf16 v[108:111], v[132:135], v[184:187], v[108:111]
	v_mfma_f32_16x16x32_bf16 v[104:107], v[140:143], v[184:187], v[104:107]
	v_mfma_f32_16x16x32_bf16 v[96:99], v[132:135], v[198:201], v[96:99]
	v_mfma_f32_16x16x32_bf16 v[88:91], v[140:143], v[198:201], v[88:91]
	v_mfma_f32_16x16x32_bf16 v[80:83], v[132:135], v[206:209], v[80:83]
	v_mfma_f32_16x16x32_bf16 v[72:75], v[140:143], v[206:209], v[72:75]
	v_mfma_f32_16x16x32_bf16 v[116:119], v[156:159], v[172:175], v[116:119]
	v_mfma_f32_16x16x32_bf16 v[112:115], v[164:167], v[172:175], v[112:115]
	v_mfma_f32_16x16x32_bf16 v[100:103], v[156:159], v[180:183], v[100:103]
	v_mfma_f32_16x16x32_bf16 v[92:95], v[164:167], v[180:183], v[92:95]
	v_mfma_f32_16x16x32_bf16 v[84:87], v[156:159], v[188:191], v[84:87]
	v_mfma_f32_16x16x32_bf16 v[76:79], v[164:167], v[188:191], v[76:79]
	v_mfma_f32_16x16x32_bf16 v[68:71], v[156:159], v[202:205], v[68:71]
	v_mfma_f32_16x16x32_bf16 v[64:67], v[164:167], v[202:205], v[64:67]
	v_mfma_f32_16x16x32_bf16 v[116:119], v[160:163], v[176:179], v[116:119]
	v_mfma_f32_16x16x32_bf16 v[112:115], v[168:171], v[176:179], v[112:115]
	v_mfma_f32_16x16x32_bf16 v[100:103], v[160:163], v[184:187], v[100:103]
	v_mfma_f32_16x16x32_bf16 v[92:95], v[168:171], v[184:187], v[92:95]
	v_mfma_f32_16x16x32_bf16 v[84:87], v[160:163], v[198:201], v[84:87]
	v_mfma_f32_16x16x32_bf16 v[76:79], v[168:171], v[198:201], v[76:79]
	v_mfma_f32_16x16x32_bf16 v[68:71], v[160:163], v[206:209], v[68:71]
	v_mfma_f32_16x16x32_bf16 v[64:67], v[168:171], v[206:209], v[64:67]
	s_barrier
	s_add_i32 s26, s73, s38
	v_lshl_add_u64 v[194:195], v[194:195], 0, s[88:89]
	s_mov_b32 m0, s26
	ds_read_b128 v[172:175], v227 offset:49152
	ds_read_b128 v[176:179], v227 offset:50176
	ds_read_b128 v[180:183], v227 offset:51200
	ds_read_b128 v[184:187], v227 offset:52224
	ds_read_b128 v[188:191], v227 offset:53248
	ds_read_b128 v[198:201], v227 offset:54272
	ds_read_b128 v[202:205], v227 offset:55296
	ds_read_b128 v[206:209], v227 offset:56320
	global_load_lds_dwordx4 v[194:195], off
	s_add_i32 m0, s26, 0x2000
	s_add_u32 s24, s24, 0x40080
	v_lshl_add_u64 v[194:195], v[196:197], 0, s[88:89]
	s_addc_u32 s25, s25, 0
	s_add_i32 s26, s74, s38
	global_load_lds_dwordx4 v[194:195], off
	v_lshl_add_u64 v[194:195], s[24:25], 0, v[148:149]
	s_mov_b32 m0, s26
	s_nop 0
	global_load_lds_dwordx4 v[194:195], off
	v_lshl_add_u64 v[194:195], s[24:25], 0, v[144:145]
	s_add_i32 m0, s26, 0x2000
	s_nop 0
	global_load_lds_dwordx4 v[194:195], off
	v_lshl_add_u64 v[194:195], v[234:235], 0, s[88:89]
	s_mov_b32 m0, s61
	s_nop 0
	global_load_lds_dwordx4 v[194:195], off
	v_lshl_add_u64 v[194:195], v[236:237], 0, s[88:89]
	s_mov_b32 m0, s62
	s_nop 0
	global_load_lds_dwordx4 v[194:195], off
	s_waitcnt vmcnt(8)
	s_waitcnt lgkmcnt(0)
	s_barrier
	s_waitcnt lgkmcnt(0)
	v_mfma_f32_16x16x32_bf16 v[60:63], v[128:131], v[172:175], v[60:63]
	v_mfma_f32_16x16x32_bf16 v[56:59], v[136:139], v[172:175], v[56:59]
	v_mfma_f32_16x16x32_bf16 v[48:51], v[128:131], v[180:183], v[48:51]
	v_mfma_f32_16x16x32_bf16 v[40:43], v[136:139], v[180:183], v[40:43]
	v_mfma_f32_16x16x32_bf16 v[32:35], v[128:131], v[188:191], v[32:35]
	v_mfma_f32_16x16x32_bf16 v[24:27], v[136:139], v[188:191], v[24:27]
	v_mfma_f32_16x16x32_bf16 v[16:19], v[128:131], v[202:205], v[16:19]
	v_mfma_f32_16x16x32_bf16 v[8:11], v[136:139], v[202:205], v[8:11]
	v_mfma_f32_16x16x32_bf16 v[60:63], v[132:135], v[176:179], v[60:63]
	v_mfma_f32_16x16x32_bf16 v[56:59], v[140:143], v[176:179], v[56:59]
	v_mfma_f32_16x16x32_bf16 v[48:51], v[132:135], v[184:187], v[48:51]
	v_mfma_f32_16x16x32_bf16 v[40:43], v[140:143], v[184:187], v[40:43]
	v_mfma_f32_16x16x32_bf16 v[32:35], v[132:135], v[198:201], v[32:35]
	v_mfma_f32_16x16x32_bf16 v[24:27], v[140:143], v[198:201], v[24:27]
	v_mfma_f32_16x16x32_bf16 v[16:19], v[132:135], v[206:209], v[16:19]
	v_mfma_f32_16x16x32_bf16 v[8:11], v[140:143], v[206:209], v[8:11]
	v_mfma_f32_16x16x32_bf16 v[52:55], v[156:159], v[172:175], v[52:55]
	v_mfma_f32_16x16x32_bf16 v[44:47], v[164:167], v[172:175], v[44:47]
	v_mfma_f32_16x16x32_bf16 v[36:39], v[156:159], v[180:183], v[36:39]
	v_mfma_f32_16x16x32_bf16 v[28:31], v[164:167], v[180:183], v[28:31]
	v_mfma_f32_16x16x32_bf16 v[20:23], v[156:159], v[188:191], v[20:23]
	v_mfma_f32_16x16x32_bf16 v[12:15], v[164:167], v[188:191], v[12:15]
	v_mfma_f32_16x16x32_bf16 v[4:7], v[156:159], v[202:205], v[4:7]
	v_mfma_f32_16x16x32_bf16 v[0:3], v[164:167], v[202:205], v[0:3]
	v_mfma_f32_16x16x32_bf16 v[52:55], v[160:163], v[176:179], v[52:55]
	v_mfma_f32_16x16x32_bf16 v[44:47], v[168:171], v[176:179], v[44:47]
	v_mfma_f32_16x16x32_bf16 v[36:39], v[160:163], v[184:187], v[36:39]
	v_mfma_f32_16x16x32_bf16 v[28:31], v[168:171], v[184:187], v[28:31]
	v_mfma_f32_16x16x32_bf16 v[20:23], v[160:163], v[198:201], v[20:23]
	v_mfma_f32_16x16x32_bf16 v[12:15], v[168:171], v[198:201], v[12:15]
	v_mfma_f32_16x16x32_bf16 v[4:7], v[160:163], v[206:209], v[4:7]
	v_mfma_f32_16x16x32_bf16 v[0:3], v[168:171], v[206:209], v[0:3]
	s_barrier
	s_add_i32 s72, s72, 2
	s_add_u32 s53, s53, 0x100
	s_addc_u32 s71, s71, 0
	s_add_u32 s22, s22, 0x100
	s_addc_u32 s23, s23, 0
	s_cmp_gt_u32 s72, 13
	s_cbranch_scc0 .LBB0_687

; #define PG8_STAGE(bufoff, gbase, voff) do { _Pragma("unroll") for (int _i = 0; _i < 2; ++_i) \
;         __builtin_amdgcn_global_load_lds((const unsigned*)((const char*)(gbase) + (voff)[_i]), (PG8_LAS unsigned*)(lds + (bufoff) + ldsw + _i * 8192), 16, 0, 0); } while (0)
; #define PG8_LDA(dst, b, h) do { _Pragma("unroll") for (int m = 0; m < 4; ++m) _Pragma("unroll") for (int k = 0; k < 2; ++k) dst[m][k] = *(const PG8_LAS bf16x8*)(lds + PG8_SA(b, h) + aoff + m * 2048 + k * 1024); } while (0)
; #define PG8_LDB(dst, b, h) do { _Pragma("unroll") for (int n = 0; n < 2; ++n) _Pragma("unroll") for (int k = 0; k < 2; ++k) dst[n][k] = *(const PG8_LAS bf16x8*)(lds + PG8_SB(b, h) + boff + n * 2048 + k * 1024); } while (0)
; #define PG8_MMA(ai, bj, At, Bt) do { __builtin_amdgcn_s_setprio(1); _Pragma("unroll") for (int m = 0; m < 4; ++m) _Pragma("unroll") for (int n = 0; n < 2; ++n) _Pragma("unroll") for (int k = 0; k < 2; ++k) \
;         acc[ai][bj][m][n] = __builtin_amdgcn_mfma_f32_16x16x32_bf16(Bt[n][k], At[m][k], acc[ai][bj][m][n], 0, 0, 0); __builtin_amdgcn_s_setprio(0); } while (0)
; #define PG8_WAIT_V(n) asm volatile("s_waitcnt vmcnt(" #n ")" ::: "memory")
; #define PG8_BAR __builtin_amdgcn_s_barrier()
; template <class Epi, class Sched, bool ALIGN_EPI = false, bool SP2 = false>
; __device__ __forceinline__ void gemm_phase(PG8_LAS unsigned char* lds, const Gemm g, const Sched& S, const Epi& E, int wave_in) {
;     ...
;         for (int t = 0; t < nt; t += 2) {
;             const bool last = (t == nt - 2);
;             const char* a1 = cA + (size_t)(t + 1) * kstep;
;             const char* a2 = last ? nA : cA + (size_t)(t + 2) * kstep; const char* b2 = last ? nB : cB + (size_t)(t + 2) * kstep;
;             const char* a3 = a2 + kstep; const char* b3 = b2 + kstep;
;             if (last && has_next) S.a_ready(nxt);
;             if constexpr (SP2) {
;             PG8_LDB(B0, 0, 0); PG8_LDB(B1, 0, 1); PG8_SCHED; PG8_LDA(At, 0, 0); PG8_STAGE(PG8_SA(1, 1), a1 + hstep, voffA);
;             PG8_WAIT_V(8); PG8_WAIT_L(0); PG8_BAR; PG8_MMA(0, 0, At, B0); PG8_MMA(0, 1, At, B1); PG8_BAR; PG8_SCHED;
;             PG8_LDA(At, 0, 1); PG8_STAGE(PG8_SB(0, 0), b2, voffB); PG8_STAGE(PG8_SB(0, 1), b2 + hstep, voffB); PG8_STAGE(PG8_SA(0, 0), a2, voffA);
;             PG8_WAIT_V(8); PG8_WAIT_L(0); PG8_BAR; PG8_MMA(1, 0, At, B0); PG8_MMA(1, 1, At, B1); PG8_BAR; PG8_SCHED;
.LBB0_803:
	s_add_u32 s15, s22, 0x100
	s_addc_u32 s17, s23, 0
	s_add_u32 s22, s24, 0x40080
	s_addc_u32 s23, s25, 0
	s_mov_b32 s34, -2
	s_add_u32 s24, s22, 0xfffc0080
	s_addc_u32 s25, s23, -1
	s_add_i32 s44, s35, 0x100
	s_cmp_eq_u32 s34, 12
	s_cselect_b32 s27, s19, s25
	s_cselect_b32 s26, s18, s24
	s_cselect_b32 s25, s21, s17
	s_cselect_b32 s24, s20, s15
	s_add_i32 s53, s90, 0x100
	v_add_u32_e32 v128, s44, v249
	v_add_u32_e32 v156, s53, v249
	ds_read_b128 v[112:115], v128
	ds_read_b128 v[120:123], v128 offset:1024
	ds_read_b128 v[124:127], v128 offset:2048
	ds_read_b128 v[128:131], v128 offset:3072
	ds_read_b128 v[136:139], v156
	ds_read_b128 v[140:143], v156 offset:1024
	ds_read_b128 v[144:147], v156 offset:2048
	ds_read_b128 v[156:159], v156 offset:3072
	v_lshl_add_u64 v[194:195], s[22:23], 0, v[206:207]
	s_add_i32 m0, s39, 0xc000
	ds_read_b128 v[160:163], v251
	ds_read_b128 v[164:167], v251 offset:1024
	ds_read_b128 v[168:171], v251 offset:2048
	ds_read_b128 v[172:175], v251 offset:3072
	ds_read_b128 v[176:179], v251 offset:4096
	ds_read_b128 v[180:183], v251 offset:5120
	ds_read_b128 v[184:187], v251 offset:6144
	ds_read_b128 v[188:191], v251 offset:7168
	global_load_lds_dwordx4 v[194:195], off
	v_lshl_add_u64 v[194:195], s[22:23], 0, v[204:205]
	s_add_i32 m0, s39, 0xe000
	s_nop 0
	global_load_lds_dwordx4 v[194:195], off
	s_waitcnt vmcnt(8)
	s_waitcnt lgkmcnt(0)
	s_barrier
	s_waitcnt lgkmcnt(0)
	v_mfma_f32_16x16x32_bf16 v[152:155], v[112:115], v[160:163], 0
	v_mfma_f32_16x16x32_bf16 v[148:151], v[124:127], v[160:163], 0
	v_mfma_f32_16x16x32_bf16 v[108:111], v[112:115], v[168:171], 0
	v_mfma_f32_16x16x32_bf16 v[104:107], v[124:127], v[168:171], 0
	v_mfma_f32_16x16x32_bf16 v[92:95], v[112:115], v[176:179], 0
	v_mfma_f32_16x16x32_bf16 v[88:91], v[124:127], v[176:179], 0
	v_mfma_f32_16x16x32_bf16 v[76:79], v[112:115], v[184:187], 0
	v_mfma_f32_16x16x32_bf16 v[72:75], v[124:127], v[184:187], 0
	v_mfma_f32_16x16x32_bf16 v[152:155], v[120:123], v[164:167], v[152:155]
	v_mfma_f32_16x16x32_bf16 v[148:151], v[128:131], v[164:167], v[148:151]
	v_mfma_f32_16x16x32_bf16 v[108:111], v[120:123], v[172:175], v[108:111]
	v_mfma_f32_16x16x32_bf16 v[104:107], v[128:131], v[172:175], v[104:107]
	v_mfma_f32_16x16x32_bf16 v[92:95], v[120:123], v[180:183], v[92:95]
	v_mfma_f32_16x16x32_bf16 v[88:91], v[128:131], v[180:183], v[88:91]
	v_mfma_f32_16x16x32_bf16 v[76:79], v[120:123], v[188:191], v[76:79]
	v_mfma_f32_16x16x32_bf16 v[72:75], v[128:131], v[188:191], v[72:75]
	v_mfma_f32_16x16x32_bf16 v[132:135], v[136:139], v[160:163], 0
	v_mfma_f32_16x16x32_bf16 v[116:119], v[144:147], v[160:163], 0
	v_mfma_f32_16x16x32_bf16 v[100:103], v[136:139], v[168:171], 0
	v_mfma_f32_16x16x32_bf16 v[96:99], v[144:147], v[168:171], 0
	v_mfma_f32_16x16x32_bf16 v[84:87], v[136:139], v[176:179], 0
	v_mfma_f32_16x16x32_bf16 v[80:83], v[144:147], v[176:179], 0
	v_mfma_f32_16x16x32_bf16 v[68:71], v[136:139], v[184:187], 0
	v_mfma_f32_16x16x32_bf16 v[64:67], v[144:147], v[184:187], 0
	v_mfma_f32_16x16x32_bf16 v[132:135], v[140:143], v[164:167], v[132:135]
	v_mfma_f32_16x16x32_bf16 v[116:119], v[156:159], v[164:167], v[116:119]
	v_mfma_f32_16x16x32_bf16 v[100:103], v[140:143], v[172:175], v[100:103]
	v_mfma_f32_16x16x32_bf16 v[96:99], v[156:159], v[172:175], v[96:99]
	v_mfma_f32_16x16x32_bf16 v[84:87], v[140:143], v[180:183], v[84:87]
	v_mfma_f32_16x16x32_bf16 v[80:83], v[156:159], v[180:183], v[80:83]
	v_mfma_f32_16x16x32_bf16 v[68:71], v[140:143], v[188:191], v[68:71]
	v_mfma_f32_16x16x32_bf16 v[64:67], v[156:159], v[188:191], v[64:67]
	s_barrier
	s_add_i32 s44, s44, s38
	v_lshl_add_u64 v[194:195], s[24:25], 0, v[192:193]
	s_mov_b32 m0, s44
	ds_read_b128 v[160:163], v251 offset:16384
	ds_read_b128 v[164:167], v251 offset:17408
	ds_read_b128 v[168:171], v251 offset:18432
	ds_read_b128 v[172:175], v251 offset:19456
	ds_read_b128 v[176:179], v251 offset:20480
	ds_read_b128 v[180:183], v251 offset:21504
	ds_read_b128 v[184:187], v251 offset:22528
	ds_read_b128 v[188:191], v251 offset:23552
	global_load_lds_dwordx4 v[194:195], off
	s_add_i32 m0, s44, 0x2000
	s_add_u32 s44, s24, 0x40000
	v_lshl_add_u64 v[196:197], s[24:25], 0, v[198:199]
	s_addc_u32 s45, s25, 0
	s_add_i32 s53, s53, s38
	global_load_lds_dwordx4 v[196:197], off
	v_lshl_add_u64 v[208:209], s[44:45], 0, v[192:193]
	s_mov_b32 m0, s53
	v_lshl_add_u64 v[210:211], s[26:27], 0, v[200:201]
	global_load_lds_dwordx4 v[208:209], off
	v_lshl_add_u64 v[208:209], s[44:45], 0, v[198:199]
	s_add_i32 m0, s53, 0x2000
	s_nop 0
	global_load_lds_dwordx4 v[208:209], off
	v_lshl_add_u64 v[208:209], s[26:27], 0, v[202:203]
	s_mov_b32 m0, s39
	s_nop 0
	global_load_lds_dwordx4 v[208:209], off
	s_mov_b32 m0, s46
	s_nop 0
	global_load_lds_dwordx4 v[210:211], off
	s_waitcnt vmcnt(8)
	s_waitcnt lgkmcnt(0)
	s_barrier
; #define PG8_STAGE(bufoff, gbase, voff) do { _Pragma("unroll") for (int _i = 0; _i < 2; ++_i) \
;         __builtin_amdgcn_global_load_lds((const unsigned*)((const char*)(gbase) + (voff)[_i]), (PG8_LAS unsigned*)(lds + (bufoff) + ldsw + _i * 8192), 16, 0, 0); } while (0)
; #define PG8_LDA(dst, b, h) do { _Pragma("unroll") for (int m = 0; m < 4; ++m) _Pragma("unroll") for (int k = 0; k < 2; ++k) dst[m][k] = *(const PG8_LAS bf16x8*)(lds + PG8_SA(b, h) + aoff + m * 2048 + k * 1024); } while (0)
; #define PG8_LDB(dst, b, h) do { _Pragma("unroll") for (int n = 0; n < 2; ++n) _Pragma("unroll") for (int k = 0; k < 2; ++k) dst[n][k] = *(const PG8_LAS bf16x8*)(lds + PG8_SB(b, h) + boff + n * 2048 + k * 1024); } while (0)
; #define PG8_MMA(ai, bj, At, Bt) do { __builtin_amdgcn_s_setprio(1); _Pragma("unroll") for (int m = 0; m < 4; ++m) _Pragma("unroll") for (int n = 0; n < 2; ++n) _Pragma("unroll") for (int k = 0; k < 2; ++k) \
;         acc[ai][bj][m][n] = __builtin_amdgcn_mfma_f32_16x16x32_bf16(Bt[n][k], At[m][k], acc[ai][bj][m][n], 0, 0, 0); __builtin_amdgcn_s_setprio(0); } while (0)
; #define PG8_WAIT_V(n) asm volatile("s_waitcnt vmcnt(" #n ")" ::: "memory")
; #define PG8_WAIT_L(n) asm volatile("s_waitcnt lgkmcnt(" #n ")" ::: "memory")
; #define PG8_BAR __builtin_amdgcn_s_barrier()
; #define PG8_SCHED __builtin_amdgcn_sched_barrier(0)
; template <class Epi, class Sched, bool ALIGN_EPI = false, bool SP2 = false>
; __device__ __forceinline__ void gemm_phase(PG8_LAS unsigned char* lds, const Gemm g, const Sched& S, const Epi& E, int wave_in) {
;     ...
;             PG8_WAIT_V(8); PG8_WAIT_L(0); PG8_BAR; PG8_MMA(1, 0, At, B0); PG8_MMA(1, 1, At, B1); PG8_BAR; PG8_SCHED;
;             PG8_LDB(B0, 1, 0); PG8_LDB(B1, 1, 1); PG8_SCHED; PG8_LDA(At, 1, 0); PG8_STAGE(PG8_SA(0, 1), a2 + hstep, voffA);
;             PG8_WAIT_V(8); PG8_WAIT_L(0); PG8_BAR; PG8_MMA(0, 0, At, B0); PG8_MMA(0, 1, At, B1); PG8_BAR; PG8_SCHED;
	s_waitcnt lgkmcnt(0)
	v_mfma_f32_16x16x32_bf16 v[60:63], v[112:115], v[160:163], 0
	v_mfma_f32_16x16x32_bf16 v[56:59], v[124:127], v[160:163], 0
	v_mfma_f32_16x16x32_bf16 v[44:47], v[112:115], v[168:171], 0
	v_mfma_f32_16x16x32_bf16 v[40:43], v[124:127], v[168:171], 0
	v_mfma_f32_16x16x32_bf16 v[28:31], v[112:115], v[176:179], 0
	v_mfma_f32_16x16x32_bf16 v[24:27], v[124:127], v[176:179], 0
	v_mfma_f32_16x16x32_bf16 v[12:15], v[112:115], v[184:187], 0
	v_mfma_f32_16x16x32_bf16 v[8:11], v[124:127], v[184:187], 0
	v_mfma_f32_16x16x32_bf16 v[60:63], v[120:123], v[164:167], v[60:63]
	v_mfma_f32_16x16x32_bf16 v[56:59], v[128:131], v[164:167], v[56:59]
	v_mfma_f32_16x16x32_bf16 v[44:47], v[120:123], v[172:175], v[44:47]
	v_mfma_f32_16x16x32_bf16 v[40:43], v[128:131], v[172:175], v[40:43]
	v_mfma_f32_16x16x32_bf16 v[28:31], v[120:123], v[180:183], v[28:31]
	v_mfma_f32_16x16x32_bf16 v[24:27], v[128:131], v[180:183], v[24:27]
	v_mfma_f32_16x16x32_bf16 v[12:15], v[120:123], v[188:191], v[12:15]
	v_mfma_f32_16x16x32_bf16 v[8:11], v[128:131], v[188:191], v[8:11]
	v_mfma_f32_16x16x32_bf16 v[52:55], v[136:139], v[160:163], 0
	v_mfma_f32_16x16x32_bf16 v[48:51], v[144:147], v[160:163], 0
	v_mfma_f32_16x16x32_bf16 v[36:39], v[136:139], v[168:171], 0
	v_mfma_f32_16x16x32_bf16 v[32:35], v[144:147], v[168:171], 0
	v_mfma_f32_16x16x32_bf16 v[20:23], v[136:139], v[176:179], 0
	v_mfma_f32_16x16x32_bf16 v[16:19], v[144:147], v[176:179], 0
	v_mfma_f32_16x16x32_bf16 v[4:7], v[136:139], v[184:187], 0
	v_mfma_f32_16x16x32_bf16 v[0:3], v[144:147], v[184:187], 0
	v_mfma_f32_16x16x32_bf16 v[52:55], v[140:143], v[164:167], v[52:55]
	v_mfma_f32_16x16x32_bf16 v[48:51], v[156:159], v[164:167], v[48:51]
	v_mfma_f32_16x16x32_bf16 v[36:39], v[140:143], v[172:175], v[36:39]
	v_mfma_f32_16x16x32_bf16 v[32:35], v[156:159], v[172:175], v[32:35]
	v_mfma_f32_16x16x32_bf16 v[20:23], v[140:143], v[180:183], v[20:23]
	v_mfma_f32_16x16x32_bf16 v[16:19], v[156:159], v[180:183], v[16:19]
	v_mfma_f32_16x16x32_bf16 v[4:7], v[140:143], v[188:191], v[4:7]
	v_mfma_f32_16x16x32_bf16 v[0:3], v[156:159], v[188:191], v[0:3]
	s_barrier
	s_add_i32 s44, s65, 0x100
	s_add_i32 s45, s52, 0x100
	v_add_u32_e32 v128, s44, v249
	v_add_u32_e32 v156, s45, v249
	ds_read_b128 v[112:115], v128
	ds_read_b128 v[120:123], v128 offset:1024
	ds_read_b128 v[124:127], v128 offset:2048
	ds_read_b128 v[128:131], v128 offset:3072
	ds_read_b128 v[136:139], v156
	ds_read_b128 v[140:143], v156 offset:1024
	ds_read_b128 v[144:147], v156 offset:2048
	ds_read_b128 v[156:159], v156 offset:3072
	s_add_u32 s26, s26, 0x40000
	s_addc_u32 s27, s27, 0
	s_mov_b32 m0, s47
	v_lshl_add_u64 v[212:213], s[26:27], 0, v[202:203]
	ds_read_b128 v[160:163], v251 offset:32768
	ds_read_b128 v[164:167], v251 offset:33792
	ds_read_b128 v[168:171], v251 offset:34816
	ds_read_b128 v[172:175], v251 offset:35840
	ds_read_b128 v[176:179], v251 offset:36864
	ds_read_b128 v[180:183], v251 offset:37888
	ds_read_b128 v[184:187], v251 offset:38912
	ds_read_b128 v[188:191], v251 offset:39936
	global_load_lds_dwordx4 v[212:213], off
	v_lshl_add_u64 v[212:213], s[26:27], 0, v[200:201]
	s_mov_b32 m0, s60
	s_nop 0
	global_load_lds_dwordx4 v[212:213], off
	s_waitcnt vmcnt(8)
	s_waitcnt lgkmcnt(0)
	s_barrier
	s_waitcnt lgkmcnt(0)
	v_mfma_f32_16x16x32_bf16 v[152:155], v[112:115], v[160:163], v[152:155]
	v_mfma_f32_16x16x32_bf16 v[148:151], v[124:127], v[160:163], v[148:151]
	v_mfma_f32_16x16x32_bf16 v[108:111], v[112:115], v[168:171], v[108:111]
	v_mfma_f32_16x16x32_bf16 v[104:107], v[124:127], v[168:171], v[104:107]
	v_mfma_f32_16x16x32_bf16 v[92:95], v[112:115], v[176:179], v[92:95]
	v_mfma_f32_16x16x32_bf16 v[88:91], v[124:127], v[176:179], v[88:91]
	v_mfma_f32_16x16x32_bf16 v[76:79], v[112:115], v[184:187], v[76:79]
	v_mfma_f32_16x16x32_bf16 v[72:75], v[124:127], v[184:187], v[72:75]
	v_mfma_f32_16x16x32_bf16 v[152:155], v[120:123], v[164:167], v[152:155]
	v_mfma_f32_16x16x32_bf16 v[148:151], v[128:131], v[164:167], v[148:151]
	v_mfma_f32_16x16x32_bf16 v[108:111], v[120:123], v[172:175], v[108:111]
	v_mfma_f32_16x16x32_bf16 v[104:107], v[128:131], v[172:175], v[104:107]
	v_mfma_f32_16x16x32_bf16 v[92:95], v[120:123], v[180:183], v[92:95]
	v_mfma_f32_16x16x32_bf16 v[88:91], v[128:131], v[180:183], v[88:91]
	v_mfma_f32_16x16x32_bf16 v[76:79], v[120:123], v[188:191], v[76:79]
	v_mfma_f32_16x16x32_bf16 v[72:75], v[128:131], v[188:191], v[72:75]
	v_mfma_f32_16x16x32_bf16 v[132:135], v[136:139], v[160:163], v[132:135]
	v_mfma_f32_16x16x32_bf16 v[116:119], v[144:147], v[160:163], v[116:119]
	v_mfma_f32_16x16x32_bf16 v[100:103], v[136:139], v[168:171], v[100:103]
	v_mfma_f32_16x16x32_bf16 v[96:99], v[144:147], v[168:171], v[96:99]
	v_mfma_f32_16x16x32_bf16 v[84:87], v[136:139], v[176:179], v[84:87]
	v_mfma_f32_16x16x32_bf16 v[80:83], v[144:147], v[176:179], v[80:83]
	v_mfma_f32_16x16x32_bf16 v[68:71], v[136:139], v[184:187], v[68:71]
	v_mfma_f32_16x16x32_bf16 v[64:67], v[144:147], v[184:187], v[64:67]
	v_mfma_f32_16x16x32_bf16 v[132:135], v[140:143], v[164:167], v[132:135]
	v_mfma_f32_16x16x32_bf16 v[116:119], v[156:159], v[164:167], v[116:119]
	v_mfma_f32_16x16x32_bf16 v[100:103], v[140:143], v[172:175], v[100:103]
	v_mfma_f32_16x16x32_bf16 v[96:99], v[156:159], v[172:175], v[96:99]
	v_mfma_f32_16x16x32_bf16 v[84:87], v[140:143], v[180:183], v[84:87]
	v_mfma_f32_16x16x32_bf16 v[80:83], v[156:159], v[180:183], v[80:83]
	v_mfma_f32_16x16x32_bf16 v[68:71], v[140:143], v[188:191], v[68:71]
	v_mfma_f32_16x16x32_bf16 v[64:67], v[156:159], v[188:191], v[64:67]
	s_barrier
; #define PG8_STAGE(bufoff, gbase, voff) do { _Pragma("unroll") for (int _i = 0; _i < 2; ++_i) \
;         __builtin_amdgcn_global_load_lds((const unsigned*)((const char*)(gbase) + (voff)[_i]), (PG8_LAS unsigned*)(lds + (bufoff) + ldsw + _i * 8192), 16, 0, 0); } while (0)
; #define PG8_LDA(dst, b, h) do { _Pragma("unroll") for (int m = 0; m < 4; ++m) _Pragma("unroll") for (int k = 0; k < 2; ++k) dst[m][k] = *(const PG8_LAS bf16x8*)(lds + PG8_SA(b, h) + aoff + m * 2048 + k * 1024); } while (0)
; #define PG8_LDB(dst, b, h) do { _Pragma("unroll") for (int n = 0; n < 2; ++n) _Pragma("unroll") for (int k = 0; k < 2; ++k) dst[n][k] = *(const PG8_LAS bf16x8*)(lds + PG8_SB(b, h) + boff + n * 2048 + k * 1024); } while (0)
; #define PG8_MMA(ai, bj, At, Bt) do { __builtin_amdgcn_s_setprio(1); _Pragma("unroll") for (int m = 0; m < 4; ++m) _Pragma("unroll") for (int n = 0; n < 2; ++n) _Pragma("unroll") for (int k = 0; k < 2; ++k) \
;         acc[ai][bj][m][n] = __builtin_amdgcn_mfma_f32_16x16x32_bf16(Bt[n][k], At[m][k], acc[ai][bj][m][n], 0, 0, 0); __builtin_amdgcn_s_setprio(0); } while (0)
; template <class Epi, class Sched, bool ALIGN_EPI = false, bool SP2 = false>
; __device__ __forceinline__ void gemm_phase(PG8_LAS unsigned char* lds, const Gemm g, const Sched& S, const Epi& E, int wave_in) {
;     ...
;         for (int t = 0; t < nt; t += 2) {
;             const bool last = (t == nt - 2);
;             const char* a1 = cA + (size_t)(t + 1) * kstep;
;             const char* a2 = last ? nA : cA + (size_t)(t + 2) * kstep; const char* b2 = last ? nB : cB + (size_t)(t + 2) * kstep;
;             const char* a3 = a2 + kstep; const char* b3 = b2 + kstep;
;             if (last && has_next) S.a_ready(nxt);
;             if constexpr (SP2) {
;             PG8_LDB(B0, 0, 0); PG8_LDB(B1, 0, 1); PG8_SCHED; PG8_LDA(At, 0, 0); PG8_STAGE(PG8_SA(1, 1), a1 + hstep, voffA);
;             PG8_WAIT_V(8); PG8_WAIT_L(0); PG8_BAR; PG8_MMA(0, 0, At, B0); PG8_MMA(0, 1, At, B1); PG8_BAR; PG8_SCHED;
;     ...
;             PG8_WAIT_V(8); PG8_WAIT_L(0); PG8_BAR; PG8_MMA(0, 0, At, B0); PG8_MMA(0, 1, At, B1); PG8_BAR; PG8_SCHED;
;             PG8_LDA(At, 1, 1); PG8_STAGE(PG8_SB(1, 0), b3, voffB); PG8_STAGE(PG8_SB(1, 1), b3 + hstep, voffB); PG8_STAGE(PG8_SA(1, 0), a3, voffA);
;             PG8_WAIT_V(8); PG8_WAIT_L(0); PG8_BAR; PG8_MMA(1, 0, At, B0); PG8_MMA(1, 1, At, B1); PG8_BAR; PG8_SCHED;
	s_add_i32 s26, s44, s38
	v_lshl_add_u64 v[194:195], v[194:195], 0, s[88:89]
	s_mov_b32 m0, s26
	ds_read_b128 v[160:163], v251 offset:49152
	ds_read_b128 v[164:167], v251 offset:50176
	ds_read_b128 v[168:171], v251 offset:51200
	ds_read_b128 v[172:175], v251 offset:52224
	ds_read_b128 v[176:179], v251 offset:53248
	ds_read_b128 v[180:183], v251 offset:54272
	ds_read_b128 v[184:187], v251 offset:55296
	ds_read_b128 v[188:191], v251 offset:56320
	global_load_lds_dwordx4 v[194:195], off
	s_add_i32 m0, s26, 0x2000
	s_add_u32 s24, s24, 0x40080
	v_lshl_add_u64 v[194:195], v[196:197], 0, s[88:89]
	s_addc_u32 s25, s25, 0
	s_add_i32 s26, s45, s38
	global_load_lds_dwordx4 v[194:195], off
	v_lshl_add_u64 v[194:195], s[24:25], 0, v[192:193]
	s_mov_b32 m0, s26
	s_nop 0
	global_load_lds_dwordx4 v[194:195], off
	v_lshl_add_u64 v[194:195], s[24:25], 0, v[198:199]
	s_add_i32 m0, s26, 0x2000
	s_nop 0
	global_load_lds_dwordx4 v[194:195], off
	v_lshl_add_u64 v[194:195], v[208:209], 0, s[88:89]
	s_mov_b32 m0, s62
	s_nop 0
	global_load_lds_dwordx4 v[194:195], off
	v_lshl_add_u64 v[194:195], v[210:211], 0, s[88:89]
	s_mov_b32 m0, s63
	s_nop 0
	global_load_lds_dwordx4 v[194:195], off
	s_waitcnt vmcnt(8)
	s_waitcnt lgkmcnt(0)
	s_barrier
	s_waitcnt lgkmcnt(0)
	v_mfma_f32_16x16x32_bf16 v[60:63], v[112:115], v[160:163], v[60:63]
	v_mfma_f32_16x16x32_bf16 v[56:59], v[124:127], v[160:163], v[56:59]
	v_mfma_f32_16x16x32_bf16 v[44:47], v[112:115], v[168:171], v[44:47]
	v_mfma_f32_16x16x32_bf16 v[40:43], v[124:127], v[168:171], v[40:43]
	v_mfma_f32_16x16x32_bf16 v[28:31], v[112:115], v[176:179], v[28:31]
	v_mfma_f32_16x16x32_bf16 v[24:27], v[124:127], v[176:179], v[24:27]
	v_mfma_f32_16x16x32_bf16 v[12:15], v[112:115], v[184:187], v[12:15]
	v_mfma_f32_16x16x32_bf16 v[8:11], v[124:127], v[184:187], v[8:11]
	v_mfma_f32_16x16x32_bf16 v[60:63], v[120:123], v[164:167], v[60:63]
	v_mfma_f32_16x16x32_bf16 v[56:59], v[128:131], v[164:167], v[56:59]
	v_mfma_f32_16x16x32_bf16 v[44:47], v[120:123], v[172:175], v[44:47]
	v_mfma_f32_16x16x32_bf16 v[40:43], v[128:131], v[172:175], v[40:43]
	v_mfma_f32_16x16x32_bf16 v[28:31], v[120:123], v[180:183], v[28:31]
	v_mfma_f32_16x16x32_bf16 v[24:27], v[128:131], v[180:183], v[24:27]
	v_mfma_f32_16x16x32_bf16 v[12:15], v[120:123], v[188:191], v[12:15]
	v_mfma_f32_16x16x32_bf16 v[8:11], v[128:131], v[188:191], v[8:11]
	v_mfma_f32_16x16x32_bf16 v[52:55], v[136:139], v[160:163], v[52:55]
	v_mfma_f32_16x16x32_bf16 v[48:51], v[144:147], v[160:163], v[48:51]
	v_mfma_f32_16x16x32_bf16 v[36:39], v[136:139], v[168:171], v[36:39]
	v_mfma_f32_16x16x32_bf16 v[32:35], v[144:147], v[168:171], v[32:35]
	v_mfma_f32_16x16x32_bf16 v[20:23], v[136:139], v[176:179], v[20:23]
	v_mfma_f32_16x16x32_bf16 v[16:19], v[144:147], v[176:179], v[16:19]
	v_mfma_f32_16x16x32_bf16 v[4:7], v[136:139], v[184:187], v[4:7]
	v_mfma_f32_16x16x32_bf16 v[0:3], v[144:147], v[184:187], v[0:3]
	v_mfma_f32_16x16x32_bf16 v[52:55], v[140:143], v[164:167], v[52:55]
	v_mfma_f32_16x16x32_bf16 v[48:51], v[156:159], v[164:167], v[48:51]
	v_mfma_f32_16x16x32_bf16 v[36:39], v[140:143], v[172:175], v[36:39]
	v_mfma_f32_16x16x32_bf16 v[32:35], v[156:159], v[172:175], v[32:35]
	v_mfma_f32_16x16x32_bf16 v[20:23], v[140:143], v[180:183], v[20:23]
	v_mfma_f32_16x16x32_bf16 v[16:19], v[156:159], v[180:183], v[16:19]
	v_mfma_f32_16x16x32_bf16 v[4:7], v[140:143], v[188:191], v[4:7]
	v_mfma_f32_16x16x32_bf16 v[0:3], v[156:159], v[188:191], v[0:3]
	s_barrier
	s_add_i32 s34, s34, 2
	s_add_u32 s15, s15, 0x100
	s_addc_u32 s17, s17, 0
	s_add_u32 s22, s22, 0x100
	s_addc_u32 s23, s23, 0
	s_cmp_gt_u32 s34, 13
	s_cbranch_scc1 .Lkexit_5
.LBB0_804:
	s_add_u32 s24, s22, 0xfffc0080
	s_addc_u32 s25, s23, -1
	s_add_i32 s44, s35, 0x100
	s_cmp_eq_u32 s34, 12
	s_cselect_b32 s27, s19, s25
	s_cselect_b32 s26, s18, s24
	s_cselect_b32 s25, s21, s17
	s_cselect_b32 s24, s20, s15
	s_add_i32 s53, s90, 0x100
	v_add_u32_e32 v128, s44, v249
	v_add_u32_e32 v156, s53, v249
	ds_read_b128 v[112:115], v128
	ds_read_b128 v[120:123], v128 offset:1024
	ds_read_b128 v[124:127], v128 offset:2048
	ds_read_b128 v[128:131], v128 offset:3072
	ds_read_b128 v[136:139], v156
	ds_read_b128 v[140:143], v156 offset:1024
	ds_read_b128 v[144:147], v156 offset:2048
	ds_read_b128 v[156:159], v156 offset:3072
	v_lshl_add_u64 v[194:195], s[22:23], 0, v[206:207]
	s_add_i32 m0, s39, 0xc000
	ds_read_b128 v[160:163], v251
	ds_read_b128 v[164:167], v251 offset:1024
	ds_read_b128 v[168:171], v251 offset:2048
	ds_read_b128 v[172:175], v251 offset:3072
	ds_read_b128 v[176:179], v251 offset:4096
	ds_read_b128 v[180:183], v251 offset:5120
	ds_read_b128 v[184:187], v251 offset:6144
	ds_read_b128 v[188:191], v251 offset:7168
	global_load_lds_dwordx4 v[194:195], off
	v_lshl_add_u64 v[194:195], s[22:23], 0, v[204:205]
	s_add_i32 m0, s39, 0xe000
	s_nop 0
	global_load_lds_dwordx4 v[194:195], off
	s_waitcnt vmcnt(8)
	s_waitcnt lgkmcnt(0)
	s_barrier
; #define PG8_STAGE(bufoff, gbase, voff) do { _Pragma("unroll") for (int _i = 0; _i < 2; ++_i) \
;         __builtin_amdgcn_global_load_lds((const unsigned*)((const char*)(gbase) + (voff)[_i]), (PG8_LAS unsigned*)(lds + (bufoff) + ldsw + _i * 8192), 16, 0, 0); } while (0)
; #define PG8_LDA(dst, b, h) do { _Pragma("unroll") for (int m = 0; m < 4; ++m) _Pragma("unroll") for (int k = 0; k < 2; ++k) dst[m][k] = *(const PG8_LAS bf16x8*)(lds + PG8_SA(b, h) + aoff + m * 2048 + k * 1024); } while (0)
; #define PG8_LDB(dst, b, h) do { _Pragma("unroll") for (int n = 0; n < 2; ++n) _Pragma("unroll") for (int k = 0; k < 2; ++k) dst[n][k] = *(const PG8_LAS bf16x8*)(lds + PG8_SB(b, h) + boff + n * 2048 + k * 1024); } while (0)
; #define PG8_MMA(ai, bj, At, Bt) do { __builtin_amdgcn_s_setprio(1); _Pragma("unroll") for (int m = 0; m < 4; ++m) _Pragma("unroll") for (int n = 0; n < 2; ++n) _Pragma("unroll") for (int k = 0; k < 2; ++k) \
;         acc[ai][bj][m][n] = __builtin_amdgcn_mfma_f32_16x16x32_bf16(Bt[n][k], At[m][k], acc[ai][bj][m][n], 0, 0, 0); __builtin_amdgcn_s_setprio(0); } while (0)
; #define PG8_WAIT_V(n) asm volatile("s_waitcnt vmcnt(" #n ")" ::: "memory")
; #define PG8_WAIT_L(n) asm volatile("s_waitcnt lgkmcnt(" #n ")" ::: "memory")
; #define PG8_BAR __builtin_amdgcn_s_barrier()
; #define PG8_SCHED __builtin_amdgcn_sched_barrier(0)
; template <class Epi, class Sched, bool ALIGN_EPI = false, bool SP2 = false>
; __device__ __forceinline__ void gemm_phase(PG8_LAS unsigned char* lds, const Gemm g, const Sched& S, const Epi& E, int wave_in) {
;     ...
;             PG8_LDB(B0, 0, 0); PG8_LDB(B1, 0, 1); PG8_SCHED; PG8_LDA(At, 0, 0); PG8_STAGE(PG8_SA(1, 1), a1 + hstep, voffA);
;             PG8_WAIT_V(8); PG8_WAIT_L(0); PG8_BAR; PG8_MMA(0, 0, At, B0); PG8_MMA(0, 1, At, B1); PG8_BAR; PG8_SCHED;
;             PG8_LDA(At, 0, 1); PG8_STAGE(PG8_SB(0, 0), b2, voffB); PG8_STAGE(PG8_SB(0, 1), b2 + hstep, voffB); PG8_STAGE(PG8_SA(0, 0), a2, voffA);
;             PG8_WAIT_V(8); PG8_WAIT_L(0); PG8_BAR; PG8_MMA(1, 0, At, B0); PG8_MMA(1, 1, At, B1); PG8_BAR; PG8_SCHED;
	s_waitcnt lgkmcnt(0)
	v_mfma_f32_16x16x32_bf16 v[152:155], v[112:115], v[160:163], v[152:155]
	v_mfma_f32_16x16x32_bf16 v[148:151], v[124:127], v[160:163], v[148:151]
	v_mfma_f32_16x16x32_bf16 v[108:111], v[112:115], v[168:171], v[108:111]
	v_mfma_f32_16x16x32_bf16 v[104:107], v[124:127], v[168:171], v[104:107]
	v_mfma_f32_16x16x32_bf16 v[92:95], v[112:115], v[176:179], v[92:95]
	v_mfma_f32_16x16x32_bf16 v[88:91], v[124:127], v[176:179], v[88:91]
	v_mfma_f32_16x16x32_bf16 v[76:79], v[112:115], v[184:187], v[76:79]
	v_mfma_f32_16x16x32_bf16 v[72:75], v[124:127], v[184:187], v[72:75]
	v_mfma_f32_16x16x32_bf16 v[152:155], v[120:123], v[164:167], v[152:155]
	v_mfma_f32_16x16x32_bf16 v[148:151], v[128:131], v[164:167], v[148:151]
	v_mfma_f32_16x16x32_bf16 v[108:111], v[120:123], v[172:175], v[108:111]
	v_mfma_f32_16x16x32_bf16 v[104:107], v[128:131], v[172:175], v[104:107]
	v_mfma_f32_16x16x32_bf16 v[92:95], v[120:123], v[180:183], v[92:95]
	v_mfma_f32_16x16x32_bf16 v[88:91], v[128:131], v[180:183], v[88:91]
	v_mfma_f32_16x16x32_bf16 v[76:79], v[120:123], v[188:191], v[76:79]
	v_mfma_f32_16x16x32_bf16 v[72:75], v[128:131], v[188:191], v[72:75]
	v_mfma_f32_16x16x32_bf16 v[132:135], v[136:139], v[160:163], v[132:135]
	v_mfma_f32_16x16x32_bf16 v[116:119], v[144:147], v[160:163], v[116:119]
	v_mfma_f32_16x16x32_bf16 v[100:103], v[136:139], v[168:171], v[100:103]
	v_mfma_f32_16x16x32_bf16 v[96:99], v[144:147], v[168:171], v[96:99]
	v_mfma_f32_16x16x32_bf16 v[84:87], v[136:139], v[176:179], v[84:87]
	v_mfma_f32_16x16x32_bf16 v[80:83], v[144:147], v[176:179], v[80:83]
	v_mfma_f32_16x16x32_bf16 v[68:71], v[136:139], v[184:187], v[68:71]
	v_mfma_f32_16x16x32_bf16 v[64:67], v[144:147], v[184:187], v[64:67]
	v_mfma_f32_16x16x32_bf16 v[132:135], v[140:143], v[164:167], v[132:135]
	v_mfma_f32_16x16x32_bf16 v[116:119], v[156:159], v[164:167], v[116:119]
	v_mfma_f32_16x16x32_bf16 v[100:103], v[140:143], v[172:175], v[100:103]
	v_mfma_f32_16x16x32_bf16 v[96:99], v[156:159], v[172:175], v[96:99]
	v_mfma_f32_16x16x32_bf16 v[84:87], v[140:143], v[180:183], v[84:87]
	v_mfma_f32_16x16x32_bf16 v[80:83], v[156:159], v[180:183], v[80:83]
	v_mfma_f32_16x16x32_bf16 v[68:71], v[140:143], v[188:191], v[68:71]
	v_mfma_f32_16x16x32_bf16 v[64:67], v[156:159], v[188:191], v[64:67]
	s_barrier
	s_add_i32 s44, s44, s38
	v_lshl_add_u64 v[194:195], s[24:25], 0, v[192:193]
	s_mov_b32 m0, s44
	ds_read_b128 v[160:163], v251 offset:16384
	ds_read_b128 v[164:167], v251 offset:17408
	ds_read_b128 v[168:171], v251 offset:18432
	ds_read_b128 v[172:175], v251 offset:19456
	ds_read_b128 v[176:179], v251 offset:20480
	ds_read_b128 v[180:183], v251 offset:21504
	ds_read_b128 v[184:187], v251 offset:22528
	ds_read_b128 v[188:191], v251 offset:23552
	global_load_lds_dwordx4 v[194:195], off
	s_add_i32 m0, s44, 0x2000
	s_add_u32 s44, s24, 0x40000
	v_lshl_add_u64 v[196:197], s[24:25], 0, v[198:199]
	s_addc_u32 s45, s25, 0
	s_add_i32 s53, s53, s38
	global_load_lds_dwordx4 v[196:197], off
	v_lshl_add_u64 v[208:209], s[44:45], 0, v[192:193]
	s_mov_b32 m0, s53
	v_lshl_add_u64 v[210:211], s[26:27], 0, v[200:201]
	global_load_lds_dwordx4 v[208:209], off
	v_lshl_add_u64 v[208:209], s[44:45], 0, v[198:199]
	s_add_i32 m0, s53, 0x2000
	s_nop 0
	global_load_lds_dwordx4 v[208:209], off
	v_lshl_add_u64 v[208:209], s[26:27], 0, v[202:203]
	s_mov_b32 m0, s39
	s_nop 0
	global_load_lds_dwordx4 v[208:209], off
	s_mov_b32 m0, s46
	s_nop 0
	global_load_lds_dwordx4 v[210:211], off
	s_waitcnt vmcnt(8)
	s_waitcnt lgkmcnt(0)
	s_barrier
	s_waitcnt lgkmcnt(0)
	v_mfma_f32_16x16x32_bf16 v[60:63], v[112:115], v[160:163], v[60:63]
	v_mfma_f32_16x16x32_bf16 v[56:59], v[124:127], v[160:163], v[56:59]
	v_mfma_f32_16x16x32_bf16 v[44:47], v[112:115], v[168:171], v[44:47]
	v_mfma_f32_16x16x32_bf16 v[40:43], v[124:127], v[168:171], v[40:43]
	v_mfma_f32_16x16x32_bf16 v[28:31], v[112:115], v[176:179], v[28:31]
	v_mfma_f32_16x16x32_bf16 v[24:27], v[124:127], v[176:179], v[24:27]
	v_mfma_f32_16x16x32_bf16 v[12:15], v[112:115], v[184:187], v[12:15]
	v_mfma_f32_16x16x32_bf16 v[8:11], v[124:127], v[184:187], v[8:11]
	v_mfma_f32_16x16x32_bf16 v[60:63], v[120:123], v[164:167], v[60:63]
	v_mfma_f32_16x16x32_bf16 v[56:59], v[128:131], v[164:167], v[56:59]
	v_mfma_f32_16x16x32_bf16 v[44:47], v[120:123], v[172:175], v[44:47]
	v_mfma_f32_16x16x32_bf16 v[40:43], v[128:131], v[172:175], v[40:43]
	v_mfma_f32_16x16x32_bf16 v[28:31], v[120:123], v[180:183], v[28:31]
	v_mfma_f32_16x16x32_bf16 v[24:27], v[128:131], v[180:183], v[24:27]
	v_mfma_f32_16x16x32_bf16 v[12:15], v[120:123], v[188:191], v[12:15]
	v_mfma_f32_16x16x32_bf16 v[8:11], v[128:131], v[188:191], v[8:11]
	v_mfma_f32_16x16x32_bf16 v[52:55], v[136:139], v[160:163], v[52:55]
	v_mfma_f32_16x16x32_bf16 v[48:51], v[144:147], v[160:163], v[48:51]
	v_mfma_f32_16x16x32_bf16 v[36:39], v[136:139], v[168:171], v[36:39]
	v_mfma_f32_16x16x32_bf16 v[32:35], v[144:147], v[168:171], v[32:35]
	v_mfma_f32_16x16x32_bf16 v[20:23], v[136:139], v[176:179], v[20:23]
	v_mfma_f32_16x16x32_bf16 v[16:19], v[144:147], v[176:179], v[16:19]
	v_mfma_f32_16x16x32_bf16 v[4:7], v[136:139], v[184:187], v[4:7]
	v_mfma_f32_16x16x32_bf16 v[0:3], v[144:147], v[184:187], v[0:3]
	v_mfma_f32_16x16x32_bf16 v[52:55], v[140:143], v[164:167], v[52:55]
	v_mfma_f32_16x16x32_bf16 v[48:51], v[156:159], v[164:167], v[48:51]
	v_mfma_f32_16x16x32_bf16 v[36:39], v[140:143], v[172:175], v[36:39]
	v_mfma_f32_16x16x32_bf16 v[32:35], v[156:159], v[172:175], v[32:35]
	v_mfma_f32_16x16x32_bf16 v[20:23], v[140:143], v[180:183], v[20:23]
	v_mfma_f32_16x16x32_bf16 v[16:19], v[156:159], v[180:183], v[16:19]
	v_mfma_f32_16x16x32_bf16 v[4:7], v[140:143], v[188:191], v[4:7]
	v_mfma_f32_16x16x32_bf16 v[0:3], v[156:159], v[188:191], v[0:3]
	s_barrier
; #define PG8_STAGE(bufoff, gbase, voff) do { _Pragma("unroll") for (int _i = 0; _i < 2; ++_i) \
;         __builtin_amdgcn_global_load_lds((const unsigned*)((const char*)(gbase) + (voff)[_i]), (PG8_LAS unsigned*)(lds + (bufoff) + ldsw + _i * 8192), 16, 0, 0); } while (0)
; #define PG8_LDA(dst, b, h) do { _Pragma("unroll") for (int m = 0; m < 4; ++m) _Pragma("unroll") for (int k = 0; k < 2; ++k) dst[m][k] = *(const PG8_LAS bf16x8*)(lds + PG8_SA(b, h) + aoff + m * 2048 + k * 1024); } while (0)
; #define PG8_LDB(dst, b, h) do { _Pragma("unroll") for (int n = 0; n < 2; ++n) _Pragma("unroll") for (int k = 0; k < 2; ++k) dst[n][k] = *(const PG8_LAS bf16x8*)(lds + PG8_SB(b, h) + boff + n * 2048 + k * 1024); } while (0)
; #define PG8_MMA(ai, bj, At, Bt) do { __builtin_amdgcn_s_setprio(1); _Pragma("unroll") for (int m = 0; m < 4; ++m) _Pragma("unroll") for (int n = 0; n < 2; ++n) _Pragma("unroll") for (int k = 0; k < 2; ++k) \
;         acc[ai][bj][m][n] = __builtin_amdgcn_mfma_f32_16x16x32_bf16(Bt[n][k], At[m][k], acc[ai][bj][m][n], 0, 0, 0); __builtin_amdgcn_s_setprio(0); } while (0)
; #define PG8_WAIT_V(n) asm volatile("s_waitcnt vmcnt(" #n ")" ::: "memory")
; #define PG8_WAIT_L(n) asm volatile("s_waitcnt lgkmcnt(" #n ")" ::: "memory")
; #define PG8_BAR __builtin_amdgcn_s_barrier()
; #define PG8_SCHED __builtin_amdgcn_sched_barrier(0)
; template <class Epi, class Sched, bool ALIGN_EPI = false, bool SP2 = false>
; __device__ __forceinline__ void gemm_phase(PG8_LAS unsigned char* lds, const Gemm g, const Sched& S, const Epi& E, int wave_in) {
;     ...
;             PG8_LDB(B0, 1, 0); PG8_LDB(B1, 1, 1); PG8_SCHED; PG8_LDA(At, 1, 0); PG8_STAGE(PG8_SA(0, 1), a2 + hstep, voffA);
;             PG8_WAIT_V(8); PG8_WAIT_L(0); PG8_BAR; PG8_MMA(0, 0, At, B0); PG8_MMA(0, 1, At, B1); PG8_BAR; PG8_SCHED;
;             PG8_LDA(At, 1, 1); PG8_STAGE(PG8_SB(1, 0), b3, voffB); PG8_STAGE(PG8_SB(1, 1), b3 + hstep, voffB); PG8_STAGE(PG8_SA(1, 0), a3, voffA);
;             PG8_WAIT_V(8); PG8_WAIT_L(0); PG8_BAR; PG8_MMA(1, 0, At, B0); PG8_MMA(1, 1, At, B1); PG8_BAR; PG8_SCHED;
	s_add_i32 s44, s65, 0x100
	s_add_i32 s45, s52, 0x100
	v_add_u32_e32 v128, s44, v249
	v_add_u32_e32 v156, s45, v249
	ds_read_b128 v[112:115], v128
	ds_read_b128 v[120:123], v128 offset:1024
	ds_read_b128 v[124:127], v128 offset:2048
	ds_read_b128 v[128:131], v128 offset:3072
	ds_read_b128 v[136:139], v156
	ds_read_b128 v[140:143], v156 offset:1024
	ds_read_b128 v[144:147], v156 offset:2048
	ds_read_b128 v[156:159], v156 offset:3072
	s_add_u32 s26, s26, 0x40000
	s_addc_u32 s27, s27, 0
	s_mov_b32 m0, s47
	v_lshl_add_u64 v[212:213], s[26:27], 0, v[202:203]
	ds_read_b128 v[160:163], v251 offset:32768
	ds_read_b128 v[164:167], v251 offset:33792
	ds_read_b128 v[168:171], v251 offset:34816
	ds_read_b128 v[172:175], v251 offset:35840
	ds_read_b128 v[176:179], v251 offset:36864
	ds_read_b128 v[180:183], v251 offset:37888
	ds_read_b128 v[184:187], v251 offset:38912
	ds_read_b128 v[188:191], v251 offset:39936
	global_load_lds_dwordx4 v[212:213], off
	v_lshl_add_u64 v[212:213], s[26:27], 0, v[200:201]
	s_mov_b32 m0, s60
	s_nop 0
	global_load_lds_dwordx4 v[212:213], off
	s_waitcnt vmcnt(8)
	s_waitcnt lgkmcnt(0)
	s_barrier
	s_waitcnt lgkmcnt(0)
	v_mfma_f32_16x16x32_bf16 v[152:155], v[112:115], v[160:163], v[152:155]
	v_mfma_f32_16x16x32_bf16 v[148:151], v[124:127], v[160:163], v[148:151]
	v_mfma_f32_16x16x32_bf16 v[108:111], v[112:115], v[168:171], v[108:111]
	v_mfma_f32_16x16x32_bf16 v[104:107], v[124:127], v[168:171], v[104:107]
	v_mfma_f32_16x16x32_bf16 v[92:95], v[112:115], v[176:179], v[92:95]
	v_mfma_f32_16x16x32_bf16 v[88:91], v[124:127], v[176:179], v[88:91]
	v_mfma_f32_16x16x32_bf16 v[76:79], v[112:115], v[184:187], v[76:79]
	v_mfma_f32_16x16x32_bf16 v[72:75], v[124:127], v[184:187], v[72:75]
	v_mfma_f32_16x16x32_bf16 v[152:155], v[120:123], v[164:167], v[152:155]
	v_mfma_f32_16x16x32_bf16 v[148:151], v[128:131], v[164:167], v[148:151]
	v_mfma_f32_16x16x32_bf16 v[108:111], v[120:123], v[172:175], v[108:111]
	v_mfma_f32_16x16x32_bf16 v[104:107], v[128:131], v[172:175], v[104:107]
	v_mfma_f32_16x16x32_bf16 v[92:95], v[120:123], v[180:183], v[92:95]
	v_mfma_f32_16x16x32_bf16 v[88:91], v[128:131], v[180:183], v[88:91]
	v_mfma_f32_16x16x32_bf16 v[76:79], v[120:123], v[188:191], v[76:79]
	v_mfma_f32_16x16x32_bf16 v[72:75], v[128:131], v[188:191], v[72:75]
	v_mfma_f32_16x16x32_bf16 v[132:135], v[136:139], v[160:163], v[132:135]
	v_mfma_f32_16x16x32_bf16 v[116:119], v[144:147], v[160:163], v[116:119]
	v_mfma_f32_16x16x32_bf16 v[100:103], v[136:139], v[168:171], v[100:103]
	v_mfma_f32_16x16x32_bf16 v[96:99], v[144:147], v[168:171], v[96:99]
	v_mfma_f32_16x16x32_bf16 v[84:87], v[136:139], v[176:179], v[84:87]
	v_mfma_f32_16x16x32_bf16 v[80:83], v[144:147], v[176:179], v[80:83]
	v_mfma_f32_16x16x32_bf16 v[68:71], v[136:139], v[184:187], v[68:71]
	v_mfma_f32_16x16x32_bf16 v[64:67], v[144:147], v[184:187], v[64:67]
	v_mfma_f32_16x16x32_bf16 v[132:135], v[140:143], v[164:167], v[132:135]
	v_mfma_f32_16x16x32_bf16 v[116:119], v[156:159], v[164:167], v[116:119]
	v_mfma_f32_16x16x32_bf16 v[100:103], v[140:143], v[172:175], v[100:103]
	v_mfma_f32_16x16x32_bf16 v[96:99], v[156:159], v[172:175], v[96:99]
	v_mfma_f32_16x16x32_bf16 v[84:87], v[140:143], v[180:183], v[84:87]
	v_mfma_f32_16x16x32_bf16 v[80:83], v[156:159], v[180:183], v[80:83]
	v_mfma_f32_16x16x32_bf16 v[68:71], v[140:143], v[188:191], v[68:71]
	v_mfma_f32_16x16x32_bf16 v[64:67], v[156:159], v[188:191], v[64:67]
	s_barrier
	s_add_i32 s26, s44, s38
	v_lshl_add_u64 v[194:195], v[194:195], 0, s[88:89]
	s_mov_b32 m0, s26
	ds_read_b128 v[160:163], v251 offset:49152
	ds_read_b128 v[164:167], v251 offset:50176
	ds_read_b128 v[168:171], v251 offset:51200
	ds_read_b128 v[172:175], v251 offset:52224
	ds_read_b128 v[176:179], v251 offset:53248
	ds_read_b128 v[180:183], v251 offset:54272
	ds_read_b128 v[184:187], v251 offset:55296
	ds_read_b128 v[188:191], v251 offset:56320
	global_load_lds_dwordx4 v[194:195], off
	s_add_i32 m0, s26, 0x2000
	s_add_u32 s24, s24, 0x40080
	v_lshl_add_u64 v[194:195], v[196:197], 0, s[88:89]
	s_addc_u32 s25, s25, 0
	s_add_i32 s26, s45, s38
	global_load_lds_dwordx4 v[194:195], off
	v_lshl_add_u64 v[194:195], s[24:25], 0, v[192:193]
	s_mov_b32 m0, s26
	s_nop 0
	global_load_lds_dwordx4 v[194:195], off
	v_lshl_add_u64 v[194:195], s[24:25], 0, v[198:199]
	s_add_i32 m0, s26, 0x2000
	s_nop 0
	global_load_lds_dwordx4 v[194:195], off
	v_lshl_add_u64 v[194:195], v[208:209], 0, s[88:89]
	s_mov_b32 m0, s62
	s_nop 0
	global_load_lds_dwordx4 v[194:195], off
	v_lshl_add_u64 v[194:195], v[210:211], 0, s[88:89]
	s_mov_b32 m0, s63
	s_nop 0
	global_load_lds_dwordx4 v[194:195], off
	s_waitcnt vmcnt(8)
	s_waitcnt lgkmcnt(0)
	s_barrier
	s_waitcnt lgkmcnt(0)
	v_mfma_f32_16x16x32_bf16 v[60:63], v[112:115], v[160:163], v[60:63]
	v_mfma_f32_16x16x32_bf16 v[56:59], v[124:127], v[160:163], v[56:59]
	v_mfma_f32_16x16x32_bf16 v[44:47], v[112:115], v[168:171], v[44:47]
	v_mfma_f32_16x16x32_bf16 v[40:43], v[124:127], v[168:171], v[40:43]
	v_mfma_f32_16x16x32_bf16 v[28:31], v[112:115], v[176:179], v[28:31]
	v_mfma_f32_16x16x32_bf16 v[24:27], v[124:127], v[176:179], v[24:27]
	v_mfma_f32_16x16x32_bf16 v[12:15], v[112:115], v[184:187], v[12:15]
	v_mfma_f32_16x16x32_bf16 v[8:11], v[124:127], v[184:187], v[8:11]
	v_mfma_f32_16x16x32_bf16 v[60:63], v[120:123], v[164:167], v[60:63]
	v_mfma_f32_16x16x32_bf16 v[56:59], v[128:131], v[164:167], v[56:59]
	v_mfma_f32_16x16x32_bf16 v[44:47], v[120:123], v[172:175], v[44:47]
	v_mfma_f32_16x16x32_bf16 v[40:43], v[128:131], v[172:175], v[40:43]
	v_mfma_f32_16x16x32_bf16 v[28:31], v[120:123], v[180:183], v[28:31]
	v_mfma_f32_16x16x32_bf16 v[24:27], v[128:131], v[180:183], v[24:27]
	v_mfma_f32_16x16x32_bf16 v[12:15], v[120:123], v[188:191], v[12:15]
	v_mfma_f32_16x16x32_bf16 v[8:11], v[128:131], v[188:191], v[8:11]
	v_mfma_f32_16x16x32_bf16 v[52:55], v[136:139], v[160:163], v[52:55]
	v_mfma_f32_16x16x32_bf16 v[48:51], v[144:147], v[160:163], v[48:51]
	v_mfma_f32_16x16x32_bf16 v[36:39], v[136:139], v[168:171], v[36:39]
	v_mfma_f32_16x16x32_bf16 v[32:35], v[144:147], v[168:171], v[32:35]
	v_mfma_f32_16x16x32_bf16 v[20:23], v[136:139], v[176:179], v[20:23]
	v_mfma_f32_16x16x32_bf16 v[16:19], v[144:147], v[176:179], v[16:19]
	v_mfma_f32_16x16x32_bf16 v[4:7], v[136:139], v[184:187], v[4:7]
	v_mfma_f32_16x16x32_bf16 v[0:3], v[144:147], v[184:187], v[0:3]
	v_mfma_f32_16x16x32_bf16 v[52:55], v[140:143], v[164:167], v[52:55]
	v_mfma_f32_16x16x32_bf16 v[48:51], v[156:159], v[164:167], v[48:51]
	v_mfma_f32_16x16x32_bf16 v[36:39], v[140:143], v[172:175], v[36:39]
	v_mfma_f32_16x16x32_bf16 v[32:35], v[156:159], v[172:175], v[32:35]
	v_mfma_f32_16x16x32_bf16 v[20:23], v[140:143], v[180:183], v[20:23]
	v_mfma_f32_16x16x32_bf16 v[16:19], v[156:159], v[180:183], v[16:19]
	v_mfma_f32_16x16x32_bf16 v[4:7], v[140:143], v[188:191], v[4:7]
	v_mfma_f32_16x16x32_bf16 v[0:3], v[156:159], v[188:191], v[0:3]
	s_barrier
	s_add_i32 s34, s34, 2
	s_add_u32 s15, s15, 0x100
	s_addc_u32 s17, s17, 0
	s_add_u32 s22, s22, 0x100
	s_addc_u32 s23, s23, 0
	s_cmp_gt_u32 s34, 13
	s_cbranch_scc0 .LBB0_804

; #define PG8_STAGE(bufoff, gbase, voff) do { _Pragma("unroll") for (int _i = 0; _i < 2; ++_i) \
;         __builtin_amdgcn_global_load_lds((const unsigned*)((const char*)(gbase) + (voff)[_i]), (PG8_LAS unsigned*)(lds + (bufoff) + ldsw + _i * 8192), 16, 0, 0); } while (0)
; #define PG8_LDA(dst, b, h) do { _Pragma("unroll") for (int m = 0; m < 4; ++m) _Pragma("unroll") for (int k = 0; k < 2; ++k) dst[m][k] = *(const PG8_LAS bf16x8*)(lds + PG8_SA(b, h) + aoff + m * 2048 + k * 1024); } while (0)
; #define PG8_LDB(dst, b, h) do { _Pragma("unroll") for (int n = 0; n < 2; ++n) _Pragma("unroll") for (int k = 0; k < 2; ++k) dst[n][k] = *(const PG8_LAS bf16x8*)(lds + PG8_SB(b, h) + boff + n * 2048 + k * 1024); } while (0)
; #define PG8_WAIT_V(n) asm volatile("s_waitcnt vmcnt(" #n ")" ::: "memory")
; #define PG8_WAIT_L(n) asm volatile("s_waitcnt lgkmcnt(" #n ")" ::: "memory")
; #define PG8_BAR __builtin_amdgcn_s_barrier()
; template <class Epi, class Sched, bool ALIGN_EPI = false, bool SP2 = false>
; __device__ __forceinline__ void gemm_phase(PG8_LAS unsigned char* lds, const Gemm g, const Sched& S, const Epi& E, int wave_in) {
;     ...
;         const bool has_next = S.next(ui + 1, nxt);
;         const char* nA = has_next ? (const char*)g.A + (size_t)(nxt.pm >> g.ash) * g.astride + (size_t)nxt.pm * tstep : cA; const char* nB = has_next ? (const char*)g.Bt + (size_t)(nxt.pm >> g.bsh) * g.bstride + (size_t)nxt.pn * tstep : cB;
;         for (int t = 0; t < nt; t += 2) {
;             const bool last = (t == nt - 2);
;             const char* a1 = cA + (size_t)(t + 1) * kstep;
;             const char* a2 = last ? nA : cA + (size_t)(t + 2) * kstep; const char* b2 = last ? nB : cB + (size_t)(t + 2) * kstep;
;             const char* a3 = a2 + kstep; const char* b3 = b2 + kstep;
;             if (last && has_next) S.a_ready(nxt);
;             if constexpr (SP2) {
;             PG8_LDB(B0, 0, 0); PG8_LDB(B1, 0, 1); PG8_SCHED; PG8_LDA(At, 0, 0); PG8_STAGE(PG8_SA(1, 1), a1 + hstep, voffA);
;             PG8_WAIT_V(8); PG8_WAIT_L(0); PG8_BAR; PG8_MMA(0, 0, At, B0); PG8_MMA(0, 1, At, B1); PG8_BAR; PG8_SCHED;
;             PG8_LDA(At, 0, 1); PG8_STAGE(PG8_SB(0, 0), b2, voffB); PG8_STAGE(PG8_SB(0, 1), b2 + hstep, voffB); PG8_STAGE(PG8_SA(0, 0), a2, voffA);
;             PG8_WAIT_V(8); PG8_WAIT_L(0); PG8_BAR; PG8_MMA(1, 0, At, B0); PG8_MMA(1, 1, At, B1); PG8_BAR; PG8_SCHED;
.LBB0_896:
	s_ashr_i32 s11, s10, 31
	s_lshl_b64 s[18:19], s[10:11], 19
	s_add_u32 s66, s6, s18
	s_addc_u32 s67, s72, s19
	s_and_b64 s[18:19], s[46:47], exec
	s_cselect_b32 s11, s67, s1
	s_cselect_b32 s34, s66, s0
	s_ashr_i32 s5, s4, 31
	s_lshl_b64 s[18:19], s[4:5], 19
	s_add_u32 s38, s73, s18
	s_addc_u32 s39, s74, s19
	s_and_b64 s[18:19], s[46:47], exec
	s_cselect_b32 s5, s39, s79
	s_cselect_b32 s53, s38, s78
	s_add_u32 s81, s78, 0x100
	s_addc_u32 s18, s79, 0
	s_add_u32 vcc_lo, s0, 0x40080
	s_addc_u32 vcc_hi, s1, 0
	s_mov_b32 s19, -2
	s_add_u32 s0, vcc_lo, 0xfffc0080
	s_addc_u32 s1, vcc_hi, -1
	s_add_i32 s76, s35, 0x100
	s_cmp_eq_u32 s19, 12
	s_cselect_b32 s79, s11, s1
	s_cselect_b32 s78, s34, s0
	s_cselect_b32 s1, s5, s18
	s_cselect_b32 s0, s53, s81
	s_add_i32 s29, s90, 0x100
	v_add_u32_e32 v140, s76, v207
	v_add_u32_e32 v156, s29, v207
	ds_read_b128 v[128:131], v140
	ds_read_b128 v[132:135], v140 offset:1024
	ds_read_b128 v[136:139], v140 offset:2048
	ds_read_b128 v[140:143], v140 offset:3072
	ds_read_b128 v[144:147], v156
	ds_read_b128 v[148:151], v156 offset:1024
	ds_read_b128 v[152:155], v156 offset:2048
	ds_read_b128 v[156:159], v156 offset:3072
	v_lshl_add_u64 v[190:191], vcc, 0, v[176:177]
	s_add_i32 m0, s33, 0xc000
	ds_read_b128 v[160:163], v219
	ds_read_b128 v[164:167], v219 offset:1024
	ds_read_b128 v[178:181], v219 offset:2048
	ds_read_b128 v[182:185], v219 offset:3072
	ds_read_b128 v[186:189], v219 offset:4096
	ds_read_b128 v[198:201], v219 offset:5120
	ds_read_b128 v[202:205], v219 offset:6144
	ds_read_b128 v[220:223], v219 offset:7168
	global_load_lds_dwordx4 v[190:191], off
	v_lshl_add_u64 v[190:191], vcc, 0, v[174:175]
	s_add_i32 m0, s33, 0xe000
	s_nop 0
	global_load_lds_dwordx4 v[190:191], off
	s_waitcnt vmcnt(8)
	s_waitcnt lgkmcnt(0)
	s_barrier
	s_waitcnt lgkmcnt(0)
	v_mfma_f32_16x16x32_bf16 v[124:127], v[128:131], v[160:163], 0
	v_mfma_f32_16x16x32_bf16 v[60:63], v[136:139], v[160:163], 0
	v_mfma_f32_16x16x32_bf16 v[116:119], v[128:131], v[178:181], 0
	v_mfma_f32_16x16x32_bf16 v[52:55], v[136:139], v[178:181], 0
	v_mfma_f32_16x16x32_bf16 v[108:111], v[128:131], v[186:189], 0
	v_mfma_f32_16x16x32_bf16 v[44:47], v[136:139], v[186:189], 0
	v_mfma_f32_16x16x32_bf16 v[100:103], v[128:131], v[202:205], 0
	v_mfma_f32_16x16x32_bf16 v[36:39], v[136:139], v[202:205], 0
	v_mfma_f32_16x16x32_bf16 v[124:127], v[132:135], v[164:167], v[124:127]
	v_mfma_f32_16x16x32_bf16 v[60:63], v[140:143], v[164:167], v[60:63]
	v_mfma_f32_16x16x32_bf16 v[116:119], v[132:135], v[182:185], v[116:119]
	v_mfma_f32_16x16x32_bf16 v[52:55], v[140:143], v[182:185], v[52:55]
	v_mfma_f32_16x16x32_bf16 v[108:111], v[132:135], v[198:201], v[108:111]
	v_mfma_f32_16x16x32_bf16 v[44:47], v[140:143], v[198:201], v[44:47]
	v_mfma_f32_16x16x32_bf16 v[100:103], v[132:135], v[220:223], v[100:103]
	v_mfma_f32_16x16x32_bf16 v[36:39], v[140:143], v[220:223], v[36:39]
	v_mfma_f32_16x16x32_bf16 v[120:123], v[144:147], v[160:163], 0
	v_mfma_f32_16x16x32_bf16 v[56:59], v[152:155], v[160:163], 0
	v_mfma_f32_16x16x32_bf16 v[112:115], v[144:147], v[178:181], 0
	v_mfma_f32_16x16x32_bf16 v[48:51], v[152:155], v[178:181], 0
	v_mfma_f32_16x16x32_bf16 v[104:107], v[144:147], v[186:189], 0
	v_mfma_f32_16x16x32_bf16 v[40:43], v[152:155], v[186:189], 0
	v_mfma_f32_16x16x32_bf16 v[96:99], v[144:147], v[202:205], 0
	v_mfma_f32_16x16x32_bf16 v[32:35], v[152:155], v[202:205], 0
	v_mfma_f32_16x16x32_bf16 v[120:123], v[148:151], v[164:167], v[120:123]
	v_mfma_f32_16x16x32_bf16 v[56:59], v[156:159], v[164:167], v[56:59]
	v_mfma_f32_16x16x32_bf16 v[112:115], v[148:151], v[182:185], v[112:115]
	v_mfma_f32_16x16x32_bf16 v[48:51], v[156:159], v[182:185], v[48:51]
	v_mfma_f32_16x16x32_bf16 v[104:107], v[148:151], v[198:201], v[104:107]
	v_mfma_f32_16x16x32_bf16 v[40:43], v[156:159], v[198:201], v[40:43]
	v_mfma_f32_16x16x32_bf16 v[96:99], v[148:151], v[220:223], v[96:99]
	v_mfma_f32_16x16x32_bf16 v[32:35], v[156:159], v[220:223], v[32:35]
	s_barrier
	s_add_i32 s76, s76, s75
	v_lshl_add_u64 v[190:191], s[0:1], 0, v[192:193]
	s_mov_b32 m0, s76
	ds_read_b128 v[160:163], v219 offset:16384
	ds_read_b128 v[164:167], v219 offset:17408
	ds_read_b128 v[178:181], v219 offset:18432
	ds_read_b128 v[182:185], v219 offset:19456
	ds_read_b128 v[186:189], v219 offset:20480
	ds_read_b128 v[198:201], v219 offset:21504
	ds_read_b128 v[202:205], v219 offset:22528
	ds_read_b128 v[220:223], v219 offset:23552
	global_load_lds_dwordx4 v[190:191], off
	s_add_i32 m0, s76, 0x2000
	s_add_u32 s76, s0, 0x40000
	v_lshl_add_u64 v[194:195], s[0:1], 0, v[168:169]
	s_addc_u32 s77, s1, 0
	s_add_i32 s29, s29, s75
	global_load_lds_dwordx4 v[194:195], off
	v_lshl_add_u64 v[196:197], s[76:77], 0, v[192:193]
	s_mov_b32 m0, s29
	v_lshl_add_u64 v[224:225], s[78:79], 0, v[170:171]
	global_load_lds_dwordx4 v[196:197], off
	v_lshl_add_u64 v[196:197], s[76:77], 0, v[168:169]
	s_add_i32 m0, s29, 0x2000
	s_nop 0
	global_load_lds_dwordx4 v[196:197], off
	v_lshl_add_u64 v[196:197], s[78:79], 0, v[172:173]
	s_mov_b32 m0, s33
	s_nop 0
	global_load_lds_dwordx4 v[196:197], off
	s_mov_b32 m0, s62
	s_nop 0
	global_load_lds_dwordx4 v[224:225], off
	s_waitcnt vmcnt(8)
	s_waitcnt lgkmcnt(0)
	s_barrier
; #define PG8_STAGE(bufoff, gbase, voff) do { _Pragma("unroll") for (int _i = 0; _i < 2; ++_i) \
;         __builtin_amdgcn_global_load_lds((const unsigned*)((const char*)(gbase) + (voff)[_i]), (PG8_LAS unsigned*)(lds + (bufoff) + ldsw + _i * 8192), 16, 0, 0); } while (0)
; #define PG8_LDA(dst, b, h) do { _Pragma("unroll") for (int m = 0; m < 4; ++m) _Pragma("unroll") for (int k = 0; k < 2; ++k) dst[m][k] = *(const PG8_LAS bf16x8*)(lds + PG8_SA(b, h) + aoff + m * 2048 + k * 1024); } while (0)
; #define PG8_LDB(dst, b, h) do { _Pragma("unroll") for (int n = 0; n < 2; ++n) _Pragma("unroll") for (int k = 0; k < 2; ++k) dst[n][k] = *(const PG8_LAS bf16x8*)(lds + PG8_SB(b, h) + boff + n * 2048 + k * 1024); } while (0)
; #define PG8_MMA(ai, bj, At, Bt) do { __builtin_amdgcn_s_setprio(1); _Pragma("unroll") for (int m = 0; m < 4; ++m) _Pragma("unroll") for (int n = 0; n < 2; ++n) _Pragma("unroll") for (int k = 0; k < 2; ++k) \
;         acc[ai][bj][m][n] = __builtin_amdgcn_mfma_f32_16x16x32_bf16(Bt[n][k], At[m][k], acc[ai][bj][m][n], 0, 0, 0); __builtin_amdgcn_s_setprio(0); } while (0)
; #define PG8_WAIT_V(n) asm volatile("s_waitcnt vmcnt(" #n ")" ::: "memory")
; #define PG8_WAIT_L(n) asm volatile("s_waitcnt lgkmcnt(" #n ")" ::: "memory")
; #define PG8_BAR __builtin_amdgcn_s_barrier()
; #define PG8_SCHED __builtin_amdgcn_sched_barrier(0)
; template <class Epi, class Sched, bool ALIGN_EPI = false, bool SP2 = false>
; __device__ __forceinline__ void gemm_phase(PG8_LAS unsigned char* lds, const Gemm g, const Sched& S, const Epi& E, int wave_in) {
;     ...
;             PG8_WAIT_V(8); PG8_WAIT_L(0); PG8_BAR; PG8_MMA(1, 0, At, B0); PG8_MMA(1, 1, At, B1); PG8_BAR; PG8_SCHED;
;             PG8_LDB(B0, 1, 0); PG8_LDB(B1, 1, 1); PG8_SCHED; PG8_LDA(At, 1, 0); PG8_STAGE(PG8_SA(0, 1), a2 + hstep, voffA);
;             PG8_WAIT_V(8); PG8_WAIT_L(0); PG8_BAR; PG8_MMA(0, 0, At, B0); PG8_MMA(0, 1, At, B1); PG8_BAR; PG8_SCHED;
	s_waitcnt lgkmcnt(0)
	v_mfma_f32_16x16x32_bf16 v[92:95], v[128:131], v[160:163], 0
	v_mfma_f32_16x16x32_bf16 v[28:31], v[136:139], v[160:163], 0
	v_mfma_f32_16x16x32_bf16 v[84:87], v[128:131], v[178:181], 0
	v_mfma_f32_16x16x32_bf16 v[20:23], v[136:139], v[178:181], 0
	v_mfma_f32_16x16x32_bf16 v[76:79], v[128:131], v[186:189], 0
	v_mfma_f32_16x16x32_bf16 v[12:15], v[136:139], v[186:189], 0
	v_mfma_f32_16x16x32_bf16 v[68:71], v[128:131], v[202:205], 0
	v_mfma_f32_16x16x32_bf16 v[4:7], v[136:139], v[202:205], 0
	v_mfma_f32_16x16x32_bf16 v[92:95], v[132:135], v[164:167], v[92:95]
	v_mfma_f32_16x16x32_bf16 v[28:31], v[140:143], v[164:167], v[28:31]
	v_mfma_f32_16x16x32_bf16 v[84:87], v[132:135], v[182:185], v[84:87]
	v_mfma_f32_16x16x32_bf16 v[20:23], v[140:143], v[182:185], v[20:23]
	v_mfma_f32_16x16x32_bf16 v[76:79], v[132:135], v[198:201], v[76:79]
	v_mfma_f32_16x16x32_bf16 v[12:15], v[140:143], v[198:201], v[12:15]
	v_mfma_f32_16x16x32_bf16 v[68:71], v[132:135], v[220:223], v[68:71]
	v_mfma_f32_16x16x32_bf16 v[4:7], v[140:143], v[220:223], v[4:7]
	v_mfma_f32_16x16x32_bf16 v[88:91], v[144:147], v[160:163], 0
	v_mfma_f32_16x16x32_bf16 v[24:27], v[152:155], v[160:163], 0
	v_mfma_f32_16x16x32_bf16 v[80:83], v[144:147], v[178:181], 0
	v_mfma_f32_16x16x32_bf16 v[16:19], v[152:155], v[178:181], 0
	v_mfma_f32_16x16x32_bf16 v[72:75], v[144:147], v[186:189], 0
	v_mfma_f32_16x16x32_bf16 v[8:11], v[152:155], v[186:189], 0
	v_mfma_f32_16x16x32_bf16 v[64:67], v[144:147], v[202:205], 0
	v_mfma_f32_16x16x32_bf16 v[0:3], v[152:155], v[202:205], 0
	v_mfma_f32_16x16x32_bf16 v[88:91], v[148:151], v[164:167], v[88:91]
	v_mfma_f32_16x16x32_bf16 v[24:27], v[156:159], v[164:167], v[24:27]
	v_mfma_f32_16x16x32_bf16 v[80:83], v[148:151], v[182:185], v[80:83]
	v_mfma_f32_16x16x32_bf16 v[16:19], v[156:159], v[182:185], v[16:19]
	v_mfma_f32_16x16x32_bf16 v[72:75], v[148:151], v[198:201], v[72:75]
	v_mfma_f32_16x16x32_bf16 v[8:11], v[156:159], v[198:201], v[8:11]
	v_mfma_f32_16x16x32_bf16 v[64:67], v[148:151], v[220:223], v[64:67]
	v_mfma_f32_16x16x32_bf16 v[0:3], v[156:159], v[220:223], v[0:3]
	s_barrier
	s_add_i32 s29, s65, 0x100
	s_add_i32 s2, s52, 0x100
	v_add_u32_e32 v140, s29, v207
	v_add_u32_e32 v156, s2, v207
	ds_read_b128 v[128:131], v140
	ds_read_b128 v[132:135], v140 offset:1024
	ds_read_b128 v[136:139], v140 offset:2048
	ds_read_b128 v[140:143], v140 offset:3072
	ds_read_b128 v[144:147], v156
	ds_read_b128 v[148:151], v156 offset:1024
	ds_read_b128 v[152:155], v156 offset:2048
	ds_read_b128 v[156:159], v156 offset:3072
	s_add_u32 s76, s78, 0x40000
	s_addc_u32 s77, s79, 0
	s_mov_b32 m0, s63
	v_lshl_add_u64 v[226:227], s[76:77], 0, v[172:173]
	ds_read_b128 v[160:163], v219 offset:32768
	ds_read_b128 v[164:167], v219 offset:33792
	ds_read_b128 v[178:181], v219 offset:34816
	ds_read_b128 v[182:185], v219 offset:35840
	ds_read_b128 v[186:189], v219 offset:36864
	ds_read_b128 v[198:201], v219 offset:37888
	ds_read_b128 v[202:205], v219 offset:38912
	ds_read_b128 v[220:223], v219 offset:39936
	global_load_lds_dwordx4 v[226:227], off
	v_lshl_add_u64 v[226:227], s[76:77], 0, v[170:171]
	s_mov_b32 m0, s31
	s_nop 0
	global_load_lds_dwordx4 v[226:227], off
	s_waitcnt vmcnt(8)
	s_waitcnt lgkmcnt(0)
	s_barrier
	s_waitcnt lgkmcnt(0)
	v_mfma_f32_16x16x32_bf16 v[124:127], v[128:131], v[160:163], v[124:127]
	v_mfma_f32_16x16x32_bf16 v[60:63], v[136:139], v[160:163], v[60:63]
	v_mfma_f32_16x16x32_bf16 v[116:119], v[128:131], v[178:181], v[116:119]
	v_mfma_f32_16x16x32_bf16 v[52:55], v[136:139], v[178:181], v[52:55]
	v_mfma_f32_16x16x32_bf16 v[108:111], v[128:131], v[186:189], v[108:111]
	v_mfma_f32_16x16x32_bf16 v[44:47], v[136:139], v[186:189], v[44:47]
	v_mfma_f32_16x16x32_bf16 v[100:103], v[128:131], v[202:205], v[100:103]
	v_mfma_f32_16x16x32_bf16 v[36:39], v[136:139], v[202:205], v[36:39]
	v_mfma_f32_16x16x32_bf16 v[124:127], v[132:135], v[164:167], v[124:127]
	v_mfma_f32_16x16x32_bf16 v[60:63], v[140:143], v[164:167], v[60:63]
	v_mfma_f32_16x16x32_bf16 v[116:119], v[132:135], v[182:185], v[116:119]
	v_mfma_f32_16x16x32_bf16 v[52:55], v[140:143], v[182:185], v[52:55]
	v_mfma_f32_16x16x32_bf16 v[108:111], v[132:135], v[198:201], v[108:111]
	v_mfma_f32_16x16x32_bf16 v[44:47], v[140:143], v[198:201], v[44:47]
	v_mfma_f32_16x16x32_bf16 v[100:103], v[132:135], v[220:223], v[100:103]
	v_mfma_f32_16x16x32_bf16 v[36:39], v[140:143], v[220:223], v[36:39]
	v_mfma_f32_16x16x32_bf16 v[120:123], v[144:147], v[160:163], v[120:123]
	v_mfma_f32_16x16x32_bf16 v[56:59], v[152:155], v[160:163], v[56:59]
	v_mfma_f32_16x16x32_bf16 v[112:115], v[144:147], v[178:181], v[112:115]
	v_mfma_f32_16x16x32_bf16 v[48:51], v[152:155], v[178:181], v[48:51]
	v_mfma_f32_16x16x32_bf16 v[104:107], v[144:147], v[186:189], v[104:107]
	v_mfma_f32_16x16x32_bf16 v[40:43], v[152:155], v[186:189], v[40:43]
	v_mfma_f32_16x16x32_bf16 v[96:99], v[144:147], v[202:205], v[96:99]
	v_mfma_f32_16x16x32_bf16 v[32:35], v[152:155], v[202:205], v[32:35]
	v_mfma_f32_16x16x32_bf16 v[120:123], v[148:151], v[164:167], v[120:123]
	v_mfma_f32_16x16x32_bf16 v[56:59], v[156:159], v[164:167], v[56:59]
	v_mfma_f32_16x16x32_bf16 v[112:115], v[148:151], v[182:185], v[112:115]
	v_mfma_f32_16x16x32_bf16 v[48:51], v[156:159], v[182:185], v[48:51]
	v_mfma_f32_16x16x32_bf16 v[104:107], v[148:151], v[198:201], v[104:107]
	v_mfma_f32_16x16x32_bf16 v[40:43], v[156:159], v[198:201], v[40:43]
	v_mfma_f32_16x16x32_bf16 v[96:99], v[148:151], v[220:223], v[96:99]
	v_mfma_f32_16x16x32_bf16 v[32:35], v[156:159], v[220:223], v[32:35]
	s_barrier
; #define PG8_STAGE(bufoff, gbase, voff) do { _Pragma("unroll") for (int _i = 0; _i < 2; ++_i) \
;         __builtin_amdgcn_global_load_lds((const unsigned*)((const char*)(gbase) + (voff)[_i]), (PG8_LAS unsigned*)(lds + (bufoff) + ldsw + _i * 8192), 16, 0, 0); } while (0)
; #define PG8_LDA(dst, b, h) do { _Pragma("unroll") for (int m = 0; m < 4; ++m) _Pragma("unroll") for (int k = 0; k < 2; ++k) dst[m][k] = *(const PG8_LAS bf16x8*)(lds + PG8_SA(b, h) + aoff + m * 2048 + k * 1024); } while (0)
; #define PG8_LDB(dst, b, h) do { _Pragma("unroll") for (int n = 0; n < 2; ++n) _Pragma("unroll") for (int k = 0; k < 2; ++k) dst[n][k] = *(const PG8_LAS bf16x8*)(lds + PG8_SB(b, h) + boff + n * 2048 + k * 1024); } while (0)
; #define PG8_MMA(ai, bj, At, Bt) do { __builtin_amdgcn_s_setprio(1); _Pragma("unroll") for (int m = 0; m < 4; ++m) _Pragma("unroll") for (int n = 0; n < 2; ++n) _Pragma("unroll") for (int k = 0; k < 2; ++k) \
;         acc[ai][bj][m][n] = __builtin_amdgcn_mfma_f32_16x16x32_bf16(Bt[n][k], At[m][k], acc[ai][bj][m][n], 0, 0, 0); __builtin_amdgcn_s_setprio(0); } while (0)
; template <class Epi, class Sched, bool ALIGN_EPI = false, bool SP2 = false>
; __device__ __forceinline__ void gemm_phase(PG8_LAS unsigned char* lds, const Gemm g, const Sched& S, const Epi& E, int wave_in) {
;     ...
;         for (int t = 0; t < nt; t += 2) {
;             const bool last = (t == nt - 2);
;             const char* a1 = cA + (size_t)(t + 1) * kstep;
;             const char* a2 = last ? nA : cA + (size_t)(t + 2) * kstep; const char* b2 = last ? nB : cB + (size_t)(t + 2) * kstep;
;             const char* a3 = a2 + kstep; const char* b3 = b2 + kstep;
;             if (last && has_next) S.a_ready(nxt);
;             if constexpr (SP2) {
;             PG8_LDB(B0, 0, 0); PG8_LDB(B1, 0, 1); PG8_SCHED; PG8_LDA(At, 0, 0); PG8_STAGE(PG8_SA(1, 1), a1 + hstep, voffA);
;             PG8_WAIT_V(8); PG8_WAIT_L(0); PG8_BAR; PG8_MMA(0, 0, At, B0); PG8_MMA(0, 1, At, B1); PG8_BAR; PG8_SCHED;
;     ...
;             PG8_WAIT_V(8); PG8_WAIT_L(0); PG8_BAR; PG8_MMA(0, 0, At, B0); PG8_MMA(0, 1, At, B1); PG8_BAR; PG8_SCHED;
;             PG8_LDA(At, 1, 1); PG8_STAGE(PG8_SB(1, 0), b3, voffB); PG8_STAGE(PG8_SB(1, 1), b3 + hstep, voffB); PG8_STAGE(PG8_SA(1, 0), a3, voffA);
;             PG8_WAIT_V(8); PG8_WAIT_L(0); PG8_BAR; PG8_MMA(1, 0, At, B0); PG8_MMA(1, 1, At, B1); PG8_BAR; PG8_SCHED;
	s_add_i32 s29, s29, s75
	v_lshl_add_u64 v[190:191], v[190:191], 0, s[88:89]
	s_mov_b32 m0, s29
	ds_read_b128 v[160:163], v219 offset:49152
	ds_read_b128 v[164:167], v219 offset:50176
	ds_read_b128 v[178:181], v219 offset:51200
	ds_read_b128 v[182:185], v219 offset:52224
	ds_read_b128 v[186:189], v219 offset:53248
	ds_read_b128 v[198:201], v219 offset:54272
	ds_read_b128 v[202:205], v219 offset:55296
	ds_read_b128 v[220:223], v219 offset:56320
	global_load_lds_dwordx4 v[190:191], off
	s_add_i32 m0, s29, 0x2000
	s_add_u32 s0, s0, 0x40080
	v_lshl_add_u64 v[190:191], v[194:195], 0, s[88:89]
	s_addc_u32 s1, s1, 0
	s_add_i32 s2, s2, s75
	global_load_lds_dwordx4 v[190:191], off
	v_lshl_add_u64 v[190:191], s[0:1], 0, v[192:193]
	s_mov_b32 m0, s2
	s_nop 0
	global_load_lds_dwordx4 v[190:191], off
	v_lshl_add_u64 v[190:191], s[0:1], 0, v[168:169]
	s_add_i32 m0, s2, 0x2000
	s_nop 0
	global_load_lds_dwordx4 v[190:191], off
	v_lshl_add_u64 v[190:191], v[196:197], 0, s[88:89]
	s_mov_b32 m0, s9
	s_nop 0
	global_load_lds_dwordx4 v[190:191], off
	v_lshl_add_u64 v[190:191], v[224:225], 0, s[88:89]
	s_mov_b32 m0, s96
	s_nop 0
	global_load_lds_dwordx4 v[190:191], off
	s_waitcnt vmcnt(8)
	s_waitcnt lgkmcnt(0)
	s_barrier
	s_waitcnt lgkmcnt(0)
	v_mfma_f32_16x16x32_bf16 v[92:95], v[128:131], v[160:163], v[92:95]
	v_mfma_f32_16x16x32_bf16 v[28:31], v[136:139], v[160:163], v[28:31]
	v_mfma_f32_16x16x32_bf16 v[84:87], v[128:131], v[178:181], v[84:87]
	v_mfma_f32_16x16x32_bf16 v[20:23], v[136:139], v[178:181], v[20:23]
	v_mfma_f32_16x16x32_bf16 v[76:79], v[128:131], v[186:189], v[76:79]
	v_mfma_f32_16x16x32_bf16 v[12:15], v[136:139], v[186:189], v[12:15]
	v_mfma_f32_16x16x32_bf16 v[68:71], v[128:131], v[202:205], v[68:71]
	v_mfma_f32_16x16x32_bf16 v[4:7], v[136:139], v[202:205], v[4:7]
	v_mfma_f32_16x16x32_bf16 v[92:95], v[132:135], v[164:167], v[92:95]
	v_mfma_f32_16x16x32_bf16 v[28:31], v[140:143], v[164:167], v[28:31]
	v_mfma_f32_16x16x32_bf16 v[84:87], v[132:135], v[182:185], v[84:87]
	v_mfma_f32_16x16x32_bf16 v[20:23], v[140:143], v[182:185], v[20:23]
	v_mfma_f32_16x16x32_bf16 v[76:79], v[132:135], v[198:201], v[76:79]
	v_mfma_f32_16x16x32_bf16 v[12:15], v[140:143], v[198:201], v[12:15]
	v_mfma_f32_16x16x32_bf16 v[68:71], v[132:135], v[220:223], v[68:71]
	v_mfma_f32_16x16x32_bf16 v[4:7], v[140:143], v[220:223], v[4:7]
	v_mfma_f32_16x16x32_bf16 v[88:91], v[144:147], v[160:163], v[88:91]
	v_mfma_f32_16x16x32_bf16 v[24:27], v[152:155], v[160:163], v[24:27]
	v_mfma_f32_16x16x32_bf16 v[80:83], v[144:147], v[178:181], v[80:83]
	v_mfma_f32_16x16x32_bf16 v[16:19], v[152:155], v[178:181], v[16:19]
	v_mfma_f32_16x16x32_bf16 v[72:75], v[144:147], v[186:189], v[72:75]
	v_mfma_f32_16x16x32_bf16 v[8:11], v[152:155], v[186:189], v[8:11]
	v_mfma_f32_16x16x32_bf16 v[64:67], v[144:147], v[202:205], v[64:67]
	v_mfma_f32_16x16x32_bf16 v[0:3], v[152:155], v[202:205], v[0:3]
	v_mfma_f32_16x16x32_bf16 v[88:91], v[148:151], v[164:167], v[88:91]
	v_mfma_f32_16x16x32_bf16 v[24:27], v[156:159], v[164:167], v[24:27]
	v_mfma_f32_16x16x32_bf16 v[80:83], v[148:151], v[182:185], v[80:83]
	v_mfma_f32_16x16x32_bf16 v[16:19], v[156:159], v[182:185], v[16:19]
	v_mfma_f32_16x16x32_bf16 v[72:75], v[148:151], v[198:201], v[72:75]
	v_mfma_f32_16x16x32_bf16 v[8:11], v[156:159], v[198:201], v[8:11]
	v_mfma_f32_16x16x32_bf16 v[64:67], v[148:151], v[220:223], v[64:67]
	v_mfma_f32_16x16x32_bf16 v[0:3], v[156:159], v[220:223], v[0:3]
	s_barrier
	s_add_i32 s19, s19, 2
	s_add_u32 s81, s81, 0x100
	s_addc_u32 s18, s18, 0
	s_add_u32 vcc_lo, vcc_lo, 0x100
	s_addc_u32 vcc_hi, vcc_hi, 0
	s_cmp_gt_u32 s19, 13
	s_cbranch_scc1 .Lkexit_6
.LBB0_897:
	s_add_u32 s0, vcc_lo, 0xfffc0080
	s_addc_u32 s1, vcc_hi, -1
	s_add_i32 s76, s35, 0x100
	s_cmp_eq_u32 s19, 12
	s_cselect_b32 s79, s11, s1
	s_cselect_b32 s78, s34, s0
	s_cselect_b32 s1, s5, s18
	s_cselect_b32 s0, s53, s81
	s_add_i32 s29, s90, 0x100
	v_add_u32_e32 v140, s76, v207
	v_add_u32_e32 v156, s29, v207
	ds_read_b128 v[128:131], v140
	ds_read_b128 v[132:135], v140 offset:1024
	ds_read_b128 v[136:139], v140 offset:2048
	ds_read_b128 v[140:143], v140 offset:3072
	ds_read_b128 v[144:147], v156
	ds_read_b128 v[148:151], v156 offset:1024
	ds_read_b128 v[152:155], v156 offset:2048
	ds_read_b128 v[156:159], v156 offset:3072
	v_lshl_add_u64 v[190:191], vcc, 0, v[176:177]
	s_add_i32 m0, s33, 0xc000
	ds_read_b128 v[160:163], v219
	ds_read_b128 v[164:167], v219 offset:1024
	ds_read_b128 v[178:181], v219 offset:2048
	ds_read_b128 v[182:185], v219 offset:3072
	ds_read_b128 v[186:189], v219 offset:4096
	ds_read_b128 v[198:201], v219 offset:5120
	ds_read_b128 v[202:205], v219 offset:6144
	ds_read_b128 v[220:223], v219 offset:7168
	global_load_lds_dwordx4 v[190:191], off
	v_lshl_add_u64 v[190:191], vcc, 0, v[174:175]
	s_add_i32 m0, s33, 0xe000
	s_nop 0
	global_load_lds_dwordx4 v[190:191], off
	s_waitcnt vmcnt(8)
	s_waitcnt lgkmcnt(0)
	s_barrier
; #define PG8_STAGE(bufoff, gbase, voff) do { _Pragma("unroll") for (int _i = 0; _i < 2; ++_i) \
;         __builtin_amdgcn_global_load_lds((const unsigned*)((const char*)(gbase) + (voff)[_i]), (PG8_LAS unsigned*)(lds + (bufoff) + ldsw + _i * 8192), 16, 0, 0); } while (0)
; #define PG8_LDA(dst, b, h) do { _Pragma("unroll") for (int m = 0; m < 4; ++m) _Pragma("unroll") for (int k = 0; k < 2; ++k) dst[m][k] = *(const PG8_LAS bf16x8*)(lds + PG8_SA(b, h) + aoff + m * 2048 + k * 1024); } while (0)
; #define PG8_LDB(dst, b, h) do { _Pragma("unroll") for (int n = 0; n < 2; ++n) _Pragma("unroll") for (int k = 0; k < 2; ++k) dst[n][k] = *(const PG8_LAS bf16x8*)(lds + PG8_SB(b, h) + boff + n * 2048 + k * 1024); } while (0)
; #define PG8_MMA(ai, bj, At, Bt) do { __builtin_amdgcn_s_setprio(1); _Pragma("unroll") for (int m = 0; m < 4; ++m) _Pragma("unroll") for (int n = 0; n < 2; ++n) _Pragma("unroll") for (int k = 0; k < 2; ++k) \
;         acc[ai][bj][m][n] = __builtin_amdgcn_mfma_f32_16x16x32_bf16(Bt[n][k], At[m][k], acc[ai][bj][m][n], 0, 0, 0); __builtin_amdgcn_s_setprio(0); } while (0)
; #define PG8_WAIT_V(n) asm volatile("s_waitcnt vmcnt(" #n ")" ::: "memory")
; #define PG8_WAIT_L(n) asm volatile("s_waitcnt lgkmcnt(" #n ")" ::: "memory")
; #define PG8_BAR __builtin_amdgcn_s_barrier()
; #define PG8_SCHED __builtin_amdgcn_sched_barrier(0)
; template <class Epi, class Sched, bool ALIGN_EPI = false, bool SP2 = false>
; __device__ __forceinline__ void gemm_phase(PG8_LAS unsigned char* lds, const Gemm g, const Sched& S, const Epi& E, int wave_in) {
;     ...
;             PG8_LDB(B0, 0, 0); PG8_LDB(B1, 0, 1); PG8_SCHED; PG8_LDA(At, 0, 0); PG8_STAGE(PG8_SA(1, 1), a1 + hstep, voffA);
;             PG8_WAIT_V(8); PG8_WAIT_L(0); PG8_BAR; PG8_MMA(0, 0, At, B0); PG8_MMA(0, 1, At, B1); PG8_BAR; PG8_SCHED;
;             PG8_LDA(At, 0, 1); PG8_STAGE(PG8_SB(0, 0), b2, voffB); PG8_STAGE(PG8_SB(0, 1), b2 + hstep, voffB); PG8_STAGE(PG8_SA(0, 0), a2, voffA);
;             PG8_WAIT_V(8); PG8_WAIT_L(0); PG8_BAR; PG8_MMA(1, 0, At, B0); PG8_MMA(1, 1, At, B1); PG8_BAR; PG8_SCHED;
	s_waitcnt lgkmcnt(0)
	v_mfma_f32_16x16x32_bf16 v[124:127], v[128:131], v[160:163], v[124:127]
	v_mfma_f32_16x16x32_bf16 v[60:63], v[136:139], v[160:163], v[60:63]
	v_mfma_f32_16x16x32_bf16 v[116:119], v[128:131], v[178:181], v[116:119]
	v_mfma_f32_16x16x32_bf16 v[52:55], v[136:139], v[178:181], v[52:55]
	v_mfma_f32_16x16x32_bf16 v[108:111], v[128:131], v[186:189], v[108:111]
	v_mfma_f32_16x16x32_bf16 v[44:47], v[136:139], v[186:189], v[44:47]
	v_mfma_f32_16x16x32_bf16 v[100:103], v[128:131], v[202:205], v[100:103]
	v_mfma_f32_16x16x32_bf16 v[36:39], v[136:139], v[202:205], v[36:39]
	v_mfma_f32_16x16x32_bf16 v[124:127], v[132:135], v[164:167], v[124:127]
	v_mfma_f32_16x16x32_bf16 v[60:63], v[140:143], v[164:167], v[60:63]
	v_mfma_f32_16x16x32_bf16 v[116:119], v[132:135], v[182:185], v[116:119]
	v_mfma_f32_16x16x32_bf16 v[52:55], v[140:143], v[182:185], v[52:55]
	v_mfma_f32_16x16x32_bf16 v[108:111], v[132:135], v[198:201], v[108:111]
	v_mfma_f32_16x16x32_bf16 v[44:47], v[140:143], v[198:201], v[44:47]
	v_mfma_f32_16x16x32_bf16 v[100:103], v[132:135], v[220:223], v[100:103]
	v_mfma_f32_16x16x32_bf16 v[36:39], v[140:143], v[220:223], v[36:39]
	v_mfma_f32_16x16x32_bf16 v[120:123], v[144:147], v[160:163], v[120:123]
	v_mfma_f32_16x16x32_bf16 v[56:59], v[152:155], v[160:163], v[56:59]
	v_mfma_f32_16x16x32_bf16 v[112:115], v[144:147], v[178:181], v[112:115]
	v_mfma_f32_16x16x32_bf16 v[48:51], v[152:155], v[178:181], v[48:51]
	v_mfma_f32_16x16x32_bf16 v[104:107], v[144:147], v[186:189], v[104:107]
	v_mfma_f32_16x16x32_bf16 v[40:43], v[152:155], v[186:189], v[40:43]
	v_mfma_f32_16x16x32_bf16 v[96:99], v[144:147], v[202:205], v[96:99]
	v_mfma_f32_16x16x32_bf16 v[32:35], v[152:155], v[202:205], v[32:35]
	v_mfma_f32_16x16x32_bf16 v[120:123], v[148:151], v[164:167], v[120:123]
	v_mfma_f32_16x16x32_bf16 v[56:59], v[156:159], v[164:167], v[56:59]
	v_mfma_f32_16x16x32_bf16 v[112:115], v[148:151], v[182:185], v[112:115]
	v_mfma_f32_16x16x32_bf16 v[48:51], v[156:159], v[182:185], v[48:51]
	v_mfma_f32_16x16x32_bf16 v[104:107], v[148:151], v[198:201], v[104:107]
	v_mfma_f32_16x16x32_bf16 v[40:43], v[156:159], v[198:201], v[40:43]
	v_mfma_f32_16x16x32_bf16 v[96:99], v[148:151], v[220:223], v[96:99]
	v_mfma_f32_16x16x32_bf16 v[32:35], v[156:159], v[220:223], v[32:35]
	s_barrier
	s_add_i32 s76, s76, s75
	v_lshl_add_u64 v[190:191], s[0:1], 0, v[192:193]
	s_mov_b32 m0, s76
	ds_read_b128 v[160:163], v219 offset:16384
	ds_read_b128 v[164:167], v219 offset:17408
	ds_read_b128 v[178:181], v219 offset:18432
	ds_read_b128 v[182:185], v219 offset:19456
	ds_read_b128 v[186:189], v219 offset:20480
	ds_read_b128 v[198:201], v219 offset:21504
	ds_read_b128 v[202:205], v219 offset:22528
	ds_read_b128 v[220:223], v219 offset:23552
	global_load_lds_dwordx4 v[190:191], off
	s_add_i32 m0, s76, 0x2000
	s_add_u32 s76, s0, 0x40000
	v_lshl_add_u64 v[194:195], s[0:1], 0, v[168:169]
	s_addc_u32 s77, s1, 0
	s_add_i32 s29, s29, s75
	global_load_lds_dwordx4 v[194:195], off
	v_lshl_add_u64 v[196:197], s[76:77], 0, v[192:193]
	s_mov_b32 m0, s29
	v_lshl_add_u64 v[224:225], s[78:79], 0, v[170:171]
	global_load_lds_dwordx4 v[196:197], off
	v_lshl_add_u64 v[196:197], s[76:77], 0, v[168:169]
	s_add_i32 m0, s29, 0x2000
	s_nop 0
	global_load_lds_dwordx4 v[196:197], off
	v_lshl_add_u64 v[196:197], s[78:79], 0, v[172:173]
	s_mov_b32 m0, s33
	s_nop 0
	global_load_lds_dwordx4 v[196:197], off
	s_mov_b32 m0, s62
	s_nop 0
	global_load_lds_dwordx4 v[224:225], off
	s_waitcnt vmcnt(8)
	s_waitcnt lgkmcnt(0)
	s_barrier
	s_waitcnt lgkmcnt(0)
	v_mfma_f32_16x16x32_bf16 v[92:95], v[128:131], v[160:163], v[92:95]
	v_mfma_f32_16x16x32_bf16 v[28:31], v[136:139], v[160:163], v[28:31]
	v_mfma_f32_16x16x32_bf16 v[84:87], v[128:131], v[178:181], v[84:87]
	v_mfma_f32_16x16x32_bf16 v[20:23], v[136:139], v[178:181], v[20:23]
	v_mfma_f32_16x16x32_bf16 v[76:79], v[128:131], v[186:189], v[76:79]
	v_mfma_f32_16x16x32_bf16 v[12:15], v[136:139], v[186:189], v[12:15]
	v_mfma_f32_16x16x32_bf16 v[68:71], v[128:131], v[202:205], v[68:71]
	v_mfma_f32_16x16x32_bf16 v[4:7], v[136:139], v[202:205], v[4:7]
	v_mfma_f32_16x16x32_bf16 v[92:95], v[132:135], v[164:167], v[92:95]
	v_mfma_f32_16x16x32_bf16 v[28:31], v[140:143], v[164:167], v[28:31]
	v_mfma_f32_16x16x32_bf16 v[84:87], v[132:135], v[182:185], v[84:87]
	v_mfma_f32_16x16x32_bf16 v[20:23], v[140:143], v[182:185], v[20:23]
	v_mfma_f32_16x16x32_bf16 v[76:79], v[132:135], v[198:201], v[76:79]
	v_mfma_f32_16x16x32_bf16 v[12:15], v[140:143], v[198:201], v[12:15]
	v_mfma_f32_16x16x32_bf16 v[68:71], v[132:135], v[220:223], v[68:71]
	v_mfma_f32_16x16x32_bf16 v[4:7], v[140:143], v[220:223], v[4:7]
	v_mfma_f32_16x16x32_bf16 v[88:91], v[144:147], v[160:163], v[88:91]
	v_mfma_f32_16x16x32_bf16 v[24:27], v[152:155], v[160:163], v[24:27]
	v_mfma_f32_16x16x32_bf16 v[80:83], v[144:147], v[178:181], v[80:83]
	v_mfma_f32_16x16x32_bf16 v[16:19], v[152:155], v[178:181], v[16:19]
	v_mfma_f32_16x16x32_bf16 v[72:75], v[144:147], v[186:189], v[72:75]
	v_mfma_f32_16x16x32_bf16 v[8:11], v[152:155], v[186:189], v[8:11]
	v_mfma_f32_16x16x32_bf16 v[64:67], v[144:147], v[202:205], v[64:67]
	v_mfma_f32_16x16x32_bf16 v[0:3], v[152:155], v[202:205], v[0:3]
	v_mfma_f32_16x16x32_bf16 v[88:91], v[148:151], v[164:167], v[88:91]
	v_mfma_f32_16x16x32_bf16 v[24:27], v[156:159], v[164:167], v[24:27]
	v_mfma_f32_16x16x32_bf16 v[80:83], v[148:151], v[182:185], v[80:83]
	v_mfma_f32_16x16x32_bf16 v[16:19], v[156:159], v[182:185], v[16:19]
	v_mfma_f32_16x16x32_bf16 v[72:75], v[148:151], v[198:201], v[72:75]
	v_mfma_f32_16x16x32_bf16 v[8:11], v[156:159], v[198:201], v[8:11]
	v_mfma_f32_16x16x32_bf16 v[64:67], v[148:151], v[220:223], v[64:67]
	v_mfma_f32_16x16x32_bf16 v[0:3], v[156:159], v[220:223], v[0:3]
	s_barrier
; #define PG8_STAGE(bufoff, gbase, voff) do { _Pragma("unroll") for (int _i = 0; _i < 2; ++_i) \
;         __builtin_amdgcn_global_load_lds((const unsigned*)((const char*)(gbase) + (voff)[_i]), (PG8_LAS unsigned*)(lds + (bufoff) + ldsw + _i * 8192), 16, 0, 0); } while (0)
; #define PG8_LDA(dst, b, h) do { _Pragma("unroll") for (int m = 0; m < 4; ++m) _Pragma("unroll") for (int k = 0; k < 2; ++k) dst[m][k] = *(const PG8_LAS bf16x8*)(lds + PG8_SA(b, h) + aoff + m * 2048 + k * 1024); } while (0)
; #define PG8_LDB(dst, b, h) do { _Pragma("unroll") for (int n = 0; n < 2; ++n) _Pragma("unroll") for (int k = 0; k < 2; ++k) dst[n][k] = *(const PG8_LAS bf16x8*)(lds + PG8_SB(b, h) + boff + n * 2048 + k * 1024); } while (0)
; #define PG8_MMA(ai, bj, At, Bt) do { __builtin_amdgcn_s_setprio(1); _Pragma("unroll") for (int m = 0; m < 4; ++m) _Pragma("unroll") for (int n = 0; n < 2; ++n) _Pragma("unroll") for (int k = 0; k < 2; ++k) \
;         acc[ai][bj][m][n] = __builtin_amdgcn_mfma_f32_16x16x32_bf16(Bt[n][k], At[m][k], acc[ai][bj][m][n], 0, 0, 0); __builtin_amdgcn_s_setprio(0); } while (0)
; #define PG8_WAIT_V(n) asm volatile("s_waitcnt vmcnt(" #n ")" ::: "memory")
; #define PG8_WAIT_L(n) asm volatile("s_waitcnt lgkmcnt(" #n ")" ::: "memory")
; #define PG8_BAR __builtin_amdgcn_s_barrier()
; #define PG8_SCHED __builtin_amdgcn_sched_barrier(0)
; template <class Epi, class Sched, bool ALIGN_EPI = false, bool SP2 = false>
; __device__ __forceinline__ void gemm_phase(PG8_LAS unsigned char* lds, const Gemm g, const Sched& S, const Epi& E, int wave_in) {
;     ...
;             PG8_LDB(B0, 1, 0); PG8_LDB(B1, 1, 1); PG8_SCHED; PG8_LDA(At, 1, 0); PG8_STAGE(PG8_SA(0, 1), a2 + hstep, voffA);
;             PG8_WAIT_V(8); PG8_WAIT_L(0); PG8_BAR; PG8_MMA(0, 0, At, B0); PG8_MMA(0, 1, At, B1); PG8_BAR; PG8_SCHED;
;             PG8_LDA(At, 1, 1); PG8_STAGE(PG8_SB(1, 0), b3, voffB); PG8_STAGE(PG8_SB(1, 1), b3 + hstep, voffB); PG8_STAGE(PG8_SA(1, 0), a3, voffA);
;             PG8_WAIT_V(8); PG8_WAIT_L(0); PG8_BAR; PG8_MMA(1, 0, At, B0); PG8_MMA(1, 1, At, B1); PG8_BAR; PG8_SCHED;
	s_add_i32 s29, s65, 0x100
	s_add_i32 s2, s52, 0x100
	v_add_u32_e32 v140, s29, v207
	v_add_u32_e32 v156, s2, v207
	ds_read_b128 v[128:131], v140
	ds_read_b128 v[132:135], v140 offset:1024
	ds_read_b128 v[136:139], v140 offset:2048
	ds_read_b128 v[140:143], v140 offset:3072
	ds_read_b128 v[144:147], v156
	ds_read_b128 v[148:151], v156 offset:1024
	ds_read_b128 v[152:155], v156 offset:2048
	ds_read_b128 v[156:159], v156 offset:3072
	s_add_u32 s76, s78, 0x40000
	s_addc_u32 s77, s79, 0
	s_mov_b32 m0, s63
	v_lshl_add_u64 v[226:227], s[76:77], 0, v[172:173]
	ds_read_b128 v[160:163], v219 offset:32768
	ds_read_b128 v[164:167], v219 offset:33792
	ds_read_b128 v[178:181], v219 offset:34816
	ds_read_b128 v[182:185], v219 offset:35840
	ds_read_b128 v[186:189], v219 offset:36864
	ds_read_b128 v[198:201], v219 offset:37888
	ds_read_b128 v[202:205], v219 offset:38912
	ds_read_b128 v[220:223], v219 offset:39936
	global_load_lds_dwordx4 v[226:227], off
	v_lshl_add_u64 v[226:227], s[76:77], 0, v[170:171]
	s_mov_b32 m0, s31
	s_nop 0
	global_load_lds_dwordx4 v[226:227], off
	s_waitcnt vmcnt(8)
	s_waitcnt lgkmcnt(0)
	s_barrier
	s_waitcnt lgkmcnt(0)
	v_mfma_f32_16x16x32_bf16 v[124:127], v[128:131], v[160:163], v[124:127]
	v_mfma_f32_16x16x32_bf16 v[60:63], v[136:139], v[160:163], v[60:63]
	v_mfma_f32_16x16x32_bf16 v[116:119], v[128:131], v[178:181], v[116:119]
	v_mfma_f32_16x16x32_bf16 v[52:55], v[136:139], v[178:181], v[52:55]
	v_mfma_f32_16x16x32_bf16 v[108:111], v[128:131], v[186:189], v[108:111]
	v_mfma_f32_16x16x32_bf16 v[44:47], v[136:139], v[186:189], v[44:47]
	v_mfma_f32_16x16x32_bf16 v[100:103], v[128:131], v[202:205], v[100:103]
	v_mfma_f32_16x16x32_bf16 v[36:39], v[136:139], v[202:205], v[36:39]
	v_mfma_f32_16x16x32_bf16 v[124:127], v[132:135], v[164:167], v[124:127]
	v_mfma_f32_16x16x32_bf16 v[60:63], v[140:143], v[164:167], v[60:63]
	v_mfma_f32_16x16x32_bf16 v[116:119], v[132:135], v[182:185], v[116:119]
	v_mfma_f32_16x16x32_bf16 v[52:55], v[140:143], v[182:185], v[52:55]
	v_mfma_f32_16x16x32_bf16 v[108:111], v[132:135], v[198:201], v[108:111]
	v_mfma_f32_16x16x32_bf16 v[44:47], v[140:143], v[198:201], v[44:47]
	v_mfma_f32_16x16x32_bf16 v[100:103], v[132:135], v[220:223], v[100:103]
	v_mfma_f32_16x16x32_bf16 v[36:39], v[140:143], v[220:223], v[36:39]
	v_mfma_f32_16x16x32_bf16 v[120:123], v[144:147], v[160:163], v[120:123]
	v_mfma_f32_16x16x32_bf16 v[56:59], v[152:155], v[160:163], v[56:59]
	v_mfma_f32_16x16x32_bf16 v[112:115], v[144:147], v[178:181], v[112:115]
	v_mfma_f32_16x16x32_bf16 v[48:51], v[152:155], v[178:181], v[48:51]
	v_mfma_f32_16x16x32_bf16 v[104:107], v[144:147], v[186:189], v[104:107]
	v_mfma_f32_16x16x32_bf16 v[40:43], v[152:155], v[186:189], v[40:43]
	v_mfma_f32_16x16x32_bf16 v[96:99], v[144:147], v[202:205], v[96:99]
	v_mfma_f32_16x16x32_bf16 v[32:35], v[152:155], v[202:205], v[32:35]
	v_mfma_f32_16x16x32_bf16 v[120:123], v[148:151], v[164:167], v[120:123]
	v_mfma_f32_16x16x32_bf16 v[56:59], v[156:159], v[164:167], v[56:59]
	v_mfma_f32_16x16x32_bf16 v[112:115], v[148:151], v[182:185], v[112:115]
	v_mfma_f32_16x16x32_bf16 v[48:51], v[156:159], v[182:185], v[48:51]
	v_mfma_f32_16x16x32_bf16 v[104:107], v[148:151], v[198:201], v[104:107]
	v_mfma_f32_16x16x32_bf16 v[40:43], v[156:159], v[198:201], v[40:43]
	v_mfma_f32_16x16x32_bf16 v[96:99], v[148:151], v[220:223], v[96:99]
	v_mfma_f32_16x16x32_bf16 v[32:35], v[156:159], v[220:223], v[32:35]
	s_barrier
	s_add_i32 s29, s29, s75
	v_lshl_add_u64 v[190:191], v[190:191], 0, s[88:89]
	s_mov_b32 m0, s29
	ds_read_b128 v[160:163], v219 offset:49152
	ds_read_b128 v[164:167], v219 offset:50176
	ds_read_b128 v[178:181], v219 offset:51200
	ds_read_b128 v[182:185], v219 offset:52224
	ds_read_b128 v[186:189], v219 offset:53248
	ds_read_b128 v[198:201], v219 offset:54272
	ds_read_b128 v[202:205], v219 offset:55296
	ds_read_b128 v[220:223], v219 offset:56320
	global_load_lds_dwordx4 v[190:191], off
	s_add_i32 m0, s29, 0x2000
	s_add_u32 s0, s0, 0x40080
	v_lshl_add_u64 v[190:191], v[194:195], 0, s[88:89]
	s_addc_u32 s1, s1, 0
	s_add_i32 s2, s2, s75
	global_load_lds_dwordx4 v[190:191], off
	v_lshl_add_u64 v[190:191], s[0:1], 0, v[192:193]
	s_mov_b32 m0, s2
	s_nop 0
	global_load_lds_dwordx4 v[190:191], off
	v_lshl_add_u64 v[190:191], s[0:1], 0, v[168:169]
	s_add_i32 m0, s2, 0x2000
	s_nop 0
	global_load_lds_dwordx4 v[190:191], off
	v_lshl_add_u64 v[190:191], v[196:197], 0, s[88:89]
	s_mov_b32 m0, s9
	s_nop 0
	global_load_lds_dwordx4 v[190:191], off
	v_lshl_add_u64 v[190:191], v[224:225], 0, s[88:89]
	s_mov_b32 m0, s96
	s_nop 0
	global_load_lds_dwordx4 v[190:191], off
	s_waitcnt vmcnt(8)
	s_waitcnt lgkmcnt(0)
	s_barrier
	s_waitcnt lgkmcnt(0)
	v_mfma_f32_16x16x32_bf16 v[92:95], v[128:131], v[160:163], v[92:95]
	v_mfma_f32_16x16x32_bf16 v[28:31], v[136:139], v[160:163], v[28:31]
	v_mfma_f32_16x16x32_bf16 v[84:87], v[128:131], v[178:181], v[84:87]
	v_mfma_f32_16x16x32_bf16 v[20:23], v[136:139], v[178:181], v[20:23]
	v_mfma_f32_16x16x32_bf16 v[76:79], v[128:131], v[186:189], v[76:79]
	v_mfma_f32_16x16x32_bf16 v[12:15], v[136:139], v[186:189], v[12:15]
	v_mfma_f32_16x16x32_bf16 v[68:71], v[128:131], v[202:205], v[68:71]
	v_mfma_f32_16x16x32_bf16 v[4:7], v[136:139], v[202:205], v[4:7]
	v_mfma_f32_16x16x32_bf16 v[92:95], v[132:135], v[164:167], v[92:95]
	v_mfma_f32_16x16x32_bf16 v[28:31], v[140:143], v[164:167], v[28:31]
	v_mfma_f32_16x16x32_bf16 v[84:87], v[132:135], v[182:185], v[84:87]
	v_mfma_f32_16x16x32_bf16 v[20:23], v[140:143], v[182:185], v[20:23]
	v_mfma_f32_16x16x32_bf16 v[76:79], v[132:135], v[198:201], v[76:79]
	v_mfma_f32_16x16x32_bf16 v[12:15], v[140:143], v[198:201], v[12:15]
	v_mfma_f32_16x16x32_bf16 v[68:71], v[132:135], v[220:223], v[68:71]
	v_mfma_f32_16x16x32_bf16 v[4:7], v[140:143], v[220:223], v[4:7]
	v_mfma_f32_16x16x32_bf16 v[88:91], v[144:147], v[160:163], v[88:91]
	v_mfma_f32_16x16x32_bf16 v[24:27], v[152:155], v[160:163], v[24:27]
	v_mfma_f32_16x16x32_bf16 v[80:83], v[144:147], v[178:181], v[80:83]
	v_mfma_f32_16x16x32_bf16 v[16:19], v[152:155], v[178:181], v[16:19]
	v_mfma_f32_16x16x32_bf16 v[72:75], v[144:147], v[186:189], v[72:75]
	v_mfma_f32_16x16x32_bf16 v[8:11], v[152:155], v[186:189], v[8:11]
	v_mfma_f32_16x16x32_bf16 v[64:67], v[144:147], v[202:205], v[64:67]
	v_mfma_f32_16x16x32_bf16 v[0:3], v[152:155], v[202:205], v[0:3]
	v_mfma_f32_16x16x32_bf16 v[88:91], v[148:151], v[164:167], v[88:91]
	v_mfma_f32_16x16x32_bf16 v[24:27], v[156:159], v[164:167], v[24:27]
	v_mfma_f32_16x16x32_bf16 v[80:83], v[148:151], v[182:185], v[80:83]
	v_mfma_f32_16x16x32_bf16 v[16:19], v[156:159], v[182:185], v[16:19]
	v_mfma_f32_16x16x32_bf16 v[72:75], v[148:151], v[198:201], v[72:75]
	v_mfma_f32_16x16x32_bf16 v[8:11], v[156:159], v[198:201], v[8:11]
	v_mfma_f32_16x16x32_bf16 v[64:67], v[148:151], v[220:223], v[64:67]
	v_mfma_f32_16x16x32_bf16 v[0:3], v[156:159], v[220:223], v[0:3]
	s_barrier
	s_add_i32 s19, s19, 2
	s_add_u32 s81, s81, 0x100
	s_addc_u32 s18, s18, 0
	s_add_u32 vcc_lo, vcc_lo, 0x100
	s_addc_u32 vcc_hi, vcc_hi, 0
	s_cmp_gt_u32 s19, 13
	s_cbranch_scc0 .LBB0_897

; #define PG8_STAGE(bufoff, gbase, voff) do { _Pragma("unroll") for (int _i = 0; _i < 2; ++_i) \
;         __builtin_amdgcn_global_load_lds((const unsigned*)((const char*)(gbase) + (voff)[_i]), (PG8_LAS unsigned*)(lds + (bufoff) + ldsw + _i * 8192), 16, 0, 0); } while (0)
; #define PG8_LDA(dst, b, h) do { _Pragma("unroll") for (int m = 0; m < 4; ++m) _Pragma("unroll") for (int k = 0; k < 2; ++k) dst[m][k] = *(const PG8_LAS bf16x8*)(lds + PG8_SA(b, h) + aoff + m * 2048 + k * 1024); } while (0)
; #define PG8_LDB(dst, b, h) do { _Pragma("unroll") for (int n = 0; n < 2; ++n) _Pragma("unroll") for (int k = 0; k < 2; ++k) dst[n][k] = *(const PG8_LAS bf16x8*)(lds + PG8_SB(b, h) + boff + n * 2048 + k * 1024); } while (0)
; #define PG8_MMA(ai, bj, At, Bt) do { __builtin_amdgcn_s_setprio(1); _Pragma("unroll") for (int m = 0; m < 4; ++m) _Pragma("unroll") for (int n = 0; n < 2; ++n) _Pragma("unroll") for (int k = 0; k < 2; ++k) \
;         acc[ai][bj][m][n] = __builtin_amdgcn_mfma_f32_16x16x32_bf16(Bt[n][k], At[m][k], acc[ai][bj][m][n], 0, 0, 0); __builtin_amdgcn_s_setprio(0); } while (0)
; #define PG8_WAIT_V(n) asm volatile("s_waitcnt vmcnt(" #n ")" ::: "memory")
; #define PG8_BAR __builtin_amdgcn_s_barrier()
; template <class Epi, class Sched, bool ALIGN_EPI = false, bool SP2 = false>
; __device__ __forceinline__ void gemm_phase(PG8_LAS unsigned char* lds, const Gemm g, const Sched& S, const Epi& E, int wave_in) {
;     ...
;         for (int t = 0; t < nt; t += 2) {
;             const bool last = (t == nt - 2);
;             const char* a1 = cA + (size_t)(t + 1) * kstep;
;             const char* a2 = last ? nA : cA + (size_t)(t + 2) * kstep; const char* b2 = last ? nB : cB + (size_t)(t + 2) * kstep;
;             const char* a3 = a2 + kstep; const char* b3 = b2 + kstep;
;             if (last && has_next) S.a_ready(nxt);
;             if constexpr (SP2) {
;             PG8_LDB(B0, 0, 0); PG8_LDB(B1, 0, 1); PG8_SCHED; PG8_LDA(At, 0, 0); PG8_STAGE(PG8_SA(1, 1), a1 + hstep, voffA);
;             PG8_WAIT_V(8); PG8_WAIT_L(0); PG8_BAR; PG8_MMA(0, 0, At, B0); PG8_MMA(0, 1, At, B1); PG8_BAR; PG8_SCHED;
;             PG8_LDA(At, 0, 1); PG8_STAGE(PG8_SB(0, 0), b2, voffB); PG8_STAGE(PG8_SB(0, 1), b2 + hstep, voffB); PG8_STAGE(PG8_SA(0, 0), a2, voffA);
;             PG8_WAIT_V(8); PG8_WAIT_L(0); PG8_BAR; PG8_MMA(1, 0, At, B0); PG8_MMA(1, 1, At, B1); PG8_BAR; PG8_SCHED;
.LBB0_1030:
	s_add_u32 s34, s20, 0x100
	s_addc_u32 s42, s21, 0
	s_mov_b32 s43, -2
	s_add_u32 s20, s16, 0x100
	s_addc_u32 s21, s17, 0
	s_add_i32 s2, s35, 0x100
	s_cmp_eq_u32 s43, 40
	s_cselect_b32 s25, s13, s21
	s_cselect_b32 s24, s12, s20
	s_cselect_b32 s23, s15, s42
	s_cselect_b32 s22, s14, s34
	s_add_i32 s29, s90, 0x100
	v_add_u32_e32 v128, s2, v249
	v_add_u32_e32 v156, s29, v249
	ds_read_b128 v[112:115], v128
	ds_read_b128 v[120:123], v128 offset:1024
	ds_read_b128 v[124:127], v128 offset:2048
	ds_read_b128 v[128:131], v128 offset:3072
	ds_read_b128 v[136:139], v156
	ds_read_b128 v[140:143], v156 offset:1024
	ds_read_b128 v[144:147], v156 offset:2048
	ds_read_b128 v[156:159], v156 offset:3072
	v_lshl_add_u64 v[194:195], s[16:17], 0, v[206:207]
	s_add_i32 m0, s45, 0xc000
	ds_read_b128 v[160:163], v251
	ds_read_b128 v[164:167], v251 offset:1024
	ds_read_b128 v[168:171], v251 offset:2048
	ds_read_b128 v[172:175], v251 offset:3072
	ds_read_b128 v[176:179], v251 offset:4096
	ds_read_b128 v[180:183], v251 offset:5120
	ds_read_b128 v[184:187], v251 offset:6144
	ds_read_b128 v[188:191], v251 offset:7168
	global_load_lds_dwordx4 v[194:195], off
	v_lshl_add_u64 v[194:195], s[16:17], 0, v[204:205]
	s_add_i32 m0, s45, 0xe000
	s_nop 0
	global_load_lds_dwordx4 v[194:195], off
	s_waitcnt vmcnt(8)
	s_waitcnt lgkmcnt(0)
	s_barrier
	s_waitcnt lgkmcnt(0)
	v_mfma_f32_16x16x32_bf16 v[152:155], v[112:115], v[160:163], 0
	v_mfma_f32_16x16x32_bf16 v[148:151], v[124:127], v[160:163], 0
	v_mfma_f32_16x16x32_bf16 v[108:111], v[112:115], v[168:171], 0
	v_mfma_f32_16x16x32_bf16 v[104:107], v[124:127], v[168:171], 0
	v_mfma_f32_16x16x32_bf16 v[92:95], v[112:115], v[176:179], 0
	v_mfma_f32_16x16x32_bf16 v[88:91], v[124:127], v[176:179], 0
	v_mfma_f32_16x16x32_bf16 v[76:79], v[112:115], v[184:187], 0
	v_mfma_f32_16x16x32_bf16 v[72:75], v[124:127], v[184:187], 0
	v_mfma_f32_16x16x32_bf16 v[152:155], v[120:123], v[164:167], v[152:155]
	v_mfma_f32_16x16x32_bf16 v[148:151], v[128:131], v[164:167], v[148:151]
	v_mfma_f32_16x16x32_bf16 v[108:111], v[120:123], v[172:175], v[108:111]
	v_mfma_f32_16x16x32_bf16 v[104:107], v[128:131], v[172:175], v[104:107]
	v_mfma_f32_16x16x32_bf16 v[92:95], v[120:123], v[180:183], v[92:95]
	v_mfma_f32_16x16x32_bf16 v[88:91], v[128:131], v[180:183], v[88:91]
	v_mfma_f32_16x16x32_bf16 v[76:79], v[120:123], v[188:191], v[76:79]
	v_mfma_f32_16x16x32_bf16 v[72:75], v[128:131], v[188:191], v[72:75]
	v_mfma_f32_16x16x32_bf16 v[132:135], v[136:139], v[160:163], 0
	v_mfma_f32_16x16x32_bf16 v[116:119], v[144:147], v[160:163], 0
	v_mfma_f32_16x16x32_bf16 v[100:103], v[136:139], v[168:171], 0
	v_mfma_f32_16x16x32_bf16 v[96:99], v[144:147], v[168:171], 0
	v_mfma_f32_16x16x32_bf16 v[84:87], v[136:139], v[176:179], 0
	v_mfma_f32_16x16x32_bf16 v[80:83], v[144:147], v[176:179], 0
	v_mfma_f32_16x16x32_bf16 v[68:71], v[136:139], v[184:187], 0
	v_mfma_f32_16x16x32_bf16 v[64:67], v[144:147], v[184:187], 0
	v_mfma_f32_16x16x32_bf16 v[132:135], v[140:143], v[164:167], v[132:135]
	v_mfma_f32_16x16x32_bf16 v[116:119], v[156:159], v[164:167], v[116:119]
	v_mfma_f32_16x16x32_bf16 v[100:103], v[140:143], v[172:175], v[100:103]
	v_mfma_f32_16x16x32_bf16 v[96:99], v[156:159], v[172:175], v[96:99]
	v_mfma_f32_16x16x32_bf16 v[84:87], v[140:143], v[180:183], v[84:87]
	v_mfma_f32_16x16x32_bf16 v[80:83], v[156:159], v[180:183], v[80:83]
	v_mfma_f32_16x16x32_bf16 v[68:71], v[140:143], v[188:191], v[68:71]
	v_mfma_f32_16x16x32_bf16 v[64:67], v[156:159], v[188:191], v[64:67]
	s_barrier
	s_add_i32 s2, s2, s44
	v_lshl_add_u64 v[194:195], s[22:23], 0, v[192:193]
	s_mov_b32 m0, s2
	ds_read_b128 v[160:163], v251 offset:16384
	ds_read_b128 v[164:167], v251 offset:17408
	ds_read_b128 v[168:171], v251 offset:18432
	ds_read_b128 v[172:175], v251 offset:19456
	ds_read_b128 v[176:179], v251 offset:20480
	ds_read_b128 v[180:183], v251 offset:21504
	ds_read_b128 v[184:187], v251 offset:22528
	ds_read_b128 v[188:191], v251 offset:23552
	global_load_lds_dwordx4 v[194:195], off
	s_add_i32 m0, s2, 0x2000
	s_add_u32 s16, s22, 0xb0000
	v_lshl_add_u64 v[196:197], s[22:23], 0, v[198:199]
	s_addc_u32 s17, s23, 0
	s_add_i32 s2, s29, s44
	global_load_lds_dwordx4 v[196:197], off
	v_lshl_add_u64 v[208:209], s[16:17], 0, v[192:193]
	s_mov_b32 m0, s2
	v_lshl_add_u64 v[210:211], s[24:25], 0, v[200:201]
	global_load_lds_dwordx4 v[208:209], off
	v_lshl_add_u64 v[208:209], s[16:17], 0, v[198:199]
	s_add_i32 m0, s2, 0x2000
	s_nop 0
	global_load_lds_dwordx4 v[208:209], off
	v_lshl_add_u64 v[208:209], s[24:25], 0, v[202:203]
	s_mov_b32 m0, s45
	s_nop 0
	global_load_lds_dwordx4 v[208:209], off
	s_mov_b32 m0, s46
	s_nop 0
	global_load_lds_dwordx4 v[210:211], off
	s_waitcnt vmcnt(8)
	s_waitcnt lgkmcnt(0)
	s_barrier
; #define PG8_STAGE(bufoff, gbase, voff) do { _Pragma("unroll") for (int _i = 0; _i < 2; ++_i) \
;         __builtin_amdgcn_global_load_lds((const unsigned*)((const char*)(gbase) + (voff)[_i]), (PG8_LAS unsigned*)(lds + (bufoff) + ldsw + _i * 8192), 16, 0, 0); } while (0)
; #define PG8_LDA(dst, b, h) do { _Pragma("unroll") for (int m = 0; m < 4; ++m) _Pragma("unroll") for (int k = 0; k < 2; ++k) dst[m][k] = *(const PG8_LAS bf16x8*)(lds + PG8_SA(b, h) + aoff + m * 2048 + k * 1024); } while (0)
; #define PG8_LDB(dst, b, h) do { _Pragma("unroll") for (int n = 0; n < 2; ++n) _Pragma("unroll") for (int k = 0; k < 2; ++k) dst[n][k] = *(const PG8_LAS bf16x8*)(lds + PG8_SB(b, h) + boff + n * 2048 + k * 1024); } while (0)
; #define PG8_MMA(ai, bj, At, Bt) do { __builtin_amdgcn_s_setprio(1); _Pragma("unroll") for (int m = 0; m < 4; ++m) _Pragma("unroll") for (int n = 0; n < 2; ++n) _Pragma("unroll") for (int k = 0; k < 2; ++k) \
;         acc[ai][bj][m][n] = __builtin_amdgcn_mfma_f32_16x16x32_bf16(Bt[n][k], At[m][k], acc[ai][bj][m][n], 0, 0, 0); __builtin_amdgcn_s_setprio(0); } while (0)
; #define PG8_BAR __builtin_amdgcn_s_barrier()
; template <class Epi, class Sched, bool ALIGN_EPI = false, bool SP2 = false>
; __device__ __forceinline__ void gemm_phase(PG8_LAS unsigned char* lds, const Gemm g, const Sched& S, const Epi& E, int wave_in) {
;     ...
;             PG8_LDB(B0, 0, 0); PG8_LDB(B1, 0, 1); PG8_SCHED; PG8_LDA(At, 0, 0); PG8_STAGE(PG8_SA(1, 1), a1 + hstep, voffA);
;             PG8_WAIT_V(8); PG8_WAIT_L(0); PG8_BAR; PG8_MMA(0, 0, At, B0); PG8_MMA(0, 1, At, B1); PG8_BAR; PG8_SCHED;
;             PG8_LDA(At, 0, 1); PG8_STAGE(PG8_SB(0, 0), b2, voffB); PG8_STAGE(PG8_SB(0, 1), b2 + hstep, voffB); PG8_STAGE(PG8_SA(0, 0), a2, voffA);
;             PG8_WAIT_V(8); PG8_WAIT_L(0); PG8_BAR; PG8_MMA(1, 0, At, B0); PG8_MMA(1, 1, At, B1); PG8_BAR; PG8_SCHED;
;             PG8_LDB(B0, 1, 0); PG8_LDB(B1, 1, 1); PG8_SCHED; PG8_LDA(At, 1, 0); PG8_STAGE(PG8_SA(0, 1), a2 + hstep, voffA);
;             PG8_WAIT_V(8); PG8_WAIT_L(0); PG8_BAR; PG8_MMA(0, 0, At, B0); PG8_MMA(0, 1, At, B1); PG8_BAR; PG8_SCHED;
;             PG8_LDA(At, 1, 1); PG8_STAGE(PG8_SB(1, 0), b3, voffB); PG8_STAGE(PG8_SB(1, 1), b3 + hstep, voffB); PG8_STAGE(PG8_SA(1, 0), a3, voffA);
;             PG8_WAIT_V(8); PG8_WAIT_L(0); PG8_BAR; PG8_MMA(1, 0, At, B0); PG8_MMA(1, 1, At, B1); PG8_BAR; PG8_SCHED;
	s_waitcnt lgkmcnt(0)
	v_mfma_f32_16x16x32_bf16 v[60:63], v[112:115], v[160:163], 0
	v_mfma_f32_16x16x32_bf16 v[56:59], v[124:127], v[160:163], 0
	v_mfma_f32_16x16x32_bf16 v[44:47], v[112:115], v[168:171], 0
	v_mfma_f32_16x16x32_bf16 v[40:43], v[124:127], v[168:171], 0
	v_mfma_f32_16x16x32_bf16 v[28:31], v[112:115], v[176:179], 0
	v_mfma_f32_16x16x32_bf16 v[24:27], v[124:127], v[176:179], 0
	v_mfma_f32_16x16x32_bf16 v[12:15], v[112:115], v[184:187], 0
	v_mfma_f32_16x16x32_bf16 v[8:11], v[124:127], v[184:187], 0
	v_mfma_f32_16x16x32_bf16 v[60:63], v[120:123], v[164:167], v[60:63]
	v_mfma_f32_16x16x32_bf16 v[56:59], v[128:131], v[164:167], v[56:59]
	v_mfma_f32_16x16x32_bf16 v[44:47], v[120:123], v[172:175], v[44:47]
	v_mfma_f32_16x16x32_bf16 v[40:43], v[128:131], v[172:175], v[40:43]
	v_mfma_f32_16x16x32_bf16 v[28:31], v[120:123], v[180:183], v[28:31]
	v_mfma_f32_16x16x32_bf16 v[24:27], v[128:131], v[180:183], v[24:27]
	v_mfma_f32_16x16x32_bf16 v[12:15], v[120:123], v[188:191], v[12:15]
	v_mfma_f32_16x16x32_bf16 v[8:11], v[128:131], v[188:191], v[8:11]
	v_mfma_f32_16x16x32_bf16 v[52:55], v[136:139], v[160:163], 0
	v_mfma_f32_16x16x32_bf16 v[48:51], v[144:147], v[160:163], 0
	v_mfma_f32_16x16x32_bf16 v[36:39], v[136:139], v[168:171], 0
	v_mfma_f32_16x16x32_bf16 v[32:35], v[144:147], v[168:171], 0
	v_mfma_f32_16x16x32_bf16 v[20:23], v[136:139], v[176:179], 0
	v_mfma_f32_16x16x32_bf16 v[16:19], v[144:147], v[176:179], 0
	v_mfma_f32_16x16x32_bf16 v[4:7], v[136:139], v[184:187], 0
	v_mfma_f32_16x16x32_bf16 v[0:3], v[144:147], v[184:187], 0
	v_mfma_f32_16x16x32_bf16 v[52:55], v[140:143], v[164:167], v[52:55]
	v_mfma_f32_16x16x32_bf16 v[48:51], v[156:159], v[164:167], v[48:51]
	v_mfma_f32_16x16x32_bf16 v[36:39], v[140:143], v[172:175], v[36:39]
	v_mfma_f32_16x16x32_bf16 v[32:35], v[156:159], v[172:175], v[32:35]
	v_mfma_f32_16x16x32_bf16 v[20:23], v[140:143], v[180:183], v[20:23]
	v_mfma_f32_16x16x32_bf16 v[16:19], v[156:159], v[180:183], v[16:19]
	v_mfma_f32_16x16x32_bf16 v[4:7], v[140:143], v[188:191], v[4:7]
	v_mfma_f32_16x16x32_bf16 v[0:3], v[156:159], v[188:191], v[0:3]
	s_barrier
	s_add_i32 s2, s65, 0x100
	s_add_i32 s29, s52, 0x100
	v_add_u32_e32 v128, s2, v249
	v_add_u32_e32 v156, s29, v249
	ds_read_b128 v[112:115], v128
	ds_read_b128 v[120:123], v128 offset:1024
	ds_read_b128 v[124:127], v128 offset:2048
	ds_read_b128 v[128:131], v128 offset:3072
	ds_read_b128 v[136:139], v156
	ds_read_b128 v[140:143], v156 offset:1024
	ds_read_b128 v[144:147], v156 offset:2048
	ds_read_b128 v[156:159], v156 offset:3072
	s_add_u32 s16, s24, 0xb0000
	s_addc_u32 s17, s25, 0
	s_mov_b32 m0, s47
	v_lshl_add_u64 v[212:213], s[16:17], 0, v[202:203]
	ds_read_b128 v[160:163], v251 offset:32768
	ds_read_b128 v[164:167], v251 offset:33792
	ds_read_b128 v[168:171], v251 offset:34816
	ds_read_b128 v[172:175], v251 offset:35840
	ds_read_b128 v[176:179], v251 offset:36864
	ds_read_b128 v[180:183], v251 offset:37888
	ds_read_b128 v[184:187], v251 offset:38912
	ds_read_b128 v[188:191], v251 offset:39936
	global_load_lds_dwordx4 v[212:213], off
	v_lshl_add_u64 v[212:213], s[16:17], 0, v[200:201]
	s_mov_b32 m0, s60
	s_nop 0
	global_load_lds_dwordx4 v[212:213], off
	s_waitcnt vmcnt(8)
	s_waitcnt lgkmcnt(0)
	s_barrier
	s_waitcnt lgkmcnt(0)
	v_mfma_f32_16x16x32_bf16 v[152:155], v[112:115], v[160:163], v[152:155]
	v_mfma_f32_16x16x32_bf16 v[148:151], v[124:127], v[160:163], v[148:151]
	v_mfma_f32_16x16x32_bf16 v[108:111], v[112:115], v[168:171], v[108:111]
	v_mfma_f32_16x16x32_bf16 v[104:107], v[124:127], v[168:171], v[104:107]
	v_mfma_f32_16x16x32_bf16 v[92:95], v[112:115], v[176:179], v[92:95]
	v_mfma_f32_16x16x32_bf16 v[88:91], v[124:127], v[176:179], v[88:91]
	v_mfma_f32_16x16x32_bf16 v[76:79], v[112:115], v[184:187], v[76:79]
	v_mfma_f32_16x16x32_bf16 v[72:75], v[124:127], v[184:187], v[72:75]
	v_mfma_f32_16x16x32_bf16 v[152:155], v[120:123], v[164:167], v[152:155]
	v_mfma_f32_16x16x32_bf16 v[148:151], v[128:131], v[164:167], v[148:151]
	v_mfma_f32_16x16x32_bf16 v[108:111], v[120:123], v[172:175], v[108:111]
	v_mfma_f32_16x16x32_bf16 v[104:107], v[128:131], v[172:175], v[104:107]
	v_mfma_f32_16x16x32_bf16 v[92:95], v[120:123], v[180:183], v[92:95]
	v_mfma_f32_16x16x32_bf16 v[88:91], v[128:131], v[180:183], v[88:91]
	v_mfma_f32_16x16x32_bf16 v[76:79], v[120:123], v[188:191], v[76:79]
	v_mfma_f32_16x16x32_bf16 v[72:75], v[128:131], v[188:191], v[72:75]
	v_mfma_f32_16x16x32_bf16 v[132:135], v[136:139], v[160:163], v[132:135]
	v_mfma_f32_16x16x32_bf16 v[116:119], v[144:147], v[160:163], v[116:119]
	v_mfma_f32_16x16x32_bf16 v[100:103], v[136:139], v[168:171], v[100:103]
	v_mfma_f32_16x16x32_bf16 v[96:99], v[144:147], v[168:171], v[96:99]
	v_mfma_f32_16x16x32_bf16 v[84:87], v[136:139], v[176:179], v[84:87]
	v_mfma_f32_16x16x32_bf16 v[80:83], v[144:147], v[176:179], v[80:83]
	v_mfma_f32_16x16x32_bf16 v[68:71], v[136:139], v[184:187], v[68:71]
	v_mfma_f32_16x16x32_bf16 v[64:67], v[144:147], v[184:187], v[64:67]
	v_mfma_f32_16x16x32_bf16 v[132:135], v[140:143], v[164:167], v[132:135]
	v_mfma_f32_16x16x32_bf16 v[116:119], v[156:159], v[164:167], v[116:119]
	v_mfma_f32_16x16x32_bf16 v[100:103], v[140:143], v[172:175], v[100:103]
	v_mfma_f32_16x16x32_bf16 v[96:99], v[156:159], v[172:175], v[96:99]
	v_mfma_f32_16x16x32_bf16 v[84:87], v[140:143], v[180:183], v[84:87]
	v_mfma_f32_16x16x32_bf16 v[80:83], v[156:159], v[180:183], v[80:83]
	v_mfma_f32_16x16x32_bf16 v[68:71], v[140:143], v[188:191], v[68:71]
	v_mfma_f32_16x16x32_bf16 v[64:67], v[156:159], v[188:191], v[64:67]
	s_barrier
; #define PG8_STAGE(bufoff, gbase, voff) do { _Pragma("unroll") for (int _i = 0; _i < 2; ++_i) \
;         __builtin_amdgcn_global_load_lds((const unsigned*)((const char*)(gbase) + (voff)[_i]), (PG8_LAS unsigned*)(lds + (bufoff) + ldsw + _i * 8192), 16, 0, 0); } while (0)
; #define PG8_LDA(dst, b, h) do { _Pragma("unroll") for (int m = 0; m < 4; ++m) _Pragma("unroll") for (int k = 0; k < 2; ++k) dst[m][k] = *(const PG8_LAS bf16x8*)(lds + PG8_SA(b, h) + aoff + m * 2048 + k * 1024); } while (0)
; #define PG8_LDB(dst, b, h) do { _Pragma("unroll") for (int n = 0; n < 2; ++n) _Pragma("unroll") for (int k = 0; k < 2; ++k) dst[n][k] = *(const PG8_LAS bf16x8*)(lds + PG8_SB(b, h) + boff + n * 2048 + k * 1024); } while (0)
; #define PG8_WAIT_V(n) asm volatile("s_waitcnt vmcnt(" #n ")" ::: "memory")
; #define PG8_WAIT_L(n) asm volatile("s_waitcnt lgkmcnt(" #n ")" ::: "memory")
; template <class Epi, class Sched, bool ALIGN_EPI = false, bool SP2 = false>
; __device__ __forceinline__ void gemm_phase(PG8_LAS unsigned char* lds, const Gemm g, const Sched& S, const Epi& E, int wave_in) {
;     ...
;         for (int t = 0; t < nt; t += 2) {
;             const bool last = (t == nt - 2);
;             const char* a1 = cA + (size_t)(t + 1) * kstep;
;             const char* a2 = last ? nA : cA + (size_t)(t + 2) * kstep; const char* b2 = last ? nB : cB + (size_t)(t + 2) * kstep;
;     ...
;             PG8_LDB(B0, 0, 0); PG8_LDB(B1, 0, 1); PG8_SCHED; PG8_LDA(At, 0, 0); PG8_STAGE(PG8_SA(1, 1), a1 + hstep, voffA);
;             PG8_WAIT_V(8); PG8_WAIT_L(0); PG8_BAR; PG8_MMA(0, 0, At, B0); PG8_MMA(0, 1, At, B1); PG8_BAR; PG8_SCHED;
;             PG8_LDA(At, 0, 1); PG8_STAGE(PG8_SB(0, 0), b2, voffB); PG8_STAGE(PG8_SB(0, 1), b2 + hstep, voffB); PG8_STAGE(PG8_SA(0, 0), a2, voffA);
;             PG8_WAIT_V(8); PG8_WAIT_L(0); PG8_BAR; PG8_MMA(1, 0, At, B0); PG8_MMA(1, 1, At, B1); PG8_BAR; PG8_SCHED;
;             PG8_LDB(B0, 1, 0); PG8_LDB(B1, 1, 1); PG8_SCHED; PG8_LDA(At, 1, 0); PG8_STAGE(PG8_SA(0, 1), a2 + hstep, voffA);
;             PG8_WAIT_V(8); PG8_WAIT_L(0); PG8_BAR; PG8_MMA(0, 0, At, B0); PG8_MMA(0, 1, At, B1); PG8_BAR; PG8_SCHED;
;             PG8_LDA(At, 1, 1); PG8_STAGE(PG8_SB(1, 0), b3, voffB); PG8_STAGE(PG8_SB(1, 1), b3 + hstep, voffB); PG8_STAGE(PG8_SA(1, 0), a3, voffA);
;             PG8_WAIT_V(8); PG8_WAIT_L(0); PG8_BAR; PG8_MMA(1, 0, At, B0); PG8_MMA(1, 1, At, B1); PG8_BAR; PG8_SCHED;
	s_add_i32 s2, s2, s44
	v_lshl_add_u64 v[194:195], v[194:195], 0, s[88:89]
	s_mov_b32 m0, s2
	ds_read_b128 v[160:163], v251 offset:49152
	ds_read_b128 v[164:167], v251 offset:50176
	ds_read_b128 v[168:171], v251 offset:51200
	ds_read_b128 v[172:175], v251 offset:52224
	ds_read_b128 v[176:179], v251 offset:53248
	ds_read_b128 v[180:183], v251 offset:54272
	ds_read_b128 v[184:187], v251 offset:55296
	ds_read_b128 v[188:191], v251 offset:56320
	global_load_lds_dwordx4 v[194:195], off
	s_add_i32 m0, s2, 0x2000
	s_add_u32 s16, s22, 0xb0080
	v_lshl_add_u64 v[194:195], v[196:197], 0, s[88:89]
	s_addc_u32 s17, s23, 0
	s_add_i32 s2, s29, s44
	global_load_lds_dwordx4 v[194:195], off
	v_lshl_add_u64 v[194:195], s[16:17], 0, v[192:193]
	s_mov_b32 m0, s2
	s_nop 0
	global_load_lds_dwordx4 v[194:195], off
	v_lshl_add_u64 v[194:195], s[16:17], 0, v[198:199]
	s_add_i32 m0, s2, 0x2000
	s_nop 0
	global_load_lds_dwordx4 v[194:195], off
	v_lshl_add_u64 v[194:195], v[208:209], 0, s[88:89]
	s_mov_b32 m0, s62
	s_nop 0
	global_load_lds_dwordx4 v[194:195], off
	v_lshl_add_u64 v[194:195], v[210:211], 0, s[88:89]
	s_mov_b32 m0, s63
	s_nop 0
	global_load_lds_dwordx4 v[194:195], off
	s_waitcnt vmcnt(8)
	s_waitcnt lgkmcnt(0)
	s_barrier
	s_waitcnt lgkmcnt(0)
	v_mfma_f32_16x16x32_bf16 v[60:63], v[112:115], v[160:163], v[60:63]
	v_mfma_f32_16x16x32_bf16 v[56:59], v[124:127], v[160:163], v[56:59]
	v_mfma_f32_16x16x32_bf16 v[44:47], v[112:115], v[168:171], v[44:47]
	v_mfma_f32_16x16x32_bf16 v[40:43], v[124:127], v[168:171], v[40:43]
	v_mfma_f32_16x16x32_bf16 v[28:31], v[112:115], v[176:179], v[28:31]
	v_mfma_f32_16x16x32_bf16 v[24:27], v[124:127], v[176:179], v[24:27]
	v_mfma_f32_16x16x32_bf16 v[12:15], v[112:115], v[184:187], v[12:15]
	v_mfma_f32_16x16x32_bf16 v[8:11], v[124:127], v[184:187], v[8:11]
	v_mfma_f32_16x16x32_bf16 v[60:63], v[120:123], v[164:167], v[60:63]
	v_mfma_f32_16x16x32_bf16 v[56:59], v[128:131], v[164:167], v[56:59]
	v_mfma_f32_16x16x32_bf16 v[44:47], v[120:123], v[172:175], v[44:47]
	v_mfma_f32_16x16x32_bf16 v[40:43], v[128:131], v[172:175], v[40:43]
	v_mfma_f32_16x16x32_bf16 v[28:31], v[120:123], v[180:183], v[28:31]
	v_mfma_f32_16x16x32_bf16 v[24:27], v[128:131], v[180:183], v[24:27]
	v_mfma_f32_16x16x32_bf16 v[12:15], v[120:123], v[188:191], v[12:15]
	v_mfma_f32_16x16x32_bf16 v[8:11], v[128:131], v[188:191], v[8:11]
	v_mfma_f32_16x16x32_bf16 v[52:55], v[136:139], v[160:163], v[52:55]
	v_mfma_f32_16x16x32_bf16 v[48:51], v[144:147], v[160:163], v[48:51]
	v_mfma_f32_16x16x32_bf16 v[36:39], v[136:139], v[168:171], v[36:39]
	v_mfma_f32_16x16x32_bf16 v[32:35], v[144:147], v[168:171], v[32:35]
	v_mfma_f32_16x16x32_bf16 v[20:23], v[136:139], v[176:179], v[20:23]
	v_mfma_f32_16x16x32_bf16 v[16:19], v[144:147], v[176:179], v[16:19]
	v_mfma_f32_16x16x32_bf16 v[4:7], v[136:139], v[184:187], v[4:7]
	v_mfma_f32_16x16x32_bf16 v[0:3], v[144:147], v[184:187], v[0:3]
	v_mfma_f32_16x16x32_bf16 v[52:55], v[140:143], v[164:167], v[52:55]
	v_mfma_f32_16x16x32_bf16 v[48:51], v[156:159], v[164:167], v[48:51]
	v_mfma_f32_16x16x32_bf16 v[36:39], v[140:143], v[172:175], v[36:39]
	v_mfma_f32_16x16x32_bf16 v[32:35], v[156:159], v[172:175], v[32:35]
	v_mfma_f32_16x16x32_bf16 v[20:23], v[140:143], v[180:183], v[20:23]
	v_mfma_f32_16x16x32_bf16 v[16:19], v[156:159], v[180:183], v[16:19]
	v_mfma_f32_16x16x32_bf16 v[4:7], v[140:143], v[188:191], v[4:7]
	v_mfma_f32_16x16x32_bf16 v[0:3], v[156:159], v[188:191], v[0:3]
	s_barrier
	s_add_i32 s43, s43, 2
	s_add_u32 s34, s34, 0x100
	s_addc_u32 s42, s42, 0
	s_cmp_gt_u32 s43, 41
	s_mov_b64 s[16:17], s[20:21]
	s_cbranch_scc1 .Lkexit_7
.LBB0_1031:
	s_add_u32 s20, s16, 0x100
	s_addc_u32 s21, s17, 0
	s_add_i32 s2, s35, 0x100
	s_cmp_eq_u32 s43, 40
	s_cselect_b32 s25, s13, s21
	s_cselect_b32 s24, s12, s20
	s_cselect_b32 s23, s15, s42
	s_cselect_b32 s22, s14, s34
	s_add_i32 s29, s90, 0x100
	v_add_u32_e32 v128, s2, v249
	v_add_u32_e32 v156, s29, v249
	ds_read_b128 v[112:115], v128
	ds_read_b128 v[120:123], v128 offset:1024
	ds_read_b128 v[124:127], v128 offset:2048
	ds_read_b128 v[128:131], v128 offset:3072
	ds_read_b128 v[136:139], v156
	ds_read_b128 v[140:143], v156 offset:1024
	ds_read_b128 v[144:147], v156 offset:2048
	ds_read_b128 v[156:159], v156 offset:3072
	v_lshl_add_u64 v[194:195], s[16:17], 0, v[206:207]
	s_add_i32 m0, s45, 0xc000
	ds_read_b128 v[160:163], v251
	ds_read_b128 v[164:167], v251 offset:1024
	ds_read_b128 v[168:171], v251 offset:2048
	ds_read_b128 v[172:175], v251 offset:3072
	ds_read_b128 v[176:179], v251 offset:4096
	ds_read_b128 v[180:183], v251 offset:5120
	ds_read_b128 v[184:187], v251 offset:6144
	ds_read_b128 v[188:191], v251 offset:7168
	global_load_lds_dwordx4 v[194:195], off
	v_lshl_add_u64 v[194:195], s[16:17], 0, v[204:205]
	s_add_i32 m0, s45, 0xe000
	s_nop 0
	global_load_lds_dwordx4 v[194:195], off
	s_waitcnt vmcnt(8)
	s_waitcnt lgkmcnt(0)
	s_barrier
; #define PG8_STAGE(bufoff, gbase, voff) do { _Pragma("unroll") for (int _i = 0; _i < 2; ++_i) \
;         __builtin_amdgcn_global_load_lds((const unsigned*)((const char*)(gbase) + (voff)[_i]), (PG8_LAS unsigned*)(lds + (bufoff) + ldsw + _i * 8192), 16, 0, 0); } while (0)
; #define PG8_LDA(dst, b, h) do { _Pragma("unroll") for (int m = 0; m < 4; ++m) _Pragma("unroll") for (int k = 0; k < 2; ++k) dst[m][k] = *(const PG8_LAS bf16x8*)(lds + PG8_SA(b, h) + aoff + m * 2048 + k * 1024); } while (0)
; #define PG8_LDB(dst, b, h) do { _Pragma("unroll") for (int n = 0; n < 2; ++n) _Pragma("unroll") for (int k = 0; k < 2; ++k) dst[n][k] = *(const PG8_LAS bf16x8*)(lds + PG8_SB(b, h) + boff + n * 2048 + k * 1024); } while (0)
; #define PG8_MMA(ai, bj, At, Bt) do { __builtin_amdgcn_s_setprio(1); _Pragma("unroll") for (int m = 0; m < 4; ++m) _Pragma("unroll") for (int n = 0; n < 2; ++n) _Pragma("unroll") for (int k = 0; k < 2; ++k) \
;         acc[ai][bj][m][n] = __builtin_amdgcn_mfma_f32_16x16x32_bf16(Bt[n][k], At[m][k], acc[ai][bj][m][n], 0, 0, 0); __builtin_amdgcn_s_setprio(0); } while (0)
; #define PG8_BAR __builtin_amdgcn_s_barrier()
; template <class Epi, class Sched, bool ALIGN_EPI = false, bool SP2 = false>
; __device__ __forceinline__ void gemm_phase(PG8_LAS unsigned char* lds, const Gemm g, const Sched& S, const Epi& E, int wave_in) {
;     ...
;             PG8_LDB(B0, 0, 0); PG8_LDB(B1, 0, 1); PG8_SCHED; PG8_LDA(At, 0, 0); PG8_STAGE(PG8_SA(1, 1), a1 + hstep, voffA);
;             PG8_WAIT_V(8); PG8_WAIT_L(0); PG8_BAR; PG8_MMA(0, 0, At, B0); PG8_MMA(0, 1, At, B1); PG8_BAR; PG8_SCHED;
;             PG8_LDA(At, 0, 1); PG8_STAGE(PG8_SB(0, 0), b2, voffB); PG8_STAGE(PG8_SB(0, 1), b2 + hstep, voffB); PG8_STAGE(PG8_SA(0, 0), a2, voffA);
;             PG8_WAIT_V(8); PG8_WAIT_L(0); PG8_BAR; PG8_MMA(1, 0, At, B0); PG8_MMA(1, 1, At, B1); PG8_BAR; PG8_SCHED;
;             PG8_LDB(B0, 1, 0); PG8_LDB(B1, 1, 1); PG8_SCHED; PG8_LDA(At, 1, 0); PG8_STAGE(PG8_SA(0, 1), a2 + hstep, voffA);
;             PG8_WAIT_V(8); PG8_WAIT_L(0); PG8_BAR; PG8_MMA(0, 0, At, B0); PG8_MMA(0, 1, At, B1); PG8_BAR; PG8_SCHED;
;             PG8_LDA(At, 1, 1); PG8_STAGE(PG8_SB(1, 0), b3, voffB); PG8_STAGE(PG8_SB(1, 1), b3 + hstep, voffB); PG8_STAGE(PG8_SA(1, 0), a3, voffA);
;             PG8_WAIT_V(8); PG8_WAIT_L(0); PG8_BAR; PG8_MMA(1, 0, At, B0); PG8_MMA(1, 1, At, B1); PG8_BAR; PG8_SCHED;
	s_waitcnt lgkmcnt(0)
	v_mfma_f32_16x16x32_bf16 v[152:155], v[112:115], v[160:163], v[152:155]
	v_mfma_f32_16x16x32_bf16 v[148:151], v[124:127], v[160:163], v[148:151]
	v_mfma_f32_16x16x32_bf16 v[108:111], v[112:115], v[168:171], v[108:111]
	v_mfma_f32_16x16x32_bf16 v[104:107], v[124:127], v[168:171], v[104:107]
	v_mfma_f32_16x16x32_bf16 v[92:95], v[112:115], v[176:179], v[92:95]
	v_mfma_f32_16x16x32_bf16 v[88:91], v[124:127], v[176:179], v[88:91]
	v_mfma_f32_16x16x32_bf16 v[76:79], v[112:115], v[184:187], v[76:79]
	v_mfma_f32_16x16x32_bf16 v[72:75], v[124:127], v[184:187], v[72:75]
	v_mfma_f32_16x16x32_bf16 v[152:155], v[120:123], v[164:167], v[152:155]
	v_mfma_f32_16x16x32_bf16 v[148:151], v[128:131], v[164:167], v[148:151]
	v_mfma_f32_16x16x32_bf16 v[108:111], v[120:123], v[172:175], v[108:111]
	v_mfma_f32_16x16x32_bf16 v[104:107], v[128:131], v[172:175], v[104:107]
	v_mfma_f32_16x16x32_bf16 v[92:95], v[120:123], v[180:183], v[92:95]
	v_mfma_f32_16x16x32_bf16 v[88:91], v[128:131], v[180:183], v[88:91]
	v_mfma_f32_16x16x32_bf16 v[76:79], v[120:123], v[188:191], v[76:79]
	v_mfma_f32_16x16x32_bf16 v[72:75], v[128:131], v[188:191], v[72:75]
	v_mfma_f32_16x16x32_bf16 v[132:135], v[136:139], v[160:163], v[132:135]
	v_mfma_f32_16x16x32_bf16 v[116:119], v[144:147], v[160:163], v[116:119]
	v_mfma_f32_16x16x32_bf16 v[100:103], v[136:139], v[168:171], v[100:103]
	v_mfma_f32_16x16x32_bf16 v[96:99], v[144:147], v[168:171], v[96:99]
	v_mfma_f32_16x16x32_bf16 v[84:87], v[136:139], v[176:179], v[84:87]
	v_mfma_f32_16x16x32_bf16 v[80:83], v[144:147], v[176:179], v[80:83]
	v_mfma_f32_16x16x32_bf16 v[68:71], v[136:139], v[184:187], v[68:71]
	v_mfma_f32_16x16x32_bf16 v[64:67], v[144:147], v[184:187], v[64:67]
	v_mfma_f32_16x16x32_bf16 v[132:135], v[140:143], v[164:167], v[132:135]
	v_mfma_f32_16x16x32_bf16 v[116:119], v[156:159], v[164:167], v[116:119]
	v_mfma_f32_16x16x32_bf16 v[100:103], v[140:143], v[172:175], v[100:103]
	v_mfma_f32_16x16x32_bf16 v[96:99], v[156:159], v[172:175], v[96:99]
	v_mfma_f32_16x16x32_bf16 v[84:87], v[140:143], v[180:183], v[84:87]
	v_mfma_f32_16x16x32_bf16 v[80:83], v[156:159], v[180:183], v[80:83]
	v_mfma_f32_16x16x32_bf16 v[68:71], v[140:143], v[188:191], v[68:71]
	v_mfma_f32_16x16x32_bf16 v[64:67], v[156:159], v[188:191], v[64:67]
	s_barrier
	s_add_i32 s2, s2, s44
	v_lshl_add_u64 v[194:195], s[22:23], 0, v[192:193]
	s_mov_b32 m0, s2
	ds_read_b128 v[160:163], v251 offset:16384
	ds_read_b128 v[164:167], v251 offset:17408
	ds_read_b128 v[168:171], v251 offset:18432
	ds_read_b128 v[172:175], v251 offset:19456
	ds_read_b128 v[176:179], v251 offset:20480
	ds_read_b128 v[180:183], v251 offset:21504
	ds_read_b128 v[184:187], v251 offset:22528
	ds_read_b128 v[188:191], v251 offset:23552
	global_load_lds_dwordx4 v[194:195], off
	s_add_i32 m0, s2, 0x2000
	s_add_u32 s16, s22, 0xb0000
	v_lshl_add_u64 v[196:197], s[22:23], 0, v[198:199]
	s_addc_u32 s17, s23, 0
	s_add_i32 s2, s29, s44
	global_load_lds_dwordx4 v[196:197], off
	v_lshl_add_u64 v[208:209], s[16:17], 0, v[192:193]
	s_mov_b32 m0, s2
	v_lshl_add_u64 v[210:211], s[24:25], 0, v[200:201]
	global_load_lds_dwordx4 v[208:209], off
	v_lshl_add_u64 v[208:209], s[16:17], 0, v[198:199]
	s_add_i32 m0, s2, 0x2000
	s_nop 0
	global_load_lds_dwordx4 v[208:209], off
	v_lshl_add_u64 v[208:209], s[24:25], 0, v[202:203]
	s_mov_b32 m0, s45
	s_nop 0
	global_load_lds_dwordx4 v[208:209], off
	s_mov_b32 m0, s46
	s_nop 0
	global_load_lds_dwordx4 v[210:211], off
	s_waitcnt vmcnt(8)
	s_waitcnt lgkmcnt(0)
	s_barrier
	s_waitcnt lgkmcnt(0)
	v_mfma_f32_16x16x32_bf16 v[60:63], v[112:115], v[160:163], v[60:63]
	v_mfma_f32_16x16x32_bf16 v[56:59], v[124:127], v[160:163], v[56:59]
	v_mfma_f32_16x16x32_bf16 v[44:47], v[112:115], v[168:171], v[44:47]
	v_mfma_f32_16x16x32_bf16 v[40:43], v[124:127], v[168:171], v[40:43]
	v_mfma_f32_16x16x32_bf16 v[28:31], v[112:115], v[176:179], v[28:31]
	v_mfma_f32_16x16x32_bf16 v[24:27], v[124:127], v[176:179], v[24:27]
	v_mfma_f32_16x16x32_bf16 v[12:15], v[112:115], v[184:187], v[12:15]
	v_mfma_f32_16x16x32_bf16 v[8:11], v[124:127], v[184:187], v[8:11]
	v_mfma_f32_16x16x32_bf16 v[60:63], v[120:123], v[164:167], v[60:63]
	v_mfma_f32_16x16x32_bf16 v[56:59], v[128:131], v[164:167], v[56:59]
	v_mfma_f32_16x16x32_bf16 v[44:47], v[120:123], v[172:175], v[44:47]
	v_mfma_f32_16x16x32_bf16 v[40:43], v[128:131], v[172:175], v[40:43]
	v_mfma_f32_16x16x32_bf16 v[28:31], v[120:123], v[180:183], v[28:31]
	v_mfma_f32_16x16x32_bf16 v[24:27], v[128:131], v[180:183], v[24:27]
	v_mfma_f32_16x16x32_bf16 v[12:15], v[120:123], v[188:191], v[12:15]
	v_mfma_f32_16x16x32_bf16 v[8:11], v[128:131], v[188:191], v[8:11]
	v_mfma_f32_16x16x32_bf16 v[52:55], v[136:139], v[160:163], v[52:55]
	v_mfma_f32_16x16x32_bf16 v[48:51], v[144:147], v[160:163], v[48:51]
	v_mfma_f32_16x16x32_bf16 v[36:39], v[136:139], v[168:171], v[36:39]
	v_mfma_f32_16x16x32_bf16 v[32:35], v[144:147], v[168:171], v[32:35]
	v_mfma_f32_16x16x32_bf16 v[20:23], v[136:139], v[176:179], v[20:23]
	v_mfma_f32_16x16x32_bf16 v[16:19], v[144:147], v[176:179], v[16:19]
	v_mfma_f32_16x16x32_bf16 v[4:7], v[136:139], v[184:187], v[4:7]
	v_mfma_f32_16x16x32_bf16 v[0:3], v[144:147], v[184:187], v[0:3]
	v_mfma_f32_16x16x32_bf16 v[52:55], v[140:143], v[164:167], v[52:55]
	v_mfma_f32_16x16x32_bf16 v[48:51], v[156:159], v[164:167], v[48:51]
	v_mfma_f32_16x16x32_bf16 v[36:39], v[140:143], v[172:175], v[36:39]
	v_mfma_f32_16x16x32_bf16 v[32:35], v[156:159], v[172:175], v[32:35]
	v_mfma_f32_16x16x32_bf16 v[20:23], v[140:143], v[180:183], v[20:23]
	v_mfma_f32_16x16x32_bf16 v[16:19], v[156:159], v[180:183], v[16:19]
	v_mfma_f32_16x16x32_bf16 v[4:7], v[140:143], v[188:191], v[4:7]
	v_mfma_f32_16x16x32_bf16 v[0:3], v[156:159], v[188:191], v[0:3]
	s_barrier
; #define PG8_STAGE(bufoff, gbase, voff) do { _Pragma("unroll") for (int _i = 0; _i < 2; ++_i) \
;         __builtin_amdgcn_global_load_lds((const unsigned*)((const char*)(gbase) + (voff)[_i]), (PG8_LAS unsigned*)(lds + (bufoff) + ldsw + _i * 8192), 16, 0, 0); } while (0)
; #define PG8_LDA(dst, b, h) do { _Pragma("unroll") for (int m = 0; m < 4; ++m) _Pragma("unroll") for (int k = 0; k < 2; ++k) dst[m][k] = *(const PG8_LAS bf16x8*)(lds + PG8_SA(b, h) + aoff + m * 2048 + k * 1024); } while (0)
; #define PG8_LDB(dst, b, h) do { _Pragma("unroll") for (int n = 0; n < 2; ++n) _Pragma("unroll") for (int k = 0; k < 2; ++k) dst[n][k] = *(const PG8_LAS bf16x8*)(lds + PG8_SB(b, h) + boff + n * 2048 + k * 1024); } while (0)
; #define PG8_MMA(ai, bj, At, Bt) do { __builtin_amdgcn_s_setprio(1); _Pragma("unroll") for (int m = 0; m < 4; ++m) _Pragma("unroll") for (int n = 0; n < 2; ++n) _Pragma("unroll") for (int k = 0; k < 2; ++k) \
;         acc[ai][bj][m][n] = __builtin_amdgcn_mfma_f32_16x16x32_bf16(Bt[n][k], At[m][k], acc[ai][bj][m][n], 0, 0, 0); __builtin_amdgcn_s_setprio(0); } while (0)
; #define PG8_WAIT_V(n) asm volatile("s_waitcnt vmcnt(" #n ")" ::: "memory")
; #define PG8_WAIT_L(n) asm volatile("s_waitcnt lgkmcnt(" #n ")" ::: "memory")
; #define PG8_BAR __builtin_amdgcn_s_barrier()
; #define PG8_SCHED __builtin_amdgcn_sched_barrier(0)
; template <class Epi, class Sched, bool ALIGN_EPI = false, bool SP2 = false>
; __device__ __forceinline__ void gemm_phase(PG8_LAS unsigned char* lds, const Gemm g, const Sched& S, const Epi& E, int wave_in) {
;     ...
;         for (int t = 0; t < nt; t += 2) {
;     ...
;             PG8_LDA(At, 0, 1); PG8_STAGE(PG8_SB(0, 0), b2, voffB); PG8_STAGE(PG8_SB(0, 1), b2 + hstep, voffB); PG8_STAGE(PG8_SA(0, 0), a2, voffA);
;             PG8_WAIT_V(8); PG8_WAIT_L(0); PG8_BAR; PG8_MMA(1, 0, At, B0); PG8_MMA(1, 1, At, B1); PG8_BAR; PG8_SCHED;
;             PG8_LDB(B0, 1, 0); PG8_LDB(B1, 1, 1); PG8_SCHED; PG8_LDA(At, 1, 0); PG8_STAGE(PG8_SA(0, 1), a2 + hstep, voffA);
;             PG8_WAIT_V(8); PG8_WAIT_L(0); PG8_BAR; PG8_MMA(0, 0, At, B0); PG8_MMA(0, 1, At, B1); PG8_BAR; PG8_SCHED;
;             PG8_LDA(At, 1, 1); PG8_STAGE(PG8_SB(1, 0), b3, voffB); PG8_STAGE(PG8_SB(1, 1), b3 + hstep, voffB); PG8_STAGE(PG8_SA(1, 0), a3, voffA);
;             PG8_WAIT_V(8); PG8_WAIT_L(0); PG8_BAR; PG8_MMA(1, 0, At, B0); PG8_MMA(1, 1, At, B1); PG8_BAR; PG8_SCHED;
	s_add_i32 s2, s65, 0x100
	s_add_i32 s29, s52, 0x100
	v_add_u32_e32 v128, s2, v249
	v_add_u32_e32 v156, s29, v249
	ds_read_b128 v[112:115], v128
	ds_read_b128 v[120:123], v128 offset:1024
	ds_read_b128 v[124:127], v128 offset:2048
	ds_read_b128 v[128:131], v128 offset:3072
	ds_read_b128 v[136:139], v156
	ds_read_b128 v[140:143], v156 offset:1024
	ds_read_b128 v[144:147], v156 offset:2048
	ds_read_b128 v[156:159], v156 offset:3072
	s_add_u32 s16, s24, 0xb0000
	s_addc_u32 s17, s25, 0
	s_mov_b32 m0, s47
	v_lshl_add_u64 v[212:213], s[16:17], 0, v[202:203]
	ds_read_b128 v[160:163], v251 offset:32768
	ds_read_b128 v[164:167], v251 offset:33792
	ds_read_b128 v[168:171], v251 offset:34816
	ds_read_b128 v[172:175], v251 offset:35840
	ds_read_b128 v[176:179], v251 offset:36864
	ds_read_b128 v[180:183], v251 offset:37888
	ds_read_b128 v[184:187], v251 offset:38912
	ds_read_b128 v[188:191], v251 offset:39936
	global_load_lds_dwordx4 v[212:213], off
	v_lshl_add_u64 v[212:213], s[16:17], 0, v[200:201]
	s_mov_b32 m0, s60
	s_nop 0
	global_load_lds_dwordx4 v[212:213], off
	s_waitcnt vmcnt(8)
	s_waitcnt lgkmcnt(0)
	s_barrier
	s_waitcnt lgkmcnt(0)
	v_mfma_f32_16x16x32_bf16 v[152:155], v[112:115], v[160:163], v[152:155]
	v_mfma_f32_16x16x32_bf16 v[148:151], v[124:127], v[160:163], v[148:151]
	v_mfma_f32_16x16x32_bf16 v[108:111], v[112:115], v[168:171], v[108:111]
	v_mfma_f32_16x16x32_bf16 v[104:107], v[124:127], v[168:171], v[104:107]
	v_mfma_f32_16x16x32_bf16 v[92:95], v[112:115], v[176:179], v[92:95]
	v_mfma_f32_16x16x32_bf16 v[88:91], v[124:127], v[176:179], v[88:91]
	v_mfma_f32_16x16x32_bf16 v[76:79], v[112:115], v[184:187], v[76:79]
	v_mfma_f32_16x16x32_bf16 v[72:75], v[124:127], v[184:187], v[72:75]
	v_mfma_f32_16x16x32_bf16 v[152:155], v[120:123], v[164:167], v[152:155]
	v_mfma_f32_16x16x32_bf16 v[148:151], v[128:131], v[164:167], v[148:151]
	v_mfma_f32_16x16x32_bf16 v[108:111], v[120:123], v[172:175], v[108:111]
	v_mfma_f32_16x16x32_bf16 v[104:107], v[128:131], v[172:175], v[104:107]
	v_mfma_f32_16x16x32_bf16 v[92:95], v[120:123], v[180:183], v[92:95]
	v_mfma_f32_16x16x32_bf16 v[88:91], v[128:131], v[180:183], v[88:91]
	v_mfma_f32_16x16x32_bf16 v[76:79], v[120:123], v[188:191], v[76:79]
	v_mfma_f32_16x16x32_bf16 v[72:75], v[128:131], v[188:191], v[72:75]
	v_mfma_f32_16x16x32_bf16 v[132:135], v[136:139], v[160:163], v[132:135]
	v_mfma_f32_16x16x32_bf16 v[116:119], v[144:147], v[160:163], v[116:119]
	v_mfma_f32_16x16x32_bf16 v[100:103], v[136:139], v[168:171], v[100:103]
	v_mfma_f32_16x16x32_bf16 v[96:99], v[144:147], v[168:171], v[96:99]
	v_mfma_f32_16x16x32_bf16 v[84:87], v[136:139], v[176:179], v[84:87]
	v_mfma_f32_16x16x32_bf16 v[80:83], v[144:147], v[176:179], v[80:83]
	v_mfma_f32_16x16x32_bf16 v[68:71], v[136:139], v[184:187], v[68:71]
	v_mfma_f32_16x16x32_bf16 v[64:67], v[144:147], v[184:187], v[64:67]
	v_mfma_f32_16x16x32_bf16 v[132:135], v[140:143], v[164:167], v[132:135]
	v_mfma_f32_16x16x32_bf16 v[116:119], v[156:159], v[164:167], v[116:119]
	v_mfma_f32_16x16x32_bf16 v[100:103], v[140:143], v[172:175], v[100:103]
	v_mfma_f32_16x16x32_bf16 v[96:99], v[156:159], v[172:175], v[96:99]
	v_mfma_f32_16x16x32_bf16 v[84:87], v[140:143], v[180:183], v[84:87]
	v_mfma_f32_16x16x32_bf16 v[80:83], v[156:159], v[180:183], v[80:83]
	v_mfma_f32_16x16x32_bf16 v[68:71], v[140:143], v[188:191], v[68:71]
	v_mfma_f32_16x16x32_bf16 v[64:67], v[156:159], v[188:191], v[64:67]
	s_barrier
	s_add_i32 s2, s2, s44
	v_lshl_add_u64 v[194:195], v[194:195], 0, s[88:89]
	s_mov_b32 m0, s2
	ds_read_b128 v[160:163], v251 offset:49152
	ds_read_b128 v[164:167], v251 offset:50176
	ds_read_b128 v[168:171], v251 offset:51200
	ds_read_b128 v[172:175], v251 offset:52224
	ds_read_b128 v[176:179], v251 offset:53248
	ds_read_b128 v[180:183], v251 offset:54272
	ds_read_b128 v[184:187], v251 offset:55296
	ds_read_b128 v[188:191], v251 offset:56320
	global_load_lds_dwordx4 v[194:195], off
	s_add_i32 m0, s2, 0x2000
	s_add_u32 s16, s22, 0xb0080
	v_lshl_add_u64 v[194:195], v[196:197], 0, s[88:89]
	s_addc_u32 s17, s23, 0
	s_add_i32 s2, s29, s44
	global_load_lds_dwordx4 v[194:195], off
	v_lshl_add_u64 v[194:195], s[16:17], 0, v[192:193]
	s_mov_b32 m0, s2
	s_nop 0
	global_load_lds_dwordx4 v[194:195], off
	v_lshl_add_u64 v[194:195], s[16:17], 0, v[198:199]
	s_add_i32 m0, s2, 0x2000
	s_nop 0
	global_load_lds_dwordx4 v[194:195], off
	v_lshl_add_u64 v[194:195], v[208:209], 0, s[88:89]
	s_mov_b32 m0, s62
	s_nop 0
	global_load_lds_dwordx4 v[194:195], off
	v_lshl_add_u64 v[194:195], v[210:211], 0, s[88:89]
	s_mov_b32 m0, s63
	s_nop 0
	global_load_lds_dwordx4 v[194:195], off
	s_waitcnt vmcnt(8)
	s_waitcnt lgkmcnt(0)
	s_barrier
	s_waitcnt lgkmcnt(0)
	v_mfma_f32_16x16x32_bf16 v[60:63], v[112:115], v[160:163], v[60:63]
	v_mfma_f32_16x16x32_bf16 v[56:59], v[124:127], v[160:163], v[56:59]
	v_mfma_f32_16x16x32_bf16 v[44:47], v[112:115], v[168:171], v[44:47]
	v_mfma_f32_16x16x32_bf16 v[40:43], v[124:127], v[168:171], v[40:43]
	v_mfma_f32_16x16x32_bf16 v[28:31], v[112:115], v[176:179], v[28:31]
	v_mfma_f32_16x16x32_bf16 v[24:27], v[124:127], v[176:179], v[24:27]
	v_mfma_f32_16x16x32_bf16 v[12:15], v[112:115], v[184:187], v[12:15]
	v_mfma_f32_16x16x32_bf16 v[8:11], v[124:127], v[184:187], v[8:11]
	v_mfma_f32_16x16x32_bf16 v[60:63], v[120:123], v[164:167], v[60:63]
	v_mfma_f32_16x16x32_bf16 v[56:59], v[128:131], v[164:167], v[56:59]
	v_mfma_f32_16x16x32_bf16 v[44:47], v[120:123], v[172:175], v[44:47]
	v_mfma_f32_16x16x32_bf16 v[40:43], v[128:131], v[172:175], v[40:43]
	v_mfma_f32_16x16x32_bf16 v[28:31], v[120:123], v[180:183], v[28:31]
	v_mfma_f32_16x16x32_bf16 v[24:27], v[128:131], v[180:183], v[24:27]
	v_mfma_f32_16x16x32_bf16 v[12:15], v[120:123], v[188:191], v[12:15]
	v_mfma_f32_16x16x32_bf16 v[8:11], v[128:131], v[188:191], v[8:11]
	v_mfma_f32_16x16x32_bf16 v[52:55], v[136:139], v[160:163], v[52:55]
	v_mfma_f32_16x16x32_bf16 v[48:51], v[144:147], v[160:163], v[48:51]
	v_mfma_f32_16x16x32_bf16 v[36:39], v[136:139], v[168:171], v[36:39]
	v_mfma_f32_16x16x32_bf16 v[32:35], v[144:147], v[168:171], v[32:35]
	v_mfma_f32_16x16x32_bf16 v[20:23], v[136:139], v[176:179], v[20:23]
	v_mfma_f32_16x16x32_bf16 v[16:19], v[144:147], v[176:179], v[16:19]
	v_mfma_f32_16x16x32_bf16 v[4:7], v[136:139], v[184:187], v[4:7]
	v_mfma_f32_16x16x32_bf16 v[0:3], v[144:147], v[184:187], v[0:3]
	v_mfma_f32_16x16x32_bf16 v[52:55], v[140:143], v[164:167], v[52:55]
	v_mfma_f32_16x16x32_bf16 v[48:51], v[156:159], v[164:167], v[48:51]
	v_mfma_f32_16x16x32_bf16 v[36:39], v[140:143], v[172:175], v[36:39]
	v_mfma_f32_16x16x32_bf16 v[32:35], v[156:159], v[172:175], v[32:35]
	v_mfma_f32_16x16x32_bf16 v[20:23], v[140:143], v[180:183], v[20:23]
	v_mfma_f32_16x16x32_bf16 v[16:19], v[156:159], v[180:183], v[16:19]
	v_mfma_f32_16x16x32_bf16 v[4:7], v[140:143], v[188:191], v[4:7]
	v_mfma_f32_16x16x32_bf16 v[0:3], v[156:159], v[188:191], v[0:3]
	s_barrier
	s_add_i32 s43, s43, 2
	s_add_u32 s34, s34, 0x100
	s_addc_u32 s42, s42, 0
	s_cmp_gt_u32 s43, 41
	s_mov_b64 s[16:17], s[20:21]
	s_cbranch_scc0 .LBB0_1031
